# speedup vs baseline: 1.2042x; 1.0039x over previous
.LBB0_241:
	ds_read_b128 v[156:159], v150
	ds_read_b128 v[160:163], v150 offset:1024
	ds_read_b128 v[164:167], v150 offset:2048
	ds_read_b128 v[168:171], v150 offset:3072
	s_add_u32 s42, s40, 0xfffc0080
	s_addc_u32 s43, s41, -1
	s_cmp_eq_u32 s70, 12
	s_cselect_b32 s45, s7, s43
	s_cselect_b32 s44, s31, s42
	s_cselect_b32 s43, s29, s69
	s_cselect_b32 s42, s39, s68
	s_mov_b32 m0, s63
	v_lshl_add_u64 v[144:145], s[40:41], 0, v[140:141]
	ds_read_b128 v[172:175], v148
	ds_read_b128 v[176:179], v148 offset:1024
	ds_read_b128 v[180:183], v148 offset:2048
	ds_read_b128 v[184:187], v148 offset:3072
	ds_read_b128 v[188:191], v148 offset:4096
	ds_read_b128 v[192:195], v148 offset:5120
	ds_read_b128 v[196:199], v148 offset:6144
	ds_read_b128 v[200:203], v148 offset:7168
	global_load_lds_dwordx4 v[144:145], off
	v_lshl_add_u64 v[144:145], s[40:41], 0, v[142:143]
	s_mov_b32 m0, s64
	s_nop 0
	global_load_lds_dwordx4 v[144:145], off
	s_waitcnt lgkmcnt(8)
	s_barrier
	s_waitcnt lgkmcnt(0)
	s_waitcnt lgkmcnt(0)
	v_mfma_f32_16x16x32_bf16 v[124:127], v[156:159], v[172:175], v[124:127]
	v_mfma_f32_16x16x32_bf16 v[120:123], v[164:167], v[172:175], v[120:123]
	v_mfma_f32_16x16x32_bf16 v[112:115], v[156:159], v[180:183], v[112:115]
	v_mfma_f32_16x16x32_bf16 v[104:107], v[164:167], v[180:183], v[104:107]
	v_mfma_f32_16x16x32_bf16 v[96:99], v[156:159], v[188:191], v[96:99]
	v_mfma_f32_16x16x32_bf16 v[88:91], v[164:167], v[188:191], v[88:91]
	v_mfma_f32_16x16x32_bf16 v[76:79], v[156:159], v[196:199], v[76:79]
	v_mfma_f32_16x16x32_bf16 v[72:75], v[164:167], v[196:199], v[72:75]
	v_mfma_f32_16x16x32_bf16 v[124:127], v[160:163], v[176:179], v[124:127]
	v_mfma_f32_16x16x32_bf16 v[120:123], v[168:171], v[176:179], v[120:123]
	v_mfma_f32_16x16x32_bf16 v[112:115], v[160:163], v[184:187], v[112:115]
	v_mfma_f32_16x16x32_bf16 v[104:107], v[168:171], v[184:187], v[104:107]
	v_mfma_f32_16x16x32_bf16 v[96:99], v[160:163], v[192:195], v[96:99]
	v_mfma_f32_16x16x32_bf16 v[88:91], v[168:171], v[192:195], v[88:91]
	v_mfma_f32_16x16x32_bf16 v[76:79], v[160:163], v[200:203], v[76:79]
	v_mfma_f32_16x16x32_bf16 v[72:75], v[168:171], v[200:203], v[72:75]
	s_barrier
	s_mov_b32 m0, s47
	v_lshl_add_u64 v[144:145], s[42:43], 0, v[132:133]
	ds_read_b128 v[204:207], v151
	ds_read_b128 v[208:211], v151 offset:1024
	ds_read_b128 v[212:215], v151 offset:2048
	ds_read_b128 v[216:219], v151 offset:3072
	global_load_lds_dwordx4 v[144:145], off
	v_lshl_add_u64 v[220:221], s[42:43], 0, v[128:129]
	s_mov_b32 m0, s48
	s_nop 0
	global_load_lds_dwordx4 v[220:221], off
	s_barrier
	s_waitcnt lgkmcnt(0)
	s_waitcnt lgkmcnt(0)
	v_mfma_f32_16x16x32_bf16 v[116:119], v[204:207], v[172:175], v[116:119]
	v_mfma_f32_16x16x32_bf16 v[108:111], v[212:215], v[172:175], v[108:111]
	v_mfma_f32_16x16x32_bf16 v[100:103], v[204:207], v[180:183], v[100:103]
	v_mfma_f32_16x16x32_bf16 v[92:95], v[212:215], v[180:183], v[92:95]
	v_mfma_f32_16x16x32_bf16 v[84:87], v[204:207], v[188:191], v[84:87]
	v_mfma_f32_16x16x32_bf16 v[80:83], v[212:215], v[188:191], v[80:83]
	v_mfma_f32_16x16x32_bf16 v[68:71], v[204:207], v[196:199], v[68:71]
	v_mfma_f32_16x16x32_bf16 v[64:67], v[212:215], v[196:199], v[64:67]
	v_mfma_f32_16x16x32_bf16 v[116:119], v[208:211], v[176:179], v[116:119]
	v_mfma_f32_16x16x32_bf16 v[108:111], v[216:219], v[176:179], v[108:111]
	v_mfma_f32_16x16x32_bf16 v[100:103], v[208:211], v[184:187], v[100:103]
	v_mfma_f32_16x16x32_bf16 v[92:95], v[216:219], v[184:187], v[92:95]
	v_mfma_f32_16x16x32_bf16 v[84:87], v[208:211], v[192:195], v[84:87]
	v_mfma_f32_16x16x32_bf16 v[80:83], v[216:219], v[192:195], v[80:83]
	v_mfma_f32_16x16x32_bf16 v[68:71], v[208:211], v[200:203], v[68:71]
	v_mfma_f32_16x16x32_bf16 v[64:67], v[216:219], v[200:203], v[64:67]
	s_mov_b32 m0, s46
	v_lshl_add_u64 v[222:223], s[44:45], 0, v[134:135]
	s_barrier
	ds_read_b128 v[172:175], v148 offset:16384
	ds_read_b128 v[176:179], v148 offset:17408
	ds_read_b128 v[180:183], v148 offset:18432
	ds_read_b128 v[184:187], v148 offset:19456
	ds_read_b128 v[188:191], v148 offset:20480
	ds_read_b128 v[192:195], v148 offset:21504
	ds_read_b128 v[196:199], v148 offset:22528
	ds_read_b128 v[200:203], v148 offset:23552
	global_load_lds_dwordx4 v[222:223], off
	v_lshl_add_u64 v[224:225], s[44:45], 0, v[130:131]
	s_mov_b32 m0, s49
	s_nop 0
	global_load_lds_dwordx4 v[224:225], off
	s_barrier
	s_waitcnt lgkmcnt(0)
	s_waitcnt lgkmcnt(0)
	v_mfma_f32_16x16x32_bf16 v[60:63], v[156:159], v[172:175], v[60:63]
	v_mfma_f32_16x16x32_bf16 v[56:59], v[164:167], v[172:175], v[56:59]
	v_mfma_f32_16x16x32_bf16 v[48:51], v[156:159], v[180:183], v[48:51]
	v_mfma_f32_16x16x32_bf16 v[40:43], v[164:167], v[180:183], v[40:43]
	v_mfma_f32_16x16x32_bf16 v[32:35], v[156:159], v[188:191], v[32:35]
	v_mfma_f32_16x16x32_bf16 v[24:27], v[164:167], v[188:191], v[24:27]
	v_mfma_f32_16x16x32_bf16 v[12:15], v[156:159], v[196:199], v[12:15]
	v_mfma_f32_16x16x32_bf16 v[8:11], v[164:167], v[196:199], v[8:11]
	v_mfma_f32_16x16x32_bf16 v[60:63], v[160:163], v[176:179], v[60:63]
	v_mfma_f32_16x16x32_bf16 v[56:59], v[168:171], v[176:179], v[56:59]
	v_mfma_f32_16x16x32_bf16 v[48:51], v[160:163], v[184:187], v[48:51]
	v_mfma_f32_16x16x32_bf16 v[40:43], v[168:171], v[184:187], v[40:43]
	v_mfma_f32_16x16x32_bf16 v[32:35], v[160:163], v[192:195], v[32:35]
	v_mfma_f32_16x16x32_bf16 v[24:27], v[168:171], v[192:195], v[24:27]
	v_mfma_f32_16x16x32_bf16 v[12:15], v[160:163], v[200:203], v[12:15]
	v_mfma_f32_16x16x32_bf16 v[8:11], v[168:171], v[200:203], v[8:11]
	s_barrier
	s_add_u32 s72, s42, 0x40000
	s_addc_u32 s73, s43, 0
	s_mov_b32 m0, s50
	v_lshl_add_u64 v[156:157], s[72:73], 0, v[132:133]
	global_load_lds_dwordx4 v[156:157], off
	v_lshl_add_u64 v[156:157], s[72:73], 0, v[128:129]
	s_mov_b32 m0, s51
	s_nop 0
	global_load_lds_dwordx4 v[156:157], off
	s_waitcnt vmcnt(6)
	s_barrier
	v_mfma_f32_16x16x32_bf16 v[52:55], v[204:207], v[172:175], v[52:55]
	v_mfma_f32_16x16x32_bf16 v[44:47], v[212:215], v[172:175], v[44:47]
	v_mfma_f32_16x16x32_bf16 v[36:39], v[204:207], v[180:183], v[36:39]
	v_mfma_f32_16x16x32_bf16 v[28:31], v[212:215], v[180:183], v[28:31]
	v_mfma_f32_16x16x32_bf16 v[20:23], v[204:207], v[188:191], v[20:23]
	v_mfma_f32_16x16x32_bf16 v[16:19], v[212:215], v[188:191], v[16:19]
	v_mfma_f32_16x16x32_bf16 v[4:7], v[204:207], v[196:199], v[4:7]
	v_mfma_f32_16x16x32_bf16 v[0:3], v[212:215], v[196:199], v[0:3]
	v_mfma_f32_16x16x32_bf16 v[52:55], v[208:211], v[176:179], v[52:55]
	v_mfma_f32_16x16x32_bf16 v[44:47], v[216:219], v[176:179], v[44:47]
	v_mfma_f32_16x16x32_bf16 v[36:39], v[208:211], v[184:187], v[36:39]
	v_mfma_f32_16x16x32_bf16 v[28:31], v[216:219], v[184:187], v[28:31]
	v_mfma_f32_16x16x32_bf16 v[20:23], v[208:211], v[192:195], v[20:23]
	v_mfma_f32_16x16x32_bf16 v[16:19], v[216:219], v[192:195], v[16:19]
	v_mfma_f32_16x16x32_bf16 v[4:7], v[208:211], v[200:203], v[4:7]
	v_mfma_f32_16x16x32_bf16 v[0:3], v[216:219], v[200:203], v[0:3]
	s_barrier
	ds_read_b128 v[156:159], v152
	ds_read_b128 v[160:163], v152 offset:1024
	ds_read_b128 v[164:167], v152 offset:2048
	ds_read_b128 v[168:171], v152 offset:3072
	s_add_u32 s44, s44, 0x40000
	s_addc_u32 s45, s45, 0
	s_mov_b32 m0, s52
	v_lshl_add_u64 v[204:205], s[44:45], 0, v[134:135]
	ds_read_b128 v[172:175], v148 offset:32768
	ds_read_b128 v[176:179], v148 offset:33792
	ds_read_b128 v[180:183], v148 offset:34816
	ds_read_b128 v[184:187], v148 offset:35840
	ds_read_b128 v[188:191], v148 offset:36864
	ds_read_b128 v[192:195], v148 offset:37888
	ds_read_b128 v[196:199], v148 offset:38912
	ds_read_b128 v[200:203], v148 offset:39936
	global_load_lds_dwordx4 v[204:205], off
	v_lshl_add_u64 v[204:205], s[44:45], 0, v[130:131]
	s_mov_b32 m0, s53
	s_nop 0
	global_load_lds_dwordx4 v[204:205], off
	s_waitcnt lgkmcnt(8)
	s_barrier
	s_waitcnt lgkmcnt(0)
	s_waitcnt lgkmcnt(0)
	v_mfma_f32_16x16x32_bf16 v[124:127], v[156:159], v[172:175], v[124:127]
	v_mfma_f32_16x16x32_bf16 v[120:123], v[164:167], v[172:175], v[120:123]
	v_mfma_f32_16x16x32_bf16 v[112:115], v[156:159], v[180:183], v[112:115]
	v_mfma_f32_16x16x32_bf16 v[104:107], v[164:167], v[180:183], v[104:107]
	v_mfma_f32_16x16x32_bf16 v[96:99], v[156:159], v[188:191], v[96:99]
	v_mfma_f32_16x16x32_bf16 v[88:91], v[164:167], v[188:191], v[88:91]
	v_mfma_f32_16x16x32_bf16 v[76:79], v[156:159], v[196:199], v[76:79]
	v_mfma_f32_16x16x32_bf16 v[72:75], v[164:167], v[196:199], v[72:75]
	v_mfma_f32_16x16x32_bf16 v[124:127], v[160:163], v[176:179], v[124:127]
	v_mfma_f32_16x16x32_bf16 v[120:123], v[168:171], v[176:179], v[120:123]
	v_mfma_f32_16x16x32_bf16 v[112:115], v[160:163], v[184:187], v[112:115]
	v_mfma_f32_16x16x32_bf16 v[104:107], v[168:171], v[184:187], v[104:107]
	v_mfma_f32_16x16x32_bf16 v[96:99], v[160:163], v[192:195], v[96:99]
	v_mfma_f32_16x16x32_bf16 v[88:91], v[168:171], v[192:195], v[88:91]
	v_mfma_f32_16x16x32_bf16 v[76:79], v[160:163], v[200:203], v[76:79]
	v_mfma_f32_16x16x32_bf16 v[72:75], v[168:171], v[200:203], v[72:75]
	s_barrier
	s_mov_b32 m0, s57
	v_lshl_add_u64 v[144:145], v[144:145], 0, s[22:23]
	ds_read_b128 v[204:207], v153
	ds_read_b128 v[208:211], v153 offset:1024
	ds_read_b128 v[212:215], v153 offset:2048
	ds_read_b128 v[216:219], v153 offset:3072
	global_load_lds_dwordx4 v[144:145], off
	v_lshl_add_u64 v[144:145], v[220:221], 0, s[22:23]
	s_mov_b32 m0, s58
	s_nop 0
	global_load_lds_dwordx4 v[144:145], off
	s_barrier
	s_waitcnt lgkmcnt(0)
	s_waitcnt lgkmcnt(0)
	v_mfma_f32_16x16x32_bf16 v[116:119], v[204:207], v[172:175], v[116:119]
	v_mfma_f32_16x16x32_bf16 v[108:111], v[212:215], v[172:175], v[108:111]
	v_mfma_f32_16x16x32_bf16 v[100:103], v[204:207], v[180:183], v[100:103]
	v_mfma_f32_16x16x32_bf16 v[92:95], v[212:215], v[180:183], v[92:95]
	v_mfma_f32_16x16x32_bf16 v[84:87], v[204:207], v[188:191], v[84:87]
	v_mfma_f32_16x16x32_bf16 v[80:83], v[212:215], v[188:191], v[80:83]
	v_mfma_f32_16x16x32_bf16 v[68:71], v[204:207], v[196:199], v[68:71]
	v_mfma_f32_16x16x32_bf16 v[64:67], v[212:215], v[196:199], v[64:67]
	v_mfma_f32_16x16x32_bf16 v[116:119], v[208:211], v[176:179], v[116:119]
	v_mfma_f32_16x16x32_bf16 v[108:111], v[216:219], v[176:179], v[108:111]
	v_mfma_f32_16x16x32_bf16 v[100:103], v[208:211], v[184:187], v[100:103]
	v_mfma_f32_16x16x32_bf16 v[92:95], v[216:219], v[184:187], v[92:95]
	v_mfma_f32_16x16x32_bf16 v[84:87], v[208:211], v[192:195], v[84:87]
	v_mfma_f32_16x16x32_bf16 v[80:83], v[216:219], v[192:195], v[80:83]
	v_mfma_f32_16x16x32_bf16 v[68:71], v[208:211], v[200:203], v[68:71]
	v_mfma_f32_16x16x32_bf16 v[64:67], v[216:219], v[200:203], v[64:67]
	s_mov_b32 m0, s59
	v_lshl_add_u64 v[144:145], v[222:223], 0, s[22:23]
	s_barrier
	ds_read_b128 v[172:175], v148 offset:49152
	ds_read_b128 v[176:179], v148 offset:50176
	ds_read_b128 v[180:183], v148 offset:51200
	ds_read_b128 v[184:187], v148 offset:52224
	ds_read_b128 v[188:191], v148 offset:53248
	ds_read_b128 v[192:195], v148 offset:54272
	ds_read_b128 v[196:199], v148 offset:55296
	ds_read_b128 v[200:203], v148 offset:56320
	global_load_lds_dwordx4 v[144:145], off
	v_lshl_add_u64 v[144:145], v[224:225], 0, s[22:23]
	s_mov_b32 m0, s60
	s_nop 0
	global_load_lds_dwordx4 v[144:145], off
	s_barrier
	s_waitcnt lgkmcnt(0)
	s_waitcnt lgkmcnt(0)
	v_mfma_f32_16x16x32_bf16 v[60:63], v[156:159], v[172:175], v[60:63]
	v_mfma_f32_16x16x32_bf16 v[56:59], v[164:167], v[172:175], v[56:59]
	v_mfma_f32_16x16x32_bf16 v[48:51], v[156:159], v[180:183], v[48:51]
	v_mfma_f32_16x16x32_bf16 v[40:43], v[164:167], v[180:183], v[40:43]
	v_mfma_f32_16x16x32_bf16 v[32:35], v[156:159], v[188:191], v[32:35]
	v_mfma_f32_16x16x32_bf16 v[24:27], v[164:167], v[188:191], v[24:27]
	v_mfma_f32_16x16x32_bf16 v[12:15], v[156:159], v[196:199], v[12:15]
	v_mfma_f32_16x16x32_bf16 v[8:11], v[164:167], v[196:199], v[8:11]
	v_mfma_f32_16x16x32_bf16 v[60:63], v[160:163], v[176:179], v[60:63]
	v_mfma_f32_16x16x32_bf16 v[56:59], v[168:171], v[176:179], v[56:59]
	v_mfma_f32_16x16x32_bf16 v[48:51], v[160:163], v[184:187], v[48:51]
	v_mfma_f32_16x16x32_bf16 v[40:43], v[168:171], v[184:187], v[40:43]
	v_mfma_f32_16x16x32_bf16 v[32:35], v[160:163], v[192:195], v[32:35]
	v_mfma_f32_16x16x32_bf16 v[24:27], v[168:171], v[192:195], v[24:27]
	v_mfma_f32_16x16x32_bf16 v[12:15], v[160:163], v[200:203], v[12:15]
	v_mfma_f32_16x16x32_bf16 v[8:11], v[168:171], v[200:203], v[8:11]
	s_barrier
	s_add_u32 s42, s42, 0x40080
	s_addc_u32 s43, s43, 0
	s_mov_b32 m0, s61
	v_lshl_add_u64 v[144:145], s[42:43], 0, v[132:133]
	global_load_lds_dwordx4 v[144:145], off
	v_lshl_add_u64 v[144:145], s[42:43], 0, v[128:129]
	s_mov_b32 m0, s62
	s_nop 0
	global_load_lds_dwordx4 v[144:145], off
	s_waitcnt vmcnt(6)
	s_barrier
	v_mfma_f32_16x16x32_bf16 v[52:55], v[204:207], v[172:175], v[52:55]
	v_mfma_f32_16x16x32_bf16 v[44:47], v[212:215], v[172:175], v[44:47]
	v_mfma_f32_16x16x32_bf16 v[36:39], v[204:207], v[180:183], v[36:39]
	v_mfma_f32_16x16x32_bf16 v[28:31], v[212:215], v[180:183], v[28:31]
	v_mfma_f32_16x16x32_bf16 v[20:23], v[204:207], v[188:191], v[20:23]
	v_mfma_f32_16x16x32_bf16 v[16:19], v[212:215], v[188:191], v[16:19]
	v_mfma_f32_16x16x32_bf16 v[4:7], v[204:207], v[196:199], v[4:7]
	v_mfma_f32_16x16x32_bf16 v[0:3], v[212:215], v[196:199], v[0:3]
	v_mfma_f32_16x16x32_bf16 v[52:55], v[208:211], v[176:179], v[52:55]
	v_mfma_f32_16x16x32_bf16 v[44:47], v[216:219], v[176:179], v[44:47]
	v_mfma_f32_16x16x32_bf16 v[36:39], v[208:211], v[184:187], v[36:39]
	v_mfma_f32_16x16x32_bf16 v[28:31], v[216:219], v[184:187], v[28:31]
	v_mfma_f32_16x16x32_bf16 v[20:23], v[208:211], v[192:195], v[20:23]
	v_mfma_f32_16x16x32_bf16 v[16:19], v[216:219], v[192:195], v[16:19]
	v_mfma_f32_16x16x32_bf16 v[4:7], v[208:211], v[200:203], v[4:7]
	v_mfma_f32_16x16x32_bf16 v[0:3], v[216:219], v[200:203], v[0:3]
	s_add_i32 s70, s70, 2
	s_add_u32 s40, s40, 0x100
	s_addc_u32 s41, s41, 0
	s_add_u32 s68, s68, 0x100
	s_addc_u32 s69, s69, 0
	s_cmp_gt_u32 s70, 13
	s_barrier
	s_cbranch_scc0 .LBB0_241
	s_lshl_b32 s29, s38, 8
	s_add_i32 s29, s29, s56
	v_cvt_pk_bf16_f32 v124, v124, v125
	v_or_b32_e32 v155, s29, v147
	v_lshl_add_u32 v144, s6, 8, v149
	v_lshlrev_b32_e32 v156, 10, v155
	v_cvt_pk_bf16_f32 v125, v126, v127
	v_cvt_pk_bf16_f32 v126, v120, v121
	v_add_u32_e32 v136, v156, v144
	v_cvt_pk_bf16_f32 v116, v116, v117
	v_cvt_pk_bf16_f32 v127, v122, v123
	v_lshl_add_u64 v[120:121], v[136:137], 1, s[10:11]
	global_store_dwordx4 v[120:121], v[124:127], off
	v_add_u32_e32 v120, 0x80, v144
	v_cvt_pk_bf16_f32 v117, v118, v119
	v_cvt_pk_bf16_f32 v118, v108, v109
	v_add_u32_e32 v136, v156, v120
	v_cvt_pk_bf16_f32 v119, v110, v111
	v_lshl_add_u64 v[108:109], v[136:137], 1, s[10:11]
	global_store_dwordx4 v[108:109], v[116:119], off
	v_cvt_pk_bf16_f32 v108, v112, v113
	v_cvt_pk_bf16_f32 v100, v100, v101
	v_or_b32_e32 v116, 0x4000, v156
	v_cvt_pk_bf16_f32 v109, v114, v115
	v_cvt_pk_bf16_f32 v110, v104, v105
	v_add_u32_e32 v136, v116, v144
	v_cvt_pk_bf16_f32 v101, v102, v103
	v_cvt_pk_bf16_f32 v102, v92, v93
	v_cvt_pk_bf16_f32 v111, v106, v107
	v_lshl_add_u64 v[104:105], v[136:137], 1, s[10:11]
	v_add_u32_e32 v136, v116, v120
	v_cvt_pk_bf16_f32 v103, v94, v95
	v_lshl_add_u64 v[92:93], v[136:137], 1, s[10:11]
	global_store_dwordx4 v[104:105], v[108:111], off
	global_store_dwordx4 v[92:93], v[100:103], off
	v_cvt_pk_bf16_f32 v92, v96, v97
	v_cvt_pk_bf16_f32 v84, v84, v85
	v_or_b32_e32 v100, 0x8000, v156
	v_cvt_pk_bf16_f32 v93, v98, v99
	v_cvt_pk_bf16_f32 v94, v88, v89
	v_add_u32_e32 v136, v100, v144
	v_cvt_pk_bf16_f32 v85, v86, v87
	v_cvt_pk_bf16_f32 v86, v80, v81
	v_cvt_pk_bf16_f32 v95, v90, v91
	v_lshl_add_u64 v[88:89], v[136:137], 1, s[10:11]
	v_add_u32_e32 v136, v100, v120
	v_cvt_pk_bf16_f32 v87, v82, v83
	v_lshl_add_u64 v[80:81], v[136:137], 1, s[10:11]
	global_store_dwordx4 v[88:89], v[92:95], off
	global_store_dwordx4 v[80:81], v[84:87], off
	s_add_i32 s6, s29, 0xfff0000
	s_lshr_b32 s6, s6, 6
	s_ashr_i32 s7, s29, 12
	v_cvt_pk_bf16_f32 v84, v76, v77
	s_mul_i32 s31, s7, 3
	v_or_b32_e32 v82, 48, v155
	v_mad_u64_u32 v[80:81], s[6:7], s6, 3, v[138:139]
	v_bitop3_b32 v90, v155, s65, 48 bitop3:0xc8
	v_cvt_pk_bf16_f32 v85, v78, v79
	v_lshlrev_b32_e32 v83, 10, v82
	v_lshl_add_u32 v136, v80, 10, v154
	v_add_lshl_u32 v80, v90, s31, 10
	v_cvt_pk_bf16_f32 v86, v72, v73
	v_ashrrev_i32_e32 v81, 31, v80
	v_cvt_pk_bf16_f32 v87, v74, v75
	v_add_u32_e32 v88, v83, v144
	v_mov_b32_e32 v89, v137
	v_lshl_add_u64 v[88:89], v[88:89], 1, s[10:11]
	v_lshl_add_u64 v[80:81], v[80:81], 2, s[18:19]
	global_store_dwordx4 v[88:89], v[84:87], off
	v_lshl_add_u64 v[80:81], v[80:81], 0, s[24:25]
	v_cmp_gt_i32_e32 vcc, s55, v82
	v_lshl_add_u64 v[84:85], v[136:137], 2, s[20:21]
	v_cmp_lt_u32_e64 s[6:7], s66, v90
	v_cndmask_b32_e32 v80, v84, v80, vcc
	v_cndmask_b32_e64 v82, 0, 1, s[4:5]
	v_cndmask_b32_e64 v84, 0, 1, s[6:7]
	v_cndmask_b32_e32 v84, v82, v84, vcc
	v_cndmask_b32_e32 v81, v85, v81, vcc
	v_and_b32_e32 v84, 1, v84
	v_cmp_eq_u32_e32 vcc, 1, v84
	v_cmp_ne_u64_e64 s[6:7], 0, v[80:81]
	s_and_b64 s[6:7], vcc, s[6:7]
	v_ashrrev_i32_e32 v145, 31, v144
	s_and_saveexec_b64 s[38:39], s[6:7]
	s_cbranch_execz .LBB0_244
	v_lshl_add_u64 v[84:85], v[144:145], 2, v[80:81]
	global_store_dwordx4 v[84:85], v[76:79], off
	global_store_dwordx4 v[84:85], v[72:75], off offset:16

.LBB0_264:
	ds_read_b128 v[158:161], v151
	ds_read_b128 v[162:165], v151 offset:1024
	ds_read_b128 v[166:169], v151 offset:2048
	ds_read_b128 v[170:173], v151 offset:3072
	s_add_u32 s34, s30, 0xfffc0080
	s_addc_u32 s35, s31, -1
	s_cmp_eq_u32 s60, 12
	s_cselect_b32 s37, s5, s35
	s_cselect_b32 s36, s23, s34
	s_cselect_b32 s35, s21, s59
	s_cselect_b32 s34, s29, s58
	s_mov_b32 m0, s54
	v_lshl_add_u64 v[206:207], s[30:31], 0, v[138:139]
	ds_read_b128 v[174:177], v144
	ds_read_b128 v[178:181], v144 offset:1024
	ds_read_b128 v[182:185], v144 offset:2048
	ds_read_b128 v[186:189], v144 offset:3072
	ds_read_b128 v[190:193], v144 offset:4096
	ds_read_b128 v[194:197], v144 offset:5120
	ds_read_b128 v[198:201], v144 offset:6144
	ds_read_b128 v[202:205], v144 offset:7168
	global_load_lds_dwordx4 v[206:207], off
	v_lshl_add_u64 v[206:207], s[30:31], 0, v[140:141]
	s_mov_b32 m0, s55
	s_nop 0
	global_load_lds_dwordx4 v[206:207], off
	s_waitcnt lgkmcnt(8)
	s_barrier
	s_waitcnt lgkmcnt(0)
	s_waitcnt lgkmcnt(0)
	v_mfma_f32_16x16x32_bf16 v[124:127], v[158:161], v[174:177], v[124:127]
	v_mfma_f32_16x16x32_bf16 v[120:123], v[166:169], v[174:177], v[120:123]
	v_mfma_f32_16x16x32_bf16 v[108:111], v[158:161], v[182:185], v[108:111]
	v_mfma_f32_16x16x32_bf16 v[104:107], v[166:169], v[182:185], v[104:107]
	v_mfma_f32_16x16x32_bf16 v[92:95], v[158:161], v[190:193], v[92:95]
	v_mfma_f32_16x16x32_bf16 v[88:91], v[166:169], v[190:193], v[88:91]
	v_mfma_f32_16x16x32_bf16 v[76:79], v[158:161], v[198:201], v[76:79]
	v_mfma_f32_16x16x32_bf16 v[72:75], v[166:169], v[198:201], v[72:75]
	v_mfma_f32_16x16x32_bf16 v[124:127], v[162:165], v[178:181], v[124:127]
	v_mfma_f32_16x16x32_bf16 v[120:123], v[170:173], v[178:181], v[120:123]
	v_mfma_f32_16x16x32_bf16 v[108:111], v[162:165], v[186:189], v[108:111]
	v_mfma_f32_16x16x32_bf16 v[104:107], v[170:173], v[186:189], v[104:107]
	v_mfma_f32_16x16x32_bf16 v[92:95], v[162:165], v[194:197], v[92:95]
	v_mfma_f32_16x16x32_bf16 v[88:91], v[170:173], v[194:197], v[88:91]
	v_mfma_f32_16x16x32_bf16 v[76:79], v[162:165], v[202:205], v[76:79]
	v_mfma_f32_16x16x32_bf16 v[72:75], v[170:173], v[202:205], v[72:75]
	s_barrier
	s_mov_b32 m0, s40
	v_lshl_add_u64 v[222:223], s[34:35], 0, v[130:131]
	ds_read_b128 v[206:209], v152
	ds_read_b128 v[210:213], v152 offset:1024
	ds_read_b128 v[214:217], v152 offset:2048
	ds_read_b128 v[218:221], v152 offset:3072
	global_load_lds_dwordx4 v[222:223], off
	v_lshl_add_u64 v[224:225], s[34:35], 0, v[134:135]
	s_mov_b32 m0, s41
	s_nop 0
	global_load_lds_dwordx4 v[224:225], off
	s_barrier
	s_waitcnt lgkmcnt(0)
	s_waitcnt lgkmcnt(0)
	v_mfma_f32_16x16x32_bf16 v[116:119], v[206:209], v[174:177], v[116:119]
	v_mfma_f32_16x16x32_bf16 v[112:115], v[214:217], v[174:177], v[112:115]
	v_mfma_f32_16x16x32_bf16 v[100:103], v[206:209], v[182:185], v[100:103]
	v_mfma_f32_16x16x32_bf16 v[96:99], v[214:217], v[182:185], v[96:99]
	v_mfma_f32_16x16x32_bf16 v[84:87], v[206:209], v[190:193], v[84:87]
	v_mfma_f32_16x16x32_bf16 v[80:83], v[214:217], v[190:193], v[80:83]
	v_mfma_f32_16x16x32_bf16 v[68:71], v[206:209], v[198:201], v[68:71]
	v_mfma_f32_16x16x32_bf16 v[64:67], v[214:217], v[198:201], v[64:67]
	v_mfma_f32_16x16x32_bf16 v[116:119], v[210:213], v[178:181], v[116:119]
	v_mfma_f32_16x16x32_bf16 v[112:115], v[218:221], v[178:181], v[112:115]
	v_mfma_f32_16x16x32_bf16 v[100:103], v[210:213], v[186:189], v[100:103]
	v_mfma_f32_16x16x32_bf16 v[96:99], v[218:221], v[186:189], v[96:99]
	v_mfma_f32_16x16x32_bf16 v[84:87], v[210:213], v[194:197], v[84:87]
	v_mfma_f32_16x16x32_bf16 v[80:83], v[218:221], v[194:197], v[80:83]
	v_mfma_f32_16x16x32_bf16 v[68:71], v[210:213], v[202:205], v[68:71]
	v_mfma_f32_16x16x32_bf16 v[64:67], v[218:221], v[202:205], v[64:67]
	s_mov_b32 m0, s3
	v_lshl_add_u64 v[226:227], s[36:37], 0, v[128:129]
	s_barrier
	ds_read_b128 v[174:177], v144 offset:16384
	ds_read_b128 v[178:181], v144 offset:17408
	ds_read_b128 v[182:185], v144 offset:18432
	ds_read_b128 v[186:189], v144 offset:19456
	ds_read_b128 v[190:193], v144 offset:20480
	ds_read_b128 v[194:197], v144 offset:21504
	ds_read_b128 v[198:201], v144 offset:22528
	ds_read_b128 v[202:205], v144 offset:23552
	global_load_lds_dwordx4 v[226:227], off
	v_lshl_add_u64 v[228:229], s[36:37], 0, v[132:133]
	s_mov_b32 m0, s42
	s_nop 0
	global_load_lds_dwordx4 v[228:229], off
	s_barrier
	s_waitcnt lgkmcnt(0)
	s_waitcnt lgkmcnt(0)
	v_mfma_f32_16x16x32_bf16 v[60:63], v[158:161], v[174:177], v[60:63]
	v_mfma_f32_16x16x32_bf16 v[56:59], v[166:169], v[174:177], v[56:59]
	v_mfma_f32_16x16x32_bf16 v[44:47], v[158:161], v[182:185], v[44:47]
	v_mfma_f32_16x16x32_bf16 v[40:43], v[166:169], v[182:185], v[40:43]
	v_mfma_f32_16x16x32_bf16 v[28:31], v[158:161], v[190:193], v[28:31]
	v_mfma_f32_16x16x32_bf16 v[24:27], v[166:169], v[190:193], v[24:27]
	v_mfma_f32_16x16x32_bf16 v[12:15], v[158:161], v[198:201], v[12:15]
	v_mfma_f32_16x16x32_bf16 v[8:11], v[166:169], v[198:201], v[8:11]
	v_mfma_f32_16x16x32_bf16 v[60:63], v[162:165], v[178:181], v[60:63]
	v_mfma_f32_16x16x32_bf16 v[56:59], v[170:173], v[178:181], v[56:59]
	v_mfma_f32_16x16x32_bf16 v[44:47], v[162:165], v[186:189], v[44:47]
	v_mfma_f32_16x16x32_bf16 v[40:43], v[170:173], v[186:189], v[40:43]
	v_mfma_f32_16x16x32_bf16 v[28:31], v[162:165], v[194:197], v[28:31]
	v_mfma_f32_16x16x32_bf16 v[24:27], v[170:173], v[194:197], v[24:27]
	v_mfma_f32_16x16x32_bf16 v[12:15], v[162:165], v[202:205], v[12:15]
	v_mfma_f32_16x16x32_bf16 v[8:11], v[170:173], v[202:205], v[8:11]
	s_barrier
	s_add_u32 s62, s34, 0x40000
	s_addc_u32 s63, s35, 0
	s_mov_b32 m0, s43
	v_lshl_add_u64 v[158:159], s[62:63], 0, v[130:131]
	global_load_lds_dwordx4 v[158:159], off
	v_lshl_add_u64 v[158:159], s[62:63], 0, v[134:135]
	s_mov_b32 m0, s44
	s_nop 0
	global_load_lds_dwordx4 v[158:159], off
	s_waitcnt vmcnt(6)
	s_barrier
	v_mfma_f32_16x16x32_bf16 v[52:55], v[206:209], v[174:177], v[52:55]
	v_mfma_f32_16x16x32_bf16 v[48:51], v[214:217], v[174:177], v[48:51]
	v_mfma_f32_16x16x32_bf16 v[36:39], v[206:209], v[182:185], v[36:39]
	v_mfma_f32_16x16x32_bf16 v[32:35], v[214:217], v[182:185], v[32:35]
	v_mfma_f32_16x16x32_bf16 v[20:23], v[206:209], v[190:193], v[20:23]
	v_mfma_f32_16x16x32_bf16 v[16:19], v[214:217], v[190:193], v[16:19]
	v_mfma_f32_16x16x32_bf16 v[4:7], v[206:209], v[198:201], v[4:7]
	v_mfma_f32_16x16x32_bf16 v[0:3], v[214:217], v[198:201], v[0:3]
	v_mfma_f32_16x16x32_bf16 v[52:55], v[210:213], v[178:181], v[52:55]
	v_mfma_f32_16x16x32_bf16 v[48:51], v[218:221], v[178:181], v[48:51]
	v_mfma_f32_16x16x32_bf16 v[36:39], v[210:213], v[186:189], v[36:39]
	v_mfma_f32_16x16x32_bf16 v[32:35], v[218:221], v[186:189], v[32:35]
	v_mfma_f32_16x16x32_bf16 v[20:23], v[210:213], v[194:197], v[20:23]
	v_mfma_f32_16x16x32_bf16 v[16:19], v[218:221], v[194:197], v[16:19]
	v_mfma_f32_16x16x32_bf16 v[4:7], v[210:213], v[202:205], v[4:7]
	v_mfma_f32_16x16x32_bf16 v[0:3], v[218:221], v[202:205], v[0:3]
	s_barrier
	ds_read_b128 v[158:161], v153
	ds_read_b128 v[162:165], v153 offset:1024
	ds_read_b128 v[166:169], v153 offset:2048
	ds_read_b128 v[170:173], v153 offset:3072
	s_add_u32 s36, s36, 0x40000
	s_addc_u32 s37, s37, 0
	s_mov_b32 m0, s45
	v_lshl_add_u64 v[206:207], s[36:37], 0, v[128:129]
	ds_read_b128 v[174:177], v144 offset:32768
	ds_read_b128 v[178:181], v144 offset:33792
	ds_read_b128 v[182:185], v144 offset:34816
	ds_read_b128 v[186:189], v144 offset:35840
	ds_read_b128 v[190:193], v144 offset:36864
	ds_read_b128 v[194:197], v144 offset:37888
	ds_read_b128 v[198:201], v144 offset:38912
	ds_read_b128 v[202:205], v144 offset:39936
	global_load_lds_dwordx4 v[206:207], off
	v_lshl_add_u64 v[206:207], s[36:37], 0, v[132:133]
	s_mov_b32 m0, s46
	s_nop 0
	global_load_lds_dwordx4 v[206:207], off
	s_waitcnt lgkmcnt(8)
	s_barrier
	s_waitcnt lgkmcnt(0)
	s_waitcnt lgkmcnt(0)
	v_mfma_f32_16x16x32_bf16 v[124:127], v[158:161], v[174:177], v[124:127]
	v_mfma_f32_16x16x32_bf16 v[120:123], v[166:169], v[174:177], v[120:123]
	v_mfma_f32_16x16x32_bf16 v[108:111], v[158:161], v[182:185], v[108:111]
	v_mfma_f32_16x16x32_bf16 v[104:107], v[166:169], v[182:185], v[104:107]
	v_mfma_f32_16x16x32_bf16 v[92:95], v[158:161], v[190:193], v[92:95]
	v_mfma_f32_16x16x32_bf16 v[88:91], v[166:169], v[190:193], v[88:91]
	v_mfma_f32_16x16x32_bf16 v[76:79], v[158:161], v[198:201], v[76:79]
	v_mfma_f32_16x16x32_bf16 v[72:75], v[166:169], v[198:201], v[72:75]
	v_mfma_f32_16x16x32_bf16 v[124:127], v[162:165], v[178:181], v[124:127]
	v_mfma_f32_16x16x32_bf16 v[120:123], v[170:173], v[178:181], v[120:123]
	v_mfma_f32_16x16x32_bf16 v[108:111], v[162:165], v[186:189], v[108:111]
	v_mfma_f32_16x16x32_bf16 v[104:107], v[170:173], v[186:189], v[104:107]
	v_mfma_f32_16x16x32_bf16 v[92:95], v[162:165], v[194:197], v[92:95]
	v_mfma_f32_16x16x32_bf16 v[88:91], v[170:173], v[194:197], v[88:91]
	v_mfma_f32_16x16x32_bf16 v[76:79], v[162:165], v[202:205], v[76:79]
	v_mfma_f32_16x16x32_bf16 v[72:75], v[170:173], v[202:205], v[72:75]
	s_barrier
	s_mov_b32 m0, s47
	v_lshl_add_u64 v[222:223], v[222:223], 0, s[6:7]
	ds_read_b128 v[206:209], v154
	ds_read_b128 v[210:213], v154 offset:1024
	ds_read_b128 v[214:217], v154 offset:2048
	ds_read_b128 v[218:221], v154 offset:3072
	global_load_lds_dwordx4 v[222:223], off
	v_lshl_add_u64 v[222:223], v[224:225], 0, s[6:7]
	s_mov_b32 m0, s48
	s_nop 0
	global_load_lds_dwordx4 v[222:223], off
	s_barrier
	s_waitcnt lgkmcnt(0)
	s_waitcnt lgkmcnt(0)
	v_mfma_f32_16x16x32_bf16 v[116:119], v[206:209], v[174:177], v[116:119]
	v_mfma_f32_16x16x32_bf16 v[112:115], v[214:217], v[174:177], v[112:115]
	v_mfma_f32_16x16x32_bf16 v[100:103], v[206:209], v[182:185], v[100:103]
	v_mfma_f32_16x16x32_bf16 v[96:99], v[214:217], v[182:185], v[96:99]
	v_mfma_f32_16x16x32_bf16 v[84:87], v[206:209], v[190:193], v[84:87]
	v_mfma_f32_16x16x32_bf16 v[80:83], v[214:217], v[190:193], v[80:83]
	v_mfma_f32_16x16x32_bf16 v[68:71], v[206:209], v[198:201], v[68:71]
	v_mfma_f32_16x16x32_bf16 v[64:67], v[214:217], v[198:201], v[64:67]
	v_mfma_f32_16x16x32_bf16 v[116:119], v[210:213], v[178:181], v[116:119]
	v_mfma_f32_16x16x32_bf16 v[112:115], v[218:221], v[178:181], v[112:115]
	v_mfma_f32_16x16x32_bf16 v[100:103], v[210:213], v[186:189], v[100:103]
	v_mfma_f32_16x16x32_bf16 v[96:99], v[218:221], v[186:189], v[96:99]
	v_mfma_f32_16x16x32_bf16 v[84:87], v[210:213], v[194:197], v[84:87]
	v_mfma_f32_16x16x32_bf16 v[80:83], v[218:221], v[194:197], v[80:83]
	v_mfma_f32_16x16x32_bf16 v[68:71], v[210:213], v[202:205], v[68:71]
	v_mfma_f32_16x16x32_bf16 v[64:67], v[218:221], v[202:205], v[64:67]
	s_mov_b32 m0, s49
	v_lshl_add_u64 v[222:223], v[226:227], 0, s[6:7]
	s_barrier
	ds_read_b128 v[174:177], v144 offset:49152
	ds_read_b128 v[178:181], v144 offset:50176
	ds_read_b128 v[182:185], v144 offset:51200
	ds_read_b128 v[186:189], v144 offset:52224
	ds_read_b128 v[190:193], v144 offset:53248
	ds_read_b128 v[194:197], v144 offset:54272
	ds_read_b128 v[198:201], v144 offset:55296
	ds_read_b128 v[202:205], v144 offset:56320
	global_load_lds_dwordx4 v[222:223], off
	v_lshl_add_u64 v[222:223], v[228:229], 0, s[6:7]
	s_mov_b32 m0, s50
	s_nop 0
	global_load_lds_dwordx4 v[222:223], off
	s_barrier
	s_waitcnt lgkmcnt(0)
	s_waitcnt lgkmcnt(0)
	v_mfma_f32_16x16x32_bf16 v[60:63], v[158:161], v[174:177], v[60:63]
	v_mfma_f32_16x16x32_bf16 v[56:59], v[166:169], v[174:177], v[56:59]
	v_mfma_f32_16x16x32_bf16 v[44:47], v[158:161], v[182:185], v[44:47]
	v_mfma_f32_16x16x32_bf16 v[40:43], v[166:169], v[182:185], v[40:43]
	v_mfma_f32_16x16x32_bf16 v[28:31], v[158:161], v[190:193], v[28:31]
	v_mfma_f32_16x16x32_bf16 v[24:27], v[166:169], v[190:193], v[24:27]
	v_mfma_f32_16x16x32_bf16 v[12:15], v[158:161], v[198:201], v[12:15]
	v_mfma_f32_16x16x32_bf16 v[8:11], v[166:169], v[198:201], v[8:11]
	v_mfma_f32_16x16x32_bf16 v[60:63], v[162:165], v[178:181], v[60:63]
	v_mfma_f32_16x16x32_bf16 v[56:59], v[170:173], v[178:181], v[56:59]
	v_mfma_f32_16x16x32_bf16 v[44:47], v[162:165], v[186:189], v[44:47]
	v_mfma_f32_16x16x32_bf16 v[40:43], v[170:173], v[186:189], v[40:43]
	v_mfma_f32_16x16x32_bf16 v[28:31], v[162:165], v[194:197], v[28:31]
	v_mfma_f32_16x16x32_bf16 v[24:27], v[170:173], v[194:197], v[24:27]
	v_mfma_f32_16x16x32_bf16 v[12:15], v[162:165], v[202:205], v[12:15]
	v_mfma_f32_16x16x32_bf16 v[8:11], v[170:173], v[202:205], v[8:11]
	s_barrier
	s_add_u32 s34, s34, 0x40080
	s_addc_u32 s35, s35, 0
	s_mov_b32 m0, s51
	v_lshl_add_u64 v[158:159], s[34:35], 0, v[130:131]
	global_load_lds_dwordx4 v[158:159], off
	v_lshl_add_u64 v[158:159], s[34:35], 0, v[134:135]
	s_mov_b32 m0, s52
	s_nop 0
	global_load_lds_dwordx4 v[158:159], off
	s_waitcnt vmcnt(6)
	s_barrier
	v_mfma_f32_16x16x32_bf16 v[52:55], v[206:209], v[174:177], v[52:55]
	v_mfma_f32_16x16x32_bf16 v[48:51], v[214:217], v[174:177], v[48:51]
	v_mfma_f32_16x16x32_bf16 v[36:39], v[206:209], v[182:185], v[36:39]
	v_mfma_f32_16x16x32_bf16 v[32:35], v[214:217], v[182:185], v[32:35]
	v_mfma_f32_16x16x32_bf16 v[20:23], v[206:209], v[190:193], v[20:23]
	v_mfma_f32_16x16x32_bf16 v[16:19], v[214:217], v[190:193], v[16:19]
	v_mfma_f32_16x16x32_bf16 v[4:7], v[206:209], v[198:201], v[4:7]
	v_mfma_f32_16x16x32_bf16 v[0:3], v[214:217], v[198:201], v[0:3]
	v_mfma_f32_16x16x32_bf16 v[52:55], v[210:213], v[178:181], v[52:55]
	v_mfma_f32_16x16x32_bf16 v[48:51], v[218:221], v[178:181], v[48:51]
	v_mfma_f32_16x16x32_bf16 v[36:39], v[210:213], v[186:189], v[36:39]
	v_mfma_f32_16x16x32_bf16 v[32:35], v[218:221], v[186:189], v[32:35]
	v_mfma_f32_16x16x32_bf16 v[20:23], v[210:213], v[194:197], v[20:23]
	v_mfma_f32_16x16x32_bf16 v[16:19], v[218:221], v[194:197], v[16:19]
	v_mfma_f32_16x16x32_bf16 v[4:7], v[210:213], v[202:205], v[4:7]
	v_mfma_f32_16x16x32_bf16 v[0:3], v[218:221], v[202:205], v[0:3]
	s_add_i32 s60, s60, 2
	s_add_u32 s30, s30, 0x100
	s_addc_u32 s31, s31, 0
	s_add_u32 s58, s58, 0x100
	s_addc_u32 s59, s59, 0
	s_cmp_gt_u32 s60, 13
	s_barrier
	s_cbranch_scc0 .LBB0_264
	v_lshl_add_u32 v157, s28, 8, v150
	s_cmp_gt_i32 s4, 3
	s_mov_b64 s[28:29], -1
	s_cbranch_scc0 .LBB0_269
	s_and_saveexec_b64 s[28:29], s[16:17]
	s_cbranch_execz .LBB0_268
	v_lshlrev_b32_e32 v160, 3, v157
	v_or_b32_e32 v136, v160, v142
	v_lshl_add_u64 v[158:159], v[136:137], 2, s[14:15]
	v_add_u32_e32 v136, v160, v145
	global_store_dword v[158:159], v124, off
	global_store_dword v[158:159], v120, off offset:128
	global_store_dword v[158:159], v125, off offset:32
	global_store_dword v[158:159], v121, off offset:160
	global_store_dword v[158:159], v126, off offset:64
	global_store_dword v[158:159], v122, off offset:192
	global_store_dword v[158:159], v127, off offset:96
	global_store_dword v[158:159], v123, off offset:224
	v_lshl_add_u64 v[158:159], v[136:137], 2, s[14:15]
	v_add_u32_e32 v136, v147, v160
	global_store_dword v[158:159], v116, off
	global_store_dword v[158:159], v112, off offset:128
	v_lshl_add_u64 v[158:159], v[136:137], 2, s[14:15]
	v_add_u32_e32 v136, v160, v148
	global_store_dword v[158:159], v117, off
	global_store_dword v[158:159], v113, off offset:128
	v_lshl_add_u64 v[158:159], v[136:137], 2, s[14:15]
	v_add_u32_e32 v136, v149, v160
	global_store_dword v[158:159], v118, off
	global_store_dword v[158:159], v114, off offset:128
	v_lshl_add_u64 v[158:159], v[136:137], 2, s[14:15]
	global_store_dword v[158:159], v119, off
	global_store_dword v[158:159], v115, off offset:128

.LBB0_733:
	ds_read_b128 v[148:151], v144
	ds_read_b128 v[152:155], v144 offset:1024
	ds_read_b128 v[156:159], v144 offset:2048
	ds_read_b128 v[160:163], v144 offset:3072
	s_add_u32 s26, s24, 0xfffc0080
	s_addc_u32 s27, s25, -1
	s_cmp_eq_u32 s62, 12
	s_cselect_b32 s29, s7, s27
	s_cselect_b32 s28, s17, s26
	s_cselect_b32 s27, s15, vcc_hi
	s_cselect_b32 s26, s23, vcc_lo
	s_mov_b32 m0, s31
	v_lshl_add_u64 v[198:199], s[24:25], 0, v[136:137]
	ds_read_b128 v[164:167], v142
	ds_read_b128 v[168:171], v142 offset:1024
	ds_read_b128 v[172:175], v142 offset:2048
	ds_read_b128 v[176:179], v142 offset:3072
	ds_read_b128 v[182:185], v142 offset:4096
	ds_read_b128 v[186:189], v142 offset:5120
	ds_read_b128 v[190:193], v142 offset:6144
	ds_read_b128 v[194:197], v142 offset:7168
	global_load_lds_dwordx4 v[198:199], off
	v_lshl_add_u64 v[198:199], s[24:25], 0, v[138:139]
	s_mov_b32 m0, s94
	s_nop 0
	global_load_lds_dwordx4 v[198:199], off
	s_waitcnt lgkmcnt(8)
	s_barrier
	s_waitcnt lgkmcnt(0)
	s_waitcnt lgkmcnt(0)
	v_mfma_f32_16x16x32_bf16 v[126:129], v[148:151], v[164:167], v[126:129]
	v_mfma_f32_16x16x32_bf16 v[122:125], v[156:159], v[164:167], v[122:125]
	v_mfma_f32_16x16x32_bf16 v[114:117], v[148:151], v[172:175], v[114:117]
	v_mfma_f32_16x16x32_bf16 v[106:109], v[156:159], v[172:175], v[106:109]
	v_mfma_f32_16x16x32_bf16 v[98:101], v[148:151], v[182:185], v[98:101]
	v_mfma_f32_16x16x32_bf16 v[90:93], v[156:159], v[182:185], v[90:93]
	v_mfma_f32_16x16x32_bf16 v[82:85], v[148:151], v[190:193], v[82:85]
	v_mfma_f32_16x16x32_bf16 v[74:77], v[156:159], v[190:193], v[74:77]
	v_mfma_f32_16x16x32_bf16 v[126:129], v[152:155], v[168:171], v[126:129]
	v_mfma_f32_16x16x32_bf16 v[122:125], v[160:163], v[168:171], v[122:125]
	v_mfma_f32_16x16x32_bf16 v[114:117], v[152:155], v[176:179], v[114:117]
	v_mfma_f32_16x16x32_bf16 v[106:109], v[160:163], v[176:179], v[106:109]
	v_mfma_f32_16x16x32_bf16 v[98:101], v[152:155], v[186:189], v[98:101]
	v_mfma_f32_16x16x32_bf16 v[90:93], v[160:163], v[186:189], v[90:93]
	v_mfma_f32_16x16x32_bf16 v[82:85], v[152:155], v[194:197], v[82:85]
	v_mfma_f32_16x16x32_bf16 v[74:77], v[160:163], v[194:197], v[74:77]
	s_barrier
	s_mov_b32 m0, s36
	v_lshl_add_u64 v[214:215], s[26:27], 0, v[0:1]
	ds_read_b128 v[198:201], v145
	ds_read_b128 v[202:205], v145 offset:1024
	ds_read_b128 v[206:209], v145 offset:2048
	ds_read_b128 v[210:213], v145 offset:3072
	global_load_lds_dwordx4 v[214:215], off
	v_lshl_add_u64 v[216:217], s[26:27], 0, v[134:135]
	s_mov_b32 m0, s37
	s_nop 0
	global_load_lds_dwordx4 v[216:217], off
	s_barrier
	s_waitcnt lgkmcnt(0)
	s_waitcnt lgkmcnt(0)
	v_mfma_f32_16x16x32_bf16 v[118:121], v[198:201], v[164:167], v[118:121]
	v_mfma_f32_16x16x32_bf16 v[110:113], v[206:209], v[164:167], v[110:113]
	v_mfma_f32_16x16x32_bf16 v[102:105], v[198:201], v[172:175], v[102:105]
	v_mfma_f32_16x16x32_bf16 v[94:97], v[206:209], v[172:175], v[94:97]
	v_mfma_f32_16x16x32_bf16 v[86:89], v[198:201], v[182:185], v[86:89]
	v_mfma_f32_16x16x32_bf16 v[78:81], v[206:209], v[182:185], v[78:81]
	v_mfma_f32_16x16x32_bf16 v[70:73], v[198:201], v[190:193], v[70:73]
	v_mfma_f32_16x16x32_bf16 v[66:69], v[206:209], v[190:193], v[66:69]
	v_mfma_f32_16x16x32_bf16 v[118:121], v[202:205], v[168:171], v[118:121]
	v_mfma_f32_16x16x32_bf16 v[110:113], v[210:213], v[168:171], v[110:113]
	v_mfma_f32_16x16x32_bf16 v[102:105], v[202:205], v[176:179], v[102:105]
	v_mfma_f32_16x16x32_bf16 v[94:97], v[210:213], v[176:179], v[94:97]
	v_mfma_f32_16x16x32_bf16 v[86:89], v[202:205], v[186:189], v[86:89]
	v_mfma_f32_16x16x32_bf16 v[78:81], v[210:213], v[186:189], v[78:81]
	v_mfma_f32_16x16x32_bf16 v[70:73], v[202:205], v[194:197], v[70:73]
	v_mfma_f32_16x16x32_bf16 v[66:69], v[210:213], v[194:197], v[66:69]
	s_mov_b32 m0, s89
	v_lshl_add_u64 v[222:223], s[28:29], 0, v[130:131]
	s_barrier
	ds_read_b128 v[164:167], v142 offset:16384
	ds_read_b128 v[168:171], v142 offset:17408
	ds_read_b128 v[172:175], v142 offset:18432
	ds_read_b128 v[176:179], v142 offset:19456
	ds_read_b128 v[182:185], v142 offset:20480
	ds_read_b128 v[186:189], v142 offset:21504
	ds_read_b128 v[190:193], v142 offset:22528
	ds_read_b128 v[194:197], v142 offset:23552
	global_load_lds_dwordx4 v[222:223], off
	v_lshl_add_u64 v[224:225], s[28:29], 0, v[132:133]
	s_mov_b32 m0, s38
	s_nop 0
	global_load_lds_dwordx4 v[224:225], off
	s_barrier
	s_waitcnt lgkmcnt(0)
	s_waitcnt lgkmcnt(0)
	v_mfma_f32_16x16x32_bf16 v[62:65], v[148:151], v[164:167], v[62:65]
	v_mfma_f32_16x16x32_bf16 v[58:61], v[156:159], v[164:167], v[58:61]
	v_mfma_f32_16x16x32_bf16 v[50:53], v[148:151], v[172:175], v[50:53]
	v_mfma_f32_16x16x32_bf16 v[42:45], v[156:159], v[172:175], v[42:45]
	v_mfma_f32_16x16x32_bf16 v[34:37], v[148:151], v[182:185], v[34:37]
	v_mfma_f32_16x16x32_bf16 v[26:29], v[156:159], v[182:185], v[26:29]
	v_mfma_f32_16x16x32_bf16 v[18:21], v[148:151], v[190:193], v[18:21]
	v_mfma_f32_16x16x32_bf16 v[10:13], v[156:159], v[190:193], v[10:13]
	v_mfma_f32_16x16x32_bf16 v[62:65], v[152:155], v[168:171], v[62:65]
	v_mfma_f32_16x16x32_bf16 v[58:61], v[160:163], v[168:171], v[58:61]
	v_mfma_f32_16x16x32_bf16 v[50:53], v[152:155], v[176:179], v[50:53]
	v_mfma_f32_16x16x32_bf16 v[42:45], v[160:163], v[176:179], v[42:45]
	v_mfma_f32_16x16x32_bf16 v[34:37], v[152:155], v[186:189], v[34:37]
	v_mfma_f32_16x16x32_bf16 v[26:29], v[160:163], v[186:189], v[26:29]
	v_mfma_f32_16x16x32_bf16 v[18:21], v[152:155], v[194:197], v[18:21]
	v_mfma_f32_16x16x32_bf16 v[10:13], v[160:163], v[194:197], v[10:13]
	s_barrier
	s_add_u32 s76, s26, 0x40000
	s_addc_u32 s77, s27, 0
	s_mov_b32 m0, s39
	v_lshl_add_u64 v[148:149], s[76:77], 0, v[0:1]
	global_load_lds_dwordx4 v[148:149], off
	v_lshl_add_u64 v[148:149], s[76:77], 0, v[134:135]
	s_mov_b32 m0, s60
	s_nop 0
	global_load_lds_dwordx4 v[148:149], off
	s_waitcnt vmcnt(6)
	s_barrier
	v_mfma_f32_16x16x32_bf16 v[54:57], v[198:201], v[164:167], v[54:57]
	v_mfma_f32_16x16x32_bf16 v[46:49], v[206:209], v[164:167], v[46:49]
	v_mfma_f32_16x16x32_bf16 v[38:41], v[198:201], v[172:175], v[38:41]
	v_mfma_f32_16x16x32_bf16 v[30:33], v[206:209], v[172:175], v[30:33]
	v_mfma_f32_16x16x32_bf16 v[22:25], v[198:201], v[182:185], v[22:25]
	v_mfma_f32_16x16x32_bf16 v[14:17], v[206:209], v[182:185], v[14:17]
	v_mfma_f32_16x16x32_bf16 v[6:9], v[198:201], v[190:193], v[6:9]
	v_mfma_f32_16x16x32_bf16 v[2:5], v[206:209], v[190:193], v[2:5]
	v_mfma_f32_16x16x32_bf16 v[54:57], v[202:205], v[168:171], v[54:57]
	v_mfma_f32_16x16x32_bf16 v[46:49], v[210:213], v[168:171], v[46:49]
	v_mfma_f32_16x16x32_bf16 v[38:41], v[202:205], v[176:179], v[38:41]
	v_mfma_f32_16x16x32_bf16 v[30:33], v[210:213], v[176:179], v[30:33]
	v_mfma_f32_16x16x32_bf16 v[22:25], v[202:205], v[186:189], v[22:25]
	v_mfma_f32_16x16x32_bf16 v[14:17], v[210:213], v[186:189], v[14:17]
	v_mfma_f32_16x16x32_bf16 v[6:9], v[202:205], v[194:197], v[6:9]
	v_mfma_f32_16x16x32_bf16 v[2:5], v[210:213], v[194:197], v[2:5]
	s_barrier
	ds_read_b128 v[148:151], v146
	ds_read_b128 v[152:155], v146 offset:1024
	ds_read_b128 v[156:159], v146 offset:2048
	ds_read_b128 v[160:163], v146 offset:3072
	s_add_u32 s28, s28, 0x40000
	s_addc_u32 s29, s29, 0
	s_mov_b32 m0, s68
	v_lshl_add_u64 v[198:199], s[28:29], 0, v[130:131]
	ds_read_b128 v[164:167], v142 offset:32768
	ds_read_b128 v[168:171], v142 offset:33792
	ds_read_b128 v[172:175], v142 offset:34816
	ds_read_b128 v[176:179], v142 offset:35840
	ds_read_b128 v[182:185], v142 offset:36864
	ds_read_b128 v[186:189], v142 offset:37888
	ds_read_b128 v[190:193], v142 offset:38912
	ds_read_b128 v[194:197], v142 offset:39936
	global_load_lds_dwordx4 v[198:199], off
	v_lshl_add_u64 v[198:199], s[28:29], 0, v[132:133]
	s_mov_b32 m0, s69
	s_nop 0
	global_load_lds_dwordx4 v[198:199], off
	s_waitcnt lgkmcnt(8)
	s_barrier
	s_waitcnt lgkmcnt(0)
	s_waitcnt lgkmcnt(0)
	v_mfma_f32_16x16x32_bf16 v[126:129], v[148:151], v[164:167], v[126:129]
	v_mfma_f32_16x16x32_bf16 v[122:125], v[156:159], v[164:167], v[122:125]
	v_mfma_f32_16x16x32_bf16 v[114:117], v[148:151], v[172:175], v[114:117]
	v_mfma_f32_16x16x32_bf16 v[106:109], v[156:159], v[172:175], v[106:109]
	v_mfma_f32_16x16x32_bf16 v[98:101], v[148:151], v[182:185], v[98:101]
	v_mfma_f32_16x16x32_bf16 v[90:93], v[156:159], v[182:185], v[90:93]
	v_mfma_f32_16x16x32_bf16 v[82:85], v[148:151], v[190:193], v[82:85]
	v_mfma_f32_16x16x32_bf16 v[74:77], v[156:159], v[190:193], v[74:77]
	v_mfma_f32_16x16x32_bf16 v[126:129], v[152:155], v[168:171], v[126:129]
	v_mfma_f32_16x16x32_bf16 v[122:125], v[160:163], v[168:171], v[122:125]
	v_mfma_f32_16x16x32_bf16 v[114:117], v[152:155], v[176:179], v[114:117]
	v_mfma_f32_16x16x32_bf16 v[106:109], v[160:163], v[176:179], v[106:109]
	v_mfma_f32_16x16x32_bf16 v[98:101], v[152:155], v[186:189], v[98:101]
	v_mfma_f32_16x16x32_bf16 v[90:93], v[160:163], v[186:189], v[90:93]
	v_mfma_f32_16x16x32_bf16 v[82:85], v[152:155], v[194:197], v[82:85]
	v_mfma_f32_16x16x32_bf16 v[74:77], v[160:163], v[194:197], v[74:77]
	s_barrier
	s_mov_b32 m0, s75
	v_lshl_add_u64 v[214:215], v[214:215], 0, s[84:85]
	ds_read_b128 v[198:201], v147
	ds_read_b128 v[202:205], v147 offset:1024
	ds_read_b128 v[206:209], v147 offset:2048
	ds_read_b128 v[210:213], v147 offset:3072
	global_load_lds_dwordx4 v[214:215], off
	v_lshl_add_u64 v[214:215], v[216:217], 0, s[84:85]
	s_mov_b32 m0, s82
	s_nop 0
	global_load_lds_dwordx4 v[214:215], off
	s_barrier
	s_waitcnt lgkmcnt(0)
	s_waitcnt lgkmcnt(0)
	v_mfma_f32_16x16x32_bf16 v[118:121], v[198:201], v[164:167], v[118:121]
	v_mfma_f32_16x16x32_bf16 v[110:113], v[206:209], v[164:167], v[110:113]
	v_mfma_f32_16x16x32_bf16 v[102:105], v[198:201], v[172:175], v[102:105]
	v_mfma_f32_16x16x32_bf16 v[94:97], v[206:209], v[172:175], v[94:97]
	v_mfma_f32_16x16x32_bf16 v[86:89], v[198:201], v[182:185], v[86:89]
	v_mfma_f32_16x16x32_bf16 v[78:81], v[206:209], v[182:185], v[78:81]
	v_mfma_f32_16x16x32_bf16 v[70:73], v[198:201], v[190:193], v[70:73]
	v_mfma_f32_16x16x32_bf16 v[66:69], v[206:209], v[190:193], v[66:69]
	v_mfma_f32_16x16x32_bf16 v[118:121], v[202:205], v[168:171], v[118:121]
	v_mfma_f32_16x16x32_bf16 v[110:113], v[210:213], v[168:171], v[110:113]
	v_mfma_f32_16x16x32_bf16 v[102:105], v[202:205], v[176:179], v[102:105]
	v_mfma_f32_16x16x32_bf16 v[94:97], v[210:213], v[176:179], v[94:97]
	v_mfma_f32_16x16x32_bf16 v[86:89], v[202:205], v[186:189], v[86:89]
	v_mfma_f32_16x16x32_bf16 v[78:81], v[210:213], v[186:189], v[78:81]
	v_mfma_f32_16x16x32_bf16 v[70:73], v[202:205], v[194:197], v[70:73]
	v_mfma_f32_16x16x32_bf16 v[66:69], v[210:213], v[194:197], v[66:69]
	s_mov_b32 m0, s92
	v_lshl_add_u64 v[214:215], v[222:223], 0, s[84:85]
	s_barrier
	ds_read_b128 v[164:167], v142 offset:49152
	ds_read_b128 v[168:171], v142 offset:50176
	ds_read_b128 v[172:175], v142 offset:51200
	ds_read_b128 v[176:179], v142 offset:52224
	ds_read_b128 v[182:185], v142 offset:53248
	ds_read_b128 v[186:189], v142 offset:54272
	ds_read_b128 v[190:193], v142 offset:55296
	ds_read_b128 v[194:197], v142 offset:56320
	global_load_lds_dwordx4 v[214:215], off
	v_lshl_add_u64 v[214:215], v[224:225], 0, s[84:85]
	s_mov_b32 m0, s93
	s_nop 0
	global_load_lds_dwordx4 v[214:215], off
	s_barrier
	s_waitcnt lgkmcnt(0)
	s_waitcnt lgkmcnt(0)
	v_mfma_f32_16x16x32_bf16 v[62:65], v[148:151], v[164:167], v[62:65]
	v_mfma_f32_16x16x32_bf16 v[58:61], v[156:159], v[164:167], v[58:61]
	v_mfma_f32_16x16x32_bf16 v[50:53], v[148:151], v[172:175], v[50:53]
	v_mfma_f32_16x16x32_bf16 v[42:45], v[156:159], v[172:175], v[42:45]
	v_mfma_f32_16x16x32_bf16 v[34:37], v[148:151], v[182:185], v[34:37]
	v_mfma_f32_16x16x32_bf16 v[26:29], v[156:159], v[182:185], v[26:29]
	v_mfma_f32_16x16x32_bf16 v[18:21], v[148:151], v[190:193], v[18:21]
	v_mfma_f32_16x16x32_bf16 v[10:13], v[156:159], v[190:193], v[10:13]
	v_mfma_f32_16x16x32_bf16 v[62:65], v[152:155], v[168:171], v[62:65]
	v_mfma_f32_16x16x32_bf16 v[58:61], v[160:163], v[168:171], v[58:61]
	v_mfma_f32_16x16x32_bf16 v[50:53], v[152:155], v[176:179], v[50:53]
	v_mfma_f32_16x16x32_bf16 v[42:45], v[160:163], v[176:179], v[42:45]
	v_mfma_f32_16x16x32_bf16 v[34:37], v[152:155], v[186:189], v[34:37]
	v_mfma_f32_16x16x32_bf16 v[26:29], v[160:163], v[186:189], v[26:29]
	v_mfma_f32_16x16x32_bf16 v[18:21], v[152:155], v[194:197], v[18:21]
	v_mfma_f32_16x16x32_bf16 v[10:13], v[160:163], v[194:197], v[10:13]
	s_barrier
	s_add_u32 s26, s26, 0x40080
	s_addc_u32 s27, s27, 0
	s_mov_b32 m0, s96
	v_lshl_add_u64 v[148:149], s[26:27], 0, v[0:1]
	global_load_lds_dwordx4 v[148:149], off
	v_lshl_add_u64 v[148:149], s[26:27], 0, v[134:135]
	s_mov_b32 m0, s97
	s_nop 0
	global_load_lds_dwordx4 v[148:149], off
	s_waitcnt vmcnt(6)
	s_barrier
	v_mfma_f32_16x16x32_bf16 v[54:57], v[198:201], v[164:167], v[54:57]
	v_mfma_f32_16x16x32_bf16 v[46:49], v[206:209], v[164:167], v[46:49]
	v_mfma_f32_16x16x32_bf16 v[38:41], v[198:201], v[172:175], v[38:41]
	v_mfma_f32_16x16x32_bf16 v[30:33], v[206:209], v[172:175], v[30:33]
	v_mfma_f32_16x16x32_bf16 v[22:25], v[198:201], v[182:185], v[22:25]
	v_mfma_f32_16x16x32_bf16 v[14:17], v[206:209], v[182:185], v[14:17]
	v_mfma_f32_16x16x32_bf16 v[6:9], v[198:201], v[190:193], v[6:9]
	v_mfma_f32_16x16x32_bf16 v[2:5], v[206:209], v[190:193], v[2:5]
	v_mfma_f32_16x16x32_bf16 v[54:57], v[202:205], v[168:171], v[54:57]
	v_mfma_f32_16x16x32_bf16 v[46:49], v[210:213], v[168:171], v[46:49]
	v_mfma_f32_16x16x32_bf16 v[38:41], v[202:205], v[176:179], v[38:41]
	v_mfma_f32_16x16x32_bf16 v[30:33], v[210:213], v[176:179], v[30:33]
	v_mfma_f32_16x16x32_bf16 v[22:25], v[202:205], v[186:189], v[22:25]
	v_mfma_f32_16x16x32_bf16 v[14:17], v[210:213], v[186:189], v[14:17]
	v_mfma_f32_16x16x32_bf16 v[6:9], v[202:205], v[194:197], v[6:9]
	v_mfma_f32_16x16x32_bf16 v[2:5], v[210:213], v[194:197], v[2:5]
	s_add_i32 s62, s62, 2
	s_add_u32 s24, s24, 0x100
	s_addc_u32 s25, s25, 0
	s_add_u32 vcc_lo, vcc_lo, 0x100
	s_addc_u32 vcc_hi, vcc_hi, 0
	s_cmp_gt_u32 s62, 13
	s_barrier
	s_cbranch_scc0 .LBB0_733
	v_lshl_add_u32 v149, s6, 8, v143
	v_add_u32_e32 v140, -8, v149
	v_lshl_add_u32 v148, s22, 8, v141
	v_cmp_gt_u32_e32 vcc, s71, v140
	s_and_saveexec_b64 s[6:7], vcc
	s_cbranch_execz .LBB0_736
	v_cvt_pk_bf16_f32 v126, v126, v127
	v_cvt_pk_bf16_f32 v127, v128, v129
	v_cvt_pk_bf16_f32 v128, v122, v123
	v_cvt_pk_bf16_f32 v129, v124, v125
	v_mad_u64_u32 v[122:123], s[22:23], v148, s71, v[140:141]
	v_mov_b32_e32 v123, v1
	v_lshl_add_u64 v[122:123], v[122:123], 1, s[10:11]
	global_store_dwordx4 v[122:123], v[126:129], off

.LBB0_781:
	v_add_u32_e32 v140, 0x10000, v143
	ds_read_b128 v[146:149], v140
	ds_read_b128 v[150:153], v140 offset:1024
	ds_read_b128 v[154:157], v140 offset:2048
	ds_read_b128 v[158:161], v140 offset:3072
	s_add_u32 s26, s24, 0xfffc0080
	s_addc_u32 s27, s25, -1
	s_cmp_eq_u32 vcc_lo, 12
	s_cselect_b32 s29, s7, s27
	s_cselect_b32 s28, s17, s26
	s_cselect_b32 s27, s15, s94
	s_cselect_b32 s26, s23, s89
	v_lshl_add_u64 v[178:179], s[24:25], 0, v[136:137]
	s_add_i32 m0, s30, 0xc000
	ds_read_b128 v[162:165], v142
	ds_read_b128 v[166:169], v142 offset:1024
	ds_read_b128 v[170:173], v142 offset:2048
	ds_read_b128 v[174:177], v142 offset:3072
	ds_read_b128 v[182:185], v142 offset:4096
	ds_read_b128 v[186:189], v142 offset:5120
	ds_read_b128 v[190:193], v142 offset:6144
	ds_read_b128 v[194:197], v142 offset:7168
	global_load_lds_dwordx4 v[178:179], off
	v_lshl_add_u64 v[178:179], s[24:25], 0, v[138:139]
	s_add_i32 m0, s30, 0xe000
	s_nop 0
	global_load_lds_dwordx4 v[178:179], off
	s_waitcnt lgkmcnt(8)
	s_barrier
	s_waitcnt lgkmcnt(0)
	s_waitcnt lgkmcnt(0)
	v_mfma_f32_16x16x32_bf16 v[126:129], v[146:149], v[162:165], v[126:129]
	v_mfma_f32_16x16x32_bf16 v[122:125], v[154:157], v[162:165], v[122:125]
	v_mfma_f32_16x16x32_bf16 v[114:117], v[146:149], v[170:173], v[114:117]
	v_mfma_f32_16x16x32_bf16 v[106:109], v[154:157], v[170:173], v[106:109]
	v_mfma_f32_16x16x32_bf16 v[98:101], v[146:149], v[182:185], v[98:101]
	v_mfma_f32_16x16x32_bf16 v[90:93], v[154:157], v[182:185], v[90:93]
	v_mfma_f32_16x16x32_bf16 v[82:85], v[146:149], v[190:193], v[82:85]
	v_mfma_f32_16x16x32_bf16 v[74:77], v[154:157], v[190:193], v[74:77]
	v_mfma_f32_16x16x32_bf16 v[126:129], v[150:153], v[166:169], v[126:129]
	v_mfma_f32_16x16x32_bf16 v[122:125], v[158:161], v[166:169], v[122:125]
	v_mfma_f32_16x16x32_bf16 v[114:117], v[150:153], v[174:177], v[114:117]
	v_mfma_f32_16x16x32_bf16 v[106:109], v[158:161], v[174:177], v[106:109]
	v_mfma_f32_16x16x32_bf16 v[98:101], v[150:153], v[186:189], v[98:101]
	v_mfma_f32_16x16x32_bf16 v[90:93], v[158:161], v[186:189], v[90:93]
	v_mfma_f32_16x16x32_bf16 v[82:85], v[150:153], v[194:197], v[82:85]
	v_mfma_f32_16x16x32_bf16 v[74:77], v[158:161], v[194:197], v[74:77]
	s_barrier
	s_mov_b32 m0, s35
	v_add_u32_e32 v140, 0x14000, v143
	v_lshl_add_u64 v[178:179], s[26:27], 0, v[0:1]
	ds_read_b128 v[198:201], v140
	ds_read_b128 v[202:205], v140 offset:1024
	ds_read_b128 v[206:209], v140 offset:2048
	ds_read_b128 v[210:213], v140 offset:3072
	global_load_lds_dwordx4 v[178:179], off
	v_lshl_add_u64 v[214:215], s[26:27], 0, v[134:135]
	s_mov_b32 m0, s36
	s_nop 0
	global_load_lds_dwordx4 v[214:215], off
	s_barrier
	s_waitcnt lgkmcnt(0)
	s_waitcnt lgkmcnt(0)
	v_mfma_f32_16x16x32_bf16 v[118:121], v[198:201], v[162:165], v[118:121]
	v_mfma_f32_16x16x32_bf16 v[110:113], v[206:209], v[162:165], v[110:113]
	v_mfma_f32_16x16x32_bf16 v[102:105], v[198:201], v[170:173], v[102:105]
	v_mfma_f32_16x16x32_bf16 v[94:97], v[206:209], v[170:173], v[94:97]
	v_mfma_f32_16x16x32_bf16 v[86:89], v[198:201], v[182:185], v[86:89]
	v_mfma_f32_16x16x32_bf16 v[78:81], v[206:209], v[182:185], v[78:81]
	v_mfma_f32_16x16x32_bf16 v[70:73], v[198:201], v[190:193], v[70:73]
	v_mfma_f32_16x16x32_bf16 v[66:69], v[206:209], v[190:193], v[66:69]
	v_mfma_f32_16x16x32_bf16 v[118:121], v[202:205], v[166:169], v[118:121]
	v_mfma_f32_16x16x32_bf16 v[110:113], v[210:213], v[166:169], v[110:113]
	v_mfma_f32_16x16x32_bf16 v[102:105], v[202:205], v[174:177], v[102:105]
	v_mfma_f32_16x16x32_bf16 v[94:97], v[210:213], v[174:177], v[94:97]
	v_mfma_f32_16x16x32_bf16 v[86:89], v[202:205], v[186:189], v[86:89]
	v_mfma_f32_16x16x32_bf16 v[78:81], v[210:213], v[186:189], v[78:81]
	v_mfma_f32_16x16x32_bf16 v[70:73], v[202:205], v[194:197], v[70:73]
	v_mfma_f32_16x16x32_bf16 v[66:69], v[210:213], v[194:197], v[66:69]
	s_mov_b32 m0, s30
	v_lshl_add_u64 v[216:217], s[28:29], 0, v[130:131]
	s_barrier
	ds_read_b128 v[162:165], v142 offset:16384
	ds_read_b128 v[166:169], v142 offset:17408
	ds_read_b128 v[170:173], v142 offset:18432
	ds_read_b128 v[174:177], v142 offset:19456
	ds_read_b128 v[182:185], v142 offset:20480
	ds_read_b128 v[186:189], v142 offset:21504
	ds_read_b128 v[190:193], v142 offset:22528
	ds_read_b128 v[194:197], v142 offset:23552
	global_load_lds_dwordx4 v[216:217], off
	v_lshl_add_u64 v[222:223], s[28:29], 0, v[132:133]
	s_mov_b32 m0, s37
	s_nop 0
	global_load_lds_dwordx4 v[222:223], off
	s_barrier
	s_waitcnt lgkmcnt(0)
	s_waitcnt lgkmcnt(0)
	v_mfma_f32_16x16x32_bf16 v[62:65], v[146:149], v[162:165], v[62:65]
	v_mfma_f32_16x16x32_bf16 v[58:61], v[154:157], v[162:165], v[58:61]
	v_mfma_f32_16x16x32_bf16 v[50:53], v[146:149], v[170:173], v[50:53]
	v_mfma_f32_16x16x32_bf16 v[42:45], v[154:157], v[170:173], v[42:45]
	v_mfma_f32_16x16x32_bf16 v[34:37], v[146:149], v[182:185], v[34:37]
	v_mfma_f32_16x16x32_bf16 v[26:29], v[154:157], v[182:185], v[26:29]
	v_mfma_f32_16x16x32_bf16 v[18:21], v[146:149], v[190:193], v[18:21]
	v_mfma_f32_16x16x32_bf16 v[10:13], v[154:157], v[190:193], v[10:13]
	v_mfma_f32_16x16x32_bf16 v[62:65], v[150:153], v[166:169], v[62:65]
	v_mfma_f32_16x16x32_bf16 v[58:61], v[158:161], v[166:169], v[58:61]
	v_mfma_f32_16x16x32_bf16 v[50:53], v[150:153], v[174:177], v[50:53]
	v_mfma_f32_16x16x32_bf16 v[42:45], v[158:161], v[174:177], v[42:45]
	v_mfma_f32_16x16x32_bf16 v[34:37], v[150:153], v[186:189], v[34:37]
	v_mfma_f32_16x16x32_bf16 v[26:29], v[158:161], v[186:189], v[26:29]
	v_mfma_f32_16x16x32_bf16 v[18:21], v[150:153], v[194:197], v[18:21]
	v_mfma_f32_16x16x32_bf16 v[10:13], v[158:161], v[194:197], v[10:13]
	s_barrier
	s_add_u32 s76, s26, 0x40000
	s_addc_u32 s77, s27, 0
	s_mov_b32 m0, s38
	v_lshl_add_u64 v[146:147], s[76:77], 0, v[0:1]
	global_load_lds_dwordx4 v[146:147], off
	v_lshl_add_u64 v[146:147], s[76:77], 0, v[134:135]
	s_mov_b32 m0, s39
	s_nop 0
	global_load_lds_dwordx4 v[146:147], off
	s_waitcnt vmcnt(6)
	s_barrier
	v_mfma_f32_16x16x32_bf16 v[54:57], v[198:201], v[162:165], v[54:57]
	v_mfma_f32_16x16x32_bf16 v[46:49], v[206:209], v[162:165], v[46:49]
	v_mfma_f32_16x16x32_bf16 v[38:41], v[198:201], v[170:173], v[38:41]
	v_mfma_f32_16x16x32_bf16 v[30:33], v[206:209], v[170:173], v[30:33]
	v_mfma_f32_16x16x32_bf16 v[22:25], v[198:201], v[182:185], v[22:25]
	v_mfma_f32_16x16x32_bf16 v[14:17], v[206:209], v[182:185], v[14:17]
	v_mfma_f32_16x16x32_bf16 v[6:9], v[198:201], v[190:193], v[6:9]
	v_mfma_f32_16x16x32_bf16 v[2:5], v[206:209], v[190:193], v[2:5]
	v_mfma_f32_16x16x32_bf16 v[54:57], v[202:205], v[166:169], v[54:57]
	v_mfma_f32_16x16x32_bf16 v[46:49], v[210:213], v[166:169], v[46:49]
	v_mfma_f32_16x16x32_bf16 v[38:41], v[202:205], v[174:177], v[38:41]
	v_mfma_f32_16x16x32_bf16 v[30:33], v[210:213], v[174:177], v[30:33]
	v_mfma_f32_16x16x32_bf16 v[22:25], v[202:205], v[186:189], v[22:25]
	v_mfma_f32_16x16x32_bf16 v[14:17], v[210:213], v[186:189], v[14:17]
	v_mfma_f32_16x16x32_bf16 v[6:9], v[202:205], v[194:197], v[6:9]
	v_mfma_f32_16x16x32_bf16 v[2:5], v[210:213], v[194:197], v[2:5]
	v_add_u32_e32 v140, 0x18000, v143
	s_barrier
	ds_read_b128 v[146:149], v140
	ds_read_b128 v[150:153], v140 offset:1024
	ds_read_b128 v[154:157], v140 offset:2048
	ds_read_b128 v[158:161], v140 offset:3072
	s_add_u32 s28, s28, 0x40000
	s_addc_u32 s29, s29, 0
	s_mov_b32 m0, s60
	v_lshl_add_u64 v[198:199], s[28:29], 0, v[130:131]
	ds_read_b128 v[162:165], v142 offset:32768
	ds_read_b128 v[166:169], v142 offset:33792
	ds_read_b128 v[170:173], v142 offset:34816
	ds_read_b128 v[174:177], v142 offset:35840
	ds_read_b128 v[182:185], v142 offset:36864
	ds_read_b128 v[186:189], v142 offset:37888
	ds_read_b128 v[190:193], v142 offset:38912
	ds_read_b128 v[194:197], v142 offset:39936
	global_load_lds_dwordx4 v[198:199], off
	v_lshl_add_u64 v[198:199], s[28:29], 0, v[132:133]
	s_mov_b32 m0, s68
	s_nop 0
	global_load_lds_dwordx4 v[198:199], off
	s_waitcnt lgkmcnt(8)
	s_barrier
	s_waitcnt lgkmcnt(0)
	s_waitcnt lgkmcnt(0)
	v_mfma_f32_16x16x32_bf16 v[126:129], v[146:149], v[162:165], v[126:129]
	v_mfma_f32_16x16x32_bf16 v[122:125], v[154:157], v[162:165], v[122:125]
	v_mfma_f32_16x16x32_bf16 v[114:117], v[146:149], v[170:173], v[114:117]
	v_mfma_f32_16x16x32_bf16 v[106:109], v[154:157], v[170:173], v[106:109]
	v_mfma_f32_16x16x32_bf16 v[98:101], v[146:149], v[182:185], v[98:101]
	v_mfma_f32_16x16x32_bf16 v[90:93], v[154:157], v[182:185], v[90:93]
	v_mfma_f32_16x16x32_bf16 v[82:85], v[146:149], v[190:193], v[82:85]
	v_mfma_f32_16x16x32_bf16 v[74:77], v[154:157], v[190:193], v[74:77]
	v_mfma_f32_16x16x32_bf16 v[126:129], v[150:153], v[166:169], v[126:129]
	v_mfma_f32_16x16x32_bf16 v[122:125], v[158:161], v[166:169], v[122:125]
	v_mfma_f32_16x16x32_bf16 v[114:117], v[150:153], v[174:177], v[114:117]
	v_mfma_f32_16x16x32_bf16 v[106:109], v[158:161], v[174:177], v[106:109]
	v_mfma_f32_16x16x32_bf16 v[98:101], v[150:153], v[186:189], v[98:101]
	v_mfma_f32_16x16x32_bf16 v[90:93], v[158:161], v[186:189], v[90:93]
	v_mfma_f32_16x16x32_bf16 v[82:85], v[150:153], v[194:197], v[82:85]
	v_mfma_f32_16x16x32_bf16 v[74:77], v[158:161], v[194:197], v[74:77]
	s_barrier
	s_mov_b32 m0, s75
	v_add_u32_e32 v140, 0x1c000, v143
	v_lshl_add_u64 v[178:179], v[178:179], 0, s[84:85]
	ds_read_b128 v[198:201], v140
	ds_read_b128 v[202:205], v140 offset:1024
	ds_read_b128 v[206:209], v140 offset:2048
	ds_read_b128 v[210:213], v140 offset:3072
	global_load_lds_dwordx4 v[178:179], off
	v_lshl_add_u64 v[178:179], v[214:215], 0, s[84:85]
	s_mov_b32 m0, s82
	s_nop 0
	global_load_lds_dwordx4 v[178:179], off
	s_barrier
	s_waitcnt lgkmcnt(0)
	s_waitcnt lgkmcnt(0)
	v_mfma_f32_16x16x32_bf16 v[118:121], v[198:201], v[162:165], v[118:121]
	v_mfma_f32_16x16x32_bf16 v[110:113], v[206:209], v[162:165], v[110:113]
	v_mfma_f32_16x16x32_bf16 v[102:105], v[198:201], v[170:173], v[102:105]
	v_mfma_f32_16x16x32_bf16 v[94:97], v[206:209], v[170:173], v[94:97]
	v_mfma_f32_16x16x32_bf16 v[86:89], v[198:201], v[182:185], v[86:89]
	v_mfma_f32_16x16x32_bf16 v[78:81], v[206:209], v[182:185], v[78:81]
	v_mfma_f32_16x16x32_bf16 v[70:73], v[198:201], v[190:193], v[70:73]
	v_mfma_f32_16x16x32_bf16 v[66:69], v[206:209], v[190:193], v[66:69]
	v_mfma_f32_16x16x32_bf16 v[118:121], v[202:205], v[166:169], v[118:121]
	v_mfma_f32_16x16x32_bf16 v[110:113], v[210:213], v[166:169], v[110:113]
	v_mfma_f32_16x16x32_bf16 v[102:105], v[202:205], v[174:177], v[102:105]
	v_mfma_f32_16x16x32_bf16 v[94:97], v[210:213], v[174:177], v[94:97]
	v_mfma_f32_16x16x32_bf16 v[86:89], v[202:205], v[186:189], v[86:89]
	v_mfma_f32_16x16x32_bf16 v[78:81], v[210:213], v[186:189], v[78:81]
	v_mfma_f32_16x16x32_bf16 v[70:73], v[202:205], v[194:197], v[70:73]
	v_mfma_f32_16x16x32_bf16 v[66:69], v[210:213], v[194:197], v[66:69]
	s_mov_b32 m0, s92
	v_lshl_add_u64 v[178:179], v[216:217], 0, s[84:85]
	s_barrier
	ds_read_b128 v[162:165], v142 offset:49152
	ds_read_b128 v[166:169], v142 offset:50176
	ds_read_b128 v[170:173], v142 offset:51200
	ds_read_b128 v[174:177], v142 offset:52224
	ds_read_b128 v[182:185], v142 offset:53248
	ds_read_b128 v[186:189], v142 offset:54272
	ds_read_b128 v[190:193], v142 offset:55296
	ds_read_b128 v[194:197], v142 offset:56320
	global_load_lds_dwordx4 v[178:179], off
	v_lshl_add_u64 v[178:179], v[222:223], 0, s[84:85]
	s_mov_b32 m0, s93
	s_nop 0
	global_load_lds_dwordx4 v[178:179], off
	s_barrier
	s_waitcnt lgkmcnt(0)
	s_waitcnt lgkmcnt(0)
	v_mfma_f32_16x16x32_bf16 v[62:65], v[146:149], v[162:165], v[62:65]
	v_mfma_f32_16x16x32_bf16 v[58:61], v[154:157], v[162:165], v[58:61]
	v_mfma_f32_16x16x32_bf16 v[50:53], v[146:149], v[170:173], v[50:53]
	v_mfma_f32_16x16x32_bf16 v[42:45], v[154:157], v[170:173], v[42:45]
	v_mfma_f32_16x16x32_bf16 v[34:37], v[146:149], v[182:185], v[34:37]
	v_mfma_f32_16x16x32_bf16 v[26:29], v[154:157], v[182:185], v[26:29]
	v_mfma_f32_16x16x32_bf16 v[18:21], v[146:149], v[190:193], v[18:21]
	v_mfma_f32_16x16x32_bf16 v[10:13], v[154:157], v[190:193], v[10:13]
	v_mfma_f32_16x16x32_bf16 v[62:65], v[150:153], v[166:169], v[62:65]
	v_mfma_f32_16x16x32_bf16 v[58:61], v[158:161], v[166:169], v[58:61]
	v_mfma_f32_16x16x32_bf16 v[50:53], v[150:153], v[174:177], v[50:53]
	v_mfma_f32_16x16x32_bf16 v[42:45], v[158:161], v[174:177], v[42:45]
	v_mfma_f32_16x16x32_bf16 v[34:37], v[150:153], v[186:189], v[34:37]
	v_mfma_f32_16x16x32_bf16 v[26:29], v[158:161], v[186:189], v[26:29]
	v_mfma_f32_16x16x32_bf16 v[18:21], v[150:153], v[194:197], v[18:21]
	v_mfma_f32_16x16x32_bf16 v[10:13], v[158:161], v[194:197], v[10:13]
	s_barrier
	s_add_u32 s26, s26, 0x40080
	s_addc_u32 s27, s27, 0
	s_mov_b32 m0, s96
	v_lshl_add_u64 v[146:147], s[26:27], 0, v[0:1]
	global_load_lds_dwordx4 v[146:147], off
	v_lshl_add_u64 v[146:147], s[26:27], 0, v[134:135]
	s_mov_b32 m0, s97
	s_nop 0
	global_load_lds_dwordx4 v[146:147], off
	s_waitcnt vmcnt(6)
	s_barrier
	v_mfma_f32_16x16x32_bf16 v[54:57], v[198:201], v[162:165], v[54:57]
	v_mfma_f32_16x16x32_bf16 v[46:49], v[206:209], v[162:165], v[46:49]
	v_mfma_f32_16x16x32_bf16 v[38:41], v[198:201], v[170:173], v[38:41]
	v_mfma_f32_16x16x32_bf16 v[30:33], v[206:209], v[170:173], v[30:33]
	v_mfma_f32_16x16x32_bf16 v[22:25], v[198:201], v[182:185], v[22:25]
	v_mfma_f32_16x16x32_bf16 v[14:17], v[206:209], v[182:185], v[14:17]
	v_mfma_f32_16x16x32_bf16 v[6:9], v[198:201], v[190:193], v[6:9]
	v_mfma_f32_16x16x32_bf16 v[2:5], v[206:209], v[190:193], v[2:5]
	v_mfma_f32_16x16x32_bf16 v[54:57], v[202:205], v[166:169], v[54:57]
	v_mfma_f32_16x16x32_bf16 v[46:49], v[210:213], v[166:169], v[46:49]
	v_mfma_f32_16x16x32_bf16 v[38:41], v[202:205], v[174:177], v[38:41]
	v_mfma_f32_16x16x32_bf16 v[30:33], v[210:213], v[174:177], v[30:33]
	v_mfma_f32_16x16x32_bf16 v[22:25], v[202:205], v[186:189], v[22:25]
	v_mfma_f32_16x16x32_bf16 v[14:17], v[210:213], v[186:189], v[14:17]
	v_mfma_f32_16x16x32_bf16 v[6:9], v[202:205], v[194:197], v[6:9]
	v_mfma_f32_16x16x32_bf16 v[2:5], v[210:213], v[194:197], v[2:5]
	s_add_i32 vcc_lo, vcc_lo, 2
	s_add_u32 s24, s24, 0x100
	s_addc_u32 s25, s25, 0
	s_add_u32 s89, s89, 0x100
	s_addc_u32 s94, s94, 0
	s_cmp_gt_u32 vcc_lo, 13
	s_barrier
	s_cbranch_scc0 .LBB0_781
	s_cmp_lt_i32 s22, s69
	s_cselect_b64 s[24:25], -1, 0
	s_and_b64 s[24:25], s[24:25], exec
	s_cselect_b32 s7, 0, s69
	v_lshl_add_u32 v146, s6, 8, v144
	s_cselect_b32 s25, s9, s11
	s_cselect_b32 s24, s8, s10
	s_sub_i32 s7, s22, s7
	v_add_u32_e32 v140, -8, v146
	v_lshl_add_u32 v145, s7, 8, v141
	v_cmp_gt_u32_e32 vcc, s71, v140
	s_and_saveexec_b64 s[6:7], vcc
	s_cbranch_execz .LBB0_784
	v_cvt_pk_bf16_f32 v126, v126, v127
	v_cvt_pk_bf16_f32 v127, v128, v129
	v_cvt_pk_bf16_f32 v128, v122, v123
	v_cvt_pk_bf16_f32 v129, v124, v125
	v_mad_u64_u32 v[122:123], s[22:23], v145, s71, v[140:141]
	v_mov_b32_e32 v123, v1
	v_lshl_add_u64 v[122:123], v[122:123], 1, s[24:25]
	global_store_dwordx4 v[122:123], v[126:129], off

.LBB0_926:
	v_add_u32_e32 v140, 0x10000, v143
	ds_read_b128 v[146:149], v140
	ds_read_b128 v[150:153], v140 offset:1024
	ds_read_b128 v[154:157], v140 offset:2048
	ds_read_b128 v[158:161], v140 offset:3072
	s_add_u32 s6, s20, 0x100
	s_addc_u32 s7, s21, 0
	s_cmp_eq_u32 s96, 2
	s_cselect_b32 s25, s17, s7
	s_cselect_b32 s24, s16, s6
	s_cselect_b32 s23, s19, s94
	s_cselect_b32 s22, s18, s93
	v_lshl_add_u64 v[178:179], s[20:21], 0, v[136:137]
	s_add_i32 m0, s27, 0xc000
	ds_read_b128 v[162:165], v142
	ds_read_b128 v[166:169], v142 offset:1024
	ds_read_b128 v[170:173], v142 offset:2048
	ds_read_b128 v[174:177], v142 offset:3072
	ds_read_b128 v[182:185], v142 offset:4096
	ds_read_b128 v[186:189], v142 offset:5120
	ds_read_b128 v[190:193], v142 offset:6144
	ds_read_b128 v[194:197], v142 offset:7168
	global_load_lds_dwordx4 v[178:179], off
	v_lshl_add_u64 v[178:179], s[20:21], 0, v[138:139]
	s_add_i32 m0, s27, 0xe000
	s_nop 0
	global_load_lds_dwordx4 v[178:179], off
	s_waitcnt lgkmcnt(8)
	s_barrier
	s_waitcnt lgkmcnt(0)
	s_waitcnt lgkmcnt(0)
	v_mfma_f32_16x16x32_bf16 v[126:129], v[146:149], v[162:165], v[126:129]
	v_mfma_f32_16x16x32_bf16 v[122:125], v[154:157], v[162:165], v[122:125]
	v_mfma_f32_16x16x32_bf16 v[114:117], v[146:149], v[170:173], v[114:117]
	v_mfma_f32_16x16x32_bf16 v[106:109], v[154:157], v[170:173], v[106:109]
	v_mfma_f32_16x16x32_bf16 v[98:101], v[146:149], v[182:185], v[98:101]
	v_mfma_f32_16x16x32_bf16 v[90:93], v[154:157], v[182:185], v[90:93]
	v_mfma_f32_16x16x32_bf16 v[82:85], v[146:149], v[190:193], v[82:85]
	v_mfma_f32_16x16x32_bf16 v[74:77], v[154:157], v[190:193], v[74:77]
	v_mfma_f32_16x16x32_bf16 v[126:129], v[150:153], v[166:169], v[126:129]
	v_mfma_f32_16x16x32_bf16 v[122:125], v[158:161], v[166:169], v[122:125]
	v_mfma_f32_16x16x32_bf16 v[114:117], v[150:153], v[174:177], v[114:117]
	v_mfma_f32_16x16x32_bf16 v[106:109], v[158:161], v[174:177], v[106:109]
	v_mfma_f32_16x16x32_bf16 v[98:101], v[150:153], v[186:189], v[98:101]
	v_mfma_f32_16x16x32_bf16 v[90:93], v[158:161], v[186:189], v[90:93]
	v_mfma_f32_16x16x32_bf16 v[82:85], v[150:153], v[194:197], v[82:85]
	v_mfma_f32_16x16x32_bf16 v[74:77], v[158:161], v[194:197], v[74:77]
	s_barrier
	s_mov_b32 m0, s28
	v_add_u32_e32 v140, 0x14000, v143
	v_lshl_add_u64 v[178:179], s[22:23], 0, v[0:1]
	ds_read_b128 v[198:201], v140
	ds_read_b128 v[202:205], v140 offset:1024
	ds_read_b128 v[206:209], v140 offset:2048
	ds_read_b128 v[210:213], v140 offset:3072
	global_load_lds_dwordx4 v[178:179], off
	v_lshl_add_u64 v[214:215], s[22:23], 0, v[134:135]
	s_mov_b32 m0, s29
	s_nop 0
	global_load_lds_dwordx4 v[214:215], off
	s_barrier
	s_waitcnt lgkmcnt(0)
	s_waitcnt lgkmcnt(0)
	v_mfma_f32_16x16x32_bf16 v[118:121], v[198:201], v[162:165], v[118:121]
	v_mfma_f32_16x16x32_bf16 v[110:113], v[206:209], v[162:165], v[110:113]
	v_mfma_f32_16x16x32_bf16 v[102:105], v[198:201], v[170:173], v[102:105]
	v_mfma_f32_16x16x32_bf16 v[94:97], v[206:209], v[170:173], v[94:97]
	v_mfma_f32_16x16x32_bf16 v[86:89], v[198:201], v[182:185], v[86:89]
	v_mfma_f32_16x16x32_bf16 v[78:81], v[206:209], v[182:185], v[78:81]
	v_mfma_f32_16x16x32_bf16 v[70:73], v[198:201], v[190:193], v[70:73]
	v_mfma_f32_16x16x32_bf16 v[66:69], v[206:209], v[190:193], v[66:69]
	v_mfma_f32_16x16x32_bf16 v[118:121], v[202:205], v[166:169], v[118:121]
	v_mfma_f32_16x16x32_bf16 v[110:113], v[210:213], v[166:169], v[110:113]
	v_mfma_f32_16x16x32_bf16 v[102:105], v[202:205], v[174:177], v[102:105]
	v_mfma_f32_16x16x32_bf16 v[94:97], v[210:213], v[174:177], v[94:97]
	v_mfma_f32_16x16x32_bf16 v[86:89], v[202:205], v[186:189], v[86:89]
	v_mfma_f32_16x16x32_bf16 v[78:81], v[210:213], v[186:189], v[78:81]
	v_mfma_f32_16x16x32_bf16 v[70:73], v[202:205], v[194:197], v[70:73]
	v_mfma_f32_16x16x32_bf16 v[66:69], v[210:213], v[194:197], v[66:69]
	s_mov_b32 m0, s27
	v_lshl_add_u64 v[216:217], s[24:25], 0, v[130:131]
	s_barrier
	ds_read_b128 v[162:165], v142 offset:16384
	ds_read_b128 v[166:169], v142 offset:17408
	ds_read_b128 v[170:173], v142 offset:18432
	ds_read_b128 v[174:177], v142 offset:19456
	ds_read_b128 v[182:185], v142 offset:20480
	ds_read_b128 v[186:189], v142 offset:21504
	ds_read_b128 v[190:193], v142 offset:22528
	ds_read_b128 v[194:197], v142 offset:23552
	global_load_lds_dwordx4 v[216:217], off
	v_lshl_add_u64 v[222:223], s[24:25], 0, v[132:133]
	s_mov_b32 m0, s30
	s_nop 0
	global_load_lds_dwordx4 v[222:223], off
	s_barrier
	s_waitcnt lgkmcnt(0)
	s_waitcnt lgkmcnt(0)
	v_mfma_f32_16x16x32_bf16 v[62:65], v[146:149], v[162:165], v[62:65]
	v_mfma_f32_16x16x32_bf16 v[58:61], v[154:157], v[162:165], v[58:61]
	v_mfma_f32_16x16x32_bf16 v[50:53], v[146:149], v[170:173], v[50:53]
	v_mfma_f32_16x16x32_bf16 v[42:45], v[154:157], v[170:173], v[42:45]
	v_mfma_f32_16x16x32_bf16 v[34:37], v[146:149], v[182:185], v[34:37]
	v_mfma_f32_16x16x32_bf16 v[26:29], v[154:157], v[182:185], v[26:29]
	v_mfma_f32_16x16x32_bf16 v[18:21], v[146:149], v[190:193], v[18:21]
	v_mfma_f32_16x16x32_bf16 v[10:13], v[154:157], v[190:193], v[10:13]
	v_mfma_f32_16x16x32_bf16 v[62:65], v[150:153], v[166:169], v[62:65]
	v_mfma_f32_16x16x32_bf16 v[58:61], v[158:161], v[166:169], v[58:61]
	v_mfma_f32_16x16x32_bf16 v[50:53], v[150:153], v[174:177], v[50:53]
	v_mfma_f32_16x16x32_bf16 v[42:45], v[158:161], v[174:177], v[42:45]
	v_mfma_f32_16x16x32_bf16 v[34:37], v[150:153], v[186:189], v[34:37]
	v_mfma_f32_16x16x32_bf16 v[26:29], v[158:161], v[186:189], v[26:29]
	v_mfma_f32_16x16x32_bf16 v[18:21], v[150:153], v[194:197], v[18:21]
	v_mfma_f32_16x16x32_bf16 v[10:13], v[158:161], v[194:197], v[10:13]
	s_barrier
	s_add_u32 s20, s22, 0x18000
	s_addc_u32 s21, s23, 0
	s_mov_b32 m0, s31
	v_lshl_add_u64 v[146:147], s[20:21], 0, v[0:1]
	global_load_lds_dwordx4 v[146:147], off
	v_lshl_add_u64 v[146:147], s[20:21], 0, v[134:135]
	s_mov_b32 m0, s34
	s_nop 0
	global_load_lds_dwordx4 v[146:147], off
	s_waitcnt vmcnt(6)
	s_barrier
	v_mfma_f32_16x16x32_bf16 v[54:57], v[198:201], v[162:165], v[54:57]
	v_mfma_f32_16x16x32_bf16 v[46:49], v[206:209], v[162:165], v[46:49]
	v_mfma_f32_16x16x32_bf16 v[38:41], v[198:201], v[170:173], v[38:41]
	v_mfma_f32_16x16x32_bf16 v[30:33], v[206:209], v[170:173], v[30:33]
	v_mfma_f32_16x16x32_bf16 v[22:25], v[198:201], v[182:185], v[22:25]
	v_mfma_f32_16x16x32_bf16 v[14:17], v[206:209], v[182:185], v[14:17]
	v_mfma_f32_16x16x32_bf16 v[6:9], v[198:201], v[190:193], v[6:9]
	v_mfma_f32_16x16x32_bf16 v[2:5], v[206:209], v[190:193], v[2:5]
	v_mfma_f32_16x16x32_bf16 v[54:57], v[202:205], v[166:169], v[54:57]
	v_mfma_f32_16x16x32_bf16 v[46:49], v[210:213], v[166:169], v[46:49]
	v_mfma_f32_16x16x32_bf16 v[38:41], v[202:205], v[174:177], v[38:41]
	v_mfma_f32_16x16x32_bf16 v[30:33], v[210:213], v[174:177], v[30:33]
	v_mfma_f32_16x16x32_bf16 v[22:25], v[202:205], v[186:189], v[22:25]
	v_mfma_f32_16x16x32_bf16 v[14:17], v[210:213], v[186:189], v[14:17]
	v_mfma_f32_16x16x32_bf16 v[6:9], v[202:205], v[194:197], v[6:9]
	v_mfma_f32_16x16x32_bf16 v[2:5], v[210:213], v[194:197], v[2:5]
	v_add_u32_e32 v140, 0x18000, v143
	s_barrier
	ds_read_b128 v[146:149], v140
	ds_read_b128 v[150:153], v140 offset:1024
	ds_read_b128 v[154:157], v140 offset:2048
	ds_read_b128 v[158:161], v140 offset:3072
	s_add_u32 s20, s24, 0x18000
	s_addc_u32 s21, s25, 0
	s_mov_b32 m0, s35
	v_lshl_add_u64 v[198:199], s[20:21], 0, v[130:131]
	ds_read_b128 v[162:165], v142 offset:32768
	ds_read_b128 v[166:169], v142 offset:33792
	ds_read_b128 v[170:173], v142 offset:34816
	ds_read_b128 v[174:177], v142 offset:35840
	ds_read_b128 v[182:185], v142 offset:36864
	ds_read_b128 v[186:189], v142 offset:37888
	ds_read_b128 v[190:193], v142 offset:38912
	ds_read_b128 v[194:197], v142 offset:39936
	global_load_lds_dwordx4 v[198:199], off
	v_lshl_add_u64 v[198:199], s[20:21], 0, v[132:133]
	s_mov_b32 m0, s36
	s_nop 0
	global_load_lds_dwordx4 v[198:199], off
	s_waitcnt lgkmcnt(8)
	s_barrier
	s_waitcnt lgkmcnt(0)
	s_waitcnt lgkmcnt(0)
	v_mfma_f32_16x16x32_bf16 v[126:129], v[146:149], v[162:165], v[126:129]
	v_mfma_f32_16x16x32_bf16 v[122:125], v[154:157], v[162:165], v[122:125]
	v_mfma_f32_16x16x32_bf16 v[114:117], v[146:149], v[170:173], v[114:117]
	v_mfma_f32_16x16x32_bf16 v[106:109], v[154:157], v[170:173], v[106:109]
	v_mfma_f32_16x16x32_bf16 v[98:101], v[146:149], v[182:185], v[98:101]
	v_mfma_f32_16x16x32_bf16 v[90:93], v[154:157], v[182:185], v[90:93]
	v_mfma_f32_16x16x32_bf16 v[82:85], v[146:149], v[190:193], v[82:85]
	v_mfma_f32_16x16x32_bf16 v[74:77], v[154:157], v[190:193], v[74:77]
	v_mfma_f32_16x16x32_bf16 v[126:129], v[150:153], v[166:169], v[126:129]
	v_mfma_f32_16x16x32_bf16 v[122:125], v[158:161], v[166:169], v[122:125]
	v_mfma_f32_16x16x32_bf16 v[114:117], v[150:153], v[174:177], v[114:117]
	v_mfma_f32_16x16x32_bf16 v[106:109], v[158:161], v[174:177], v[106:109]
	v_mfma_f32_16x16x32_bf16 v[98:101], v[150:153], v[186:189], v[98:101]
	v_mfma_f32_16x16x32_bf16 v[90:93], v[158:161], v[186:189], v[90:93]
	v_mfma_f32_16x16x32_bf16 v[82:85], v[150:153], v[194:197], v[82:85]
	v_mfma_f32_16x16x32_bf16 v[74:77], v[158:161], v[194:197], v[74:77]
	s_barrier
	s_mov_b32 m0, s37
	v_add_u32_e32 v140, 0x1c000, v143
	v_lshl_add_u64 v[178:179], v[178:179], 0, s[84:85]
	ds_read_b128 v[198:201], v140
	ds_read_b128 v[202:205], v140 offset:1024
	ds_read_b128 v[206:209], v140 offset:2048
	ds_read_b128 v[210:213], v140 offset:3072
	global_load_lds_dwordx4 v[178:179], off
	v_lshl_add_u64 v[178:179], v[214:215], 0, s[84:85]
	s_mov_b32 m0, s38
	s_nop 0
	global_load_lds_dwordx4 v[178:179], off
	s_barrier
	s_waitcnt lgkmcnt(0)
	s_waitcnt lgkmcnt(0)
	v_mfma_f32_16x16x32_bf16 v[118:121], v[198:201], v[162:165], v[118:121]
	v_mfma_f32_16x16x32_bf16 v[110:113], v[206:209], v[162:165], v[110:113]
	v_mfma_f32_16x16x32_bf16 v[102:105], v[198:201], v[170:173], v[102:105]
	v_mfma_f32_16x16x32_bf16 v[94:97], v[206:209], v[170:173], v[94:97]
	v_mfma_f32_16x16x32_bf16 v[86:89], v[198:201], v[182:185], v[86:89]
	v_mfma_f32_16x16x32_bf16 v[78:81], v[206:209], v[182:185], v[78:81]
	v_mfma_f32_16x16x32_bf16 v[70:73], v[198:201], v[190:193], v[70:73]
	v_mfma_f32_16x16x32_bf16 v[66:69], v[206:209], v[190:193], v[66:69]
	v_mfma_f32_16x16x32_bf16 v[118:121], v[202:205], v[166:169], v[118:121]
	v_mfma_f32_16x16x32_bf16 v[110:113], v[210:213], v[166:169], v[110:113]
	v_mfma_f32_16x16x32_bf16 v[102:105], v[202:205], v[174:177], v[102:105]
	v_mfma_f32_16x16x32_bf16 v[94:97], v[210:213], v[174:177], v[94:97]
	v_mfma_f32_16x16x32_bf16 v[86:89], v[202:205], v[186:189], v[86:89]
	v_mfma_f32_16x16x32_bf16 v[78:81], v[210:213], v[186:189], v[78:81]
	v_mfma_f32_16x16x32_bf16 v[70:73], v[202:205], v[194:197], v[70:73]
	v_mfma_f32_16x16x32_bf16 v[66:69], v[210:213], v[194:197], v[66:69]
	s_mov_b32 m0, s39
	v_lshl_add_u64 v[178:179], v[216:217], 0, s[84:85]
	s_barrier
	ds_read_b128 v[162:165], v142 offset:49152
	ds_read_b128 v[166:169], v142 offset:50176
	ds_read_b128 v[170:173], v142 offset:51200
	ds_read_b128 v[174:177], v142 offset:52224
	ds_read_b128 v[182:185], v142 offset:53248
	ds_read_b128 v[186:189], v142 offset:54272
	ds_read_b128 v[190:193], v142 offset:55296
	ds_read_b128 v[194:197], v142 offset:56320
	global_load_lds_dwordx4 v[178:179], off
	v_lshl_add_u64 v[178:179], v[222:223], 0, s[84:85]
	s_mov_b32 m0, s60
	s_nop 0
	global_load_lds_dwordx4 v[178:179], off
	s_barrier
	s_waitcnt lgkmcnt(0)
	s_waitcnt lgkmcnt(0)
	v_mfma_f32_16x16x32_bf16 v[62:65], v[146:149], v[162:165], v[62:65]
	v_mfma_f32_16x16x32_bf16 v[58:61], v[154:157], v[162:165], v[58:61]
	v_mfma_f32_16x16x32_bf16 v[50:53], v[146:149], v[170:173], v[50:53]
	v_mfma_f32_16x16x32_bf16 v[42:45], v[154:157], v[170:173], v[42:45]
	v_mfma_f32_16x16x32_bf16 v[34:37], v[146:149], v[182:185], v[34:37]
	v_mfma_f32_16x16x32_bf16 v[26:29], v[154:157], v[182:185], v[26:29]
	v_mfma_f32_16x16x32_bf16 v[18:21], v[146:149], v[190:193], v[18:21]
	v_mfma_f32_16x16x32_bf16 v[10:13], v[154:157], v[190:193], v[10:13]
	v_mfma_f32_16x16x32_bf16 v[62:65], v[150:153], v[166:169], v[62:65]
	v_mfma_f32_16x16x32_bf16 v[58:61], v[158:161], v[166:169], v[58:61]
	v_mfma_f32_16x16x32_bf16 v[50:53], v[150:153], v[174:177], v[50:53]
	v_mfma_f32_16x16x32_bf16 v[42:45], v[158:161], v[174:177], v[42:45]
	v_mfma_f32_16x16x32_bf16 v[34:37], v[150:153], v[186:189], v[34:37]
	v_mfma_f32_16x16x32_bf16 v[26:29], v[158:161], v[186:189], v[26:29]
	v_mfma_f32_16x16x32_bf16 v[18:21], v[150:153], v[194:197], v[18:21]
	v_mfma_f32_16x16x32_bf16 v[10:13], v[158:161], v[194:197], v[10:13]
	s_barrier
	s_add_u32 s20, s22, 0x18080
	s_addc_u32 s21, s23, 0
	s_mov_b32 m0, s68
	v_lshl_add_u64 v[146:147], s[20:21], 0, v[0:1]
	global_load_lds_dwordx4 v[146:147], off
	v_lshl_add_u64 v[146:147], s[20:21], 0, v[134:135]
	s_mov_b32 m0, s69
	s_nop 0
	global_load_lds_dwordx4 v[146:147], off
	s_waitcnt vmcnt(6)
	s_barrier
	v_mfma_f32_16x16x32_bf16 v[54:57], v[198:201], v[162:165], v[54:57]
	v_mfma_f32_16x16x32_bf16 v[46:49], v[206:209], v[162:165], v[46:49]
	v_mfma_f32_16x16x32_bf16 v[38:41], v[198:201], v[170:173], v[38:41]
	v_mfma_f32_16x16x32_bf16 v[30:33], v[206:209], v[170:173], v[30:33]
	v_mfma_f32_16x16x32_bf16 v[22:25], v[198:201], v[182:185], v[22:25]
	v_mfma_f32_16x16x32_bf16 v[14:17], v[206:209], v[182:185], v[14:17]
	v_mfma_f32_16x16x32_bf16 v[6:9], v[198:201], v[190:193], v[6:9]
	v_mfma_f32_16x16x32_bf16 v[2:5], v[206:209], v[190:193], v[2:5]
	v_mfma_f32_16x16x32_bf16 v[54:57], v[202:205], v[166:169], v[54:57]
	v_mfma_f32_16x16x32_bf16 v[46:49], v[210:213], v[166:169], v[46:49]
	v_mfma_f32_16x16x32_bf16 v[38:41], v[202:205], v[174:177], v[38:41]
	v_mfma_f32_16x16x32_bf16 v[30:33], v[210:213], v[174:177], v[30:33]
	v_mfma_f32_16x16x32_bf16 v[22:25], v[202:205], v[186:189], v[22:25]
	v_mfma_f32_16x16x32_bf16 v[14:17], v[210:213], v[186:189], v[14:17]
	v_mfma_f32_16x16x32_bf16 v[6:9], v[202:205], v[194:197], v[6:9]
	v_mfma_f32_16x16x32_bf16 v[2:5], v[210:213], v[194:197], v[2:5]
	s_add_i32 s96, s96, 2
	s_add_u32 s93, s93, 0x100
	s_addc_u32 s94, s94, 0
	s_cmp_gt_u32 s96, 3
	s_mov_b64 s[20:21], s[6:7]
	s_barrier
	s_cbranch_scc0 .LBB0_926
	v_lshl_add_u32 v140, s90, 8, v144
	v_lshl_add_u32 v145, s92, 8, v141
	v_cmp_gt_u32_e32 vcc, s63, v140
	s_and_saveexec_b64 s[6:7], vcc
	s_cbranch_execz .LBB0_929
	v_cvt_pk_bf16_f32 v126, v126, v127
	v_cvt_pk_bf16_f32 v127, v128, v129
	v_cvt_pk_bf16_f32 v128, v122, v123
	v_cvt_pk_bf16_f32 v129, v124, v125
	v_mad_u64_u32 v[122:123], s[20:21], v145, s63, v[140:141]
	v_mov_b32_e32 v123, v1
	v_lshl_add_u64 v[122:123], v[122:123], 1, s[10:11]
	global_store_dwordx4 v[122:123], v[126:129], off

.LBB0_1052:
	v_add_u32_e32 v140, 0x10000, v143
	ds_read_b128 v[146:149], v140
	ds_read_b128 v[150:153], v140 offset:1024
	ds_read_b128 v[154:157], v140 offset:2048
	ds_read_b128 v[158:161], v140 offset:3072
	s_add_u32 s6, s20, 0x100
	s_addc_u32 s7, s21, 0
	s_cmp_eq_u32 s94, 2
	s_cselect_b32 s25, s17, s7
	s_cselect_b32 s24, s16, s6
	s_cselect_b32 s23, s19, s93
	s_cselect_b32 s22, s18, s92
	v_lshl_add_u64 v[178:179], s[20:21], 0, v[136:137]
	s_add_i32 m0, s26, 0xc000
	ds_read_b128 v[162:165], v142
	ds_read_b128 v[166:169], v142 offset:1024
	ds_read_b128 v[170:173], v142 offset:2048
	ds_read_b128 v[174:177], v142 offset:3072
	ds_read_b128 v[182:185], v142 offset:4096
	ds_read_b128 v[186:189], v142 offset:5120
	ds_read_b128 v[190:193], v142 offset:6144
	ds_read_b128 v[194:197], v142 offset:7168
	global_load_lds_dwordx4 v[178:179], off
	v_lshl_add_u64 v[178:179], s[20:21], 0, v[138:139]
	s_add_i32 m0, s26, 0xe000
	s_nop 0
	global_load_lds_dwordx4 v[178:179], off
	s_waitcnt lgkmcnt(8)
	s_barrier
	s_waitcnt lgkmcnt(0)
	s_waitcnt lgkmcnt(0)
	v_mfma_f32_16x16x32_bf16 v[126:129], v[146:149], v[162:165], v[126:129]
	v_mfma_f32_16x16x32_bf16 v[122:125], v[154:157], v[162:165], v[122:125]
	v_mfma_f32_16x16x32_bf16 v[114:117], v[146:149], v[170:173], v[114:117]
	v_mfma_f32_16x16x32_bf16 v[106:109], v[154:157], v[170:173], v[106:109]
	v_mfma_f32_16x16x32_bf16 v[98:101], v[146:149], v[182:185], v[98:101]
	v_mfma_f32_16x16x32_bf16 v[90:93], v[154:157], v[182:185], v[90:93]
	v_mfma_f32_16x16x32_bf16 v[82:85], v[146:149], v[190:193], v[82:85]
	v_mfma_f32_16x16x32_bf16 v[74:77], v[154:157], v[190:193], v[74:77]
	v_mfma_f32_16x16x32_bf16 v[126:129], v[150:153], v[166:169], v[126:129]
	v_mfma_f32_16x16x32_bf16 v[122:125], v[158:161], v[166:169], v[122:125]
	v_mfma_f32_16x16x32_bf16 v[114:117], v[150:153], v[174:177], v[114:117]
	v_mfma_f32_16x16x32_bf16 v[106:109], v[158:161], v[174:177], v[106:109]
	v_mfma_f32_16x16x32_bf16 v[98:101], v[150:153], v[186:189], v[98:101]
	v_mfma_f32_16x16x32_bf16 v[90:93], v[158:161], v[186:189], v[90:93]
	v_mfma_f32_16x16x32_bf16 v[82:85], v[150:153], v[194:197], v[82:85]
	v_mfma_f32_16x16x32_bf16 v[74:77], v[158:161], v[194:197], v[74:77]
	s_barrier
	s_mov_b32 m0, s27
	v_add_u32_e32 v140, 0x14000, v143
	v_lshl_add_u64 v[178:179], s[22:23], 0, v[0:1]
	ds_read_b128 v[198:201], v140
	ds_read_b128 v[202:205], v140 offset:1024
	ds_read_b128 v[206:209], v140 offset:2048
	ds_read_b128 v[210:213], v140 offset:3072
	global_load_lds_dwordx4 v[178:179], off
	v_lshl_add_u64 v[214:215], s[22:23], 0, v[134:135]
	s_mov_b32 m0, s28
	s_nop 0
	global_load_lds_dwordx4 v[214:215], off
	s_barrier
	s_waitcnt lgkmcnt(0)
	s_waitcnt lgkmcnt(0)
	v_mfma_f32_16x16x32_bf16 v[118:121], v[198:201], v[162:165], v[118:121]
	v_mfma_f32_16x16x32_bf16 v[110:113], v[206:209], v[162:165], v[110:113]
	v_mfma_f32_16x16x32_bf16 v[102:105], v[198:201], v[170:173], v[102:105]
	v_mfma_f32_16x16x32_bf16 v[94:97], v[206:209], v[170:173], v[94:97]
	v_mfma_f32_16x16x32_bf16 v[86:89], v[198:201], v[182:185], v[86:89]
	v_mfma_f32_16x16x32_bf16 v[78:81], v[206:209], v[182:185], v[78:81]
	v_mfma_f32_16x16x32_bf16 v[70:73], v[198:201], v[190:193], v[70:73]
	v_mfma_f32_16x16x32_bf16 v[66:69], v[206:209], v[190:193], v[66:69]
	v_mfma_f32_16x16x32_bf16 v[118:121], v[202:205], v[166:169], v[118:121]
	v_mfma_f32_16x16x32_bf16 v[110:113], v[210:213], v[166:169], v[110:113]
	v_mfma_f32_16x16x32_bf16 v[102:105], v[202:205], v[174:177], v[102:105]
	v_mfma_f32_16x16x32_bf16 v[94:97], v[210:213], v[174:177], v[94:97]
	v_mfma_f32_16x16x32_bf16 v[86:89], v[202:205], v[186:189], v[86:89]
	v_mfma_f32_16x16x32_bf16 v[78:81], v[210:213], v[186:189], v[78:81]
	v_mfma_f32_16x16x32_bf16 v[70:73], v[202:205], v[194:197], v[70:73]
	v_mfma_f32_16x16x32_bf16 v[66:69], v[210:213], v[194:197], v[66:69]
	s_mov_b32 m0, s26
	v_lshl_add_u64 v[216:217], s[24:25], 0, v[130:131]
	s_barrier
	ds_read_b128 v[162:165], v142 offset:16384
	ds_read_b128 v[166:169], v142 offset:17408
	ds_read_b128 v[170:173], v142 offset:18432
	ds_read_b128 v[174:177], v142 offset:19456
	ds_read_b128 v[182:185], v142 offset:20480
	ds_read_b128 v[186:189], v142 offset:21504
	ds_read_b128 v[190:193], v142 offset:22528
	ds_read_b128 v[194:197], v142 offset:23552
	global_load_lds_dwordx4 v[216:217], off
	v_lshl_add_u64 v[222:223], s[24:25], 0, v[132:133]
	s_mov_b32 m0, s29
	s_nop 0
	global_load_lds_dwordx4 v[222:223], off
	s_barrier
	s_waitcnt lgkmcnt(0)
	s_waitcnt lgkmcnt(0)
	v_mfma_f32_16x16x32_bf16 v[62:65], v[146:149], v[162:165], v[62:65]
	v_mfma_f32_16x16x32_bf16 v[58:61], v[154:157], v[162:165], v[58:61]
	v_mfma_f32_16x16x32_bf16 v[50:53], v[146:149], v[170:173], v[50:53]
	v_mfma_f32_16x16x32_bf16 v[42:45], v[154:157], v[170:173], v[42:45]
	v_mfma_f32_16x16x32_bf16 v[34:37], v[146:149], v[182:185], v[34:37]
	v_mfma_f32_16x16x32_bf16 v[26:29], v[154:157], v[182:185], v[26:29]
	v_mfma_f32_16x16x32_bf16 v[18:21], v[146:149], v[190:193], v[18:21]
	v_mfma_f32_16x16x32_bf16 v[10:13], v[154:157], v[190:193], v[10:13]
	v_mfma_f32_16x16x32_bf16 v[62:65], v[150:153], v[166:169], v[62:65]
	v_mfma_f32_16x16x32_bf16 v[58:61], v[158:161], v[166:169], v[58:61]
	v_mfma_f32_16x16x32_bf16 v[50:53], v[150:153], v[174:177], v[50:53]
	v_mfma_f32_16x16x32_bf16 v[42:45], v[158:161], v[174:177], v[42:45]
	v_mfma_f32_16x16x32_bf16 v[34:37], v[150:153], v[186:189], v[34:37]
	v_mfma_f32_16x16x32_bf16 v[26:29], v[158:161], v[186:189], v[26:29]
	v_mfma_f32_16x16x32_bf16 v[18:21], v[150:153], v[194:197], v[18:21]
	v_mfma_f32_16x16x32_bf16 v[10:13], v[158:161], v[194:197], v[10:13]
	s_barrier
	s_add_u32 s20, s22, 0x18000
	s_addc_u32 s21, s23, 0
	s_mov_b32 m0, s30
	v_lshl_add_u64 v[146:147], s[20:21], 0, v[0:1]
	global_load_lds_dwordx4 v[146:147], off
	v_lshl_add_u64 v[146:147], s[20:21], 0, v[134:135]
	s_mov_b32 m0, s31
	s_nop 0
	global_load_lds_dwordx4 v[146:147], off
	s_waitcnt vmcnt(6)
	s_barrier
	v_mfma_f32_16x16x32_bf16 v[54:57], v[198:201], v[162:165], v[54:57]
	v_mfma_f32_16x16x32_bf16 v[46:49], v[206:209], v[162:165], v[46:49]
	v_mfma_f32_16x16x32_bf16 v[38:41], v[198:201], v[170:173], v[38:41]
	v_mfma_f32_16x16x32_bf16 v[30:33], v[206:209], v[170:173], v[30:33]
	v_mfma_f32_16x16x32_bf16 v[22:25], v[198:201], v[182:185], v[22:25]
	v_mfma_f32_16x16x32_bf16 v[14:17], v[206:209], v[182:185], v[14:17]
	v_mfma_f32_16x16x32_bf16 v[6:9], v[198:201], v[190:193], v[6:9]
	v_mfma_f32_16x16x32_bf16 v[2:5], v[206:209], v[190:193], v[2:5]
	v_mfma_f32_16x16x32_bf16 v[54:57], v[202:205], v[166:169], v[54:57]
	v_mfma_f32_16x16x32_bf16 v[46:49], v[210:213], v[166:169], v[46:49]
	v_mfma_f32_16x16x32_bf16 v[38:41], v[202:205], v[174:177], v[38:41]
	v_mfma_f32_16x16x32_bf16 v[30:33], v[210:213], v[174:177], v[30:33]
	v_mfma_f32_16x16x32_bf16 v[22:25], v[202:205], v[186:189], v[22:25]
	v_mfma_f32_16x16x32_bf16 v[14:17], v[210:213], v[186:189], v[14:17]
	v_mfma_f32_16x16x32_bf16 v[6:9], v[202:205], v[194:197], v[6:9]
	v_mfma_f32_16x16x32_bf16 v[2:5], v[210:213], v[194:197], v[2:5]
	v_add_u32_e32 v140, 0x18000, v143
	s_barrier
	ds_read_b128 v[146:149], v140
	ds_read_b128 v[150:153], v140 offset:1024
	ds_read_b128 v[154:157], v140 offset:2048
	ds_read_b128 v[158:161], v140 offset:3072
	s_add_u32 s20, s24, 0x18000
	s_addc_u32 s21, s25, 0
	s_mov_b32 m0, s34
	v_lshl_add_u64 v[198:199], s[20:21], 0, v[130:131]
	ds_read_b128 v[162:165], v142 offset:32768
	ds_read_b128 v[166:169], v142 offset:33792
	ds_read_b128 v[170:173], v142 offset:34816
	ds_read_b128 v[174:177], v142 offset:35840
	ds_read_b128 v[182:185], v142 offset:36864
	ds_read_b128 v[186:189], v142 offset:37888
	ds_read_b128 v[190:193], v142 offset:38912
	ds_read_b128 v[194:197], v142 offset:39936
	global_load_lds_dwordx4 v[198:199], off
	v_lshl_add_u64 v[198:199], s[20:21], 0, v[132:133]
	s_mov_b32 m0, s35
	s_nop 0
	global_load_lds_dwordx4 v[198:199], off
	s_waitcnt lgkmcnt(8)
	s_barrier
	s_waitcnt lgkmcnt(0)
	s_waitcnt lgkmcnt(0)
	v_mfma_f32_16x16x32_bf16 v[126:129], v[146:149], v[162:165], v[126:129]
	v_mfma_f32_16x16x32_bf16 v[122:125], v[154:157], v[162:165], v[122:125]
	v_mfma_f32_16x16x32_bf16 v[114:117], v[146:149], v[170:173], v[114:117]
	v_mfma_f32_16x16x32_bf16 v[106:109], v[154:157], v[170:173], v[106:109]
	v_mfma_f32_16x16x32_bf16 v[98:101], v[146:149], v[182:185], v[98:101]
	v_mfma_f32_16x16x32_bf16 v[90:93], v[154:157], v[182:185], v[90:93]
	v_mfma_f32_16x16x32_bf16 v[82:85], v[146:149], v[190:193], v[82:85]
	v_mfma_f32_16x16x32_bf16 v[74:77], v[154:157], v[190:193], v[74:77]
	v_mfma_f32_16x16x32_bf16 v[126:129], v[150:153], v[166:169], v[126:129]
	v_mfma_f32_16x16x32_bf16 v[122:125], v[158:161], v[166:169], v[122:125]
	v_mfma_f32_16x16x32_bf16 v[114:117], v[150:153], v[174:177], v[114:117]
	v_mfma_f32_16x16x32_bf16 v[106:109], v[158:161], v[174:177], v[106:109]
	v_mfma_f32_16x16x32_bf16 v[98:101], v[150:153], v[186:189], v[98:101]
	v_mfma_f32_16x16x32_bf16 v[90:93], v[158:161], v[186:189], v[90:93]
	v_mfma_f32_16x16x32_bf16 v[82:85], v[150:153], v[194:197], v[82:85]
	v_mfma_f32_16x16x32_bf16 v[74:77], v[158:161], v[194:197], v[74:77]
	s_barrier
	s_mov_b32 m0, s36
	v_add_u32_e32 v140, 0x1c000, v143
	v_lshl_add_u64 v[178:179], v[178:179], 0, s[84:85]
	ds_read_b128 v[198:201], v140
	ds_read_b128 v[202:205], v140 offset:1024
	ds_read_b128 v[206:209], v140 offset:2048
	ds_read_b128 v[210:213], v140 offset:3072
	global_load_lds_dwordx4 v[178:179], off
	v_lshl_add_u64 v[178:179], v[214:215], 0, s[84:85]
	s_mov_b32 m0, s37
	s_nop 0
	global_load_lds_dwordx4 v[178:179], off
	s_barrier
	s_waitcnt lgkmcnt(0)
	s_waitcnt lgkmcnt(0)
	v_mfma_f32_16x16x32_bf16 v[118:121], v[198:201], v[162:165], v[118:121]
	v_mfma_f32_16x16x32_bf16 v[110:113], v[206:209], v[162:165], v[110:113]
	v_mfma_f32_16x16x32_bf16 v[102:105], v[198:201], v[170:173], v[102:105]
	v_mfma_f32_16x16x32_bf16 v[94:97], v[206:209], v[170:173], v[94:97]
	v_mfma_f32_16x16x32_bf16 v[86:89], v[198:201], v[182:185], v[86:89]
	v_mfma_f32_16x16x32_bf16 v[78:81], v[206:209], v[182:185], v[78:81]
	v_mfma_f32_16x16x32_bf16 v[70:73], v[198:201], v[190:193], v[70:73]
	v_mfma_f32_16x16x32_bf16 v[66:69], v[206:209], v[190:193], v[66:69]
	v_mfma_f32_16x16x32_bf16 v[118:121], v[202:205], v[166:169], v[118:121]
	v_mfma_f32_16x16x32_bf16 v[110:113], v[210:213], v[166:169], v[110:113]
	v_mfma_f32_16x16x32_bf16 v[102:105], v[202:205], v[174:177], v[102:105]
	v_mfma_f32_16x16x32_bf16 v[94:97], v[210:213], v[174:177], v[94:97]
	v_mfma_f32_16x16x32_bf16 v[86:89], v[202:205], v[186:189], v[86:89]
	v_mfma_f32_16x16x32_bf16 v[78:81], v[210:213], v[186:189], v[78:81]
	v_mfma_f32_16x16x32_bf16 v[70:73], v[202:205], v[194:197], v[70:73]
	v_mfma_f32_16x16x32_bf16 v[66:69], v[210:213], v[194:197], v[66:69]
	s_mov_b32 m0, s38
	v_lshl_add_u64 v[178:179], v[216:217], 0, s[84:85]
	s_barrier
	ds_read_b128 v[162:165], v142 offset:49152
	ds_read_b128 v[166:169], v142 offset:50176
	ds_read_b128 v[170:173], v142 offset:51200
	ds_read_b128 v[174:177], v142 offset:52224
	ds_read_b128 v[182:185], v142 offset:53248
	ds_read_b128 v[186:189], v142 offset:54272
	ds_read_b128 v[190:193], v142 offset:55296
	ds_read_b128 v[194:197], v142 offset:56320
	global_load_lds_dwordx4 v[178:179], off
	v_lshl_add_u64 v[178:179], v[222:223], 0, s[84:85]
	s_mov_b32 m0, s39
	s_nop 0
	global_load_lds_dwordx4 v[178:179], off
	s_barrier
	s_waitcnt lgkmcnt(0)
	s_waitcnt lgkmcnt(0)
	v_mfma_f32_16x16x32_bf16 v[62:65], v[146:149], v[162:165], v[62:65]
	v_mfma_f32_16x16x32_bf16 v[58:61], v[154:157], v[162:165], v[58:61]
	v_mfma_f32_16x16x32_bf16 v[50:53], v[146:149], v[170:173], v[50:53]
	v_mfma_f32_16x16x32_bf16 v[42:45], v[154:157], v[170:173], v[42:45]
	v_mfma_f32_16x16x32_bf16 v[34:37], v[146:149], v[182:185], v[34:37]
	v_mfma_f32_16x16x32_bf16 v[26:29], v[154:157], v[182:185], v[26:29]
	v_mfma_f32_16x16x32_bf16 v[18:21], v[146:149], v[190:193], v[18:21]
	v_mfma_f32_16x16x32_bf16 v[10:13], v[154:157], v[190:193], v[10:13]
	v_mfma_f32_16x16x32_bf16 v[62:65], v[150:153], v[166:169], v[62:65]
	v_mfma_f32_16x16x32_bf16 v[58:61], v[158:161], v[166:169], v[58:61]
	v_mfma_f32_16x16x32_bf16 v[50:53], v[150:153], v[174:177], v[50:53]
	v_mfma_f32_16x16x32_bf16 v[42:45], v[158:161], v[174:177], v[42:45]
	v_mfma_f32_16x16x32_bf16 v[34:37], v[150:153], v[186:189], v[34:37]
	v_mfma_f32_16x16x32_bf16 v[26:29], v[158:161], v[186:189], v[26:29]
	v_mfma_f32_16x16x32_bf16 v[18:21], v[150:153], v[194:197], v[18:21]
	v_mfma_f32_16x16x32_bf16 v[10:13], v[158:161], v[194:197], v[10:13]
	s_barrier
	s_add_u32 s20, s22, 0x18080
	s_addc_u32 s21, s23, 0
	s_mov_b32 m0, s60
	v_lshl_add_u64 v[146:147], s[20:21], 0, v[0:1]
	global_load_lds_dwordx4 v[146:147], off
	v_lshl_add_u64 v[146:147], s[20:21], 0, v[134:135]
	s_mov_b32 m0, s68
	s_nop 0
	global_load_lds_dwordx4 v[146:147], off
	s_waitcnt vmcnt(6)
	s_barrier
	v_mfma_f32_16x16x32_bf16 v[54:57], v[198:201], v[162:165], v[54:57]
	v_mfma_f32_16x16x32_bf16 v[46:49], v[206:209], v[162:165], v[46:49]
	v_mfma_f32_16x16x32_bf16 v[38:41], v[198:201], v[170:173], v[38:41]
	v_mfma_f32_16x16x32_bf16 v[30:33], v[206:209], v[170:173], v[30:33]
	v_mfma_f32_16x16x32_bf16 v[22:25], v[198:201], v[182:185], v[22:25]
	v_mfma_f32_16x16x32_bf16 v[14:17], v[206:209], v[182:185], v[14:17]
	v_mfma_f32_16x16x32_bf16 v[6:9], v[198:201], v[190:193], v[6:9]
	v_mfma_f32_16x16x32_bf16 v[2:5], v[206:209], v[190:193], v[2:5]
	v_mfma_f32_16x16x32_bf16 v[54:57], v[202:205], v[166:169], v[54:57]
	v_mfma_f32_16x16x32_bf16 v[46:49], v[210:213], v[166:169], v[46:49]
	v_mfma_f32_16x16x32_bf16 v[38:41], v[202:205], v[174:177], v[38:41]
	v_mfma_f32_16x16x32_bf16 v[30:33], v[210:213], v[174:177], v[30:33]
	v_mfma_f32_16x16x32_bf16 v[22:25], v[202:205], v[186:189], v[22:25]
	v_mfma_f32_16x16x32_bf16 v[14:17], v[210:213], v[186:189], v[14:17]
	v_mfma_f32_16x16x32_bf16 v[6:9], v[202:205], v[194:197], v[6:9]
	v_mfma_f32_16x16x32_bf16 v[2:5], v[210:213], v[194:197], v[2:5]
	s_add_i32 s94, s94, 2
	s_add_u32 s92, s92, 0x100
	s_addc_u32 s93, s93, 0
	s_cmp_gt_u32 s94, 3
	s_mov_b64 s[20:21], s[6:7]
	s_barrier
	s_cbranch_scc0 .LBB0_1052
	v_lshl_add_u32 v140, s89, 8, v144
	v_lshl_add_u32 v145, s90, 8, v141
	v_cmp_gt_u32_e32 vcc, s63, v140
	s_and_saveexec_b64 s[6:7], vcc
	s_cbranch_execz .LBB0_1055
	v_cvt_pk_bf16_f32 v126, v126, v127
	v_cvt_pk_bf16_f32 v127, v128, v129
	v_cvt_pk_bf16_f32 v128, v122, v123
	v_cvt_pk_bf16_f32 v129, v124, v125
	v_mad_u64_u32 v[122:123], s[20:21], v145, s63, v[140:141]
	v_mov_b32_e32 v123, v1
	v_lshl_add_u64 v[122:123], v[122:123], 1, s[10:11]
	global_store_dwordx4 v[122:123], v[126:129], off

.LBB0_1334:
	v_add_u32_e32 v0, 0x10000, v148
	ds_read_b128 v[142:145], v0
	ds_read_b128 v[150:153], v0 offset:1024
	ds_read_b128 v[154:157], v0 offset:2048
	ds_read_b128 v[158:161], v0 offset:3072
	s_add_u32 s26, s24, 0xfffc0080
	s_addc_u32 s27, s25, -1
	s_cmp_eq_u32 vcc_lo, 12
	s_cselect_b32 s29, s2, s27
	s_cselect_b32 s28, s15, s26
	s_cselect_b32 s27, s13, s94
	s_cselect_b32 s26, s89, s90
	v_lshl_add_u64 v[178:179], s[24:25], 0, v[138:139]
	s_add_i32 m0, s36, 0xc000
	ds_read_b128 v[162:165], v147
	ds_read_b128 v[166:169], v147 offset:1024
	ds_read_b128 v[170:173], v147 offset:2048
	ds_read_b128 v[174:177], v147 offset:3072
	ds_read_b128 v[182:185], v147 offset:4096
	ds_read_b128 v[186:189], v147 offset:5120
	ds_read_b128 v[190:193], v147 offset:6144
	ds_read_b128 v[194:197], v147 offset:7168
	global_load_lds_dwordx4 v[178:179], off
	v_lshl_add_u64 v[178:179], s[24:25], 0, v[140:141]
	s_add_i32 m0, s36, 0xe000
	s_nop 0
	global_load_lds_dwordx4 v[178:179], off
	s_waitcnt lgkmcnt(8)
	s_barrier
	s_waitcnt lgkmcnt(0)
	s_waitcnt lgkmcnt(0)
	v_mfma_f32_16x16x32_bf16 v[126:129], v[142:145], v[162:165], v[126:129]
	v_mfma_f32_16x16x32_bf16 v[122:125], v[154:157], v[162:165], v[122:125]
	v_mfma_f32_16x16x32_bf16 v[110:113], v[142:145], v[170:173], v[110:113]
	v_mfma_f32_16x16x32_bf16 v[106:109], v[154:157], v[170:173], v[106:109]
	v_mfma_f32_16x16x32_bf16 v[94:97], v[142:145], v[182:185], v[94:97]
	v_mfma_f32_16x16x32_bf16 v[90:93], v[154:157], v[182:185], v[90:93]
	v_mfma_f32_16x16x32_bf16 v[78:81], v[142:145], v[190:193], v[78:81]
	v_mfma_f32_16x16x32_bf16 v[74:77], v[154:157], v[190:193], v[74:77]
	v_mfma_f32_16x16x32_bf16 v[126:129], v[150:153], v[166:169], v[126:129]
	v_mfma_f32_16x16x32_bf16 v[122:125], v[158:161], v[166:169], v[122:125]
	v_mfma_f32_16x16x32_bf16 v[110:113], v[150:153], v[174:177], v[110:113]
	v_mfma_f32_16x16x32_bf16 v[106:109], v[158:161], v[174:177], v[106:109]
	v_mfma_f32_16x16x32_bf16 v[94:97], v[150:153], v[186:189], v[94:97]
	v_mfma_f32_16x16x32_bf16 v[90:93], v[158:161], v[186:189], v[90:93]
	v_mfma_f32_16x16x32_bf16 v[78:81], v[150:153], v[194:197], v[78:81]
	v_mfma_f32_16x16x32_bf16 v[74:77], v[158:161], v[194:197], v[74:77]
	s_barrier
	s_mov_b32 m0, s21
	v_add_u32_e32 v0, 0x14000, v148
	v_lshl_add_u64 v[178:179], s[26:27], 0, v[134:135]
	ds_read_b128 v[198:201], v0
	ds_read_b128 v[202:205], v0 offset:1024
	ds_read_b128 v[206:209], v0 offset:2048
	ds_read_b128 v[210:213], v0 offset:3072
	global_load_lds_dwordx4 v[178:179], off
	v_lshl_add_u64 v[214:215], s[26:27], 0, v[130:131]
	s_mov_b32 m0, s23
	s_nop 0
	global_load_lds_dwordx4 v[214:215], off
	s_barrier
	s_waitcnt lgkmcnt(0)
	s_waitcnt lgkmcnt(0)
	v_mfma_f32_16x16x32_bf16 v[118:121], v[198:201], v[162:165], v[118:121]
	v_mfma_f32_16x16x32_bf16 v[114:117], v[206:209], v[162:165], v[114:117]
	v_mfma_f32_16x16x32_bf16 v[102:105], v[198:201], v[170:173], v[102:105]
	v_mfma_f32_16x16x32_bf16 v[98:101], v[206:209], v[170:173], v[98:101]
	v_mfma_f32_16x16x32_bf16 v[86:89], v[198:201], v[182:185], v[86:89]
	v_mfma_f32_16x16x32_bf16 v[82:85], v[206:209], v[182:185], v[82:85]
	v_mfma_f32_16x16x32_bf16 v[70:73], v[198:201], v[190:193], v[70:73]
	v_mfma_f32_16x16x32_bf16 v[66:69], v[206:209], v[190:193], v[66:69]
	v_mfma_f32_16x16x32_bf16 v[118:121], v[202:205], v[166:169], v[118:121]
	v_mfma_f32_16x16x32_bf16 v[114:117], v[210:213], v[166:169], v[114:117]
	v_mfma_f32_16x16x32_bf16 v[102:105], v[202:205], v[174:177], v[102:105]
	v_mfma_f32_16x16x32_bf16 v[98:101], v[210:213], v[174:177], v[98:101]
	v_mfma_f32_16x16x32_bf16 v[86:89], v[202:205], v[186:189], v[86:89]
	v_mfma_f32_16x16x32_bf16 v[82:85], v[210:213], v[186:189], v[82:85]
	v_mfma_f32_16x16x32_bf16 v[70:73], v[202:205], v[194:197], v[70:73]
	v_mfma_f32_16x16x32_bf16 v[66:69], v[210:213], v[194:197], v[66:69]
	s_mov_b32 m0, s36
	v_lshl_add_u64 v[216:217], s[28:29], 0, v[136:137]
	s_barrier
	ds_read_b128 v[162:165], v147 offset:16384
	ds_read_b128 v[166:169], v147 offset:17408
	ds_read_b128 v[170:173], v147 offset:18432
	ds_read_b128 v[174:177], v147 offset:19456
	ds_read_b128 v[182:185], v147 offset:20480
	ds_read_b128 v[186:189], v147 offset:21504
	ds_read_b128 v[190:193], v147 offset:22528
	ds_read_b128 v[194:197], v147 offset:23552
	global_load_lds_dwordx4 v[216:217], off
	v_lshl_add_u64 v[222:223], s[28:29], 0, v[132:133]
	s_mov_b32 m0, s37
	s_nop 0
	global_load_lds_dwordx4 v[222:223], off
	s_barrier
	s_waitcnt lgkmcnt(0)
	s_waitcnt lgkmcnt(0)
	v_mfma_f32_16x16x32_bf16 v[62:65], v[142:145], v[162:165], v[62:65]
	v_mfma_f32_16x16x32_bf16 v[58:61], v[154:157], v[162:165], v[58:61]
	v_mfma_f32_16x16x32_bf16 v[46:49], v[142:145], v[170:173], v[46:49]
	v_mfma_f32_16x16x32_bf16 v[42:45], v[154:157], v[170:173], v[42:45]
	v_mfma_f32_16x16x32_bf16 v[30:33], v[142:145], v[182:185], v[30:33]
	v_mfma_f32_16x16x32_bf16 v[26:29], v[154:157], v[182:185], v[26:29]
	v_mfma_f32_16x16x32_bf16 v[14:17], v[142:145], v[190:193], v[14:17]
	v_mfma_f32_16x16x32_bf16 v[10:13], v[154:157], v[190:193], v[10:13]
	v_mfma_f32_16x16x32_bf16 v[62:65], v[150:153], v[166:169], v[62:65]
	v_mfma_f32_16x16x32_bf16 v[58:61], v[158:161], v[166:169], v[58:61]
	v_mfma_f32_16x16x32_bf16 v[46:49], v[150:153], v[174:177], v[46:49]
	v_mfma_f32_16x16x32_bf16 v[42:45], v[158:161], v[174:177], v[42:45]
	v_mfma_f32_16x16x32_bf16 v[30:33], v[150:153], v[186:189], v[30:33]
	v_mfma_f32_16x16x32_bf16 v[26:29], v[158:161], v[186:189], v[26:29]
	v_mfma_f32_16x16x32_bf16 v[14:17], v[150:153], v[194:197], v[14:17]
	v_mfma_f32_16x16x32_bf16 v[10:13], v[158:161], v[194:197], v[10:13]
	s_barrier
	s_add_u32 s76, s26, 0x40000
	s_addc_u32 s77, s27, 0
	s_mov_b32 m0, s38
	v_lshl_add_u64 v[142:143], s[76:77], 0, v[134:135]
	global_load_lds_dwordx4 v[142:143], off
	v_lshl_add_u64 v[142:143], s[76:77], 0, v[130:131]
	s_mov_b32 m0, s39
	s_nop 0
	global_load_lds_dwordx4 v[142:143], off
	s_waitcnt vmcnt(6)
	s_barrier
	v_mfma_f32_16x16x32_bf16 v[54:57], v[198:201], v[162:165], v[54:57]
	v_mfma_f32_16x16x32_bf16 v[50:53], v[206:209], v[162:165], v[50:53]
	v_mfma_f32_16x16x32_bf16 v[38:41], v[198:201], v[170:173], v[38:41]
	v_mfma_f32_16x16x32_bf16 v[34:37], v[206:209], v[170:173], v[34:37]
	v_mfma_f32_16x16x32_bf16 v[22:25], v[198:201], v[182:185], v[22:25]
	v_mfma_f32_16x16x32_bf16 v[18:21], v[206:209], v[182:185], v[18:21]
	v_mfma_f32_16x16x32_bf16 v[6:9], v[198:201], v[190:193], v[6:9]
	v_mfma_f32_16x16x32_bf16 v[2:5], v[206:209], v[190:193], v[2:5]
	v_mfma_f32_16x16x32_bf16 v[54:57], v[202:205], v[166:169], v[54:57]
	v_mfma_f32_16x16x32_bf16 v[50:53], v[210:213], v[166:169], v[50:53]
	v_mfma_f32_16x16x32_bf16 v[38:41], v[202:205], v[174:177], v[38:41]
	v_mfma_f32_16x16x32_bf16 v[34:37], v[210:213], v[174:177], v[34:37]
	v_mfma_f32_16x16x32_bf16 v[22:25], v[202:205], v[186:189], v[22:25]
	v_mfma_f32_16x16x32_bf16 v[18:21], v[210:213], v[186:189], v[18:21]
	v_mfma_f32_16x16x32_bf16 v[6:9], v[202:205], v[194:197], v[6:9]
	v_mfma_f32_16x16x32_bf16 v[2:5], v[210:213], v[194:197], v[2:5]
	v_add_u32_e32 v0, 0x18000, v148
	s_barrier
	ds_read_b128 v[142:145], v0
	ds_read_b128 v[150:153], v0 offset:1024
	ds_read_b128 v[154:157], v0 offset:2048
	ds_read_b128 v[158:161], v0 offset:3072
	s_add_u32 s28, s28, 0x40000
	s_addc_u32 s29, s29, 0
	s_mov_b32 m0, s60
	v_lshl_add_u64 v[198:199], s[28:29], 0, v[136:137]
	ds_read_b128 v[162:165], v147 offset:32768
	ds_read_b128 v[166:169], v147 offset:33792
	ds_read_b128 v[170:173], v147 offset:34816
	ds_read_b128 v[174:177], v147 offset:35840
	ds_read_b128 v[182:185], v147 offset:36864
	ds_read_b128 v[186:189], v147 offset:37888
	ds_read_b128 v[190:193], v147 offset:38912
	ds_read_b128 v[194:197], v147 offset:39936
	global_load_lds_dwordx4 v[198:199], off
	v_lshl_add_u64 v[198:199], s[28:29], 0, v[132:133]
	s_mov_b32 m0, s68
	s_nop 0
	global_load_lds_dwordx4 v[198:199], off
	s_waitcnt lgkmcnt(8)
	s_barrier
	s_waitcnt lgkmcnt(0)
	s_waitcnt lgkmcnt(0)
	v_mfma_f32_16x16x32_bf16 v[126:129], v[142:145], v[162:165], v[126:129]
	v_mfma_f32_16x16x32_bf16 v[122:125], v[154:157], v[162:165], v[122:125]
	v_mfma_f32_16x16x32_bf16 v[110:113], v[142:145], v[170:173], v[110:113]
	v_mfma_f32_16x16x32_bf16 v[106:109], v[154:157], v[170:173], v[106:109]
	v_mfma_f32_16x16x32_bf16 v[94:97], v[142:145], v[182:185], v[94:97]
	v_mfma_f32_16x16x32_bf16 v[90:93], v[154:157], v[182:185], v[90:93]
	v_mfma_f32_16x16x32_bf16 v[78:81], v[142:145], v[190:193], v[78:81]
	v_mfma_f32_16x16x32_bf16 v[74:77], v[154:157], v[190:193], v[74:77]
	v_mfma_f32_16x16x32_bf16 v[126:129], v[150:153], v[166:169], v[126:129]
	v_mfma_f32_16x16x32_bf16 v[122:125], v[158:161], v[166:169], v[122:125]
	v_mfma_f32_16x16x32_bf16 v[110:113], v[150:153], v[174:177], v[110:113]
	v_mfma_f32_16x16x32_bf16 v[106:109], v[158:161], v[174:177], v[106:109]
	v_mfma_f32_16x16x32_bf16 v[94:97], v[150:153], v[186:189], v[94:97]
	v_mfma_f32_16x16x32_bf16 v[90:93], v[158:161], v[186:189], v[90:93]
	v_mfma_f32_16x16x32_bf16 v[78:81], v[150:153], v[194:197], v[78:81]
	v_mfma_f32_16x16x32_bf16 v[74:77], v[158:161], v[194:197], v[74:77]
	s_barrier
	s_mov_b32 m0, s69
	v_add_u32_e32 v0, 0x1c000, v148
	v_lshl_add_u64 v[178:179], v[178:179], 0, s[84:85]
	ds_read_b128 v[198:201], v0
	ds_read_b128 v[202:205], v0 offset:1024
	ds_read_b128 v[206:209], v0 offset:2048
	ds_read_b128 v[210:213], v0 offset:3072
	global_load_lds_dwordx4 v[178:179], off
	v_lshl_add_u64 v[178:179], v[214:215], 0, s[84:85]
	s_mov_b32 m0, s75
	s_nop 0
	global_load_lds_dwordx4 v[178:179], off
	s_barrier
	s_waitcnt lgkmcnt(0)
	s_waitcnt lgkmcnt(0)
	v_mfma_f32_16x16x32_bf16 v[118:121], v[198:201], v[162:165], v[118:121]
	v_mfma_f32_16x16x32_bf16 v[114:117], v[206:209], v[162:165], v[114:117]
	v_mfma_f32_16x16x32_bf16 v[102:105], v[198:201], v[170:173], v[102:105]
	v_mfma_f32_16x16x32_bf16 v[98:101], v[206:209], v[170:173], v[98:101]
	v_mfma_f32_16x16x32_bf16 v[86:89], v[198:201], v[182:185], v[86:89]
	v_mfma_f32_16x16x32_bf16 v[82:85], v[206:209], v[182:185], v[82:85]
	v_mfma_f32_16x16x32_bf16 v[70:73], v[198:201], v[190:193], v[70:73]
	v_mfma_f32_16x16x32_bf16 v[66:69], v[206:209], v[190:193], v[66:69]
	v_mfma_f32_16x16x32_bf16 v[118:121], v[202:205], v[166:169], v[118:121]
	v_mfma_f32_16x16x32_bf16 v[114:117], v[210:213], v[166:169], v[114:117]
	v_mfma_f32_16x16x32_bf16 v[102:105], v[202:205], v[174:177], v[102:105]
	v_mfma_f32_16x16x32_bf16 v[98:101], v[210:213], v[174:177], v[98:101]
	v_mfma_f32_16x16x32_bf16 v[86:89], v[202:205], v[186:189], v[86:89]
	v_mfma_f32_16x16x32_bf16 v[82:85], v[210:213], v[186:189], v[82:85]
	v_mfma_f32_16x16x32_bf16 v[70:73], v[202:205], v[194:197], v[70:73]
	v_mfma_f32_16x16x32_bf16 v[66:69], v[210:213], v[194:197], v[66:69]
	s_mov_b32 m0, s82
	v_lshl_add_u64 v[178:179], v[216:217], 0, s[84:85]
	s_barrier
	ds_read_b128 v[162:165], v147 offset:49152
	ds_read_b128 v[166:169], v147 offset:50176
	ds_read_b128 v[170:173], v147 offset:51200
	ds_read_b128 v[174:177], v147 offset:52224
	ds_read_b128 v[182:185], v147 offset:53248
	ds_read_b128 v[186:189], v147 offset:54272
	ds_read_b128 v[190:193], v147 offset:55296
	ds_read_b128 v[194:197], v147 offset:56320
	global_load_lds_dwordx4 v[178:179], off
	v_lshl_add_u64 v[178:179], v[222:223], 0, s[84:85]
	s_mov_b32 m0, s92
	s_nop 0
	global_load_lds_dwordx4 v[178:179], off
	s_barrier
	s_waitcnt lgkmcnt(0)
	s_waitcnt lgkmcnt(0)
	v_mfma_f32_16x16x32_bf16 v[62:65], v[142:145], v[162:165], v[62:65]
	v_mfma_f32_16x16x32_bf16 v[58:61], v[154:157], v[162:165], v[58:61]
	v_mfma_f32_16x16x32_bf16 v[46:49], v[142:145], v[170:173], v[46:49]
	v_mfma_f32_16x16x32_bf16 v[42:45], v[154:157], v[170:173], v[42:45]
	v_mfma_f32_16x16x32_bf16 v[30:33], v[142:145], v[182:185], v[30:33]
	v_mfma_f32_16x16x32_bf16 v[26:29], v[154:157], v[182:185], v[26:29]
	v_mfma_f32_16x16x32_bf16 v[14:17], v[142:145], v[190:193], v[14:17]
	v_mfma_f32_16x16x32_bf16 v[10:13], v[154:157], v[190:193], v[10:13]
	v_mfma_f32_16x16x32_bf16 v[62:65], v[150:153], v[166:169], v[62:65]
	v_mfma_f32_16x16x32_bf16 v[58:61], v[158:161], v[166:169], v[58:61]
	v_mfma_f32_16x16x32_bf16 v[46:49], v[150:153], v[174:177], v[46:49]
	v_mfma_f32_16x16x32_bf16 v[42:45], v[158:161], v[174:177], v[42:45]
	v_mfma_f32_16x16x32_bf16 v[30:33], v[150:153], v[186:189], v[30:33]
	v_mfma_f32_16x16x32_bf16 v[26:29], v[158:161], v[186:189], v[26:29]
	v_mfma_f32_16x16x32_bf16 v[14:17], v[150:153], v[194:197], v[14:17]
	v_mfma_f32_16x16x32_bf16 v[10:13], v[158:161], v[194:197], v[10:13]
	s_barrier
	s_add_u32 s26, s26, 0x40080
	s_addc_u32 s27, s27, 0
	s_mov_b32 m0, s93
	v_lshl_add_u64 v[142:143], s[26:27], 0, v[134:135]
	global_load_lds_dwordx4 v[142:143], off
	v_lshl_add_u64 v[142:143], s[26:27], 0, v[130:131]
	s_mov_b32 m0, s96
	s_nop 0
	global_load_lds_dwordx4 v[142:143], off
	s_waitcnt vmcnt(6)
	s_barrier
	v_mfma_f32_16x16x32_bf16 v[54:57], v[198:201], v[162:165], v[54:57]
	v_mfma_f32_16x16x32_bf16 v[50:53], v[206:209], v[162:165], v[50:53]
	v_mfma_f32_16x16x32_bf16 v[38:41], v[198:201], v[170:173], v[38:41]
	v_mfma_f32_16x16x32_bf16 v[34:37], v[206:209], v[170:173], v[34:37]
	v_mfma_f32_16x16x32_bf16 v[22:25], v[198:201], v[182:185], v[22:25]
	v_mfma_f32_16x16x32_bf16 v[18:21], v[206:209], v[182:185], v[18:21]
	v_mfma_f32_16x16x32_bf16 v[6:9], v[198:201], v[190:193], v[6:9]
	v_mfma_f32_16x16x32_bf16 v[2:5], v[206:209], v[190:193], v[2:5]
	v_mfma_f32_16x16x32_bf16 v[54:57], v[202:205], v[166:169], v[54:57]
	v_mfma_f32_16x16x32_bf16 v[50:53], v[210:213], v[166:169], v[50:53]
	v_mfma_f32_16x16x32_bf16 v[38:41], v[202:205], v[174:177], v[38:41]
	v_mfma_f32_16x16x32_bf16 v[34:37], v[210:213], v[174:177], v[34:37]
	v_mfma_f32_16x16x32_bf16 v[22:25], v[202:205], v[186:189], v[22:25]
	v_mfma_f32_16x16x32_bf16 v[18:21], v[210:213], v[186:189], v[18:21]
	v_mfma_f32_16x16x32_bf16 v[6:9], v[202:205], v[194:197], v[6:9]
	v_mfma_f32_16x16x32_bf16 v[2:5], v[210:213], v[194:197], v[2:5]
	s_add_i32 vcc_lo, vcc_lo, 2
	s_add_u32 s24, s24, 0x100
	s_addc_u32 s25, s25, 0
	s_add_u32 s90, s90, 0x100
	s_addc_u32 s94, s94, 0
	s_cmp_gt_u32 vcc_lo, 13
	s_barrier
	s_cbranch_scc0 .LBB0_1334
	v_lshl_add_u32 v152, s22, 8, v146
	v_lshl_add_u32 v150, s20, 8, v149
	v_mul_lo_u32 v151, v152, s71
	v_add_u32_e32 v0, v151, v150
	v_lshl_add_u64 v[142:143], v[0:1], 1, s[8:9]
	global_load_dwordx4 v[142:145], v[142:143], off
	v_mov_b32_e32 v178, v0
	v_mov_b32_e32 v161, 0
	v_add_u32_e32 v160, 0x80, v178
	v_lshl_add_u64 v[162:163], v[160:161], 1, s[8:9]
	global_load_dwordx4 v[162:165], v[162:163], off
	v_add_u32_e32 v160, 0x16c00, v178
	v_lshl_add_u64 v[166:167], v[160:161], 1, s[8:9]
	global_load_dwordx4 v[166:169], v[166:167], off
	v_add_u32_e32 v160, 0x16c80, v178
	v_lshl_add_u64 v[170:171], v[160:161], 1, s[8:9]
	global_load_dwordx4 v[170:173], v[170:171], off
	v_add_u32_e32 v160, 0x2d800, v178
	v_lshl_add_u64 v[174:175], v[160:161], 1, s[8:9]
	global_load_dwordx4 v[174:177], v[174:175], off
	v_add_u32_e32 v160, 0x2d880, v178
	v_lshl_add_u64 v[182:183], v[160:161], 1, s[8:9]
	global_load_dwordx4 v[182:185], v[182:183], off
	v_add_u32_e32 v160, 0x44400, v178
	v_lshl_add_u64 v[186:187], v[160:161], 1, s[8:9]
	global_load_dwordx4 v[186:189], v[186:187], off
	v_add_u32_e32 v160, 0x44480, v178
	v_lshl_add_u64 v[190:191], v[160:161], 1, s[8:9]
	global_load_dwordx4 v[190:193], v[190:191], off
	v_add_u32_e32 v160, 0xb6000, v178
	v_lshl_add_u64 v[194:195], v[160:161], 1, s[8:9]
	global_load_dwordx4 v[194:197], v[194:195], off
	v_add_u32_e32 v160, 0xb6080, v178
	v_lshl_add_u64 v[198:199], v[160:161], 1, s[8:9]
	global_load_dwordx4 v[198:201], v[198:199], off
	v_add_u32_e32 v160, 0xccc00, v178
	v_lshl_add_u64 v[202:203], v[160:161], 1, s[8:9]
	global_load_dwordx4 v[202:205], v[202:203], off
	v_add_u32_e32 v160, 0xccc80, v178
	v_lshl_add_u64 v[206:207], v[160:161], 1, s[8:9]
	global_load_dwordx4 v[206:209], v[206:207], off
	v_add_u32_e32 v160, 0xe3800, v178
	v_lshl_add_u64 v[210:211], v[160:161], 1, s[8:9]
	global_load_dwordx4 v[210:213], v[210:211], off
	s_mov_b32 s20, s12
	s_mov_b32 s22, s14
	s_mov_b64 s[26:27], s[18:19]
	s_waitcnt vmcnt(12)
	v_lshlrev_b32_e32 v153, 16, v142
	v_lshlrev_b32_e32 v155, 16, v143
	v_lshlrev_b32_e32 v156, 16, v144
	v_and_b32_e32 v157, 0xffff0000, v144
	v_lshlrev_b32_e32 v158, 16, v145
	v_and_b32_e32 v159, 0xffff0000, v145
	v_mul_f32_e32 v144, 0xbfb8aa3b, v153
	v_mul_f32_e32 v145, 0xbfb8aa3b, v155
	v_exp_f32_e32 v154, v144
	v_exp_f32_e32 v155, v145
	v_mul_f32_e32 v145, 0xbfb8aa3b, v158
	v_and_b32_e32 v142, 0xffff0000, v142
	v_and_b32_e32 v143, 0xffff0000, v143
	v_pk_add_f32 v[154:155], v[154:155], 1.0 op_sel_hi:[1,0]
	v_mul_f32_e32 v142, 0xbfb8aa3b, v142
	v_mul_f32_e32 v143, 0xbfb8aa3b, v143
	v_mul_f32_e32 v144, 0xbfb8aa3b, v156
	v_exp_f32_e32 v156, v142
	v_mul_f32_e32 v142, 0xbfb8aa3b, v157
	v_exp_f32_e32 v157, v143
	v_mul_f32_e32 v143, 0xbfb8aa3b, v159
	v_rcp_f32_e32 v155, v155
	s_nop 0
	v_pk_add_f32 v[156:157], v[156:157], 1.0 op_sel_hi:[1,0]
	v_exp_f32_e32 v144, v144
	v_exp_f32_e32 v145, v145
	v_mov_b32_e32 v158, v126
	v_mov_b32_e32 v159, v128
	v_rcp_f32_e32 v154, v154
	s_nop 0
	v_pk_mul_f32 v[154:155], v[158:159], v[154:155]
	v_exp_f32_e32 v142, v142
	v_rcp_f32_e32 v157, v157
	s_nop 0
	v_exp_f32_e32 v143, v143
	v_rcp_f32_e32 v156, v156
	s_nop 0
	v_mov_b32_e32 v128, v127
	v_pk_mul_f32 v[126:127], v[128:129], v[156:157]
	v_cvt_pk_bf16_f32 v128, v154, v155
	v_cvt_pk_bf16_f32 v126, v126, v127
	v_and_b32_e32 v127, 0xffff0000, v126
	v_lshlrev_b32_e32 v126, 16, v126
	v_or_b32_sdwa v127, v127, v128 dst_sel:DWORD dst_unused:UNUSED_PAD src0_sel:DWORD src1_sel:WORD_1
	v_or_b32_sdwa v126, v126, v128 dst_sel:DWORD dst_unused:UNUSED_PAD src0_sel:DWORD src1_sel:WORD_0
	v_pk_add_f32 v[128:129], v[144:145], 1.0 op_sel_hi:[1,0]
	v_pk_add_f32 v[142:143], v[142:143], 1.0 op_sel_hi:[1,0]
	s_nop 0
	v_rcp_f32_e32 v129, v129
	s_nop 0
	s_nop 0
	v_rcp_f32_e32 v128, v128
	s_nop 0
	v_mov_b32_e32 v144, v122
	v_mov_b32_e32 v145, v124
	v_pk_mul_f32 v[128:129], v[144:145], v[128:129]
	v_rcp_f32_e32 v143, v143
	s_nop 0
	s_nop 0
	v_rcp_f32_e32 v142, v142
	s_nop 0
	v_mov_b32_e32 v124, v123
	v_pk_mul_f32 v[122:123], v[124:125], v[142:143]
	v_cvt_pk_bf16_f32 v124, v128, v129
	v_cvt_pk_bf16_f32 v122, v122, v123
	v_and_b32_e32 v123, 0xffff0000, v122
	v_lshlrev_b32_e32 v122, 16, v122
	v_or_b32_sdwa v129, v123, v124 dst_sel:DWORD dst_unused:UNUSED_PAD src0_sel:DWORD src1_sel:WORD_1
	v_or_b32_sdwa v128, v122, v124 dst_sel:DWORD dst_unused:UNUSED_PAD src0_sel:DWORD src1_sel:WORD_0
	v_mul_lo_u32 v124, v152, s61
	v_add_u32_e32 v0, v0, v124
	v_add_u32_e32 v125, 0x80, v150
	v_lshl_add_u64 v[122:123], v[0:1], 1, s[6:7]
	v_add_u32_e32 v0, v151, v125
	global_store_dwordx4 v[122:123], v[126:129], off
	v_add_u32_e32 v0, v0, v124
	s_waitcnt vmcnt(12)
	v_lshlrev_b32_e32 v122, 16, v162
	v_lshlrev_b32_e32 v143, 16, v163
	v_and_b32_e32 v144, 0xffff0000, v163
	v_lshlrev_b32_e32 v127, 16, v164
	v_mul_f32_e32 v122, 0xbfb8aa3b, v122
	v_and_b32_e32 v123, 0xffff0000, v162
	v_exp_f32_e32 v126, v122
	v_mul_f32_e32 v122, 0xbfb8aa3b, v127
	v_and_b32_e32 v145, 0xffff0000, v164
	v_exp_f32_e32 v128, v122
	v_mul_f32_e32 v122, 0xbfb8aa3b, v123
	v_mul_f32_e32 v123, 0xbfb8aa3b, v143
	v_exp_f32_e32 v127, v123
	v_lshlrev_b32_e32 v153, 16, v165
	v_mul_f32_e32 v123, 0xbfb8aa3b, v153
	v_and_b32_e32 v154, 0xffff0000, v165
	v_pk_add_f32 v[126:127], v[126:127], 1.0 op_sel_hi:[1,0]
	v_exp_f32_e32 v129, v123
	v_mul_f32_e32 v123, 0xbfb8aa3b, v144
	v_exp_f32_e32 v142, v122
	v_mul_f32_e32 v122, 0xbfb8aa3b, v145
	v_exp_f32_e32 v143, v123
	v_mul_f32_e32 v123, 0xbfb8aa3b, v154
	v_exp_f32_e32 v122, v122
	v_rcp_f32_e32 v127, v127
	s_nop 0
	v_pk_add_f32 v[142:143], v[142:143], 1.0 op_sel_hi:[1,0]
	v_exp_f32_e32 v123, v123
	v_rcp_f32_e32 v126, v126
	s_nop 0
	v_mov_b32_e32 v144, v118
	v_mov_b32_e32 v145, v120
	v_pk_mul_f32 v[126:127], v[144:145], v[126:127]
	v_pk_add_f32 v[122:123], v[122:123], 1.0 op_sel_hi:[1,0]
	v_rcp_f32_e32 v143, v143
	s_nop 0
	s_nop 0
	v_rcp_f32_e32 v142, v142
	s_nop 0
	v_mov_b32_e32 v120, v119
	v_pk_mul_f32 v[118:119], v[120:121], v[142:143]
	v_cvt_pk_bf16_f32 v120, v126, v127
	v_cvt_pk_bf16_f32 v118, v118, v119
	v_and_b32_e32 v119, 0xffff0000, v118
	v_lshlrev_b32_e32 v118, 16, v118
	v_or_b32_sdwa v119, v119, v120 dst_sel:DWORD dst_unused:UNUSED_PAD src0_sel:DWORD src1_sel:WORD_1
	v_or_b32_sdwa v118, v118, v120 dst_sel:DWORD dst_unused:UNUSED_PAD src0_sel:DWORD src1_sel:WORD_0
	v_pk_add_f32 v[120:121], v[128:129], 1.0 op_sel_hi:[1,0]
	s_nop 0
	s_nop 0
	v_rcp_f32_e32 v121, v121
	s_nop 0
	s_nop 0
	v_rcp_f32_e32 v120, v120
	s_nop 0
	v_mov_b32_e32 v126, v114
	v_mov_b32_e32 v127, v116
	v_pk_mul_f32 v[120:121], v[126:127], v[120:121]
	v_rcp_f32_e32 v123, v123
	s_nop 0
	s_nop 0
	v_rcp_f32_e32 v122, v122
	s_nop 0
	v_mov_b32_e32 v116, v115
	v_pk_mul_f32 v[114:115], v[116:117], v[122:123]
	v_cvt_pk_bf16_f32 v116, v120, v121
	v_cvt_pk_bf16_f32 v114, v114, v115
	v_and_b32_e32 v115, 0xffff0000, v114
	v_lshlrev_b32_e32 v114, 16, v114
	v_add_u32_e32 v127, 0x16c00, v151
	v_or_b32_sdwa v121, v115, v116 dst_sel:DWORD dst_unused:UNUSED_PAD src0_sel:DWORD src1_sel:WORD_1
	v_or_b32_sdwa v120, v114, v116 dst_sel:DWORD dst_unused:UNUSED_PAD src0_sel:DWORD src1_sel:WORD_0
	v_lshl_add_u64 v[114:115], v[0:1], 1, s[6:7]
	v_add_u32_e32 v0, v127, v150
	v_add_u32_e32 v160, 0xe3880, v178
	v_lshl_add_u64 v[162:163], v[160:161], 1, s[8:9]
	global_load_dwordx4 v[162:165], v[162:163], off
	global_store_dwordx4 v[114:115], v[118:121], off
	v_or_b32_e32 v126, 16, v152
	s_waitcnt vmcnt(13)
	v_lshlrev_b32_e32 v121, 16, v167
	v_and_b32_e32 v122, 0xffff0000, v167
	v_lshlrev_b32_e32 v115, 16, v168
	v_and_b32_e32 v119, 0xffff0000, v166
	v_mul_f32_e32 v115, 0xbfb8aa3b, v115
	v_lshlrev_b32_e32 v118, 16, v166
	v_and_b32_e32 v120, 0xffff0000, v168
	v_exp_f32_e32 v116, v115
	v_mul_f32_e32 v115, 0xbfb8aa3b, v119
	v_mul_f32_e32 v114, 0xbfb8aa3b, v118
	v_exp_f32_e32 v118, v115
	v_mul_f32_e32 v115, 0xbfb8aa3b, v120
	v_exp_f32_e32 v120, v115
	v_mul_f32_e32 v115, 0xbfb8aa3b, v121
	v_exp_f32_e32 v114, v114
	v_exp_f32_e32 v115, v115
	v_lshlrev_b32_e32 v123, 16, v169
	v_mul_f32_e32 v119, 0xbfb8aa3b, v122
	v_and_b32_e32 v128, 0xffff0000, v169
	v_pk_add_f32 v[114:115], v[114:115], 1.0 op_sel_hi:[1,0]
	v_mul_f32_e32 v117, 0xbfb8aa3b, v123
	v_mul_f32_e32 v121, 0xbfb8aa3b, v128
	v_exp_f32_e32 v119, v119
	v_exp_f32_e32 v117, v117
	v_rcp_f32_e32 v115, v115
	s_nop 0
	v_pk_add_f32 v[118:119], v[118:119], 1.0 op_sel_hi:[1,0]
	v_exp_f32_e32 v121, v121
	v_rcp_f32_e32 v114, v114
	s_nop 0
	v_mov_b32_e32 v122, v110
	v_mov_b32_e32 v123, v112
	v_pk_mul_f32 v[114:115], v[122:123], v[114:115]
	v_rcp_f32_e32 v119, v119
	s_nop 0
	s_nop 0
	v_rcp_f32_e32 v118, v118
	s_nop 0
	v_mov_b32_e32 v112, v111
	v_pk_mul_f32 v[110:111], v[112:113], v[118:119]
	v_cvt_pk_bf16_f32 v112, v114, v115
	v_cvt_pk_bf16_f32 v110, v110, v111
	v_and_b32_e32 v111, 0xffff0000, v110
	v_lshlrev_b32_e32 v110, 16, v110
	v_or_b32_sdwa v111, v111, v112 dst_sel:DWORD dst_unused:UNUSED_PAD src0_sel:DWORD src1_sel:WORD_1
	v_or_b32_sdwa v110, v110, v112 dst_sel:DWORD dst_unused:UNUSED_PAD src0_sel:DWORD src1_sel:WORD_0
	v_pk_add_f32 v[112:113], v[116:117], 1.0 op_sel_hi:[1,0]
	s_nop 0
	s_nop 0
	v_rcp_f32_e32 v113, v113
	s_nop 0
	s_nop 0
	v_rcp_f32_e32 v112, v112
	s_nop 0
	v_mov_b32_e32 v114, v106
	v_mov_b32_e32 v115, v108
	v_pk_mul_f32 v[112:113], v[114:115], v[112:113]
	v_pk_add_f32 v[114:115], v[120:121], 1.0 op_sel_hi:[1,0]
	s_nop 0
	s_nop 0
	v_rcp_f32_e32 v115, v115
	s_nop 0
	s_nop 0
	v_rcp_f32_e32 v114, v114
	s_nop 0
	v_mov_b32_e32 v108, v107
	v_pk_mul_f32 v[106:107], v[108:109], v[114:115]
	v_mul_lo_u32 v116, v126, s61
	v_cvt_pk_bf16_f32 v106, v106, v107
	v_cvt_pk_bf16_f32 v108, v112, v113
	v_and_b32_e32 v107, 0xffff0000, v106
	v_lshlrev_b32_e32 v106, 16, v106
	v_add_u32_e32 v0, v0, v116
	v_or_b32_sdwa v113, v107, v108 dst_sel:DWORD dst_unused:UNUSED_PAD src0_sel:DWORD src1_sel:WORD_1
	v_or_b32_sdwa v112, v106, v108 dst_sel:DWORD dst_unused:UNUSED_PAD src0_sel:DWORD src1_sel:WORD_0
	v_lshl_add_u64 v[106:107], v[0:1], 1, s[6:7]
	v_add_u32_e32 v0, v127, v125
	v_add_u32_e32 v160, 0xfa400, v178
	v_lshl_add_u64 v[166:167], v[160:161], 1, s[8:9]
	global_load_dwordx4 v[166:169], v[166:167], off
	global_store_dwordx4 v[106:107], v[110:113], off
	v_add_u32_e32 v0, v0, v116
	s_waitcnt vmcnt(14)
	v_lshlrev_b32_e32 v113, 16, v171
	v_and_b32_e32 v114, 0xffff0000, v171
	v_lshlrev_b32_e32 v107, 16, v172
	v_and_b32_e32 v111, 0xffff0000, v170
	v_mul_f32_e32 v107, 0xbfb8aa3b, v107
	v_lshlrev_b32_e32 v110, 16, v170
	v_and_b32_e32 v112, 0xffff0000, v172
	v_exp_f32_e32 v108, v107
	v_mul_f32_e32 v107, 0xbfb8aa3b, v111
	v_mul_f32_e32 v106, 0xbfb8aa3b, v110
	v_exp_f32_e32 v110, v107
	v_mul_f32_e32 v107, 0xbfb8aa3b, v112
	v_exp_f32_e32 v112, v107
	v_mul_f32_e32 v107, 0xbfb8aa3b, v113
	v_exp_f32_e32 v106, v106
	v_exp_f32_e32 v107, v107
	v_lshlrev_b32_e32 v115, 16, v173
	v_mul_f32_e32 v111, 0xbfb8aa3b, v114
	v_and_b32_e32 v117, 0xffff0000, v173
	v_pk_add_f32 v[106:107], v[106:107], 1.0 op_sel_hi:[1,0]
	v_mul_f32_e32 v109, 0xbfb8aa3b, v115
	v_mul_f32_e32 v113, 0xbfb8aa3b, v117
	v_exp_f32_e32 v111, v111
	v_exp_f32_e32 v109, v109
	v_rcp_f32_e32 v107, v107
	s_nop 0
	v_pk_add_f32 v[110:111], v[110:111], 1.0 op_sel_hi:[1,0]
	v_exp_f32_e32 v113, v113
	v_rcp_f32_e32 v106, v106
	s_nop 0
	v_mov_b32_e32 v114, v102
	v_mov_b32_e32 v115, v104
	v_pk_mul_f32 v[106:107], v[114:115], v[106:107]
	v_rcp_f32_e32 v111, v111
	s_nop 0
	s_nop 0
	v_rcp_f32_e32 v110, v110
	s_nop 0
	v_mov_b32_e32 v104, v103
	v_pk_mul_f32 v[102:103], v[104:105], v[110:111]
	v_cvt_pk_bf16_f32 v104, v106, v107
	v_cvt_pk_bf16_f32 v102, v102, v103
	v_and_b32_e32 v103, 0xffff0000, v102
	v_lshlrev_b32_e32 v102, 16, v102
	v_or_b32_sdwa v103, v103, v104 dst_sel:DWORD dst_unused:UNUSED_PAD src0_sel:DWORD src1_sel:WORD_1
	v_or_b32_sdwa v102, v102, v104 dst_sel:DWORD dst_unused:UNUSED_PAD src0_sel:DWORD src1_sel:WORD_0
	v_pk_add_f32 v[104:105], v[108:109], 1.0 op_sel_hi:[1,0]
	s_nop 0
	s_nop 0
	v_rcp_f32_e32 v105, v105
	s_nop 0
	s_nop 0
	v_rcp_f32_e32 v104, v104
	s_nop 0
	v_mov_b32_e32 v106, v98
	v_mov_b32_e32 v107, v100
	v_pk_mul_f32 v[104:105], v[106:107], v[104:105]
	v_pk_add_f32 v[106:107], v[112:113], 1.0 op_sel_hi:[1,0]
	s_nop 0
	s_nop 0
	v_rcp_f32_e32 v107, v107
	s_nop 0
	s_nop 0
	v_rcp_f32_e32 v106, v106
	s_nop 0
	v_mov_b32_e32 v100, v99
	v_pk_mul_f32 v[98:99], v[100:101], v[106:107]
	v_cvt_pk_bf16_f32 v100, v104, v105
	v_cvt_pk_bf16_f32 v98, v98, v99
	v_and_b32_e32 v99, 0xffff0000, v98
	v_lshlrev_b32_e32 v98, 16, v98
	v_add_u32_e32 v109, 0x2d800, v151
	v_or_b32_sdwa v105, v99, v100 dst_sel:DWORD dst_unused:UNUSED_PAD src0_sel:DWORD src1_sel:WORD_1
	v_or_b32_sdwa v104, v98, v100 dst_sel:DWORD dst_unused:UNUSED_PAD src0_sel:DWORD src1_sel:WORD_0
	v_lshl_add_u64 v[98:99], v[0:1], 1, s[6:7]
	v_add_u32_e32 v0, v109, v150
	v_add_u32_e32 v160, 0xfa480, v178
	v_lshl_add_u64 v[170:171], v[160:161], 1, s[8:9]
	global_load_dwordx4 v[170:173], v[170:171], off
	global_store_dwordx4 v[98:99], v[102:105], off
	v_or_b32_e32 v108, 32, v152
	s_waitcnt vmcnt(15)
	v_lshlrev_b32_e32 v105, 16, v175
	v_and_b32_e32 v106, 0xffff0000, v175
	v_lshlrev_b32_e32 v99, 16, v176
	v_and_b32_e32 v103, 0xffff0000, v174
	v_mul_f32_e32 v99, 0xbfb8aa3b, v99
	v_lshlrev_b32_e32 v102, 16, v174
	v_and_b32_e32 v104, 0xffff0000, v176
	v_exp_f32_e32 v100, v99
	v_mul_f32_e32 v99, 0xbfb8aa3b, v103
	v_mul_f32_e32 v98, 0xbfb8aa3b, v102
	v_exp_f32_e32 v102, v99
	v_mul_f32_e32 v99, 0xbfb8aa3b, v104
	v_exp_f32_e32 v104, v99
	v_mul_f32_e32 v99, 0xbfb8aa3b, v105
	v_exp_f32_e32 v98, v98
	v_exp_f32_e32 v99, v99
	v_lshlrev_b32_e32 v107, 16, v177
	v_mul_f32_e32 v103, 0xbfb8aa3b, v106
	v_and_b32_e32 v110, 0xffff0000, v177
	v_pk_add_f32 v[98:99], v[98:99], 1.0 op_sel_hi:[1,0]
	v_mul_f32_e32 v101, 0xbfb8aa3b, v107
	v_mul_f32_e32 v105, 0xbfb8aa3b, v110
	v_exp_f32_e32 v103, v103
	v_exp_f32_e32 v101, v101
	v_rcp_f32_e32 v99, v99
	s_nop 0
	v_pk_add_f32 v[102:103], v[102:103], 1.0 op_sel_hi:[1,0]
	v_exp_f32_e32 v105, v105
	v_rcp_f32_e32 v98, v98
	s_nop 0
	v_mov_b32_e32 v106, v94
	v_mov_b32_e32 v107, v96
	v_pk_mul_f32 v[98:99], v[106:107], v[98:99]
	v_rcp_f32_e32 v103, v103
	s_nop 0
	s_nop 0
	v_rcp_f32_e32 v102, v102
	s_nop 0
	v_mov_b32_e32 v96, v95
	v_pk_mul_f32 v[94:95], v[96:97], v[102:103]
	v_cvt_pk_bf16_f32 v96, v98, v99
	v_cvt_pk_bf16_f32 v94, v94, v95
	v_and_b32_e32 v95, 0xffff0000, v94
	v_lshlrev_b32_e32 v94, 16, v94
	v_or_b32_sdwa v95, v95, v96 dst_sel:DWORD dst_unused:UNUSED_PAD src0_sel:DWORD src1_sel:WORD_1
	v_or_b32_sdwa v94, v94, v96 dst_sel:DWORD dst_unused:UNUSED_PAD src0_sel:DWORD src1_sel:WORD_0
	v_pk_add_f32 v[96:97], v[100:101], 1.0 op_sel_hi:[1,0]
	s_nop 0
	s_nop 0
	v_rcp_f32_e32 v97, v97
	s_nop 0
	s_nop 0
	v_rcp_f32_e32 v96, v96
	s_nop 0
	v_mov_b32_e32 v98, v90
	v_mov_b32_e32 v99, v92
	v_pk_mul_f32 v[96:97], v[98:99], v[96:97]
	v_pk_add_f32 v[98:99], v[104:105], 1.0 op_sel_hi:[1,0]
	s_nop 0
	s_nop 0
	v_rcp_f32_e32 v99, v99
	s_nop 0
	s_nop 0
	v_rcp_f32_e32 v98, v98
	s_nop 0
	v_mov_b32_e32 v92, v91
	v_pk_mul_f32 v[90:91], v[92:93], v[98:99]
	v_mul_lo_u32 v100, v108, s61
	v_cvt_pk_bf16_f32 v90, v90, v91
	v_cvt_pk_bf16_f32 v92, v96, v97
	v_and_b32_e32 v91, 0xffff0000, v90
	v_lshlrev_b32_e32 v90, 16, v90
	v_add_u32_e32 v0, v0, v100
	v_or_b32_sdwa v97, v91, v92 dst_sel:DWORD dst_unused:UNUSED_PAD src0_sel:DWORD src1_sel:WORD_1
	v_or_b32_sdwa v96, v90, v92 dst_sel:DWORD dst_unused:UNUSED_PAD src0_sel:DWORD src1_sel:WORD_0
	v_lshl_add_u64 v[90:91], v[0:1], 1, s[6:7]
	v_add_u32_e32 v0, v109, v125
	global_store_dwordx4 v[90:91], v[94:97], off
	v_add_u32_e32 v0, v0, v100
	s_waitcnt vmcnt(15)
	v_lshlrev_b32_e32 v97, 16, v183
	v_and_b32_e32 v98, 0xffff0000, v183
	v_lshlrev_b32_e32 v91, 16, v184
	v_and_b32_e32 v95, 0xffff0000, v182
	v_mul_f32_e32 v91, 0xbfb8aa3b, v91
	v_lshlrev_b32_e32 v94, 16, v182
	v_and_b32_e32 v96, 0xffff0000, v184
	v_exp_f32_e32 v92, v91
	v_mul_f32_e32 v91, 0xbfb8aa3b, v95
	v_mul_f32_e32 v90, 0xbfb8aa3b, v94
	v_exp_f32_e32 v94, v91
	v_mul_f32_e32 v91, 0xbfb8aa3b, v96
	v_exp_f32_e32 v96, v91
	v_mul_f32_e32 v91, 0xbfb8aa3b, v97
	v_exp_f32_e32 v90, v90
	v_exp_f32_e32 v91, v91
	v_lshlrev_b32_e32 v99, 16, v185
	v_mul_f32_e32 v95, 0xbfb8aa3b, v98
	v_and_b32_e32 v101, 0xffff0000, v185
	v_pk_add_f32 v[90:91], v[90:91], 1.0 op_sel_hi:[1,0]
	v_mul_f32_e32 v93, 0xbfb8aa3b, v99
	v_mul_f32_e32 v97, 0xbfb8aa3b, v101
	v_exp_f32_e32 v95, v95
	v_exp_f32_e32 v93, v93
	v_rcp_f32_e32 v91, v91
	s_nop 0
	v_pk_add_f32 v[94:95], v[94:95], 1.0 op_sel_hi:[1,0]
	v_exp_f32_e32 v97, v97
	v_rcp_f32_e32 v90, v90
	s_nop 0
	v_mov_b32_e32 v98, v86
	v_mov_b32_e32 v99, v88
	v_pk_mul_f32 v[90:91], v[98:99], v[90:91]
	v_rcp_f32_e32 v95, v95
	s_nop 0
	s_nop 0
	v_rcp_f32_e32 v94, v94
	s_nop 0
	v_mov_b32_e32 v88, v87
	v_pk_mul_f32 v[86:87], v[88:89], v[94:95]
	v_cvt_pk_bf16_f32 v88, v90, v91
	v_cvt_pk_bf16_f32 v86, v86, v87
	v_and_b32_e32 v87, 0xffff0000, v86
	v_lshlrev_b32_e32 v86, 16, v86
	v_or_b32_sdwa v87, v87, v88 dst_sel:DWORD dst_unused:UNUSED_PAD src0_sel:DWORD src1_sel:WORD_1
	v_or_b32_sdwa v86, v86, v88 dst_sel:DWORD dst_unused:UNUSED_PAD src0_sel:DWORD src1_sel:WORD_0
	v_pk_add_f32 v[88:89], v[92:93], 1.0 op_sel_hi:[1,0]
	s_nop 0
	s_nop 0
	v_rcp_f32_e32 v89, v89
	s_nop 0
	s_nop 0
	v_rcp_f32_e32 v88, v88
	s_nop 0
	v_mov_b32_e32 v90, v82
	v_mov_b32_e32 v91, v84
	v_pk_mul_f32 v[88:89], v[90:91], v[88:89]
	v_pk_add_f32 v[90:91], v[96:97], 1.0 op_sel_hi:[1,0]
	s_nop 0
	s_nop 0
	v_rcp_f32_e32 v91, v91
	s_nop 0
	s_nop 0
	v_rcp_f32_e32 v90, v90
	s_nop 0
	v_mov_b32_e32 v84, v83
	v_pk_mul_f32 v[82:83], v[84:85], v[90:91]
	v_cvt_pk_bf16_f32 v84, v88, v89
	v_cvt_pk_bf16_f32 v82, v82, v83
	v_and_b32_e32 v83, 0xffff0000, v82
	v_lshlrev_b32_e32 v82, 16, v82
	v_add_u32_e32 v93, 0x44400, v151
	v_or_b32_sdwa v89, v83, v84 dst_sel:DWORD dst_unused:UNUSED_PAD src0_sel:DWORD src1_sel:WORD_1
	v_or_b32_sdwa v88, v82, v84 dst_sel:DWORD dst_unused:UNUSED_PAD src0_sel:DWORD src1_sel:WORD_0
	v_lshl_add_u64 v[82:83], v[0:1], 1, s[6:7]
	v_add_u32_e32 v0, v93, v150
	global_store_dwordx4 v[82:83], v[86:89], off
	v_or_b32_e32 v92, 48, v152
	s_waitcnt vmcnt(15)
	v_lshlrev_b32_e32 v89, 16, v187
	v_and_b32_e32 v90, 0xffff0000, v187
	v_lshlrev_b32_e32 v83, 16, v188
	v_and_b32_e32 v87, 0xffff0000, v186
	v_mul_f32_e32 v83, 0xbfb8aa3b, v83
	v_lshlrev_b32_e32 v86, 16, v186
	v_and_b32_e32 v88, 0xffff0000, v188
	v_exp_f32_e32 v84, v83
	v_mul_f32_e32 v83, 0xbfb8aa3b, v87
	v_mul_f32_e32 v82, 0xbfb8aa3b, v86
	v_exp_f32_e32 v86, v83
	v_mul_f32_e32 v83, 0xbfb8aa3b, v88
	v_exp_f32_e32 v88, v83
	v_mul_f32_e32 v83, 0xbfb8aa3b, v89
	v_exp_f32_e32 v82, v82
	v_exp_f32_e32 v83, v83
	v_lshlrev_b32_e32 v91, 16, v189
	v_mul_f32_e32 v87, 0xbfb8aa3b, v90
	v_and_b32_e32 v94, 0xffff0000, v189
	v_pk_add_f32 v[82:83], v[82:83], 1.0 op_sel_hi:[1,0]
	v_mul_f32_e32 v85, 0xbfb8aa3b, v91
	v_mul_f32_e32 v89, 0xbfb8aa3b, v94
	v_exp_f32_e32 v87, v87
	v_exp_f32_e32 v85, v85
	v_rcp_f32_e32 v83, v83
	s_nop 0
	v_pk_add_f32 v[86:87], v[86:87], 1.0 op_sel_hi:[1,0]
	v_exp_f32_e32 v89, v89
	v_rcp_f32_e32 v82, v82
	s_nop 0
	v_mov_b32_e32 v90, v78
	v_mov_b32_e32 v91, v80
	v_pk_mul_f32 v[82:83], v[90:91], v[82:83]
	v_rcp_f32_e32 v87, v87
	s_nop 0
	s_nop 0
	v_rcp_f32_e32 v86, v86
	s_nop 0
	v_mov_b32_e32 v80, v79
	v_pk_mul_f32 v[78:79], v[80:81], v[86:87]
	v_cvt_pk_bf16_f32 v80, v82, v83
	v_cvt_pk_bf16_f32 v78, v78, v79
	v_and_b32_e32 v79, 0xffff0000, v78
	v_lshlrev_b32_e32 v78, 16, v78
	v_or_b32_sdwa v79, v79, v80 dst_sel:DWORD dst_unused:UNUSED_PAD src0_sel:DWORD src1_sel:WORD_1
	v_or_b32_sdwa v78, v78, v80 dst_sel:DWORD dst_unused:UNUSED_PAD src0_sel:DWORD src1_sel:WORD_0
	v_pk_add_f32 v[80:81], v[84:85], 1.0 op_sel_hi:[1,0]
	s_nop 0
	s_nop 0
	v_rcp_f32_e32 v81, v81
	s_nop 0
	s_nop 0
	v_rcp_f32_e32 v80, v80
	s_nop 0
	v_mov_b32_e32 v82, v74
	v_mov_b32_e32 v83, v76
	v_pk_mul_f32 v[80:81], v[82:83], v[80:81]
	v_pk_add_f32 v[82:83], v[88:89], 1.0 op_sel_hi:[1,0]
	s_nop 0
	s_nop 0
	v_rcp_f32_e32 v83, v83
	s_nop 0
	s_nop 0
	v_rcp_f32_e32 v82, v82
	s_nop 0
	v_mov_b32_e32 v76, v75
	v_pk_mul_f32 v[74:75], v[76:77], v[82:83]
	v_mul_lo_u32 v84, v92, s61
	v_cvt_pk_bf16_f32 v74, v74, v75
	v_cvt_pk_bf16_f32 v76, v80, v81
	v_and_b32_e32 v75, 0xffff0000, v74
	v_lshlrev_b32_e32 v74, 16, v74
	v_add_u32_e32 v0, v0, v84
	v_or_b32_sdwa v81, v75, v76 dst_sel:DWORD dst_unused:UNUSED_PAD src0_sel:DWORD src1_sel:WORD_1
	v_or_b32_sdwa v80, v74, v76 dst_sel:DWORD dst_unused:UNUSED_PAD src0_sel:DWORD src1_sel:WORD_0
	v_lshl_add_u64 v[74:75], v[0:1], 1, s[6:7]
	v_add_u32_e32 v0, v93, v125
	global_store_dwordx4 v[74:75], v[78:81], off
	v_add_u32_e32 v0, v0, v84
	s_waitcnt vmcnt(15)
	v_lshlrev_b32_e32 v81, 16, v191
	v_and_b32_e32 v82, 0xffff0000, v191
	v_lshlrev_b32_e32 v75, 16, v192
	v_and_b32_e32 v79, 0xffff0000, v190
	v_mul_f32_e32 v75, 0xbfb8aa3b, v75
	v_lshlrev_b32_e32 v78, 16, v190
	v_and_b32_e32 v80, 0xffff0000, v192
	v_exp_f32_e32 v76, v75
	v_mul_f32_e32 v75, 0xbfb8aa3b, v79
	v_mul_f32_e32 v74, 0xbfb8aa3b, v78
	v_exp_f32_e32 v78, v75
	v_mul_f32_e32 v75, 0xbfb8aa3b, v80
	v_exp_f32_e32 v80, v75
	v_mul_f32_e32 v75, 0xbfb8aa3b, v81
	v_exp_f32_e32 v74, v74
	v_exp_f32_e32 v75, v75
	v_lshlrev_b32_e32 v83, 16, v193
	v_mul_f32_e32 v79, 0xbfb8aa3b, v82
	v_and_b32_e32 v85, 0xffff0000, v193
	v_pk_add_f32 v[74:75], v[74:75], 1.0 op_sel_hi:[1,0]
	v_mul_f32_e32 v77, 0xbfb8aa3b, v83
	v_mul_f32_e32 v81, 0xbfb8aa3b, v85
	v_exp_f32_e32 v79, v79
	v_exp_f32_e32 v77, v77
	v_rcp_f32_e32 v75, v75
	s_nop 0
	v_pk_add_f32 v[78:79], v[78:79], 1.0 op_sel_hi:[1,0]
	v_exp_f32_e32 v81, v81
	v_rcp_f32_e32 v74, v74
	s_nop 0
	v_mov_b32_e32 v82, v70
	v_mov_b32_e32 v83, v72
	v_pk_mul_f32 v[74:75], v[82:83], v[74:75]
	v_rcp_f32_e32 v79, v79
	s_nop 0
	s_nop 0
	v_rcp_f32_e32 v78, v78
	s_nop 0
	v_mov_b32_e32 v72, v71
	v_pk_mul_f32 v[70:71], v[72:73], v[78:79]
	v_cvt_pk_bf16_f32 v72, v74, v75
	v_cvt_pk_bf16_f32 v70, v70, v71
	v_and_b32_e32 v71, 0xffff0000, v70
	v_lshlrev_b32_e32 v70, 16, v70
	v_or_b32_sdwa v71, v71, v72 dst_sel:DWORD dst_unused:UNUSED_PAD src0_sel:DWORD src1_sel:WORD_1
	v_or_b32_sdwa v70, v70, v72 dst_sel:DWORD dst_unused:UNUSED_PAD src0_sel:DWORD src1_sel:WORD_0
	v_pk_add_f32 v[72:73], v[76:77], 1.0 op_sel_hi:[1,0]
	s_nop 0
	s_nop 0
	v_rcp_f32_e32 v73, v73
	s_nop 0
	s_nop 0
	v_rcp_f32_e32 v72, v72
	s_nop 0
	v_mov_b32_e32 v74, v66
	v_mov_b32_e32 v75, v68
	v_pk_mul_f32 v[72:73], v[74:75], v[72:73]
	v_pk_add_f32 v[74:75], v[80:81], 1.0 op_sel_hi:[1,0]
	s_nop 0
	s_nop 0
	v_rcp_f32_e32 v75, v75
	s_nop 0
	s_nop 0
	v_rcp_f32_e32 v74, v74
	s_nop 0
	v_mov_b32_e32 v68, v67
	v_pk_mul_f32 v[66:67], v[68:69], v[74:75]
	v_cvt_pk_bf16_f32 v68, v72, v73
	v_cvt_pk_bf16_f32 v66, v66, v67
	v_and_b32_e32 v67, 0xffff0000, v66
	v_lshlrev_b32_e32 v66, 16, v66
	v_add_u32_e32 v76, 0xb6000, v151
	v_or_b32_sdwa v73, v67, v68 dst_sel:DWORD dst_unused:UNUSED_PAD src0_sel:DWORD src1_sel:WORD_1
	v_or_b32_sdwa v72, v66, v68 dst_sel:DWORD dst_unused:UNUSED_PAD src0_sel:DWORD src1_sel:WORD_0
	v_lshl_add_u64 v[66:67], v[0:1], 1, s[6:7]
	v_add_u32_e32 v0, v76, v150
	global_store_dwordx4 v[66:67], v[70:73], off
	s_nop 1
	s_waitcnt vmcnt(15)
	v_lshlrev_b32_e32 v73, 16, v195
	v_and_b32_e32 v74, 0xffff0000, v195
	v_lshlrev_b32_e32 v67, 16, v196
	v_and_b32_e32 v71, 0xffff0000, v194
	v_mul_f32_e32 v67, 0xbfb8aa3b, v67
	v_lshlrev_b32_e32 v70, 16, v194
	v_and_b32_e32 v72, 0xffff0000, v196
	v_exp_f32_e32 v68, v67
	v_mul_f32_e32 v67, 0xbfb8aa3b, v71
	v_mul_f32_e32 v66, 0xbfb8aa3b, v70
	v_exp_f32_e32 v70, v67
	v_mul_f32_e32 v67, 0xbfb8aa3b, v72
	v_exp_f32_e32 v72, v67
	v_mul_f32_e32 v67, 0xbfb8aa3b, v73
	v_exp_f32_e32 v66, v66
	v_exp_f32_e32 v67, v67
	v_lshlrev_b32_e32 v75, 16, v197
	v_mul_f32_e32 v71, 0xbfb8aa3b, v74
	v_and_b32_e32 v77, 0xffff0000, v197
	v_pk_add_f32 v[66:67], v[66:67], 1.0 op_sel_hi:[1,0]
	v_mul_f32_e32 v69, 0xbfb8aa3b, v75
	v_mul_f32_e32 v73, 0xbfb8aa3b, v77
	v_exp_f32_e32 v71, v71
	v_exp_f32_e32 v69, v69
	v_rcp_f32_e32 v67, v67
	s_nop 0
	v_pk_add_f32 v[70:71], v[70:71], 1.0 op_sel_hi:[1,0]
	v_exp_f32_e32 v73, v73
	v_rcp_f32_e32 v66, v66
	s_nop 0
	v_mov_b32_e32 v74, v62
	v_mov_b32_e32 v75, v64
	v_pk_mul_f32 v[66:67], v[74:75], v[66:67]
	v_rcp_f32_e32 v71, v71
	s_nop 0
	s_nop 0
	v_rcp_f32_e32 v70, v70
	s_nop 0
	v_mov_b32_e32 v64, v63
	v_pk_mul_f32 v[62:63], v[64:65], v[70:71]
	v_cvt_pk_bf16_f32 v64, v66, v67
	v_cvt_pk_bf16_f32 v62, v62, v63
	v_and_b32_e32 v63, 0xffff0000, v62
	v_lshlrev_b32_e32 v62, 16, v62
	v_or_b32_sdwa v63, v63, v64 dst_sel:DWORD dst_unused:UNUSED_PAD src0_sel:DWORD src1_sel:WORD_1
	v_or_b32_sdwa v62, v62, v64 dst_sel:DWORD dst_unused:UNUSED_PAD src0_sel:DWORD src1_sel:WORD_0
	v_pk_add_f32 v[64:65], v[68:69], 1.0 op_sel_hi:[1,0]
	s_nop 0
	s_nop 0
	v_rcp_f32_e32 v65, v65
	s_nop 0
	s_nop 0
	v_rcp_f32_e32 v64, v64
	s_nop 0
	v_mov_b32_e32 v66, v58
	v_mov_b32_e32 v67, v60
	v_pk_mul_f32 v[64:65], v[66:67], v[64:65]
	v_pk_add_f32 v[66:67], v[72:73], 1.0 op_sel_hi:[1,0]
	s_nop 0
	s_nop 0
	v_rcp_f32_e32 v67, v67
	s_nop 0
	s_nop 0
	v_rcp_f32_e32 v66, v66
	s_nop 0
	v_mov_b32_e32 v60, v59
	v_pk_mul_f32 v[58:59], v[60:61], v[66:67]
	v_add_u32_e32 v68, 0xfff6a000, v124
	v_cvt_pk_bf16_f32 v58, v58, v59
	v_cvt_pk_bf16_f32 v60, v64, v65
	v_and_b32_e32 v59, 0xffff0000, v58
	v_lshlrev_b32_e32 v58, 16, v58
	v_add_u32_e32 v0, v0, v68
	v_or_b32_sdwa v65, v59, v60 dst_sel:DWORD dst_unused:UNUSED_PAD src0_sel:DWORD src1_sel:WORD_1
	v_or_b32_sdwa v64, v58, v60 dst_sel:DWORD dst_unused:UNUSED_PAD src0_sel:DWORD src1_sel:WORD_0
	v_lshl_add_u64 v[58:59], v[0:1], 1, s[6:7]
	v_add_u32_e32 v0, v76, v125
	global_store_dwordx4 v[58:59], v[62:65], off
	v_add_u32_e32 v0, v0, v68
	s_waitcnt vmcnt(15)
	v_lshlrev_b32_e32 v65, 16, v199
	v_and_b32_e32 v66, 0xffff0000, v199
	v_lshlrev_b32_e32 v59, 16, v200
	v_and_b32_e32 v63, 0xffff0000, v198
	v_mul_f32_e32 v59, 0xbfb8aa3b, v59
	v_lshlrev_b32_e32 v62, 16, v198
	v_and_b32_e32 v64, 0xffff0000, v200
	v_exp_f32_e32 v60, v59
	v_mul_f32_e32 v59, 0xbfb8aa3b, v63
	v_mul_f32_e32 v58, 0xbfb8aa3b, v62
	v_exp_f32_e32 v62, v59
	v_mul_f32_e32 v59, 0xbfb8aa3b, v64
	v_exp_f32_e32 v64, v59
	v_mul_f32_e32 v59, 0xbfb8aa3b, v65
	v_exp_f32_e32 v58, v58
	v_exp_f32_e32 v59, v59
	v_lshlrev_b32_e32 v67, 16, v201
	v_mul_f32_e32 v63, 0xbfb8aa3b, v66
	v_and_b32_e32 v69, 0xffff0000, v201
	v_pk_add_f32 v[58:59], v[58:59], 1.0 op_sel_hi:[1,0]
	v_mul_f32_e32 v61, 0xbfb8aa3b, v67
	v_mul_f32_e32 v65, 0xbfb8aa3b, v69
	v_exp_f32_e32 v63, v63
	v_exp_f32_e32 v61, v61
	v_rcp_f32_e32 v59, v59
	s_nop 0
	v_pk_add_f32 v[62:63], v[62:63], 1.0 op_sel_hi:[1,0]
	v_exp_f32_e32 v65, v65
	v_rcp_f32_e32 v58, v58
	s_nop 0
	v_mov_b32_e32 v66, v54
	v_mov_b32_e32 v67, v56
	v_pk_mul_f32 v[58:59], v[66:67], v[58:59]
	v_rcp_f32_e32 v63, v63
	s_nop 0
	s_nop 0
	v_rcp_f32_e32 v62, v62
	s_nop 0
	v_mov_b32_e32 v56, v55
	v_pk_mul_f32 v[54:55], v[56:57], v[62:63]
	v_cvt_pk_bf16_f32 v56, v58, v59
	v_cvt_pk_bf16_f32 v54, v54, v55
	v_and_b32_e32 v55, 0xffff0000, v54
	v_lshlrev_b32_e32 v54, 16, v54
	v_or_b32_sdwa v55, v55, v56 dst_sel:DWORD dst_unused:UNUSED_PAD src0_sel:DWORD src1_sel:WORD_1
	v_or_b32_sdwa v54, v54, v56 dst_sel:DWORD dst_unused:UNUSED_PAD src0_sel:DWORD src1_sel:WORD_0
	v_pk_add_f32 v[56:57], v[60:61], 1.0 op_sel_hi:[1,0]
	s_nop 0
	s_nop 0
	v_rcp_f32_e32 v57, v57
	s_nop 0
	s_nop 0
	v_rcp_f32_e32 v56, v56
	s_nop 0
	v_mov_b32_e32 v58, v50
	v_mov_b32_e32 v59, v52
	v_pk_mul_f32 v[56:57], v[58:59], v[56:57]
	v_pk_add_f32 v[58:59], v[64:65], 1.0 op_sel_hi:[1,0]
	s_nop 0
	s_nop 0
	v_rcp_f32_e32 v59, v59
	s_nop 0
	s_nop 0
	v_rcp_f32_e32 v58, v58
	s_nop 0
	v_mov_b32_e32 v52, v51
	v_pk_mul_f32 v[50:51], v[52:53], v[58:59]
	v_cvt_pk_bf16_f32 v52, v56, v57
	v_cvt_pk_bf16_f32 v50, v50, v51
	v_and_b32_e32 v51, 0xffff0000, v50
	v_lshlrev_b32_e32 v50, 16, v50
	v_add_u32_e32 v60, 0xccc00, v151
	v_or_b32_sdwa v57, v51, v52 dst_sel:DWORD dst_unused:UNUSED_PAD src0_sel:DWORD src1_sel:WORD_1
	v_or_b32_sdwa v56, v50, v52 dst_sel:DWORD dst_unused:UNUSED_PAD src0_sel:DWORD src1_sel:WORD_0
	v_lshl_add_u64 v[50:51], v[0:1], 1, s[6:7]
	v_add_u32_e32 v0, v60, v150
	global_store_dwordx4 v[50:51], v[54:57], off
	s_nop 1
	s_waitcnt vmcnt(15)
	v_lshlrev_b32_e32 v57, 16, v203
	v_and_b32_e32 v58, 0xffff0000, v203
	v_lshlrev_b32_e32 v51, 16, v204
	v_and_b32_e32 v55, 0xffff0000, v202
	v_mul_f32_e32 v51, 0xbfb8aa3b, v51
	v_lshlrev_b32_e32 v54, 16, v202
	v_and_b32_e32 v56, 0xffff0000, v204
	v_exp_f32_e32 v52, v51
	v_mul_f32_e32 v51, 0xbfb8aa3b, v55
	v_mul_f32_e32 v50, 0xbfb8aa3b, v54
	v_exp_f32_e32 v54, v51
	v_mul_f32_e32 v51, 0xbfb8aa3b, v56
	v_exp_f32_e32 v56, v51
	v_mul_f32_e32 v51, 0xbfb8aa3b, v57
	v_exp_f32_e32 v50, v50
	v_exp_f32_e32 v51, v51
	v_lshlrev_b32_e32 v59, 16, v205
	v_mul_f32_e32 v55, 0xbfb8aa3b, v58
	v_and_b32_e32 v61, 0xffff0000, v205
	v_pk_add_f32 v[50:51], v[50:51], 1.0 op_sel_hi:[1,0]
	v_mul_f32_e32 v53, 0xbfb8aa3b, v59
	v_mul_f32_e32 v57, 0xbfb8aa3b, v61
	v_exp_f32_e32 v55, v55
	v_exp_f32_e32 v53, v53
	v_rcp_f32_e32 v51, v51
	s_nop 0
	v_pk_add_f32 v[54:55], v[54:55], 1.0 op_sel_hi:[1,0]
	v_exp_f32_e32 v57, v57
	v_rcp_f32_e32 v50, v50
	s_nop 0
	v_mov_b32_e32 v58, v46
	v_mov_b32_e32 v59, v48
	v_pk_mul_f32 v[50:51], v[58:59], v[50:51]
	v_rcp_f32_e32 v55, v55
	s_nop 0
	s_nop 0
	v_rcp_f32_e32 v54, v54
	s_nop 0
	v_mov_b32_e32 v48, v47
	v_pk_mul_f32 v[46:47], v[48:49], v[54:55]
	v_cvt_pk_bf16_f32 v48, v50, v51
	v_cvt_pk_bf16_f32 v46, v46, v47
	v_and_b32_e32 v47, 0xffff0000, v46
	v_lshlrev_b32_e32 v46, 16, v46
	v_or_b32_sdwa v47, v47, v48 dst_sel:DWORD dst_unused:UNUSED_PAD src0_sel:DWORD src1_sel:WORD_1
	v_or_b32_sdwa v46, v46, v48 dst_sel:DWORD dst_unused:UNUSED_PAD src0_sel:DWORD src1_sel:WORD_0
	v_pk_add_f32 v[48:49], v[52:53], 1.0 op_sel_hi:[1,0]
	s_nop 0
	s_nop 0
	v_rcp_f32_e32 v49, v49
	s_nop 0
	s_nop 0
	v_rcp_f32_e32 v48, v48
	s_nop 0
	v_mov_b32_e32 v50, v42
	v_mov_b32_e32 v51, v44
	v_pk_mul_f32 v[48:49], v[50:51], v[48:49]
	v_pk_add_f32 v[50:51], v[56:57], 1.0 op_sel_hi:[1,0]
	s_nop 0
	s_nop 0
	v_rcp_f32_e32 v51, v51
	s_nop 0
	s_nop 0
	v_rcp_f32_e32 v50, v50
	s_nop 0
	v_mov_b32_e32 v44, v43
	v_pk_mul_f32 v[42:43], v[44:45], v[50:51]
	v_add_u32_e32 v52, 0xfff57400, v124
	v_cvt_pk_bf16_f32 v42, v42, v43
	v_cvt_pk_bf16_f32 v44, v48, v49
	v_and_b32_e32 v43, 0xffff0000, v42
	v_lshlrev_b32_e32 v42, 16, v42
	v_add_u32_e32 v0, v0, v52
	v_or_b32_sdwa v49, v43, v44 dst_sel:DWORD dst_unused:UNUSED_PAD src0_sel:DWORD src1_sel:WORD_1
	v_or_b32_sdwa v48, v42, v44 dst_sel:DWORD dst_unused:UNUSED_PAD src0_sel:DWORD src1_sel:WORD_0
	v_lshl_add_u64 v[42:43], v[0:1], 1, s[6:7]
	v_add_u32_e32 v0, v60, v125
	global_store_dwordx4 v[42:43], v[46:49], off
	v_add_u32_e32 v0, v0, v52
	s_waitcnt vmcnt(15)
	v_lshlrev_b32_e32 v49, 16, v207
	v_and_b32_e32 v50, 0xffff0000, v207
	v_lshlrev_b32_e32 v43, 16, v208
	v_and_b32_e32 v47, 0xffff0000, v206
	v_mul_f32_e32 v43, 0xbfb8aa3b, v43
	v_lshlrev_b32_e32 v46, 16, v206
	v_and_b32_e32 v48, 0xffff0000, v208
	v_exp_f32_e32 v44, v43
	v_mul_f32_e32 v43, 0xbfb8aa3b, v47
	v_mul_f32_e32 v42, 0xbfb8aa3b, v46
	v_exp_f32_e32 v46, v43
	v_mul_f32_e32 v43, 0xbfb8aa3b, v48
	v_exp_f32_e32 v48, v43
	v_mul_f32_e32 v43, 0xbfb8aa3b, v49
	v_exp_f32_e32 v42, v42
	v_exp_f32_e32 v43, v43
	v_lshlrev_b32_e32 v51, 16, v209
	v_mul_f32_e32 v47, 0xbfb8aa3b, v50
	v_and_b32_e32 v53, 0xffff0000, v209
	v_pk_add_f32 v[42:43], v[42:43], 1.0 op_sel_hi:[1,0]
	v_mul_f32_e32 v45, 0xbfb8aa3b, v51
	v_mul_f32_e32 v49, 0xbfb8aa3b, v53
	v_exp_f32_e32 v47, v47
	v_exp_f32_e32 v45, v45
	v_rcp_f32_e32 v43, v43
	s_nop 0
	v_pk_add_f32 v[46:47], v[46:47], 1.0 op_sel_hi:[1,0]
	v_exp_f32_e32 v49, v49
	v_rcp_f32_e32 v42, v42
	s_nop 0
	v_mov_b32_e32 v50, v38
	v_mov_b32_e32 v51, v40
	v_pk_mul_f32 v[42:43], v[50:51], v[42:43]
	v_rcp_f32_e32 v47, v47
	s_nop 0
	s_nop 0
	v_rcp_f32_e32 v46, v46
	s_nop 0
	v_mov_b32_e32 v40, v39
	v_pk_mul_f32 v[38:39], v[40:41], v[46:47]
	v_cvt_pk_bf16_f32 v40, v42, v43
	v_cvt_pk_bf16_f32 v38, v38, v39
	v_and_b32_e32 v39, 0xffff0000, v38
	v_lshlrev_b32_e32 v38, 16, v38
	v_or_b32_sdwa v39, v39, v40 dst_sel:DWORD dst_unused:UNUSED_PAD src0_sel:DWORD src1_sel:WORD_1
	v_or_b32_sdwa v38, v38, v40 dst_sel:DWORD dst_unused:UNUSED_PAD src0_sel:DWORD src1_sel:WORD_0
	v_pk_add_f32 v[40:41], v[44:45], 1.0 op_sel_hi:[1,0]
	s_nop 0
	s_nop 0
	v_rcp_f32_e32 v41, v41
	s_nop 0
	s_nop 0
	v_rcp_f32_e32 v40, v40
	s_nop 0
	v_mov_b32_e32 v42, v34
	v_mov_b32_e32 v43, v36
	v_pk_mul_f32 v[40:41], v[42:43], v[40:41]
	v_pk_add_f32 v[42:43], v[48:49], 1.0 op_sel_hi:[1,0]
	s_nop 0
	s_nop 0
	v_rcp_f32_e32 v43, v43
	s_nop 0
	s_nop 0
	v_rcp_f32_e32 v42, v42
	s_nop 0
	v_mov_b32_e32 v36, v35
	v_pk_mul_f32 v[34:35], v[36:37], v[42:43]
	v_cvt_pk_bf16_f32 v36, v40, v41
	v_cvt_pk_bf16_f32 v34, v34, v35
	v_and_b32_e32 v35, 0xffff0000, v34
	v_lshlrev_b32_e32 v34, 16, v34
	v_add_u32_e32 v44, 0xe3800, v151
	v_or_b32_sdwa v41, v35, v36 dst_sel:DWORD dst_unused:UNUSED_PAD src0_sel:DWORD src1_sel:WORD_1
	v_or_b32_sdwa v40, v34, v36 dst_sel:DWORD dst_unused:UNUSED_PAD src0_sel:DWORD src1_sel:WORD_0
	v_lshl_add_u64 v[34:35], v[0:1], 1, s[6:7]
	v_add_u32_e32 v0, v44, v150
	global_store_dwordx4 v[34:35], v[38:41], off
	s_nop 1
	s_waitcnt vmcnt(15)
	v_lshlrev_b32_e32 v41, 16, v211
	v_and_b32_e32 v42, 0xffff0000, v211
	v_lshlrev_b32_e32 v35, 16, v212
	v_and_b32_e32 v39, 0xffff0000, v210
	v_mul_f32_e32 v35, 0xbfb8aa3b, v35
	v_lshlrev_b32_e32 v38, 16, v210
	v_and_b32_e32 v40, 0xffff0000, v212
	v_exp_f32_e32 v36, v35
	v_mul_f32_e32 v35, 0xbfb8aa3b, v39
	v_mul_f32_e32 v34, 0xbfb8aa3b, v38
	v_exp_f32_e32 v38, v35
	v_mul_f32_e32 v35, 0xbfb8aa3b, v40
	v_exp_f32_e32 v40, v35
	v_mul_f32_e32 v35, 0xbfb8aa3b, v41
	v_exp_f32_e32 v34, v34
	v_exp_f32_e32 v35, v35
	v_lshlrev_b32_e32 v43, 16, v213
	v_mul_f32_e32 v39, 0xbfb8aa3b, v42
	v_and_b32_e32 v45, 0xffff0000, v213
	v_pk_add_f32 v[34:35], v[34:35], 1.0 op_sel_hi:[1,0]
	v_mul_f32_e32 v37, 0xbfb8aa3b, v43
	v_mul_f32_e32 v41, 0xbfb8aa3b, v45
	v_exp_f32_e32 v39, v39
	v_exp_f32_e32 v37, v37
	v_rcp_f32_e32 v35, v35
	s_nop 0
	v_pk_add_f32 v[38:39], v[38:39], 1.0 op_sel_hi:[1,0]
	v_exp_f32_e32 v41, v41
	v_rcp_f32_e32 v34, v34
	s_nop 0
	v_mov_b32_e32 v42, v30
	v_mov_b32_e32 v43, v32
	v_pk_mul_f32 v[34:35], v[42:43], v[34:35]
	v_rcp_f32_e32 v39, v39
	s_nop 0
	s_nop 0
	v_rcp_f32_e32 v38, v38
	s_nop 0
	v_mov_b32_e32 v32, v31
	v_pk_mul_f32 v[30:31], v[32:33], v[38:39]
	v_cvt_pk_bf16_f32 v32, v34, v35
	v_cvt_pk_bf16_f32 v30, v30, v31
	v_and_b32_e32 v31, 0xffff0000, v30
	v_lshlrev_b32_e32 v30, 16, v30
	v_or_b32_sdwa v31, v31, v32 dst_sel:DWORD dst_unused:UNUSED_PAD src0_sel:DWORD src1_sel:WORD_1
	v_or_b32_sdwa v30, v30, v32 dst_sel:DWORD dst_unused:UNUSED_PAD src0_sel:DWORD src1_sel:WORD_0
	v_pk_add_f32 v[32:33], v[36:37], 1.0 op_sel_hi:[1,0]
	s_nop 0
	s_nop 0
	v_rcp_f32_e32 v33, v33
	s_nop 0
	s_nop 0
	v_rcp_f32_e32 v32, v32
	s_nop 0
	v_mov_b32_e32 v34, v26
	v_mov_b32_e32 v35, v28
	v_pk_mul_f32 v[32:33], v[34:35], v[32:33]
	v_pk_add_f32 v[34:35], v[40:41], 1.0 op_sel_hi:[1,0]
	s_nop 0
	s_nop 0
	v_rcp_f32_e32 v35, v35
	s_nop 0
	s_nop 0
	v_rcp_f32_e32 v34, v34
	s_nop 0
	v_mov_b32_e32 v28, v27
	v_pk_mul_f32 v[26:27], v[28:29], v[34:35]
	v_add_u32_e32 v36, 0xfff44800, v124
	v_cvt_pk_bf16_f32 v26, v26, v27
	v_cvt_pk_bf16_f32 v28, v32, v33
	v_and_b32_e32 v27, 0xffff0000, v26
	v_lshlrev_b32_e32 v26, 16, v26
	v_add_u32_e32 v0, v0, v36
	v_or_b32_sdwa v33, v27, v28 dst_sel:DWORD dst_unused:UNUSED_PAD src0_sel:DWORD src1_sel:WORD_1
	v_or_b32_sdwa v32, v26, v28 dst_sel:DWORD dst_unused:UNUSED_PAD src0_sel:DWORD src1_sel:WORD_0
	v_lshl_add_u64 v[26:27], v[0:1], 1, s[6:7]
	v_add_u32_e32 v0, v44, v125
	global_store_dwordx4 v[26:27], v[30:33], off
	v_add_u32_e32 v0, v0, v36
	s_waitcnt vmcnt(14)
	v_lshlrev_b32_e32 v33, 16, v163
	v_and_b32_e32 v34, 0xffff0000, v163
	v_lshlrev_b32_e32 v27, 16, v164
	v_and_b32_e32 v31, 0xffff0000, v162
	v_mul_f32_e32 v27, 0xbfb8aa3b, v27
	v_lshlrev_b32_e32 v30, 16, v162
	v_and_b32_e32 v32, 0xffff0000, v164
	v_exp_f32_e32 v28, v27
	v_mul_f32_e32 v27, 0xbfb8aa3b, v31
	v_mul_f32_e32 v26, 0xbfb8aa3b, v30
	v_exp_f32_e32 v30, v27
	v_mul_f32_e32 v27, 0xbfb8aa3b, v32
	v_exp_f32_e32 v32, v27
	v_mul_f32_e32 v27, 0xbfb8aa3b, v33
	v_exp_f32_e32 v26, v26
	v_exp_f32_e32 v27, v27
	v_lshlrev_b32_e32 v35, 16, v165
	v_mul_f32_e32 v31, 0xbfb8aa3b, v34
	v_and_b32_e32 v37, 0xffff0000, v165
	v_pk_add_f32 v[26:27], v[26:27], 1.0 op_sel_hi:[1,0]
	v_mul_f32_e32 v29, 0xbfb8aa3b, v35
	v_mul_f32_e32 v33, 0xbfb8aa3b, v37
	v_exp_f32_e32 v31, v31
	v_exp_f32_e32 v29, v29
	v_rcp_f32_e32 v27, v27
	s_nop 0
	v_pk_add_f32 v[30:31], v[30:31], 1.0 op_sel_hi:[1,0]
	v_exp_f32_e32 v33, v33
	v_rcp_f32_e32 v26, v26
	s_nop 0
	v_mov_b32_e32 v34, v22
	v_mov_b32_e32 v35, v24
	v_pk_mul_f32 v[26:27], v[34:35], v[26:27]
	v_rcp_f32_e32 v31, v31
	s_nop 0
	s_nop 0
	v_rcp_f32_e32 v30, v30
	s_nop 0
	v_mov_b32_e32 v24, v23
	v_pk_mul_f32 v[22:23], v[24:25], v[30:31]
	v_cvt_pk_bf16_f32 v24, v26, v27
	v_cvt_pk_bf16_f32 v22, v22, v23
	v_and_b32_e32 v23, 0xffff0000, v22
	v_lshlrev_b32_e32 v22, 16, v22
	v_or_b32_sdwa v23, v23, v24 dst_sel:DWORD dst_unused:UNUSED_PAD src0_sel:DWORD src1_sel:WORD_1
	v_or_b32_sdwa v22, v22, v24 dst_sel:DWORD dst_unused:UNUSED_PAD src0_sel:DWORD src1_sel:WORD_0
	v_pk_add_f32 v[24:25], v[28:29], 1.0 op_sel_hi:[1,0]
	s_nop 0
	s_nop 0
	v_rcp_f32_e32 v25, v25
	s_nop 0
	s_nop 0
	v_rcp_f32_e32 v24, v24
	s_nop 0
	v_mov_b32_e32 v26, v18
	v_mov_b32_e32 v27, v20
	v_pk_mul_f32 v[24:25], v[26:27], v[24:25]
	v_pk_add_f32 v[26:27], v[32:33], 1.0 op_sel_hi:[1,0]
	s_nop 0
	s_nop 0
	v_rcp_f32_e32 v27, v27
	s_nop 0
	s_nop 0
	v_rcp_f32_e32 v26, v26
	s_nop 0
	v_mov_b32_e32 v20, v19
	v_pk_mul_f32 v[18:19], v[20:21], v[26:27]
	v_cvt_pk_bf16_f32 v20, v24, v25
	v_cvt_pk_bf16_f32 v18, v18, v19
	v_and_b32_e32 v19, 0xffff0000, v18
	v_lshlrev_b32_e32 v18, 16, v18
	v_add_u32_e32 v28, 0xfa400, v151
	v_or_b32_sdwa v25, v19, v20 dst_sel:DWORD dst_unused:UNUSED_PAD src0_sel:DWORD src1_sel:WORD_1
	v_or_b32_sdwa v24, v18, v20 dst_sel:DWORD dst_unused:UNUSED_PAD src0_sel:DWORD src1_sel:WORD_0
	v_lshl_add_u64 v[18:19], v[0:1], 1, s[6:7]
	v_add_u32_e32 v0, v28, v150
	global_store_dwordx4 v[18:19], v[22:25], off
	s_nop 1
	s_waitcnt vmcnt(13)
	v_lshlrev_b32_e32 v25, 16, v167
	v_and_b32_e32 v26, 0xffff0000, v167
	v_lshlrev_b32_e32 v19, 16, v168
	v_and_b32_e32 v23, 0xffff0000, v166
	v_mul_f32_e32 v19, 0xbfb8aa3b, v19
	v_lshlrev_b32_e32 v22, 16, v166
	v_and_b32_e32 v24, 0xffff0000, v168
	v_exp_f32_e32 v20, v19
	v_mul_f32_e32 v19, 0xbfb8aa3b, v23
	v_mul_f32_e32 v18, 0xbfb8aa3b, v22
	v_exp_f32_e32 v22, v19
	v_mul_f32_e32 v19, 0xbfb8aa3b, v24
	v_exp_f32_e32 v24, v19
	v_mul_f32_e32 v19, 0xbfb8aa3b, v25
	v_exp_f32_e32 v18, v18
	v_exp_f32_e32 v19, v19
	v_lshlrev_b32_e32 v27, 16, v169
	v_mul_f32_e32 v23, 0xbfb8aa3b, v26
	v_and_b32_e32 v29, 0xffff0000, v169
	v_pk_add_f32 v[18:19], v[18:19], 1.0 op_sel_hi:[1,0]
	v_mul_f32_e32 v21, 0xbfb8aa3b, v27
	v_mul_f32_e32 v25, 0xbfb8aa3b, v29
	v_exp_f32_e32 v23, v23
	v_exp_f32_e32 v21, v21
	v_rcp_f32_e32 v19, v19
	s_nop 0
	v_pk_add_f32 v[22:23], v[22:23], 1.0 op_sel_hi:[1,0]
	v_exp_f32_e32 v25, v25
	v_rcp_f32_e32 v18, v18
	s_nop 0
	v_mov_b32_e32 v26, v14
	v_mov_b32_e32 v27, v16
	v_pk_mul_f32 v[18:19], v[26:27], v[18:19]
	v_rcp_f32_e32 v23, v23
	s_nop 0
	s_nop 0
	v_rcp_f32_e32 v22, v22
	s_nop 0
	v_mov_b32_e32 v16, v15
	v_pk_mul_f32 v[14:15], v[16:17], v[22:23]
	v_cvt_pk_bf16_f32 v16, v18, v19
	v_cvt_pk_bf16_f32 v14, v14, v15
	v_and_b32_e32 v15, 0xffff0000, v14
	v_lshlrev_b32_e32 v14, 16, v14
	v_or_b32_sdwa v15, v15, v16 dst_sel:DWORD dst_unused:UNUSED_PAD src0_sel:DWORD src1_sel:WORD_1
	v_or_b32_sdwa v14, v14, v16 dst_sel:DWORD dst_unused:UNUSED_PAD src0_sel:DWORD src1_sel:WORD_0
	v_pk_add_f32 v[16:17], v[20:21], 1.0 op_sel_hi:[1,0]
	s_nop 0
	s_nop 0
	v_rcp_f32_e32 v17, v17
	s_nop 0
	s_nop 0
	v_rcp_f32_e32 v16, v16
	s_nop 0
	v_mov_b32_e32 v18, v10
	v_mov_b32_e32 v19, v12
	v_pk_mul_f32 v[16:17], v[18:19], v[16:17]
	v_pk_add_f32 v[18:19], v[24:25], 1.0 op_sel_hi:[1,0]
	s_nop 0
	s_nop 0
	v_rcp_f32_e32 v19, v19
	s_nop 0
	s_nop 0
	v_rcp_f32_e32 v18, v18
	s_nop 0
	v_mov_b32_e32 v12, v11
	v_pk_mul_f32 v[10:11], v[12:13], v[18:19]
	v_add_u32_e32 v20, 0xfff31c00, v124
	v_cvt_pk_bf16_f32 v10, v10, v11
	v_cvt_pk_bf16_f32 v12, v16, v17
	v_and_b32_e32 v11, 0xffff0000, v10
	v_lshlrev_b32_e32 v10, 16, v10
	v_add_u32_e32 v0, v0, v20
	v_or_b32_sdwa v17, v11, v12 dst_sel:DWORD dst_unused:UNUSED_PAD src0_sel:DWORD src1_sel:WORD_1
	v_or_b32_sdwa v16, v10, v12 dst_sel:DWORD dst_unused:UNUSED_PAD src0_sel:DWORD src1_sel:WORD_0
	v_lshl_add_u64 v[10:11], v[0:1], 1, s[6:7]
	v_add_u32_e32 v0, v28, v125
	global_store_dwordx4 v[10:11], v[14:17], off
	v_add_u32_e32 v0, v0, v20
	s_waitcnt vmcnt(12)
	v_lshlrev_b32_e32 v17, 16, v171
	v_and_b32_e32 v18, 0xffff0000, v171
	v_lshlrev_b32_e32 v11, 16, v172
	v_and_b32_e32 v15, 0xffff0000, v170
	v_mul_f32_e32 v11, 0xbfb8aa3b, v11
	v_lshlrev_b32_e32 v14, 16, v170
	v_and_b32_e32 v16, 0xffff0000, v172
	v_exp_f32_e32 v12, v11
	v_mul_f32_e32 v11, 0xbfb8aa3b, v15
	v_mul_f32_e32 v10, 0xbfb8aa3b, v14
	v_exp_f32_e32 v14, v11
	v_mul_f32_e32 v11, 0xbfb8aa3b, v16
	v_exp_f32_e32 v16, v11
	v_mul_f32_e32 v11, 0xbfb8aa3b, v17
	v_exp_f32_e32 v10, v10
	v_exp_f32_e32 v11, v11
	v_lshlrev_b32_e32 v19, 16, v173
	v_mul_f32_e32 v15, 0xbfb8aa3b, v18
	v_and_b32_e32 v21, 0xffff0000, v173
	v_pk_add_f32 v[10:11], v[10:11], 1.0 op_sel_hi:[1,0]
	v_mul_f32_e32 v13, 0xbfb8aa3b, v19
	v_mul_f32_e32 v17, 0xbfb8aa3b, v21
	v_exp_f32_e32 v15, v15
	v_exp_f32_e32 v13, v13
	v_rcp_f32_e32 v11, v11
	s_nop 0
	v_pk_add_f32 v[14:15], v[14:15], 1.0 op_sel_hi:[1,0]
	v_exp_f32_e32 v17, v17
	v_rcp_f32_e32 v10, v10
	s_nop 0
	v_mov_b32_e32 v18, v6
	v_mov_b32_e32 v19, v8
	v_pk_mul_f32 v[10:11], v[18:19], v[10:11]
	v_rcp_f32_e32 v15, v15
	s_nop 0
	s_nop 0
	v_rcp_f32_e32 v14, v14
	s_nop 0
	v_mov_b32_e32 v8, v7
	v_pk_mul_f32 v[6:7], v[8:9], v[14:15]
	v_cvt_pk_bf16_f32 v8, v10, v11
	v_cvt_pk_bf16_f32 v6, v6, v7
	v_and_b32_e32 v7, 0xffff0000, v6
	v_lshlrev_b32_e32 v6, 16, v6
	v_or_b32_sdwa v7, v7, v8 dst_sel:DWORD dst_unused:UNUSED_PAD src0_sel:DWORD src1_sel:WORD_1
	v_or_b32_sdwa v6, v6, v8 dst_sel:DWORD dst_unused:UNUSED_PAD src0_sel:DWORD src1_sel:WORD_0
	v_pk_add_f32 v[8:9], v[12:13], 1.0 op_sel_hi:[1,0]
	s_nop 0
	s_nop 0
	v_rcp_f32_e32 v9, v9
	s_nop 0
	s_nop 0
	v_rcp_f32_e32 v8, v8
	s_nop 0
	v_mov_b32_e32 v10, v2
	v_mov_b32_e32 v11, v4
	v_pk_mul_f32 v[8:9], v[10:11], v[8:9]
	v_pk_add_f32 v[10:11], v[16:17], 1.0 op_sel_hi:[1,0]
	s_nop 0
	s_nop 0
	v_rcp_f32_e32 v11, v11
	s_nop 0
	s_mov_b64 s[24:25], s[16:17]
	v_rcp_f32_e32 v10, v10
	s_nop 0
	v_mov_b32_e32 v4, v3
	v_pk_mul_f32 v[2:3], v[4:5], v[10:11]
	v_cvt_pk_bf16_f32 v4, v8, v9
	v_cvt_pk_bf16_f32 v2, v2, v3
	v_and_b32_e32 v3, 0xffff0000, v2
	v_lshlrev_b32_e32 v2, 16, v2
	v_or_b32_sdwa v9, v3, v4 dst_sel:DWORD dst_unused:UNUSED_PAD src0_sel:DWORD src1_sel:WORD_1
	v_or_b32_sdwa v8, v2, v4 dst_sel:DWORD dst_unused:UNUSED_PAD src0_sel:DWORD src1_sel:WORD_0
	v_lshl_add_u64 v[2:3], v[0:1], 1, s[6:7]
	s_and_b64 vcc, exec, s[10:11]
	global_store_dwordx4 v[2:3], v[6:9], off
	s_cbranch_vccz .LBB0_1331
	s_waitcnt vmcnt(0)
	v_readlane_b32 s76, v255, 8
	s_mov_b32 s92, 0x3b2aaaab
	s_cmp_gt_u32 s5, 3
	v_readlane_b32 s77, v255, 9
	s_mul_i32 s60, s33, 0x1800
	s_mul_hi_i32 s62, s64, 0x300
	s_mul_i32 s75, s33, 0x16c00
	s_mov_b32 s93, 0x3c800000
	s_mov_b32 s82, s70
	s_cbranch_scc1 .LBB0_1338
	s_barrier

.LBB0_1347:
	v_add_u32_e32 v0, 0x10000, v148
	ds_read_b128 v[142:145], v0
	ds_read_b128 v[150:153], v0 offset:1024
	ds_read_b128 v[154:157], v0 offset:2048
	ds_read_b128 v[158:161], v0 offset:3072
	s_add_u32 s26, s24, 0xfffc0080
	s_addc_u32 s27, s25, -1
	s_cmp_eq_u32 s97, 12
	s_cselect_b32 s29, s2, s27
	s_cselect_b32 s28, s15, s26
	s_cselect_b32 s27, s13, s94
	s_cselect_b32 s26, s89, s90
	v_lshl_add_u64 v[178:179], s[24:25], 0, v[138:139]
	s_add_i32 m0, s35, 0xc000
	ds_read_b128 v[162:165], v147
	ds_read_b128 v[166:169], v147 offset:1024
	ds_read_b128 v[170:173], v147 offset:2048
	ds_read_b128 v[174:177], v147 offset:3072
	ds_read_b128 v[182:185], v147 offset:4096
	ds_read_b128 v[186:189], v147 offset:5120
	ds_read_b128 v[190:193], v147 offset:6144
	ds_read_b128 v[194:197], v147 offset:7168
	global_load_lds_dwordx4 v[178:179], off
	v_lshl_add_u64 v[178:179], s[24:25], 0, v[140:141]
	s_add_i32 m0, s35, 0xe000
	s_nop 0
	global_load_lds_dwordx4 v[178:179], off
	s_waitcnt lgkmcnt(8)
	s_barrier
	s_waitcnt lgkmcnt(0)
	s_waitcnt lgkmcnt(0)
	v_mfma_f32_16x16x32_bf16 v[126:129], v[142:145], v[162:165], v[126:129]
	v_mfma_f32_16x16x32_bf16 v[122:125], v[154:157], v[162:165], v[122:125]
	v_mfma_f32_16x16x32_bf16 v[110:113], v[142:145], v[170:173], v[110:113]
	v_mfma_f32_16x16x32_bf16 v[106:109], v[154:157], v[170:173], v[106:109]
	v_mfma_f32_16x16x32_bf16 v[94:97], v[142:145], v[182:185], v[94:97]
	v_mfma_f32_16x16x32_bf16 v[90:93], v[154:157], v[182:185], v[90:93]
	v_mfma_f32_16x16x32_bf16 v[78:81], v[142:145], v[190:193], v[78:81]
	v_mfma_f32_16x16x32_bf16 v[74:77], v[154:157], v[190:193], v[74:77]
	v_mfma_f32_16x16x32_bf16 v[126:129], v[150:153], v[166:169], v[126:129]
	v_mfma_f32_16x16x32_bf16 v[122:125], v[158:161], v[166:169], v[122:125]
	v_mfma_f32_16x16x32_bf16 v[110:113], v[150:153], v[174:177], v[110:113]
	v_mfma_f32_16x16x32_bf16 v[106:109], v[158:161], v[174:177], v[106:109]
	v_mfma_f32_16x16x32_bf16 v[94:97], v[150:153], v[186:189], v[94:97]
	v_mfma_f32_16x16x32_bf16 v[90:93], v[158:161], v[186:189], v[90:93]
	v_mfma_f32_16x16x32_bf16 v[78:81], v[150:153], v[194:197], v[78:81]
	v_mfma_f32_16x16x32_bf16 v[74:77], v[158:161], v[194:197], v[74:77]
	s_barrier
	s_mov_b32 m0, s21
	v_add_u32_e32 v0, 0x14000, v148
	v_lshl_add_u64 v[178:179], s[26:27], 0, v[134:135]
	ds_read_b128 v[198:201], v0
	ds_read_b128 v[202:205], v0 offset:1024
	ds_read_b128 v[206:209], v0 offset:2048
	ds_read_b128 v[210:213], v0 offset:3072
	global_load_lds_dwordx4 v[178:179], off
	v_lshl_add_u64 v[214:215], s[26:27], 0, v[130:131]
	s_mov_b32 m0, s23
	s_nop 0
	global_load_lds_dwordx4 v[214:215], off
	s_barrier
	s_waitcnt lgkmcnt(0)
	s_waitcnt lgkmcnt(0)
	v_mfma_f32_16x16x32_bf16 v[118:121], v[198:201], v[162:165], v[118:121]
	v_mfma_f32_16x16x32_bf16 v[114:117], v[206:209], v[162:165], v[114:117]
	v_mfma_f32_16x16x32_bf16 v[102:105], v[198:201], v[170:173], v[102:105]
	v_mfma_f32_16x16x32_bf16 v[98:101], v[206:209], v[170:173], v[98:101]
	v_mfma_f32_16x16x32_bf16 v[86:89], v[198:201], v[182:185], v[86:89]
	v_mfma_f32_16x16x32_bf16 v[82:85], v[206:209], v[182:185], v[82:85]
	v_mfma_f32_16x16x32_bf16 v[70:73], v[198:201], v[190:193], v[70:73]
	v_mfma_f32_16x16x32_bf16 v[66:69], v[206:209], v[190:193], v[66:69]
	v_mfma_f32_16x16x32_bf16 v[118:121], v[202:205], v[166:169], v[118:121]
	v_mfma_f32_16x16x32_bf16 v[114:117], v[210:213], v[166:169], v[114:117]
	v_mfma_f32_16x16x32_bf16 v[102:105], v[202:205], v[174:177], v[102:105]
	v_mfma_f32_16x16x32_bf16 v[98:101], v[210:213], v[174:177], v[98:101]
	v_mfma_f32_16x16x32_bf16 v[86:89], v[202:205], v[186:189], v[86:89]
	v_mfma_f32_16x16x32_bf16 v[82:85], v[210:213], v[186:189], v[82:85]
	v_mfma_f32_16x16x32_bf16 v[70:73], v[202:205], v[194:197], v[70:73]
	v_mfma_f32_16x16x32_bf16 v[66:69], v[210:213], v[194:197], v[66:69]
	s_mov_b32 m0, s35
	v_lshl_add_u64 v[216:217], s[28:29], 0, v[136:137]
	s_barrier
	ds_read_b128 v[162:165], v147 offset:16384
	ds_read_b128 v[166:169], v147 offset:17408
	ds_read_b128 v[170:173], v147 offset:18432
	ds_read_b128 v[174:177], v147 offset:19456
	ds_read_b128 v[182:185], v147 offset:20480
	ds_read_b128 v[186:189], v147 offset:21504
	ds_read_b128 v[190:193], v147 offset:22528
	ds_read_b128 v[194:197], v147 offset:23552
	global_load_lds_dwordx4 v[216:217], off
	v_lshl_add_u64 v[222:223], s[28:29], 0, v[132:133]
	s_mov_b32 m0, s36
	s_nop 0
	global_load_lds_dwordx4 v[222:223], off
	s_barrier
	s_waitcnt lgkmcnt(0)
	s_waitcnt lgkmcnt(0)
	v_mfma_f32_16x16x32_bf16 v[62:65], v[142:145], v[162:165], v[62:65]
	v_mfma_f32_16x16x32_bf16 v[58:61], v[154:157], v[162:165], v[58:61]
	v_mfma_f32_16x16x32_bf16 v[46:49], v[142:145], v[170:173], v[46:49]
	v_mfma_f32_16x16x32_bf16 v[42:45], v[154:157], v[170:173], v[42:45]
	v_mfma_f32_16x16x32_bf16 v[30:33], v[142:145], v[182:185], v[30:33]
	v_mfma_f32_16x16x32_bf16 v[26:29], v[154:157], v[182:185], v[26:29]
	v_mfma_f32_16x16x32_bf16 v[14:17], v[142:145], v[190:193], v[14:17]
	v_mfma_f32_16x16x32_bf16 v[10:13], v[154:157], v[190:193], v[10:13]
	v_mfma_f32_16x16x32_bf16 v[62:65], v[150:153], v[166:169], v[62:65]
	v_mfma_f32_16x16x32_bf16 v[58:61], v[158:161], v[166:169], v[58:61]
	v_mfma_f32_16x16x32_bf16 v[46:49], v[150:153], v[174:177], v[46:49]
	v_mfma_f32_16x16x32_bf16 v[42:45], v[158:161], v[174:177], v[42:45]
	v_mfma_f32_16x16x32_bf16 v[30:33], v[150:153], v[186:189], v[30:33]
	v_mfma_f32_16x16x32_bf16 v[26:29], v[158:161], v[186:189], v[26:29]
	v_mfma_f32_16x16x32_bf16 v[14:17], v[150:153], v[194:197], v[14:17]
	v_mfma_f32_16x16x32_bf16 v[10:13], v[158:161], v[194:197], v[10:13]
	s_barrier
	s_add_u32 s76, s26, 0x40000
	s_addc_u32 s77, s27, 0
	s_mov_b32 m0, s37
	v_lshl_add_u64 v[142:143], s[76:77], 0, v[134:135]
	global_load_lds_dwordx4 v[142:143], off
	v_lshl_add_u64 v[142:143], s[76:77], 0, v[130:131]
	s_mov_b32 m0, s38
	s_nop 0
	global_load_lds_dwordx4 v[142:143], off
	s_waitcnt vmcnt(6)
	s_barrier
	v_mfma_f32_16x16x32_bf16 v[54:57], v[198:201], v[162:165], v[54:57]
	v_mfma_f32_16x16x32_bf16 v[50:53], v[206:209], v[162:165], v[50:53]
	v_mfma_f32_16x16x32_bf16 v[38:41], v[198:201], v[170:173], v[38:41]
	v_mfma_f32_16x16x32_bf16 v[34:37], v[206:209], v[170:173], v[34:37]
	v_mfma_f32_16x16x32_bf16 v[22:25], v[198:201], v[182:185], v[22:25]
	v_mfma_f32_16x16x32_bf16 v[18:21], v[206:209], v[182:185], v[18:21]
	v_mfma_f32_16x16x32_bf16 v[6:9], v[198:201], v[190:193], v[6:9]
	v_mfma_f32_16x16x32_bf16 v[2:5], v[206:209], v[190:193], v[2:5]
	v_mfma_f32_16x16x32_bf16 v[54:57], v[202:205], v[166:169], v[54:57]
	v_mfma_f32_16x16x32_bf16 v[50:53], v[210:213], v[166:169], v[50:53]
	v_mfma_f32_16x16x32_bf16 v[38:41], v[202:205], v[174:177], v[38:41]
	v_mfma_f32_16x16x32_bf16 v[34:37], v[210:213], v[174:177], v[34:37]
	v_mfma_f32_16x16x32_bf16 v[22:25], v[202:205], v[186:189], v[22:25]
	v_mfma_f32_16x16x32_bf16 v[18:21], v[210:213], v[186:189], v[18:21]
	v_mfma_f32_16x16x32_bf16 v[6:9], v[202:205], v[194:197], v[6:9]
	v_mfma_f32_16x16x32_bf16 v[2:5], v[210:213], v[194:197], v[2:5]
	v_add_u32_e32 v0, 0x18000, v148
	s_barrier
	ds_read_b128 v[142:145], v0
	ds_read_b128 v[150:153], v0 offset:1024
	ds_read_b128 v[154:157], v0 offset:2048
	ds_read_b128 v[158:161], v0 offset:3072
	s_add_u32 s28, s28, 0x40000
	s_addc_u32 s29, s29, 0
	s_mov_b32 m0, s39
	v_lshl_add_u64 v[198:199], s[28:29], 0, v[136:137]
	ds_read_b128 v[162:165], v147 offset:32768
	ds_read_b128 v[166:169], v147 offset:33792
	ds_read_b128 v[170:173], v147 offset:34816
	ds_read_b128 v[174:177], v147 offset:35840
	ds_read_b128 v[182:185], v147 offset:36864
	ds_read_b128 v[186:189], v147 offset:37888
	ds_read_b128 v[190:193], v147 offset:38912
	ds_read_b128 v[194:197], v147 offset:39936
	global_load_lds_dwordx4 v[198:199], off
	v_lshl_add_u64 v[198:199], s[28:29], 0, v[132:133]
	s_mov_b32 m0, s60
	s_nop 0
	global_load_lds_dwordx4 v[198:199], off
	s_waitcnt lgkmcnt(8)
	s_barrier
	s_waitcnt lgkmcnt(0)
	s_waitcnt lgkmcnt(0)
	v_mfma_f32_16x16x32_bf16 v[126:129], v[142:145], v[162:165], v[126:129]
	v_mfma_f32_16x16x32_bf16 v[122:125], v[154:157], v[162:165], v[122:125]
	v_mfma_f32_16x16x32_bf16 v[110:113], v[142:145], v[170:173], v[110:113]
	v_mfma_f32_16x16x32_bf16 v[106:109], v[154:157], v[170:173], v[106:109]
	v_mfma_f32_16x16x32_bf16 v[94:97], v[142:145], v[182:185], v[94:97]
	v_mfma_f32_16x16x32_bf16 v[90:93], v[154:157], v[182:185], v[90:93]
	v_mfma_f32_16x16x32_bf16 v[78:81], v[142:145], v[190:193], v[78:81]
	v_mfma_f32_16x16x32_bf16 v[74:77], v[154:157], v[190:193], v[74:77]
	v_mfma_f32_16x16x32_bf16 v[126:129], v[150:153], v[166:169], v[126:129]
	v_mfma_f32_16x16x32_bf16 v[122:125], v[158:161], v[166:169], v[122:125]
	v_mfma_f32_16x16x32_bf16 v[110:113], v[150:153], v[174:177], v[110:113]
	v_mfma_f32_16x16x32_bf16 v[106:109], v[158:161], v[174:177], v[106:109]
	v_mfma_f32_16x16x32_bf16 v[94:97], v[150:153], v[186:189], v[94:97]
	v_mfma_f32_16x16x32_bf16 v[90:93], v[158:161], v[186:189], v[90:93]
	v_mfma_f32_16x16x32_bf16 v[78:81], v[150:153], v[194:197], v[78:81]
	v_mfma_f32_16x16x32_bf16 v[74:77], v[158:161], v[194:197], v[74:77]
	s_barrier
	s_mov_b32 m0, s68
	v_add_u32_e32 v0, 0x1c000, v148
	v_lshl_add_u64 v[178:179], v[178:179], 0, s[84:85]
	ds_read_b128 v[198:201], v0
	ds_read_b128 v[202:205], v0 offset:1024
	ds_read_b128 v[206:209], v0 offset:2048
	ds_read_b128 v[210:213], v0 offset:3072
	global_load_lds_dwordx4 v[178:179], off
	v_lshl_add_u64 v[178:179], v[214:215], 0, s[84:85]
	s_mov_b32 m0, s69
	s_nop 0
	global_load_lds_dwordx4 v[178:179], off
	s_barrier
	s_waitcnt lgkmcnt(0)
	s_waitcnt lgkmcnt(0)
	v_mfma_f32_16x16x32_bf16 v[118:121], v[198:201], v[162:165], v[118:121]
	v_mfma_f32_16x16x32_bf16 v[114:117], v[206:209], v[162:165], v[114:117]
	v_mfma_f32_16x16x32_bf16 v[102:105], v[198:201], v[170:173], v[102:105]
	v_mfma_f32_16x16x32_bf16 v[98:101], v[206:209], v[170:173], v[98:101]
	v_mfma_f32_16x16x32_bf16 v[86:89], v[198:201], v[182:185], v[86:89]
	v_mfma_f32_16x16x32_bf16 v[82:85], v[206:209], v[182:185], v[82:85]
	v_mfma_f32_16x16x32_bf16 v[70:73], v[198:201], v[190:193], v[70:73]
	v_mfma_f32_16x16x32_bf16 v[66:69], v[206:209], v[190:193], v[66:69]
	v_mfma_f32_16x16x32_bf16 v[118:121], v[202:205], v[166:169], v[118:121]
	v_mfma_f32_16x16x32_bf16 v[114:117], v[210:213], v[166:169], v[114:117]
	v_mfma_f32_16x16x32_bf16 v[102:105], v[202:205], v[174:177], v[102:105]
	v_mfma_f32_16x16x32_bf16 v[98:101], v[210:213], v[174:177], v[98:101]
	v_mfma_f32_16x16x32_bf16 v[86:89], v[202:205], v[186:189], v[86:89]
	v_mfma_f32_16x16x32_bf16 v[82:85], v[210:213], v[186:189], v[82:85]
	v_mfma_f32_16x16x32_bf16 v[70:73], v[202:205], v[194:197], v[70:73]
	v_mfma_f32_16x16x32_bf16 v[66:69], v[210:213], v[194:197], v[66:69]
	s_mov_b32 m0, s75
	v_lshl_add_u64 v[178:179], v[216:217], 0, s[84:85]
	s_barrier
	ds_read_b128 v[162:165], v147 offset:49152
	ds_read_b128 v[166:169], v147 offset:50176
	ds_read_b128 v[170:173], v147 offset:51200
	ds_read_b128 v[174:177], v147 offset:52224
	ds_read_b128 v[182:185], v147 offset:53248
	ds_read_b128 v[186:189], v147 offset:54272
	ds_read_b128 v[190:193], v147 offset:55296
	ds_read_b128 v[194:197], v147 offset:56320
	global_load_lds_dwordx4 v[178:179], off
	v_lshl_add_u64 v[178:179], v[222:223], 0, s[84:85]
	s_mov_b32 m0, s82
	s_nop 0
	global_load_lds_dwordx4 v[178:179], off
	s_barrier
	s_waitcnt lgkmcnt(0)
	s_waitcnt lgkmcnt(0)
	v_mfma_f32_16x16x32_bf16 v[62:65], v[142:145], v[162:165], v[62:65]
	v_mfma_f32_16x16x32_bf16 v[58:61], v[154:157], v[162:165], v[58:61]
	v_mfma_f32_16x16x32_bf16 v[46:49], v[142:145], v[170:173], v[46:49]
	v_mfma_f32_16x16x32_bf16 v[42:45], v[154:157], v[170:173], v[42:45]
	v_mfma_f32_16x16x32_bf16 v[30:33], v[142:145], v[182:185], v[30:33]
	v_mfma_f32_16x16x32_bf16 v[26:29], v[154:157], v[182:185], v[26:29]
	v_mfma_f32_16x16x32_bf16 v[14:17], v[142:145], v[190:193], v[14:17]
	v_mfma_f32_16x16x32_bf16 v[10:13], v[154:157], v[190:193], v[10:13]
	v_mfma_f32_16x16x32_bf16 v[62:65], v[150:153], v[166:169], v[62:65]
	v_mfma_f32_16x16x32_bf16 v[58:61], v[158:161], v[166:169], v[58:61]
	v_mfma_f32_16x16x32_bf16 v[46:49], v[150:153], v[174:177], v[46:49]
	v_mfma_f32_16x16x32_bf16 v[42:45], v[158:161], v[174:177], v[42:45]
	v_mfma_f32_16x16x32_bf16 v[30:33], v[150:153], v[186:189], v[30:33]
	v_mfma_f32_16x16x32_bf16 v[26:29], v[158:161], v[186:189], v[26:29]
	v_mfma_f32_16x16x32_bf16 v[14:17], v[150:153], v[194:197], v[14:17]
	v_mfma_f32_16x16x32_bf16 v[10:13], v[158:161], v[194:197], v[10:13]
	s_barrier
	s_add_u32 s26, s26, 0x40080
	s_addc_u32 s27, s27, 0
	s_mov_b32 m0, s92
	v_lshl_add_u64 v[142:143], s[26:27], 0, v[134:135]
	global_load_lds_dwordx4 v[142:143], off
	v_lshl_add_u64 v[142:143], s[26:27], 0, v[130:131]
	s_mov_b32 m0, s93
	s_nop 0
	global_load_lds_dwordx4 v[142:143], off
	s_waitcnt vmcnt(6)
	s_barrier
	v_mfma_f32_16x16x32_bf16 v[54:57], v[198:201], v[162:165], v[54:57]
	v_mfma_f32_16x16x32_bf16 v[50:53], v[206:209], v[162:165], v[50:53]
	v_mfma_f32_16x16x32_bf16 v[38:41], v[198:201], v[170:173], v[38:41]
	v_mfma_f32_16x16x32_bf16 v[34:37], v[206:209], v[170:173], v[34:37]
	v_mfma_f32_16x16x32_bf16 v[22:25], v[198:201], v[182:185], v[22:25]
	v_mfma_f32_16x16x32_bf16 v[18:21], v[206:209], v[182:185], v[18:21]
	v_mfma_f32_16x16x32_bf16 v[6:9], v[198:201], v[190:193], v[6:9]
	v_mfma_f32_16x16x32_bf16 v[2:5], v[206:209], v[190:193], v[2:5]
	v_mfma_f32_16x16x32_bf16 v[54:57], v[202:205], v[166:169], v[54:57]
	v_mfma_f32_16x16x32_bf16 v[50:53], v[210:213], v[166:169], v[50:53]
	v_mfma_f32_16x16x32_bf16 v[38:41], v[202:205], v[174:177], v[38:41]
	v_mfma_f32_16x16x32_bf16 v[34:37], v[210:213], v[174:177], v[34:37]
	v_mfma_f32_16x16x32_bf16 v[22:25], v[202:205], v[186:189], v[22:25]
	v_mfma_f32_16x16x32_bf16 v[18:21], v[210:213], v[186:189], v[18:21]
	v_mfma_f32_16x16x32_bf16 v[6:9], v[202:205], v[194:197], v[6:9]
	v_mfma_f32_16x16x32_bf16 v[2:5], v[210:213], v[194:197], v[2:5]
	s_add_i32 s97, s97, 2
	s_add_u32 s24, s24, 0x100
	s_addc_u32 s25, s25, 0
	s_add_u32 s90, s90, 0x100
	s_addc_u32 s94, s94, 0
	s_cmp_gt_u32 s97, 13
	s_barrier
	s_cbranch_scc0 .LBB0_1347
	v_lshl_add_u32 v152, s22, 8, v146
	v_lshl_add_u32 v150, s20, 8, v149
	v_mul_lo_u32 v151, v152, s71
	v_add_u32_e32 v0, v151, v150
	v_lshl_add_u64 v[142:143], v[0:1], 1, s[8:9]
	global_load_dwordx4 v[142:145], v[142:143], off
	v_mov_b32_e32 v178, v0
	v_mov_b32_e32 v161, 0
	v_add_u32_e32 v160, 0x80, v178
	v_lshl_add_u64 v[162:163], v[160:161], 1, s[8:9]
	global_load_dwordx4 v[162:165], v[162:163], off
	v_add_u32_e32 v160, 0x16c00, v178
	v_lshl_add_u64 v[166:167], v[160:161], 1, s[8:9]
	global_load_dwordx4 v[166:169], v[166:167], off
	v_add_u32_e32 v160, 0x16c80, v178
	v_lshl_add_u64 v[170:171], v[160:161], 1, s[8:9]
	global_load_dwordx4 v[170:173], v[170:171], off
	v_add_u32_e32 v160, 0x2d800, v178
	v_lshl_add_u64 v[174:175], v[160:161], 1, s[8:9]
	global_load_dwordx4 v[174:177], v[174:175], off
	v_add_u32_e32 v160, 0x2d880, v178
	v_lshl_add_u64 v[182:183], v[160:161], 1, s[8:9]
	global_load_dwordx4 v[182:185], v[182:183], off
	v_add_u32_e32 v160, 0x44400, v178
	v_lshl_add_u64 v[186:187], v[160:161], 1, s[8:9]
	global_load_dwordx4 v[186:189], v[186:187], off
	v_add_u32_e32 v160, 0x44480, v178
	v_lshl_add_u64 v[190:191], v[160:161], 1, s[8:9]
	global_load_dwordx4 v[190:193], v[190:191], off
	v_add_u32_e32 v160, 0xb6000, v178
	v_lshl_add_u64 v[194:195], v[160:161], 1, s[8:9]
	global_load_dwordx4 v[194:197], v[194:195], off
	v_add_u32_e32 v160, 0xb6080, v178
	v_lshl_add_u64 v[198:199], v[160:161], 1, s[8:9]
	global_load_dwordx4 v[198:201], v[198:199], off
	v_add_u32_e32 v160, 0xccc00, v178
	v_lshl_add_u64 v[202:203], v[160:161], 1, s[8:9]
	global_load_dwordx4 v[202:205], v[202:203], off
	v_add_u32_e32 v160, 0xccc80, v178
	v_lshl_add_u64 v[206:207], v[160:161], 1, s[8:9]
	global_load_dwordx4 v[206:209], v[206:207], off
	v_add_u32_e32 v160, 0xe3800, v178
	v_lshl_add_u64 v[210:211], v[160:161], 1, s[8:9]
	global_load_dwordx4 v[210:213], v[210:211], off
	s_mov_b32 s20, s12
	s_mov_b32 s22, s14
	s_mov_b64 s[26:27], s[18:19]
	s_waitcnt vmcnt(12)
	v_lshlrev_b32_e32 v153, 16, v142
	v_lshlrev_b32_e32 v155, 16, v143
	v_lshlrev_b32_e32 v156, 16, v144
	v_and_b32_e32 v157, 0xffff0000, v144
	v_lshlrev_b32_e32 v158, 16, v145
	v_and_b32_e32 v159, 0xffff0000, v145
	v_mul_f32_e32 v144, 0xbfb8aa3b, v153
	v_mul_f32_e32 v145, 0xbfb8aa3b, v155
	v_exp_f32_e32 v154, v144
	v_exp_f32_e32 v155, v145
	v_mul_f32_e32 v145, 0xbfb8aa3b, v158
	v_and_b32_e32 v142, 0xffff0000, v142
	v_and_b32_e32 v143, 0xffff0000, v143
	v_pk_add_f32 v[154:155], v[154:155], 1.0 op_sel_hi:[1,0]
	v_mul_f32_e32 v142, 0xbfb8aa3b, v142
	v_mul_f32_e32 v143, 0xbfb8aa3b, v143
	v_mul_f32_e32 v144, 0xbfb8aa3b, v156
	v_exp_f32_e32 v156, v142
	v_mul_f32_e32 v142, 0xbfb8aa3b, v157
	v_exp_f32_e32 v157, v143
	v_mul_f32_e32 v143, 0xbfb8aa3b, v159
	v_rcp_f32_e32 v155, v155
	s_nop 0
	v_pk_add_f32 v[156:157], v[156:157], 1.0 op_sel_hi:[1,0]
	v_exp_f32_e32 v144, v144
	v_exp_f32_e32 v145, v145
	v_mov_b32_e32 v158, v126
	v_mov_b32_e32 v159, v128
	v_rcp_f32_e32 v154, v154
	s_nop 0
	v_pk_mul_f32 v[154:155], v[158:159], v[154:155]
	v_exp_f32_e32 v142, v142
	v_rcp_f32_e32 v157, v157
	s_nop 0
	v_exp_f32_e32 v143, v143
	v_rcp_f32_e32 v156, v156
	s_nop 0
	v_mov_b32_e32 v128, v127
	v_pk_mul_f32 v[126:127], v[128:129], v[156:157]
	v_cvt_pk_bf16_f32 v128, v154, v155
	v_cvt_pk_bf16_f32 v126, v126, v127
	v_and_b32_e32 v127, 0xffff0000, v126
	v_lshlrev_b32_e32 v126, 16, v126
	v_or_b32_sdwa v127, v127, v128 dst_sel:DWORD dst_unused:UNUSED_PAD src0_sel:DWORD src1_sel:WORD_1
	v_or_b32_sdwa v126, v126, v128 dst_sel:DWORD dst_unused:UNUSED_PAD src0_sel:DWORD src1_sel:WORD_0
	v_pk_add_f32 v[128:129], v[144:145], 1.0 op_sel_hi:[1,0]
	v_pk_add_f32 v[142:143], v[142:143], 1.0 op_sel_hi:[1,0]
	s_nop 0
	v_rcp_f32_e32 v129, v129
	s_nop 0
	s_nop 0
	v_rcp_f32_e32 v128, v128
	s_nop 0
	v_mov_b32_e32 v144, v122
	v_mov_b32_e32 v145, v124
	v_pk_mul_f32 v[128:129], v[144:145], v[128:129]
	v_rcp_f32_e32 v143, v143
	s_nop 0
	s_nop 0
	v_rcp_f32_e32 v142, v142
	s_nop 0
	v_mov_b32_e32 v124, v123
	v_pk_mul_f32 v[122:123], v[124:125], v[142:143]
	v_cvt_pk_bf16_f32 v124, v128, v129
	v_cvt_pk_bf16_f32 v122, v122, v123
	v_and_b32_e32 v123, 0xffff0000, v122
	v_lshlrev_b32_e32 v122, 16, v122
	v_or_b32_sdwa v129, v123, v124 dst_sel:DWORD dst_unused:UNUSED_PAD src0_sel:DWORD src1_sel:WORD_1
	v_or_b32_sdwa v128, v122, v124 dst_sel:DWORD dst_unused:UNUSED_PAD src0_sel:DWORD src1_sel:WORD_0
	v_mul_lo_u32 v124, v152, s61
	v_add_u32_e32 v0, v0, v124
	v_add_u32_e32 v125, 0x80, v150
	v_lshl_add_u64 v[122:123], v[0:1], 1, s[6:7]
	v_add_u32_e32 v0, v151, v125
	global_store_dwordx4 v[122:123], v[126:129], off
	v_add_u32_e32 v0, v0, v124
	s_waitcnt vmcnt(12)
	v_lshlrev_b32_e32 v122, 16, v162
	v_lshlrev_b32_e32 v143, 16, v163
	v_and_b32_e32 v144, 0xffff0000, v163
	v_lshlrev_b32_e32 v127, 16, v164
	v_mul_f32_e32 v122, 0xbfb8aa3b, v122
	v_and_b32_e32 v123, 0xffff0000, v162
	v_exp_f32_e32 v126, v122
	v_mul_f32_e32 v122, 0xbfb8aa3b, v127
	v_and_b32_e32 v145, 0xffff0000, v164
	v_exp_f32_e32 v128, v122
	v_mul_f32_e32 v122, 0xbfb8aa3b, v123
	v_mul_f32_e32 v123, 0xbfb8aa3b, v143
	v_exp_f32_e32 v127, v123
	v_lshlrev_b32_e32 v153, 16, v165
	v_mul_f32_e32 v123, 0xbfb8aa3b, v153
	v_and_b32_e32 v154, 0xffff0000, v165
	v_pk_add_f32 v[126:127], v[126:127], 1.0 op_sel_hi:[1,0]
	v_exp_f32_e32 v129, v123
	v_mul_f32_e32 v123, 0xbfb8aa3b, v144
	v_exp_f32_e32 v142, v122
	v_mul_f32_e32 v122, 0xbfb8aa3b, v145
	v_exp_f32_e32 v143, v123
	v_mul_f32_e32 v123, 0xbfb8aa3b, v154
	v_exp_f32_e32 v122, v122
	v_rcp_f32_e32 v127, v127
	s_nop 0
	v_pk_add_f32 v[142:143], v[142:143], 1.0 op_sel_hi:[1,0]
	v_exp_f32_e32 v123, v123
	v_rcp_f32_e32 v126, v126
	s_nop 0
	v_mov_b32_e32 v144, v118
	v_mov_b32_e32 v145, v120
	v_pk_mul_f32 v[126:127], v[144:145], v[126:127]
	v_pk_add_f32 v[122:123], v[122:123], 1.0 op_sel_hi:[1,0]
	v_rcp_f32_e32 v143, v143
	s_nop 0
	s_nop 0
	v_rcp_f32_e32 v142, v142
	s_nop 0
	v_mov_b32_e32 v120, v119
	v_pk_mul_f32 v[118:119], v[120:121], v[142:143]
	v_cvt_pk_bf16_f32 v120, v126, v127
	v_cvt_pk_bf16_f32 v118, v118, v119
	v_and_b32_e32 v119, 0xffff0000, v118
	v_lshlrev_b32_e32 v118, 16, v118
	v_or_b32_sdwa v119, v119, v120 dst_sel:DWORD dst_unused:UNUSED_PAD src0_sel:DWORD src1_sel:WORD_1
	v_or_b32_sdwa v118, v118, v120 dst_sel:DWORD dst_unused:UNUSED_PAD src0_sel:DWORD src1_sel:WORD_0
	v_pk_add_f32 v[120:121], v[128:129], 1.0 op_sel_hi:[1,0]
	s_nop 0
	s_nop 0
	v_rcp_f32_e32 v121, v121
	s_nop 0
	s_nop 0
	v_rcp_f32_e32 v120, v120
	s_nop 0
	v_mov_b32_e32 v126, v114
	v_mov_b32_e32 v127, v116
	v_pk_mul_f32 v[120:121], v[126:127], v[120:121]
	v_rcp_f32_e32 v123, v123
	s_nop 0
	s_nop 0
	v_rcp_f32_e32 v122, v122
	s_nop 0
	v_mov_b32_e32 v116, v115
	v_pk_mul_f32 v[114:115], v[116:117], v[122:123]
	v_cvt_pk_bf16_f32 v116, v120, v121
	v_cvt_pk_bf16_f32 v114, v114, v115
	v_and_b32_e32 v115, 0xffff0000, v114
	v_lshlrev_b32_e32 v114, 16, v114
	v_add_u32_e32 v127, 0x16c00, v151
	v_or_b32_sdwa v121, v115, v116 dst_sel:DWORD dst_unused:UNUSED_PAD src0_sel:DWORD src1_sel:WORD_1
	v_or_b32_sdwa v120, v114, v116 dst_sel:DWORD dst_unused:UNUSED_PAD src0_sel:DWORD src1_sel:WORD_0
	v_lshl_add_u64 v[114:115], v[0:1], 1, s[6:7]
	v_add_u32_e32 v0, v127, v150
	v_add_u32_e32 v160, 0xe3880, v178
	v_lshl_add_u64 v[162:163], v[160:161], 1, s[8:9]
	global_load_dwordx4 v[162:165], v[162:163], off
	global_store_dwordx4 v[114:115], v[118:121], off
	v_or_b32_e32 v126, 16, v152
	s_waitcnt vmcnt(13)
	v_lshlrev_b32_e32 v121, 16, v167
	v_and_b32_e32 v122, 0xffff0000, v167
	v_lshlrev_b32_e32 v115, 16, v168
	v_and_b32_e32 v119, 0xffff0000, v166
	v_mul_f32_e32 v115, 0xbfb8aa3b, v115
	v_lshlrev_b32_e32 v118, 16, v166
	v_and_b32_e32 v120, 0xffff0000, v168
	v_exp_f32_e32 v116, v115
	v_mul_f32_e32 v115, 0xbfb8aa3b, v119
	v_mul_f32_e32 v114, 0xbfb8aa3b, v118
	v_exp_f32_e32 v118, v115
	v_mul_f32_e32 v115, 0xbfb8aa3b, v120
	v_exp_f32_e32 v120, v115
	v_mul_f32_e32 v115, 0xbfb8aa3b, v121
	v_exp_f32_e32 v114, v114
	v_exp_f32_e32 v115, v115
	v_lshlrev_b32_e32 v123, 16, v169
	v_mul_f32_e32 v119, 0xbfb8aa3b, v122
	v_and_b32_e32 v128, 0xffff0000, v169
	v_pk_add_f32 v[114:115], v[114:115], 1.0 op_sel_hi:[1,0]
	v_mul_f32_e32 v117, 0xbfb8aa3b, v123
	v_mul_f32_e32 v121, 0xbfb8aa3b, v128
	v_exp_f32_e32 v119, v119
	v_exp_f32_e32 v117, v117
	v_rcp_f32_e32 v115, v115
	s_nop 0
	v_pk_add_f32 v[118:119], v[118:119], 1.0 op_sel_hi:[1,0]
	v_exp_f32_e32 v121, v121
	v_rcp_f32_e32 v114, v114
	s_nop 0
	v_mov_b32_e32 v122, v110
	v_mov_b32_e32 v123, v112
	v_pk_mul_f32 v[114:115], v[122:123], v[114:115]
	v_rcp_f32_e32 v119, v119
	s_nop 0
	s_nop 0
	v_rcp_f32_e32 v118, v118
	s_nop 0
	v_mov_b32_e32 v112, v111
	v_pk_mul_f32 v[110:111], v[112:113], v[118:119]
	v_cvt_pk_bf16_f32 v112, v114, v115
	v_cvt_pk_bf16_f32 v110, v110, v111
	v_and_b32_e32 v111, 0xffff0000, v110
	v_lshlrev_b32_e32 v110, 16, v110
	v_or_b32_sdwa v111, v111, v112 dst_sel:DWORD dst_unused:UNUSED_PAD src0_sel:DWORD src1_sel:WORD_1
	v_or_b32_sdwa v110, v110, v112 dst_sel:DWORD dst_unused:UNUSED_PAD src0_sel:DWORD src1_sel:WORD_0
	v_pk_add_f32 v[112:113], v[116:117], 1.0 op_sel_hi:[1,0]
	s_nop 0
	s_nop 0
	v_rcp_f32_e32 v113, v113
	s_nop 0
	s_nop 0
	v_rcp_f32_e32 v112, v112
	s_nop 0
	v_mov_b32_e32 v114, v106
	v_mov_b32_e32 v115, v108
	v_pk_mul_f32 v[112:113], v[114:115], v[112:113]
	v_pk_add_f32 v[114:115], v[120:121], 1.0 op_sel_hi:[1,0]
	s_nop 0
	s_nop 0
	v_rcp_f32_e32 v115, v115
	s_nop 0
	s_nop 0
	v_rcp_f32_e32 v114, v114
	s_nop 0
	v_mov_b32_e32 v108, v107
	v_pk_mul_f32 v[106:107], v[108:109], v[114:115]
	v_mul_lo_u32 v116, v126, s61
	v_cvt_pk_bf16_f32 v106, v106, v107
	v_cvt_pk_bf16_f32 v108, v112, v113
	v_and_b32_e32 v107, 0xffff0000, v106
	v_lshlrev_b32_e32 v106, 16, v106
	v_add_u32_e32 v0, v0, v116
	v_or_b32_sdwa v113, v107, v108 dst_sel:DWORD dst_unused:UNUSED_PAD src0_sel:DWORD src1_sel:WORD_1
	v_or_b32_sdwa v112, v106, v108 dst_sel:DWORD dst_unused:UNUSED_PAD src0_sel:DWORD src1_sel:WORD_0
	v_lshl_add_u64 v[106:107], v[0:1], 1, s[6:7]
	v_add_u32_e32 v0, v127, v125
	v_add_u32_e32 v160, 0xfa400, v178
	v_lshl_add_u64 v[166:167], v[160:161], 1, s[8:9]
	global_load_dwordx4 v[166:169], v[166:167], off
	global_store_dwordx4 v[106:107], v[110:113], off
	v_add_u32_e32 v0, v0, v116
	s_waitcnt vmcnt(14)
	v_lshlrev_b32_e32 v113, 16, v171
	v_and_b32_e32 v114, 0xffff0000, v171
	v_lshlrev_b32_e32 v107, 16, v172
	v_and_b32_e32 v111, 0xffff0000, v170
	v_mul_f32_e32 v107, 0xbfb8aa3b, v107
	v_lshlrev_b32_e32 v110, 16, v170
	v_and_b32_e32 v112, 0xffff0000, v172
	v_exp_f32_e32 v108, v107
	v_mul_f32_e32 v107, 0xbfb8aa3b, v111
	v_mul_f32_e32 v106, 0xbfb8aa3b, v110
	v_exp_f32_e32 v110, v107
	v_mul_f32_e32 v107, 0xbfb8aa3b, v112
	v_exp_f32_e32 v112, v107
	v_mul_f32_e32 v107, 0xbfb8aa3b, v113
	v_exp_f32_e32 v106, v106
	v_exp_f32_e32 v107, v107
	v_lshlrev_b32_e32 v115, 16, v173
	v_mul_f32_e32 v111, 0xbfb8aa3b, v114
	v_and_b32_e32 v117, 0xffff0000, v173
	v_pk_add_f32 v[106:107], v[106:107], 1.0 op_sel_hi:[1,0]
	v_mul_f32_e32 v109, 0xbfb8aa3b, v115
	v_mul_f32_e32 v113, 0xbfb8aa3b, v117
	v_exp_f32_e32 v111, v111
	v_exp_f32_e32 v109, v109
	v_rcp_f32_e32 v107, v107
	s_nop 0
	v_pk_add_f32 v[110:111], v[110:111], 1.0 op_sel_hi:[1,0]
	v_exp_f32_e32 v113, v113
	v_rcp_f32_e32 v106, v106
	s_nop 0
	v_mov_b32_e32 v114, v102
	v_mov_b32_e32 v115, v104
	v_pk_mul_f32 v[106:107], v[114:115], v[106:107]
	v_rcp_f32_e32 v111, v111
	s_nop 0
	s_nop 0
	v_rcp_f32_e32 v110, v110
	s_nop 0
	v_mov_b32_e32 v104, v103
	v_pk_mul_f32 v[102:103], v[104:105], v[110:111]
	v_cvt_pk_bf16_f32 v104, v106, v107
	v_cvt_pk_bf16_f32 v102, v102, v103
	v_and_b32_e32 v103, 0xffff0000, v102
	v_lshlrev_b32_e32 v102, 16, v102
	v_or_b32_sdwa v103, v103, v104 dst_sel:DWORD dst_unused:UNUSED_PAD src0_sel:DWORD src1_sel:WORD_1
	v_or_b32_sdwa v102, v102, v104 dst_sel:DWORD dst_unused:UNUSED_PAD src0_sel:DWORD src1_sel:WORD_0
	v_pk_add_f32 v[104:105], v[108:109], 1.0 op_sel_hi:[1,0]
	s_nop 0
	s_nop 0
	v_rcp_f32_e32 v105, v105
	s_nop 0
	s_nop 0
	v_rcp_f32_e32 v104, v104
	s_nop 0
	v_mov_b32_e32 v106, v98
	v_mov_b32_e32 v107, v100
	v_pk_mul_f32 v[104:105], v[106:107], v[104:105]
	v_pk_add_f32 v[106:107], v[112:113], 1.0 op_sel_hi:[1,0]
	s_nop 0
	s_nop 0
	v_rcp_f32_e32 v107, v107
	s_nop 0
	s_nop 0
	v_rcp_f32_e32 v106, v106
	s_nop 0
	v_mov_b32_e32 v100, v99
	v_pk_mul_f32 v[98:99], v[100:101], v[106:107]
	v_cvt_pk_bf16_f32 v100, v104, v105
	v_cvt_pk_bf16_f32 v98, v98, v99
	v_and_b32_e32 v99, 0xffff0000, v98
	v_lshlrev_b32_e32 v98, 16, v98
	v_add_u32_e32 v109, 0x2d800, v151
	v_or_b32_sdwa v105, v99, v100 dst_sel:DWORD dst_unused:UNUSED_PAD src0_sel:DWORD src1_sel:WORD_1
	v_or_b32_sdwa v104, v98, v100 dst_sel:DWORD dst_unused:UNUSED_PAD src0_sel:DWORD src1_sel:WORD_0
	v_lshl_add_u64 v[98:99], v[0:1], 1, s[6:7]
	v_add_u32_e32 v0, v109, v150
	v_add_u32_e32 v160, 0xfa480, v178
	v_lshl_add_u64 v[170:171], v[160:161], 1, s[8:9]
	global_load_dwordx4 v[170:173], v[170:171], off
	global_store_dwordx4 v[98:99], v[102:105], off
	v_or_b32_e32 v108, 32, v152
	s_waitcnt vmcnt(15)
	v_lshlrev_b32_e32 v105, 16, v175
	v_and_b32_e32 v106, 0xffff0000, v175
	v_lshlrev_b32_e32 v99, 16, v176
	v_and_b32_e32 v103, 0xffff0000, v174
	v_mul_f32_e32 v99, 0xbfb8aa3b, v99
	v_lshlrev_b32_e32 v102, 16, v174
	v_and_b32_e32 v104, 0xffff0000, v176
	v_exp_f32_e32 v100, v99
	v_mul_f32_e32 v99, 0xbfb8aa3b, v103
	v_mul_f32_e32 v98, 0xbfb8aa3b, v102
	v_exp_f32_e32 v102, v99
	v_mul_f32_e32 v99, 0xbfb8aa3b, v104
	v_exp_f32_e32 v104, v99
	v_mul_f32_e32 v99, 0xbfb8aa3b, v105
	v_exp_f32_e32 v98, v98
	v_exp_f32_e32 v99, v99
	v_lshlrev_b32_e32 v107, 16, v177
	v_mul_f32_e32 v103, 0xbfb8aa3b, v106
	v_and_b32_e32 v110, 0xffff0000, v177
	v_pk_add_f32 v[98:99], v[98:99], 1.0 op_sel_hi:[1,0]
	v_mul_f32_e32 v101, 0xbfb8aa3b, v107
	v_mul_f32_e32 v105, 0xbfb8aa3b, v110
	v_exp_f32_e32 v103, v103
	v_exp_f32_e32 v101, v101
	v_rcp_f32_e32 v99, v99
	s_nop 0
	v_pk_add_f32 v[102:103], v[102:103], 1.0 op_sel_hi:[1,0]
	v_exp_f32_e32 v105, v105
	v_rcp_f32_e32 v98, v98
	s_nop 0
	v_mov_b32_e32 v106, v94
	v_mov_b32_e32 v107, v96
	v_pk_mul_f32 v[98:99], v[106:107], v[98:99]
	v_rcp_f32_e32 v103, v103
	s_nop 0
	s_nop 0
	v_rcp_f32_e32 v102, v102
	s_nop 0
	v_mov_b32_e32 v96, v95
	v_pk_mul_f32 v[94:95], v[96:97], v[102:103]
	v_cvt_pk_bf16_f32 v96, v98, v99
	v_cvt_pk_bf16_f32 v94, v94, v95
	v_and_b32_e32 v95, 0xffff0000, v94
	v_lshlrev_b32_e32 v94, 16, v94
	v_or_b32_sdwa v95, v95, v96 dst_sel:DWORD dst_unused:UNUSED_PAD src0_sel:DWORD src1_sel:WORD_1
	v_or_b32_sdwa v94, v94, v96 dst_sel:DWORD dst_unused:UNUSED_PAD src0_sel:DWORD src1_sel:WORD_0
	v_pk_add_f32 v[96:97], v[100:101], 1.0 op_sel_hi:[1,0]
	s_nop 0
	s_nop 0
	v_rcp_f32_e32 v97, v97
	s_nop 0
	s_nop 0
	v_rcp_f32_e32 v96, v96
	s_nop 0
	v_mov_b32_e32 v98, v90
	v_mov_b32_e32 v99, v92
	v_pk_mul_f32 v[96:97], v[98:99], v[96:97]
	v_pk_add_f32 v[98:99], v[104:105], 1.0 op_sel_hi:[1,0]
	s_nop 0
	s_nop 0
	v_rcp_f32_e32 v99, v99
	s_nop 0
	s_nop 0
	v_rcp_f32_e32 v98, v98
	s_nop 0
	v_mov_b32_e32 v92, v91
	v_pk_mul_f32 v[90:91], v[92:93], v[98:99]
	v_mul_lo_u32 v100, v108, s61
	v_cvt_pk_bf16_f32 v90, v90, v91
	v_cvt_pk_bf16_f32 v92, v96, v97
	v_and_b32_e32 v91, 0xffff0000, v90
	v_lshlrev_b32_e32 v90, 16, v90
	v_add_u32_e32 v0, v0, v100
	v_or_b32_sdwa v97, v91, v92 dst_sel:DWORD dst_unused:UNUSED_PAD src0_sel:DWORD src1_sel:WORD_1
	v_or_b32_sdwa v96, v90, v92 dst_sel:DWORD dst_unused:UNUSED_PAD src0_sel:DWORD src1_sel:WORD_0
	v_lshl_add_u64 v[90:91], v[0:1], 1, s[6:7]
	v_add_u32_e32 v0, v109, v125
	global_store_dwordx4 v[90:91], v[94:97], off
	v_add_u32_e32 v0, v0, v100
	s_waitcnt vmcnt(15)
	v_lshlrev_b32_e32 v97, 16, v183
	v_and_b32_e32 v98, 0xffff0000, v183
	v_lshlrev_b32_e32 v91, 16, v184
	v_and_b32_e32 v95, 0xffff0000, v182
	v_mul_f32_e32 v91, 0xbfb8aa3b, v91
	v_lshlrev_b32_e32 v94, 16, v182
	v_and_b32_e32 v96, 0xffff0000, v184
	v_exp_f32_e32 v92, v91
	v_mul_f32_e32 v91, 0xbfb8aa3b, v95
	v_mul_f32_e32 v90, 0xbfb8aa3b, v94
	v_exp_f32_e32 v94, v91
	v_mul_f32_e32 v91, 0xbfb8aa3b, v96
	v_exp_f32_e32 v96, v91
	v_mul_f32_e32 v91, 0xbfb8aa3b, v97
	v_exp_f32_e32 v90, v90
	v_exp_f32_e32 v91, v91
	v_lshlrev_b32_e32 v99, 16, v185
	v_mul_f32_e32 v95, 0xbfb8aa3b, v98
	v_and_b32_e32 v101, 0xffff0000, v185
	v_pk_add_f32 v[90:91], v[90:91], 1.0 op_sel_hi:[1,0]
	v_mul_f32_e32 v93, 0xbfb8aa3b, v99
	v_mul_f32_e32 v97, 0xbfb8aa3b, v101
	v_exp_f32_e32 v95, v95
	v_exp_f32_e32 v93, v93
	v_rcp_f32_e32 v91, v91
	s_nop 0
	v_pk_add_f32 v[94:95], v[94:95], 1.0 op_sel_hi:[1,0]
	v_exp_f32_e32 v97, v97
	v_rcp_f32_e32 v90, v90
	s_nop 0
	v_mov_b32_e32 v98, v86
	v_mov_b32_e32 v99, v88
	v_pk_mul_f32 v[90:91], v[98:99], v[90:91]
	v_rcp_f32_e32 v95, v95
	s_nop 0
	s_nop 0
	v_rcp_f32_e32 v94, v94
	s_nop 0
	v_mov_b32_e32 v88, v87
	v_pk_mul_f32 v[86:87], v[88:89], v[94:95]
	v_cvt_pk_bf16_f32 v88, v90, v91
	v_cvt_pk_bf16_f32 v86, v86, v87
	v_and_b32_e32 v87, 0xffff0000, v86
	v_lshlrev_b32_e32 v86, 16, v86
	v_or_b32_sdwa v87, v87, v88 dst_sel:DWORD dst_unused:UNUSED_PAD src0_sel:DWORD src1_sel:WORD_1
	v_or_b32_sdwa v86, v86, v88 dst_sel:DWORD dst_unused:UNUSED_PAD src0_sel:DWORD src1_sel:WORD_0
	v_pk_add_f32 v[88:89], v[92:93], 1.0 op_sel_hi:[1,0]
	s_nop 0
	s_nop 0
	v_rcp_f32_e32 v89, v89
	s_nop 0
	s_nop 0
	v_rcp_f32_e32 v88, v88
	s_nop 0
	v_mov_b32_e32 v90, v82
	v_mov_b32_e32 v91, v84
	v_pk_mul_f32 v[88:89], v[90:91], v[88:89]
	v_pk_add_f32 v[90:91], v[96:97], 1.0 op_sel_hi:[1,0]
	s_nop 0
	s_nop 0
	v_rcp_f32_e32 v91, v91
	s_nop 0
	s_nop 0
	v_rcp_f32_e32 v90, v90
	s_nop 0
	v_mov_b32_e32 v84, v83
	v_pk_mul_f32 v[82:83], v[84:85], v[90:91]
	v_cvt_pk_bf16_f32 v84, v88, v89
	v_cvt_pk_bf16_f32 v82, v82, v83
	v_and_b32_e32 v83, 0xffff0000, v82
	v_lshlrev_b32_e32 v82, 16, v82
	v_add_u32_e32 v93, 0x44400, v151
	v_or_b32_sdwa v89, v83, v84 dst_sel:DWORD dst_unused:UNUSED_PAD src0_sel:DWORD src1_sel:WORD_1
	v_or_b32_sdwa v88, v82, v84 dst_sel:DWORD dst_unused:UNUSED_PAD src0_sel:DWORD src1_sel:WORD_0
	v_lshl_add_u64 v[82:83], v[0:1], 1, s[6:7]
	v_add_u32_e32 v0, v93, v150
	global_store_dwordx4 v[82:83], v[86:89], off
	v_or_b32_e32 v92, 48, v152
	s_waitcnt vmcnt(15)
	v_lshlrev_b32_e32 v89, 16, v187
	v_and_b32_e32 v90, 0xffff0000, v187
	v_lshlrev_b32_e32 v83, 16, v188
	v_and_b32_e32 v87, 0xffff0000, v186
	v_mul_f32_e32 v83, 0xbfb8aa3b, v83
	v_lshlrev_b32_e32 v86, 16, v186
	v_and_b32_e32 v88, 0xffff0000, v188
	v_exp_f32_e32 v84, v83
	v_mul_f32_e32 v83, 0xbfb8aa3b, v87
	v_mul_f32_e32 v82, 0xbfb8aa3b, v86
	v_exp_f32_e32 v86, v83
	v_mul_f32_e32 v83, 0xbfb8aa3b, v88
	v_exp_f32_e32 v88, v83
	v_mul_f32_e32 v83, 0xbfb8aa3b, v89
	v_exp_f32_e32 v82, v82
	v_exp_f32_e32 v83, v83
	v_lshlrev_b32_e32 v91, 16, v189
	v_mul_f32_e32 v87, 0xbfb8aa3b, v90
	v_and_b32_e32 v94, 0xffff0000, v189
	v_pk_add_f32 v[82:83], v[82:83], 1.0 op_sel_hi:[1,0]
	v_mul_f32_e32 v85, 0xbfb8aa3b, v91
	v_mul_f32_e32 v89, 0xbfb8aa3b, v94
	v_exp_f32_e32 v87, v87
	v_exp_f32_e32 v85, v85
	v_rcp_f32_e32 v83, v83
	s_nop 0
	v_pk_add_f32 v[86:87], v[86:87], 1.0 op_sel_hi:[1,0]
	v_exp_f32_e32 v89, v89
	v_rcp_f32_e32 v82, v82
	s_nop 0
	v_mov_b32_e32 v90, v78
	v_mov_b32_e32 v91, v80
	v_pk_mul_f32 v[82:83], v[90:91], v[82:83]
	v_rcp_f32_e32 v87, v87
	s_nop 0
	s_nop 0
	v_rcp_f32_e32 v86, v86
	s_nop 0
	v_mov_b32_e32 v80, v79
	v_pk_mul_f32 v[78:79], v[80:81], v[86:87]
	v_cvt_pk_bf16_f32 v80, v82, v83
	v_cvt_pk_bf16_f32 v78, v78, v79
	v_and_b32_e32 v79, 0xffff0000, v78
	v_lshlrev_b32_e32 v78, 16, v78
	v_or_b32_sdwa v79, v79, v80 dst_sel:DWORD dst_unused:UNUSED_PAD src0_sel:DWORD src1_sel:WORD_1
	v_or_b32_sdwa v78, v78, v80 dst_sel:DWORD dst_unused:UNUSED_PAD src0_sel:DWORD src1_sel:WORD_0
	v_pk_add_f32 v[80:81], v[84:85], 1.0 op_sel_hi:[1,0]
	s_nop 0
	s_nop 0
	v_rcp_f32_e32 v81, v81
	s_nop 0
	s_nop 0
	v_rcp_f32_e32 v80, v80
	s_nop 0
	v_mov_b32_e32 v82, v74
	v_mov_b32_e32 v83, v76
	v_pk_mul_f32 v[80:81], v[82:83], v[80:81]
	v_pk_add_f32 v[82:83], v[88:89], 1.0 op_sel_hi:[1,0]
	s_nop 0
	s_nop 0
	v_rcp_f32_e32 v83, v83
	s_nop 0
	s_nop 0
	v_rcp_f32_e32 v82, v82
	s_nop 0
	v_mov_b32_e32 v76, v75
	v_pk_mul_f32 v[74:75], v[76:77], v[82:83]
	v_mul_lo_u32 v84, v92, s61
	v_cvt_pk_bf16_f32 v74, v74, v75
	v_cvt_pk_bf16_f32 v76, v80, v81
	v_and_b32_e32 v75, 0xffff0000, v74
	v_lshlrev_b32_e32 v74, 16, v74
	v_add_u32_e32 v0, v0, v84
	v_or_b32_sdwa v81, v75, v76 dst_sel:DWORD dst_unused:UNUSED_PAD src0_sel:DWORD src1_sel:WORD_1
	v_or_b32_sdwa v80, v74, v76 dst_sel:DWORD dst_unused:UNUSED_PAD src0_sel:DWORD src1_sel:WORD_0
	v_lshl_add_u64 v[74:75], v[0:1], 1, s[6:7]
	v_add_u32_e32 v0, v93, v125
	global_store_dwordx4 v[74:75], v[78:81], off
	v_add_u32_e32 v0, v0, v84
	s_waitcnt vmcnt(15)
	v_lshlrev_b32_e32 v81, 16, v191
	v_and_b32_e32 v82, 0xffff0000, v191
	v_lshlrev_b32_e32 v75, 16, v192
	v_and_b32_e32 v79, 0xffff0000, v190
	v_mul_f32_e32 v75, 0xbfb8aa3b, v75
	v_lshlrev_b32_e32 v78, 16, v190
	v_and_b32_e32 v80, 0xffff0000, v192
	v_exp_f32_e32 v76, v75
	v_mul_f32_e32 v75, 0xbfb8aa3b, v79
	v_mul_f32_e32 v74, 0xbfb8aa3b, v78
	v_exp_f32_e32 v78, v75
	v_mul_f32_e32 v75, 0xbfb8aa3b, v80
	v_exp_f32_e32 v80, v75
	v_mul_f32_e32 v75, 0xbfb8aa3b, v81
	v_exp_f32_e32 v74, v74
	v_exp_f32_e32 v75, v75
	v_lshlrev_b32_e32 v83, 16, v193
	v_mul_f32_e32 v79, 0xbfb8aa3b, v82
	v_and_b32_e32 v85, 0xffff0000, v193
	v_pk_add_f32 v[74:75], v[74:75], 1.0 op_sel_hi:[1,0]
	v_mul_f32_e32 v77, 0xbfb8aa3b, v83
	v_mul_f32_e32 v81, 0xbfb8aa3b, v85
	v_exp_f32_e32 v79, v79
	v_exp_f32_e32 v77, v77
	v_rcp_f32_e32 v75, v75
	s_nop 0
	v_pk_add_f32 v[78:79], v[78:79], 1.0 op_sel_hi:[1,0]
	v_exp_f32_e32 v81, v81
	v_rcp_f32_e32 v74, v74
	s_nop 0
	v_mov_b32_e32 v82, v70
	v_mov_b32_e32 v83, v72
	v_pk_mul_f32 v[74:75], v[82:83], v[74:75]
	v_rcp_f32_e32 v79, v79
	s_nop 0
	s_nop 0
	v_rcp_f32_e32 v78, v78
	s_nop 0
	v_mov_b32_e32 v72, v71
	v_pk_mul_f32 v[70:71], v[72:73], v[78:79]
	v_cvt_pk_bf16_f32 v72, v74, v75
	v_cvt_pk_bf16_f32 v70, v70, v71
	v_and_b32_e32 v71, 0xffff0000, v70
	v_lshlrev_b32_e32 v70, 16, v70
	v_or_b32_sdwa v71, v71, v72 dst_sel:DWORD dst_unused:UNUSED_PAD src0_sel:DWORD src1_sel:WORD_1
	v_or_b32_sdwa v70, v70, v72 dst_sel:DWORD dst_unused:UNUSED_PAD src0_sel:DWORD src1_sel:WORD_0
	v_pk_add_f32 v[72:73], v[76:77], 1.0 op_sel_hi:[1,0]
	s_nop 0
	s_nop 0
	v_rcp_f32_e32 v73, v73
	s_nop 0
	s_nop 0
	v_rcp_f32_e32 v72, v72
	s_nop 0
	v_mov_b32_e32 v74, v66
	v_mov_b32_e32 v75, v68
	v_pk_mul_f32 v[72:73], v[74:75], v[72:73]
	v_pk_add_f32 v[74:75], v[80:81], 1.0 op_sel_hi:[1,0]
	s_nop 0
	s_nop 0
	v_rcp_f32_e32 v75, v75
	s_nop 0
	s_nop 0
	v_rcp_f32_e32 v74, v74
	s_nop 0
	v_mov_b32_e32 v68, v67
	v_pk_mul_f32 v[66:67], v[68:69], v[74:75]
	v_cvt_pk_bf16_f32 v68, v72, v73
	v_cvt_pk_bf16_f32 v66, v66, v67
	v_and_b32_e32 v67, 0xffff0000, v66
	v_lshlrev_b32_e32 v66, 16, v66
	v_add_u32_e32 v76, 0xb6000, v151
	v_or_b32_sdwa v73, v67, v68 dst_sel:DWORD dst_unused:UNUSED_PAD src0_sel:DWORD src1_sel:WORD_1
	v_or_b32_sdwa v72, v66, v68 dst_sel:DWORD dst_unused:UNUSED_PAD src0_sel:DWORD src1_sel:WORD_0
	v_lshl_add_u64 v[66:67], v[0:1], 1, s[6:7]
	v_add_u32_e32 v0, v76, v150
	global_store_dwordx4 v[66:67], v[70:73], off
	s_nop 1
	s_waitcnt vmcnt(15)
	v_lshlrev_b32_e32 v73, 16, v195
	v_and_b32_e32 v74, 0xffff0000, v195
	v_lshlrev_b32_e32 v67, 16, v196
	v_and_b32_e32 v71, 0xffff0000, v194
	v_mul_f32_e32 v67, 0xbfb8aa3b, v67
	v_lshlrev_b32_e32 v70, 16, v194
	v_and_b32_e32 v72, 0xffff0000, v196
	v_exp_f32_e32 v68, v67
	v_mul_f32_e32 v67, 0xbfb8aa3b, v71
	v_mul_f32_e32 v66, 0xbfb8aa3b, v70
	v_exp_f32_e32 v70, v67
	v_mul_f32_e32 v67, 0xbfb8aa3b, v72
	v_exp_f32_e32 v72, v67
	v_mul_f32_e32 v67, 0xbfb8aa3b, v73
	v_exp_f32_e32 v66, v66
	v_exp_f32_e32 v67, v67
	v_lshlrev_b32_e32 v75, 16, v197
	v_mul_f32_e32 v71, 0xbfb8aa3b, v74
	v_and_b32_e32 v77, 0xffff0000, v197
	v_pk_add_f32 v[66:67], v[66:67], 1.0 op_sel_hi:[1,0]
	v_mul_f32_e32 v69, 0xbfb8aa3b, v75
	v_mul_f32_e32 v73, 0xbfb8aa3b, v77
	v_exp_f32_e32 v71, v71
	v_exp_f32_e32 v69, v69
	v_rcp_f32_e32 v67, v67
	s_nop 0
	v_pk_add_f32 v[70:71], v[70:71], 1.0 op_sel_hi:[1,0]
	v_exp_f32_e32 v73, v73
	v_rcp_f32_e32 v66, v66
	s_nop 0
	v_mov_b32_e32 v74, v62
	v_mov_b32_e32 v75, v64
	v_pk_mul_f32 v[66:67], v[74:75], v[66:67]
	v_rcp_f32_e32 v71, v71
	s_nop 0
	s_nop 0
	v_rcp_f32_e32 v70, v70
	s_nop 0
	v_mov_b32_e32 v64, v63
	v_pk_mul_f32 v[62:63], v[64:65], v[70:71]
	v_cvt_pk_bf16_f32 v64, v66, v67
	v_cvt_pk_bf16_f32 v62, v62, v63
	v_and_b32_e32 v63, 0xffff0000, v62
	v_lshlrev_b32_e32 v62, 16, v62
	v_or_b32_sdwa v63, v63, v64 dst_sel:DWORD dst_unused:UNUSED_PAD src0_sel:DWORD src1_sel:WORD_1
	v_or_b32_sdwa v62, v62, v64 dst_sel:DWORD dst_unused:UNUSED_PAD src0_sel:DWORD src1_sel:WORD_0
	v_pk_add_f32 v[64:65], v[68:69], 1.0 op_sel_hi:[1,0]
	s_nop 0
	s_nop 0
	v_rcp_f32_e32 v65, v65
	s_nop 0
	s_nop 0
	v_rcp_f32_e32 v64, v64
	s_nop 0
	v_mov_b32_e32 v66, v58
	v_mov_b32_e32 v67, v60
	v_pk_mul_f32 v[64:65], v[66:67], v[64:65]
	v_pk_add_f32 v[66:67], v[72:73], 1.0 op_sel_hi:[1,0]
	s_nop 0
	s_nop 0
	v_rcp_f32_e32 v67, v67
	s_nop 0
	s_nop 0
	v_rcp_f32_e32 v66, v66
	s_nop 0
	v_mov_b32_e32 v60, v59
	v_pk_mul_f32 v[58:59], v[60:61], v[66:67]
	v_add_u32_e32 v68, 0xfff6a000, v124
	v_cvt_pk_bf16_f32 v58, v58, v59
	v_cvt_pk_bf16_f32 v60, v64, v65
	v_and_b32_e32 v59, 0xffff0000, v58
	v_lshlrev_b32_e32 v58, 16, v58
	v_add_u32_e32 v0, v0, v68
	v_or_b32_sdwa v65, v59, v60 dst_sel:DWORD dst_unused:UNUSED_PAD src0_sel:DWORD src1_sel:WORD_1
	v_or_b32_sdwa v64, v58, v60 dst_sel:DWORD dst_unused:UNUSED_PAD src0_sel:DWORD src1_sel:WORD_0
	v_lshl_add_u64 v[58:59], v[0:1], 1, s[6:7]
	v_add_u32_e32 v0, v76, v125
	global_store_dwordx4 v[58:59], v[62:65], off
	v_add_u32_e32 v0, v0, v68
	s_waitcnt vmcnt(15)
	v_lshlrev_b32_e32 v65, 16, v199
	v_and_b32_e32 v66, 0xffff0000, v199
	v_lshlrev_b32_e32 v59, 16, v200
	v_and_b32_e32 v63, 0xffff0000, v198
	v_mul_f32_e32 v59, 0xbfb8aa3b, v59
	v_lshlrev_b32_e32 v62, 16, v198
	v_and_b32_e32 v64, 0xffff0000, v200
	v_exp_f32_e32 v60, v59
	v_mul_f32_e32 v59, 0xbfb8aa3b, v63
	v_mul_f32_e32 v58, 0xbfb8aa3b, v62
	v_exp_f32_e32 v62, v59
	v_mul_f32_e32 v59, 0xbfb8aa3b, v64
	v_exp_f32_e32 v64, v59
	v_mul_f32_e32 v59, 0xbfb8aa3b, v65
	v_exp_f32_e32 v58, v58
	v_exp_f32_e32 v59, v59
	v_lshlrev_b32_e32 v67, 16, v201
	v_mul_f32_e32 v63, 0xbfb8aa3b, v66
	v_and_b32_e32 v69, 0xffff0000, v201
	v_pk_add_f32 v[58:59], v[58:59], 1.0 op_sel_hi:[1,0]
	v_mul_f32_e32 v61, 0xbfb8aa3b, v67
	v_mul_f32_e32 v65, 0xbfb8aa3b, v69
	v_exp_f32_e32 v63, v63
	v_exp_f32_e32 v61, v61
	v_rcp_f32_e32 v59, v59
	s_nop 0
	v_pk_add_f32 v[62:63], v[62:63], 1.0 op_sel_hi:[1,0]
	v_exp_f32_e32 v65, v65
	v_rcp_f32_e32 v58, v58
	s_nop 0
	v_mov_b32_e32 v66, v54
	v_mov_b32_e32 v67, v56
	v_pk_mul_f32 v[58:59], v[66:67], v[58:59]
	v_rcp_f32_e32 v63, v63
	s_nop 0
	s_nop 0
	v_rcp_f32_e32 v62, v62
	s_nop 0
	v_mov_b32_e32 v56, v55
	v_pk_mul_f32 v[54:55], v[56:57], v[62:63]
	v_cvt_pk_bf16_f32 v56, v58, v59
	v_cvt_pk_bf16_f32 v54, v54, v55
	v_and_b32_e32 v55, 0xffff0000, v54
	v_lshlrev_b32_e32 v54, 16, v54
	v_or_b32_sdwa v55, v55, v56 dst_sel:DWORD dst_unused:UNUSED_PAD src0_sel:DWORD src1_sel:WORD_1
	v_or_b32_sdwa v54, v54, v56 dst_sel:DWORD dst_unused:UNUSED_PAD src0_sel:DWORD src1_sel:WORD_0
	v_pk_add_f32 v[56:57], v[60:61], 1.0 op_sel_hi:[1,0]
	s_nop 0
	s_nop 0
	v_rcp_f32_e32 v57, v57
	s_nop 0
	s_nop 0
	v_rcp_f32_e32 v56, v56
	s_nop 0
	v_mov_b32_e32 v58, v50
	v_mov_b32_e32 v59, v52
	v_pk_mul_f32 v[56:57], v[58:59], v[56:57]
	v_pk_add_f32 v[58:59], v[64:65], 1.0 op_sel_hi:[1,0]
	s_nop 0
	s_nop 0
	v_rcp_f32_e32 v59, v59
	s_nop 0
	s_nop 0
	v_rcp_f32_e32 v58, v58
	s_nop 0
	v_mov_b32_e32 v52, v51
	v_pk_mul_f32 v[50:51], v[52:53], v[58:59]
	v_cvt_pk_bf16_f32 v52, v56, v57
	v_cvt_pk_bf16_f32 v50, v50, v51
	v_and_b32_e32 v51, 0xffff0000, v50
	v_lshlrev_b32_e32 v50, 16, v50
	v_add_u32_e32 v60, 0xccc00, v151
	v_or_b32_sdwa v57, v51, v52 dst_sel:DWORD dst_unused:UNUSED_PAD src0_sel:DWORD src1_sel:WORD_1
	v_or_b32_sdwa v56, v50, v52 dst_sel:DWORD dst_unused:UNUSED_PAD src0_sel:DWORD src1_sel:WORD_0
	v_lshl_add_u64 v[50:51], v[0:1], 1, s[6:7]
	v_add_u32_e32 v0, v60, v150
	global_store_dwordx4 v[50:51], v[54:57], off
	s_nop 1
	s_waitcnt vmcnt(15)
	v_lshlrev_b32_e32 v57, 16, v203
	v_and_b32_e32 v58, 0xffff0000, v203
	v_lshlrev_b32_e32 v51, 16, v204
	v_and_b32_e32 v55, 0xffff0000, v202
	v_mul_f32_e32 v51, 0xbfb8aa3b, v51
	v_lshlrev_b32_e32 v54, 16, v202
	v_and_b32_e32 v56, 0xffff0000, v204
	v_exp_f32_e32 v52, v51
	v_mul_f32_e32 v51, 0xbfb8aa3b, v55
	v_mul_f32_e32 v50, 0xbfb8aa3b, v54
	v_exp_f32_e32 v54, v51
	v_mul_f32_e32 v51, 0xbfb8aa3b, v56
	v_exp_f32_e32 v56, v51
	v_mul_f32_e32 v51, 0xbfb8aa3b, v57
	v_exp_f32_e32 v50, v50
	v_exp_f32_e32 v51, v51
	v_lshlrev_b32_e32 v59, 16, v205
	v_mul_f32_e32 v55, 0xbfb8aa3b, v58
	v_and_b32_e32 v61, 0xffff0000, v205
	v_pk_add_f32 v[50:51], v[50:51], 1.0 op_sel_hi:[1,0]
	v_mul_f32_e32 v53, 0xbfb8aa3b, v59
	v_mul_f32_e32 v57, 0xbfb8aa3b, v61
	v_exp_f32_e32 v55, v55
	v_exp_f32_e32 v53, v53
	v_rcp_f32_e32 v51, v51
	s_nop 0
	v_pk_add_f32 v[54:55], v[54:55], 1.0 op_sel_hi:[1,0]
	v_exp_f32_e32 v57, v57
	v_rcp_f32_e32 v50, v50
	s_nop 0
	v_mov_b32_e32 v58, v46
	v_mov_b32_e32 v59, v48
	v_pk_mul_f32 v[50:51], v[58:59], v[50:51]
	v_rcp_f32_e32 v55, v55
	s_nop 0
	s_nop 0
	v_rcp_f32_e32 v54, v54
	s_nop 0
	v_mov_b32_e32 v48, v47
	v_pk_mul_f32 v[46:47], v[48:49], v[54:55]
	v_cvt_pk_bf16_f32 v48, v50, v51
	v_cvt_pk_bf16_f32 v46, v46, v47
	v_and_b32_e32 v47, 0xffff0000, v46
	v_lshlrev_b32_e32 v46, 16, v46
	v_or_b32_sdwa v47, v47, v48 dst_sel:DWORD dst_unused:UNUSED_PAD src0_sel:DWORD src1_sel:WORD_1
	v_or_b32_sdwa v46, v46, v48 dst_sel:DWORD dst_unused:UNUSED_PAD src0_sel:DWORD src1_sel:WORD_0
	v_pk_add_f32 v[48:49], v[52:53], 1.0 op_sel_hi:[1,0]
	s_nop 0
	s_nop 0
	v_rcp_f32_e32 v49, v49
	s_nop 0
	s_nop 0
	v_rcp_f32_e32 v48, v48
	s_nop 0
	v_mov_b32_e32 v50, v42
	v_mov_b32_e32 v51, v44
	v_pk_mul_f32 v[48:49], v[50:51], v[48:49]
	v_pk_add_f32 v[50:51], v[56:57], 1.0 op_sel_hi:[1,0]
	s_nop 0
	s_nop 0
	v_rcp_f32_e32 v51, v51
	s_nop 0
	s_nop 0
	v_rcp_f32_e32 v50, v50
	s_nop 0
	v_mov_b32_e32 v44, v43
	v_pk_mul_f32 v[42:43], v[44:45], v[50:51]
	v_add_u32_e32 v52, 0xfff57400, v124
	v_cvt_pk_bf16_f32 v42, v42, v43
	v_cvt_pk_bf16_f32 v44, v48, v49
	v_and_b32_e32 v43, 0xffff0000, v42
	v_lshlrev_b32_e32 v42, 16, v42
	v_add_u32_e32 v0, v0, v52
	v_or_b32_sdwa v49, v43, v44 dst_sel:DWORD dst_unused:UNUSED_PAD src0_sel:DWORD src1_sel:WORD_1
	v_or_b32_sdwa v48, v42, v44 dst_sel:DWORD dst_unused:UNUSED_PAD src0_sel:DWORD src1_sel:WORD_0
	v_lshl_add_u64 v[42:43], v[0:1], 1, s[6:7]
	v_add_u32_e32 v0, v60, v125
	global_store_dwordx4 v[42:43], v[46:49], off
	v_add_u32_e32 v0, v0, v52
	s_waitcnt vmcnt(15)
	v_lshlrev_b32_e32 v49, 16, v207
	v_and_b32_e32 v50, 0xffff0000, v207
	v_lshlrev_b32_e32 v43, 16, v208
	v_and_b32_e32 v47, 0xffff0000, v206
	v_mul_f32_e32 v43, 0xbfb8aa3b, v43
	v_lshlrev_b32_e32 v46, 16, v206
	v_and_b32_e32 v48, 0xffff0000, v208
	v_exp_f32_e32 v44, v43
	v_mul_f32_e32 v43, 0xbfb8aa3b, v47
	v_mul_f32_e32 v42, 0xbfb8aa3b, v46
	v_exp_f32_e32 v46, v43
	v_mul_f32_e32 v43, 0xbfb8aa3b, v48
	v_exp_f32_e32 v48, v43
	v_mul_f32_e32 v43, 0xbfb8aa3b, v49
	v_exp_f32_e32 v42, v42
	v_exp_f32_e32 v43, v43
	v_lshlrev_b32_e32 v51, 16, v209
	v_mul_f32_e32 v47, 0xbfb8aa3b, v50
	v_and_b32_e32 v53, 0xffff0000, v209
	v_pk_add_f32 v[42:43], v[42:43], 1.0 op_sel_hi:[1,0]
	v_mul_f32_e32 v45, 0xbfb8aa3b, v51
	v_mul_f32_e32 v49, 0xbfb8aa3b, v53
	v_exp_f32_e32 v47, v47
	v_exp_f32_e32 v45, v45
	v_rcp_f32_e32 v43, v43
	s_nop 0
	v_pk_add_f32 v[46:47], v[46:47], 1.0 op_sel_hi:[1,0]
	v_exp_f32_e32 v49, v49
	v_rcp_f32_e32 v42, v42
	s_nop 0
	v_mov_b32_e32 v50, v38
	v_mov_b32_e32 v51, v40
	v_pk_mul_f32 v[42:43], v[50:51], v[42:43]
	v_rcp_f32_e32 v47, v47
	s_nop 0
	s_nop 0
	v_rcp_f32_e32 v46, v46
	s_nop 0
	v_mov_b32_e32 v40, v39
	v_pk_mul_f32 v[38:39], v[40:41], v[46:47]
	v_cvt_pk_bf16_f32 v40, v42, v43
	v_cvt_pk_bf16_f32 v38, v38, v39
	v_and_b32_e32 v39, 0xffff0000, v38
	v_lshlrev_b32_e32 v38, 16, v38
	v_or_b32_sdwa v39, v39, v40 dst_sel:DWORD dst_unused:UNUSED_PAD src0_sel:DWORD src1_sel:WORD_1
	v_or_b32_sdwa v38, v38, v40 dst_sel:DWORD dst_unused:UNUSED_PAD src0_sel:DWORD src1_sel:WORD_0
	v_pk_add_f32 v[40:41], v[44:45], 1.0 op_sel_hi:[1,0]
	s_nop 0
	s_nop 0
	v_rcp_f32_e32 v41, v41
	s_nop 0
	s_nop 0
	v_rcp_f32_e32 v40, v40
	s_nop 0
	v_mov_b32_e32 v42, v34
	v_mov_b32_e32 v43, v36
	v_pk_mul_f32 v[40:41], v[42:43], v[40:41]
	v_pk_add_f32 v[42:43], v[48:49], 1.0 op_sel_hi:[1,0]
	s_nop 0
	s_nop 0
	v_rcp_f32_e32 v43, v43
	s_nop 0
	s_nop 0
	v_rcp_f32_e32 v42, v42
	s_nop 0
	v_mov_b32_e32 v36, v35
	v_pk_mul_f32 v[34:35], v[36:37], v[42:43]
	v_cvt_pk_bf16_f32 v36, v40, v41
	v_cvt_pk_bf16_f32 v34, v34, v35
	v_and_b32_e32 v35, 0xffff0000, v34
	v_lshlrev_b32_e32 v34, 16, v34
	v_add_u32_e32 v44, 0xe3800, v151
	v_or_b32_sdwa v41, v35, v36 dst_sel:DWORD dst_unused:UNUSED_PAD src0_sel:DWORD src1_sel:WORD_1
	v_or_b32_sdwa v40, v34, v36 dst_sel:DWORD dst_unused:UNUSED_PAD src0_sel:DWORD src1_sel:WORD_0
	v_lshl_add_u64 v[34:35], v[0:1], 1, s[6:7]
	v_add_u32_e32 v0, v44, v150
	global_store_dwordx4 v[34:35], v[38:41], off
	s_nop 1
	s_waitcnt vmcnt(15)
	v_lshlrev_b32_e32 v41, 16, v211
	v_and_b32_e32 v42, 0xffff0000, v211
	v_lshlrev_b32_e32 v35, 16, v212
	v_and_b32_e32 v39, 0xffff0000, v210
	v_mul_f32_e32 v35, 0xbfb8aa3b, v35
	v_lshlrev_b32_e32 v38, 16, v210
	v_and_b32_e32 v40, 0xffff0000, v212
	v_exp_f32_e32 v36, v35
	v_mul_f32_e32 v35, 0xbfb8aa3b, v39
	v_mul_f32_e32 v34, 0xbfb8aa3b, v38
	v_exp_f32_e32 v38, v35
	v_mul_f32_e32 v35, 0xbfb8aa3b, v40
	v_exp_f32_e32 v40, v35
	v_mul_f32_e32 v35, 0xbfb8aa3b, v41
	v_exp_f32_e32 v34, v34
	v_exp_f32_e32 v35, v35
	v_lshlrev_b32_e32 v43, 16, v213
	v_mul_f32_e32 v39, 0xbfb8aa3b, v42
	v_and_b32_e32 v45, 0xffff0000, v213
	v_pk_add_f32 v[34:35], v[34:35], 1.0 op_sel_hi:[1,0]
	v_mul_f32_e32 v37, 0xbfb8aa3b, v43
	v_mul_f32_e32 v41, 0xbfb8aa3b, v45
	v_exp_f32_e32 v39, v39
	v_exp_f32_e32 v37, v37
	v_rcp_f32_e32 v35, v35
	s_nop 0
	v_pk_add_f32 v[38:39], v[38:39], 1.0 op_sel_hi:[1,0]
	v_exp_f32_e32 v41, v41
	v_rcp_f32_e32 v34, v34
	s_nop 0
	v_mov_b32_e32 v42, v30
	v_mov_b32_e32 v43, v32
	v_pk_mul_f32 v[34:35], v[42:43], v[34:35]
	v_rcp_f32_e32 v39, v39
	s_nop 0
	s_nop 0
	v_rcp_f32_e32 v38, v38
	s_nop 0
	v_mov_b32_e32 v32, v31
	v_pk_mul_f32 v[30:31], v[32:33], v[38:39]
	v_cvt_pk_bf16_f32 v32, v34, v35
	v_cvt_pk_bf16_f32 v30, v30, v31
	v_and_b32_e32 v31, 0xffff0000, v30
	v_lshlrev_b32_e32 v30, 16, v30
	v_or_b32_sdwa v31, v31, v32 dst_sel:DWORD dst_unused:UNUSED_PAD src0_sel:DWORD src1_sel:WORD_1
	v_or_b32_sdwa v30, v30, v32 dst_sel:DWORD dst_unused:UNUSED_PAD src0_sel:DWORD src1_sel:WORD_0
	v_pk_add_f32 v[32:33], v[36:37], 1.0 op_sel_hi:[1,0]
	s_nop 0
	s_nop 0
	v_rcp_f32_e32 v33, v33
	s_nop 0
	s_nop 0
	v_rcp_f32_e32 v32, v32
	s_nop 0
	v_mov_b32_e32 v34, v26
	v_mov_b32_e32 v35, v28
	v_pk_mul_f32 v[32:33], v[34:35], v[32:33]
	v_pk_add_f32 v[34:35], v[40:41], 1.0 op_sel_hi:[1,0]
	s_nop 0
	s_nop 0
	v_rcp_f32_e32 v35, v35
	s_nop 0
	s_nop 0
	v_rcp_f32_e32 v34, v34
	s_nop 0
	v_mov_b32_e32 v28, v27
	v_pk_mul_f32 v[26:27], v[28:29], v[34:35]
	v_add_u32_e32 v36, 0xfff44800, v124
	v_cvt_pk_bf16_f32 v26, v26, v27
	v_cvt_pk_bf16_f32 v28, v32, v33
	v_and_b32_e32 v27, 0xffff0000, v26
	v_lshlrev_b32_e32 v26, 16, v26
	v_add_u32_e32 v0, v0, v36
	v_or_b32_sdwa v33, v27, v28 dst_sel:DWORD dst_unused:UNUSED_PAD src0_sel:DWORD src1_sel:WORD_1
	v_or_b32_sdwa v32, v26, v28 dst_sel:DWORD dst_unused:UNUSED_PAD src0_sel:DWORD src1_sel:WORD_0
	v_lshl_add_u64 v[26:27], v[0:1], 1, s[6:7]
	v_add_u32_e32 v0, v44, v125
	global_store_dwordx4 v[26:27], v[30:33], off
	v_add_u32_e32 v0, v0, v36
	s_waitcnt vmcnt(14)
	v_lshlrev_b32_e32 v33, 16, v163
	v_and_b32_e32 v34, 0xffff0000, v163
	v_lshlrev_b32_e32 v27, 16, v164
	v_and_b32_e32 v31, 0xffff0000, v162
	v_mul_f32_e32 v27, 0xbfb8aa3b, v27
	v_lshlrev_b32_e32 v30, 16, v162
	v_and_b32_e32 v32, 0xffff0000, v164
	v_exp_f32_e32 v28, v27
	v_mul_f32_e32 v27, 0xbfb8aa3b, v31
	v_mul_f32_e32 v26, 0xbfb8aa3b, v30
	v_exp_f32_e32 v30, v27
	v_mul_f32_e32 v27, 0xbfb8aa3b, v32
	v_exp_f32_e32 v32, v27
	v_mul_f32_e32 v27, 0xbfb8aa3b, v33
	v_exp_f32_e32 v26, v26
	v_exp_f32_e32 v27, v27
	v_lshlrev_b32_e32 v35, 16, v165
	v_mul_f32_e32 v31, 0xbfb8aa3b, v34
	v_and_b32_e32 v37, 0xffff0000, v165
	v_pk_add_f32 v[26:27], v[26:27], 1.0 op_sel_hi:[1,0]
	v_mul_f32_e32 v29, 0xbfb8aa3b, v35
	v_mul_f32_e32 v33, 0xbfb8aa3b, v37
	v_exp_f32_e32 v31, v31
	v_exp_f32_e32 v29, v29
	v_rcp_f32_e32 v27, v27
	s_nop 0
	v_pk_add_f32 v[30:31], v[30:31], 1.0 op_sel_hi:[1,0]
	v_exp_f32_e32 v33, v33
	v_rcp_f32_e32 v26, v26
	s_nop 0
	v_mov_b32_e32 v34, v22
	v_mov_b32_e32 v35, v24
	v_pk_mul_f32 v[26:27], v[34:35], v[26:27]
	v_rcp_f32_e32 v31, v31
	s_nop 0
	s_nop 0
	v_rcp_f32_e32 v30, v30
	s_nop 0
	v_mov_b32_e32 v24, v23
	v_pk_mul_f32 v[22:23], v[24:25], v[30:31]
	v_cvt_pk_bf16_f32 v24, v26, v27
	v_cvt_pk_bf16_f32 v22, v22, v23
	v_and_b32_e32 v23, 0xffff0000, v22
	v_lshlrev_b32_e32 v22, 16, v22
	v_or_b32_sdwa v23, v23, v24 dst_sel:DWORD dst_unused:UNUSED_PAD src0_sel:DWORD src1_sel:WORD_1
	v_or_b32_sdwa v22, v22, v24 dst_sel:DWORD dst_unused:UNUSED_PAD src0_sel:DWORD src1_sel:WORD_0
	v_pk_add_f32 v[24:25], v[28:29], 1.0 op_sel_hi:[1,0]
	s_nop 0
	s_nop 0
	v_rcp_f32_e32 v25, v25
	s_nop 0
	s_nop 0
	v_rcp_f32_e32 v24, v24
	s_nop 0
	v_mov_b32_e32 v26, v18
	v_mov_b32_e32 v27, v20
	v_pk_mul_f32 v[24:25], v[26:27], v[24:25]
	v_pk_add_f32 v[26:27], v[32:33], 1.0 op_sel_hi:[1,0]
	s_nop 0
	s_nop 0
	v_rcp_f32_e32 v27, v27
	s_nop 0
	s_nop 0
	v_rcp_f32_e32 v26, v26
	s_nop 0
	v_mov_b32_e32 v20, v19
	v_pk_mul_f32 v[18:19], v[20:21], v[26:27]
	v_cvt_pk_bf16_f32 v20, v24, v25
	v_cvt_pk_bf16_f32 v18, v18, v19
	v_and_b32_e32 v19, 0xffff0000, v18
	v_lshlrev_b32_e32 v18, 16, v18
	v_add_u32_e32 v28, 0xfa400, v151
	v_or_b32_sdwa v25, v19, v20 dst_sel:DWORD dst_unused:UNUSED_PAD src0_sel:DWORD src1_sel:WORD_1
	v_or_b32_sdwa v24, v18, v20 dst_sel:DWORD dst_unused:UNUSED_PAD src0_sel:DWORD src1_sel:WORD_0
	v_lshl_add_u64 v[18:19], v[0:1], 1, s[6:7]
	v_add_u32_e32 v0, v28, v150
	global_store_dwordx4 v[18:19], v[22:25], off
	s_nop 1
	s_waitcnt vmcnt(13)
	v_lshlrev_b32_e32 v25, 16, v167
	v_and_b32_e32 v26, 0xffff0000, v167
	v_lshlrev_b32_e32 v19, 16, v168
	v_and_b32_e32 v23, 0xffff0000, v166
	v_mul_f32_e32 v19, 0xbfb8aa3b, v19
	v_lshlrev_b32_e32 v22, 16, v166
	v_and_b32_e32 v24, 0xffff0000, v168
	v_exp_f32_e32 v20, v19
	v_mul_f32_e32 v19, 0xbfb8aa3b, v23
	v_mul_f32_e32 v18, 0xbfb8aa3b, v22
	v_exp_f32_e32 v22, v19
	v_mul_f32_e32 v19, 0xbfb8aa3b, v24
	v_exp_f32_e32 v24, v19
	v_mul_f32_e32 v19, 0xbfb8aa3b, v25
	v_exp_f32_e32 v18, v18
	v_exp_f32_e32 v19, v19
	v_lshlrev_b32_e32 v27, 16, v169
	v_mul_f32_e32 v23, 0xbfb8aa3b, v26
	v_and_b32_e32 v29, 0xffff0000, v169
	v_pk_add_f32 v[18:19], v[18:19], 1.0 op_sel_hi:[1,0]
	v_mul_f32_e32 v21, 0xbfb8aa3b, v27
	v_mul_f32_e32 v25, 0xbfb8aa3b, v29
	v_exp_f32_e32 v23, v23
	v_exp_f32_e32 v21, v21
	v_rcp_f32_e32 v19, v19
	s_nop 0
	v_pk_add_f32 v[22:23], v[22:23], 1.0 op_sel_hi:[1,0]
	v_exp_f32_e32 v25, v25
	v_rcp_f32_e32 v18, v18
	s_nop 0
	v_mov_b32_e32 v26, v14
	v_mov_b32_e32 v27, v16
	v_pk_mul_f32 v[18:19], v[26:27], v[18:19]
	v_rcp_f32_e32 v23, v23
	s_nop 0
	s_nop 0
	v_rcp_f32_e32 v22, v22
	s_nop 0
	v_mov_b32_e32 v16, v15
	v_pk_mul_f32 v[14:15], v[16:17], v[22:23]
	v_cvt_pk_bf16_f32 v16, v18, v19
	v_cvt_pk_bf16_f32 v14, v14, v15
	v_and_b32_e32 v15, 0xffff0000, v14
	v_lshlrev_b32_e32 v14, 16, v14
	v_or_b32_sdwa v15, v15, v16 dst_sel:DWORD dst_unused:UNUSED_PAD src0_sel:DWORD src1_sel:WORD_1
	v_or_b32_sdwa v14, v14, v16 dst_sel:DWORD dst_unused:UNUSED_PAD src0_sel:DWORD src1_sel:WORD_0
	v_pk_add_f32 v[16:17], v[20:21], 1.0 op_sel_hi:[1,0]
	s_nop 0
	s_nop 0
	v_rcp_f32_e32 v17, v17
	s_nop 0
	s_nop 0
	v_rcp_f32_e32 v16, v16
	s_nop 0
	v_mov_b32_e32 v18, v10
	v_mov_b32_e32 v19, v12
	v_pk_mul_f32 v[16:17], v[18:19], v[16:17]
	v_pk_add_f32 v[18:19], v[24:25], 1.0 op_sel_hi:[1,0]
	s_nop 0
	s_nop 0
	v_rcp_f32_e32 v19, v19
	s_nop 0
	s_nop 0
	v_rcp_f32_e32 v18, v18
	s_nop 0
	v_mov_b32_e32 v12, v11
	v_pk_mul_f32 v[10:11], v[12:13], v[18:19]
	v_add_u32_e32 v20, 0xfff31c00, v124
	v_cvt_pk_bf16_f32 v10, v10, v11
	v_cvt_pk_bf16_f32 v12, v16, v17
	v_and_b32_e32 v11, 0xffff0000, v10
	v_lshlrev_b32_e32 v10, 16, v10
	v_add_u32_e32 v0, v0, v20
	v_or_b32_sdwa v17, v11, v12 dst_sel:DWORD dst_unused:UNUSED_PAD src0_sel:DWORD src1_sel:WORD_1
	v_or_b32_sdwa v16, v10, v12 dst_sel:DWORD dst_unused:UNUSED_PAD src0_sel:DWORD src1_sel:WORD_0
	v_lshl_add_u64 v[10:11], v[0:1], 1, s[6:7]
	v_add_u32_e32 v0, v28, v125
	global_store_dwordx4 v[10:11], v[14:17], off
	v_add_u32_e32 v0, v0, v20
	s_waitcnt vmcnt(12)
	v_lshlrev_b32_e32 v17, 16, v171
	v_and_b32_e32 v18, 0xffff0000, v171
	v_lshlrev_b32_e32 v11, 16, v172
	v_and_b32_e32 v15, 0xffff0000, v170
	v_mul_f32_e32 v11, 0xbfb8aa3b, v11
	v_lshlrev_b32_e32 v14, 16, v170
	v_and_b32_e32 v16, 0xffff0000, v172
	v_exp_f32_e32 v12, v11
	v_mul_f32_e32 v11, 0xbfb8aa3b, v15
	v_mul_f32_e32 v10, 0xbfb8aa3b, v14
	v_exp_f32_e32 v14, v11
	v_mul_f32_e32 v11, 0xbfb8aa3b, v16
	v_exp_f32_e32 v16, v11
	v_mul_f32_e32 v11, 0xbfb8aa3b, v17
	v_exp_f32_e32 v10, v10
	v_exp_f32_e32 v11, v11
	v_lshlrev_b32_e32 v19, 16, v173
	v_mul_f32_e32 v15, 0xbfb8aa3b, v18
	v_and_b32_e32 v21, 0xffff0000, v173
	v_pk_add_f32 v[10:11], v[10:11], 1.0 op_sel_hi:[1,0]
	v_mul_f32_e32 v13, 0xbfb8aa3b, v19
	v_mul_f32_e32 v17, 0xbfb8aa3b, v21
	v_exp_f32_e32 v15, v15
	v_exp_f32_e32 v13, v13
	v_rcp_f32_e32 v11, v11
	s_nop 0
	v_pk_add_f32 v[14:15], v[14:15], 1.0 op_sel_hi:[1,0]
	v_exp_f32_e32 v17, v17
	v_rcp_f32_e32 v10, v10
	s_nop 0
	v_mov_b32_e32 v18, v6
	v_mov_b32_e32 v19, v8
	v_pk_mul_f32 v[10:11], v[18:19], v[10:11]
	v_rcp_f32_e32 v15, v15
	s_nop 0
	s_nop 0
	v_rcp_f32_e32 v14, v14
	s_nop 0
	v_mov_b32_e32 v8, v7
	v_pk_mul_f32 v[6:7], v[8:9], v[14:15]
	v_cvt_pk_bf16_f32 v8, v10, v11
	v_cvt_pk_bf16_f32 v6, v6, v7
	v_and_b32_e32 v7, 0xffff0000, v6
	v_lshlrev_b32_e32 v6, 16, v6
	v_or_b32_sdwa v7, v7, v8 dst_sel:DWORD dst_unused:UNUSED_PAD src0_sel:DWORD src1_sel:WORD_1
	v_or_b32_sdwa v6, v6, v8 dst_sel:DWORD dst_unused:UNUSED_PAD src0_sel:DWORD src1_sel:WORD_0
	v_pk_add_f32 v[8:9], v[12:13], 1.0 op_sel_hi:[1,0]
	s_nop 0
	s_nop 0
	v_rcp_f32_e32 v9, v9
	s_nop 0
	s_nop 0
	v_rcp_f32_e32 v8, v8
	s_nop 0
	v_mov_b32_e32 v10, v2
	v_mov_b32_e32 v11, v4
	v_pk_mul_f32 v[8:9], v[10:11], v[8:9]
	v_pk_add_f32 v[10:11], v[16:17], 1.0 op_sel_hi:[1,0]
	s_nop 0
	s_nop 0
	v_rcp_f32_e32 v11, v11
	s_nop 0
	s_mov_b64 s[24:25], s[16:17]
	v_rcp_f32_e32 v10, v10
	s_nop 0
	v_mov_b32_e32 v4, v3
	v_pk_mul_f32 v[2:3], v[4:5], v[10:11]
	v_cvt_pk_bf16_f32 v4, v8, v9
	v_cvt_pk_bf16_f32 v2, v2, v3
	v_and_b32_e32 v3, 0xffff0000, v2
	v_lshlrev_b32_e32 v2, 16, v2
	v_or_b32_sdwa v9, v3, v4 dst_sel:DWORD dst_unused:UNUSED_PAD src0_sel:DWORD src1_sel:WORD_1
	v_or_b32_sdwa v8, v2, v4 dst_sel:DWORD dst_unused:UNUSED_PAD src0_sel:DWORD src1_sel:WORD_0
	v_lshl_add_u64 v[2:3], v[0:1], 1, s[6:7]
	s_and_b64 vcc, exec, s[10:11]
	global_store_dwordx4 v[2:3], v[6:9], off
	s_cbranch_vccz .LBB0_1344
	s_waitcnt vmcnt(0)
	v_readlane_b32 s76, v255, 8
	s_mov_b32 s92, 0x3b2aaaab
	s_cmp_gt_u32 s4, 3
	v_readlane_b32 s77, v255, 9
	s_mul_i32 s60, s33, 0x1800
	s_mul_hi_i32 s62, s64, 0x300
	s_mul_i32 s75, s33, 0x16c00
	s_mov_b32 s93, 0x3c800000
	s_mov_b32 s82, s70
	s_cbranch_scc1 .LBB0_1351
	s_barrier

.LBB0_1359:
	v_add_u32_e32 v0, 0x10000, v154
	ds_read_b128 v[130:133], v0
	ds_read_b128 v[146:149], v0 offset:1024
	ds_read_b128 v[156:159], v0 offset:2048
	ds_read_b128 v[160:163], v0 offset:3072
	s_add_u32 s28, s26, 0xfffc0080
	s_addc_u32 s29, s27, -1
	s_cmp_eq_u32 vcc_lo, 12
	s_cselect_b32 s31, s2, s29
	s_cselect_b32 s30, s17, s28
	s_cselect_b32 s29, s15, s94
	s_cselect_b32 s28, s89, s90
	v_lshl_add_u64 v[150:151], s[26:27], 0, v[142:143]
	s_add_i32 m0, s39, 0xc000
	ds_read_b128 v[164:167], v153
	ds_read_b128 v[168:171], v153 offset:1024
	ds_read_b128 v[172:175], v153 offset:2048
	ds_read_b128 v[176:179], v153 offset:3072
	ds_read_b128 v[182:185], v153 offset:4096
	ds_read_b128 v[186:189], v153 offset:5120
	ds_read_b128 v[190:193], v153 offset:6144
	ds_read_b128 v[194:197], v153 offset:7168
	global_load_lds_dwordx4 v[150:151], off
	v_lshl_add_u64 v[150:151], s[26:27], 0, v[144:145]
	s_add_i32 m0, s39, 0xe000
	s_nop 0
	global_load_lds_dwordx4 v[150:151], off
	s_waitcnt lgkmcnt(8)
	s_barrier
	s_waitcnt lgkmcnt(0)
	s_waitcnt lgkmcnt(0)
	v_mfma_f32_16x16x32_bf16 v[126:129], v[130:133], v[164:167], v[126:129]
	v_mfma_f32_16x16x32_bf16 v[122:125], v[156:159], v[164:167], v[122:125]
	v_mfma_f32_16x16x32_bf16 v[110:113], v[130:133], v[172:175], v[110:113]
	v_mfma_f32_16x16x32_bf16 v[106:109], v[156:159], v[172:175], v[106:109]
	v_mfma_f32_16x16x32_bf16 v[94:97], v[130:133], v[182:185], v[94:97]
	v_mfma_f32_16x16x32_bf16 v[90:93], v[156:159], v[182:185], v[90:93]
	v_mfma_f32_16x16x32_bf16 v[78:81], v[130:133], v[190:193], v[78:81]
	v_mfma_f32_16x16x32_bf16 v[74:77], v[156:159], v[190:193], v[74:77]
	v_mfma_f32_16x16x32_bf16 v[126:129], v[146:149], v[168:171], v[126:129]
	v_mfma_f32_16x16x32_bf16 v[122:125], v[160:163], v[168:171], v[122:125]
	v_mfma_f32_16x16x32_bf16 v[110:113], v[146:149], v[176:179], v[110:113]
	v_mfma_f32_16x16x32_bf16 v[106:109], v[160:163], v[176:179], v[106:109]
	v_mfma_f32_16x16x32_bf16 v[94:97], v[146:149], v[186:189], v[94:97]
	v_mfma_f32_16x16x32_bf16 v[90:93], v[160:163], v[186:189], v[90:93]
	v_mfma_f32_16x16x32_bf16 v[78:81], v[146:149], v[194:197], v[78:81]
	v_mfma_f32_16x16x32_bf16 v[74:77], v[160:163], v[194:197], v[74:77]
	s_barrier
	s_mov_b32 m0, s23
	v_add_u32_e32 v0, 0x14000, v154
	v_lshl_add_u64 v[150:151], s[28:29], 0, v[138:139]
	ds_read_b128 v[198:201], v0
	ds_read_b128 v[202:205], v0 offset:1024
	ds_read_b128 v[206:209], v0 offset:2048
	ds_read_b128 v[210:213], v0 offset:3072
	global_load_lds_dwordx4 v[150:151], off
	v_lshl_add_u64 v[214:215], s[28:29], 0, v[134:135]
	s_mov_b32 m0, s25
	s_nop 0
	global_load_lds_dwordx4 v[214:215], off
	s_barrier
	s_waitcnt lgkmcnt(0)
	s_waitcnt lgkmcnt(0)
	v_mfma_f32_16x16x32_bf16 v[118:121], v[198:201], v[164:167], v[118:121]
	v_mfma_f32_16x16x32_bf16 v[114:117], v[206:209], v[164:167], v[114:117]
	v_mfma_f32_16x16x32_bf16 v[102:105], v[198:201], v[172:175], v[102:105]
	v_mfma_f32_16x16x32_bf16 v[98:101], v[206:209], v[172:175], v[98:101]
	v_mfma_f32_16x16x32_bf16 v[86:89], v[198:201], v[182:185], v[86:89]
	v_mfma_f32_16x16x32_bf16 v[82:85], v[206:209], v[182:185], v[82:85]
	v_mfma_f32_16x16x32_bf16 v[70:73], v[198:201], v[190:193], v[70:73]
	v_mfma_f32_16x16x32_bf16 v[66:69], v[206:209], v[190:193], v[66:69]
	v_mfma_f32_16x16x32_bf16 v[118:121], v[202:205], v[168:171], v[118:121]
	v_mfma_f32_16x16x32_bf16 v[114:117], v[210:213], v[168:171], v[114:117]
	v_mfma_f32_16x16x32_bf16 v[102:105], v[202:205], v[176:179], v[102:105]
	v_mfma_f32_16x16x32_bf16 v[98:101], v[210:213], v[176:179], v[98:101]
	v_mfma_f32_16x16x32_bf16 v[86:89], v[202:205], v[186:189], v[86:89]
	v_mfma_f32_16x16x32_bf16 v[82:85], v[210:213], v[186:189], v[82:85]
	v_mfma_f32_16x16x32_bf16 v[70:73], v[202:205], v[194:197], v[70:73]
	v_mfma_f32_16x16x32_bf16 v[66:69], v[210:213], v[194:197], v[66:69]
	s_mov_b32 m0, s39
	v_lshl_add_u64 v[216:217], s[30:31], 0, v[140:141]
	s_barrier
	ds_read_b128 v[164:167], v153 offset:16384
	ds_read_b128 v[168:171], v153 offset:17408
	ds_read_b128 v[172:175], v153 offset:18432
	ds_read_b128 v[176:179], v153 offset:19456
	ds_read_b128 v[182:185], v153 offset:20480
	ds_read_b128 v[186:189], v153 offset:21504
	ds_read_b128 v[190:193], v153 offset:22528
	ds_read_b128 v[194:197], v153 offset:23552
	global_load_lds_dwordx4 v[216:217], off
	v_lshl_add_u64 v[222:223], s[30:31], 0, v[136:137]
	s_mov_b32 m0, s82
	s_nop 0
	global_load_lds_dwordx4 v[222:223], off
	s_barrier
	s_waitcnt lgkmcnt(0)
	s_waitcnt lgkmcnt(0)
	v_mfma_f32_16x16x32_bf16 v[62:65], v[130:133], v[164:167], v[62:65]
	v_mfma_f32_16x16x32_bf16 v[58:61], v[156:159], v[164:167], v[58:61]
	v_mfma_f32_16x16x32_bf16 v[46:49], v[130:133], v[172:175], v[46:49]
	v_mfma_f32_16x16x32_bf16 v[42:45], v[156:159], v[172:175], v[42:45]
	v_mfma_f32_16x16x32_bf16 v[30:33], v[130:133], v[182:185], v[30:33]
	v_mfma_f32_16x16x32_bf16 v[26:29], v[156:159], v[182:185], v[26:29]
	v_mfma_f32_16x16x32_bf16 v[14:17], v[130:133], v[190:193], v[14:17]
	v_mfma_f32_16x16x32_bf16 v[10:13], v[156:159], v[190:193], v[10:13]
	v_mfma_f32_16x16x32_bf16 v[62:65], v[146:149], v[168:171], v[62:65]
	v_mfma_f32_16x16x32_bf16 v[58:61], v[160:163], v[168:171], v[58:61]
	v_mfma_f32_16x16x32_bf16 v[46:49], v[146:149], v[176:179], v[46:49]
	v_mfma_f32_16x16x32_bf16 v[42:45], v[160:163], v[176:179], v[42:45]
	v_mfma_f32_16x16x32_bf16 v[30:33], v[146:149], v[186:189], v[30:33]
	v_mfma_f32_16x16x32_bf16 v[26:29], v[160:163], v[186:189], v[26:29]
	v_mfma_f32_16x16x32_bf16 v[14:17], v[146:149], v[194:197], v[14:17]
	v_mfma_f32_16x16x32_bf16 v[10:13], v[160:163], v[194:197], v[10:13]
	s_barrier
	s_add_u32 s76, s28, 0x40000
	s_addc_u32 s77, s29, 0
	s_mov_b32 m0, s96
	v_lshl_add_u64 v[130:131], s[76:77], 0, v[138:139]
	global_load_lds_dwordx4 v[130:131], off
	v_lshl_add_u64 v[130:131], s[76:77], 0, v[134:135]
	s_mov_b32 m0, s97
	s_nop 0
	global_load_lds_dwordx4 v[130:131], off
	s_waitcnt vmcnt(6)
	s_barrier
	v_mfma_f32_16x16x32_bf16 v[54:57], v[198:201], v[164:167], v[54:57]
	v_mfma_f32_16x16x32_bf16 v[50:53], v[206:209], v[164:167], v[50:53]
	v_mfma_f32_16x16x32_bf16 v[38:41], v[198:201], v[172:175], v[38:41]
	v_mfma_f32_16x16x32_bf16 v[34:37], v[206:209], v[172:175], v[34:37]
	v_mfma_f32_16x16x32_bf16 v[22:25], v[198:201], v[182:185], v[22:25]
	v_mfma_f32_16x16x32_bf16 v[18:21], v[206:209], v[182:185], v[18:21]
	v_mfma_f32_16x16x32_bf16 v[6:9], v[198:201], v[190:193], v[6:9]
	v_mfma_f32_16x16x32_bf16 v[2:5], v[206:209], v[190:193], v[2:5]
	v_mfma_f32_16x16x32_bf16 v[54:57], v[202:205], v[168:171], v[54:57]
	v_mfma_f32_16x16x32_bf16 v[50:53], v[210:213], v[168:171], v[50:53]
	v_mfma_f32_16x16x32_bf16 v[38:41], v[202:205], v[176:179], v[38:41]
	v_mfma_f32_16x16x32_bf16 v[34:37], v[210:213], v[176:179], v[34:37]
	v_mfma_f32_16x16x32_bf16 v[22:25], v[202:205], v[186:189], v[22:25]
	v_mfma_f32_16x16x32_bf16 v[18:21], v[210:213], v[186:189], v[18:21]
	v_mfma_f32_16x16x32_bf16 v[6:9], v[202:205], v[194:197], v[6:9]
	v_mfma_f32_16x16x32_bf16 v[2:5], v[210:213], v[194:197], v[2:5]
	v_add_u32_e32 v0, 0x18000, v154
	s_barrier
	ds_read_b128 v[130:133], v0
	ds_read_b128 v[146:149], v0 offset:1024
	ds_read_b128 v[156:159], v0 offset:2048
	ds_read_b128 v[160:163], v0 offset:3072
	s_add_u32 s30, s30, 0x40000
	s_addc_u32 s31, s31, 0
	s_mov_b32 m0, s68
	v_lshl_add_u64 v[198:199], s[30:31], 0, v[140:141]
	ds_read_b128 v[164:167], v153 offset:32768
	ds_read_b128 v[168:171], v153 offset:33792
	ds_read_b128 v[172:175], v153 offset:34816
	ds_read_b128 v[176:179], v153 offset:35840
	ds_read_b128 v[182:185], v153 offset:36864
	ds_read_b128 v[186:189], v153 offset:37888
	ds_read_b128 v[190:193], v153 offset:38912
	ds_read_b128 v[194:197], v153 offset:39936
	global_load_lds_dwordx4 v[198:199], off
	v_lshl_add_u64 v[198:199], s[30:31], 0, v[136:137]
	s_mov_b32 m0, s69
	s_nop 0
	global_load_lds_dwordx4 v[198:199], off
	s_waitcnt lgkmcnt(8)
	s_barrier
	s_waitcnt lgkmcnt(0)
	s_waitcnt lgkmcnt(0)
	v_mfma_f32_16x16x32_bf16 v[126:129], v[130:133], v[164:167], v[126:129]
	v_mfma_f32_16x16x32_bf16 v[122:125], v[156:159], v[164:167], v[122:125]
	v_mfma_f32_16x16x32_bf16 v[110:113], v[130:133], v[172:175], v[110:113]
	v_mfma_f32_16x16x32_bf16 v[106:109], v[156:159], v[172:175], v[106:109]
	v_mfma_f32_16x16x32_bf16 v[94:97], v[130:133], v[182:185], v[94:97]
	v_mfma_f32_16x16x32_bf16 v[90:93], v[156:159], v[182:185], v[90:93]
	v_mfma_f32_16x16x32_bf16 v[78:81], v[130:133], v[190:193], v[78:81]
	v_mfma_f32_16x16x32_bf16 v[74:77], v[156:159], v[190:193], v[74:77]
	v_mfma_f32_16x16x32_bf16 v[126:129], v[146:149], v[168:171], v[126:129]
	v_mfma_f32_16x16x32_bf16 v[122:125], v[160:163], v[168:171], v[122:125]
	v_mfma_f32_16x16x32_bf16 v[110:113], v[146:149], v[176:179], v[110:113]
	v_mfma_f32_16x16x32_bf16 v[106:109], v[160:163], v[176:179], v[106:109]
	v_mfma_f32_16x16x32_bf16 v[94:97], v[146:149], v[186:189], v[94:97]
	v_mfma_f32_16x16x32_bf16 v[90:93], v[160:163], v[186:189], v[90:93]
	v_mfma_f32_16x16x32_bf16 v[78:81], v[146:149], v[194:197], v[78:81]
	v_mfma_f32_16x16x32_bf16 v[74:77], v[160:163], v[194:197], v[74:77]
	s_barrier
	s_mov_b32 m0, s4
	v_add_u32_e32 v0, 0x1c000, v154
	v_lshl_add_u64 v[150:151], v[150:151], 0, s[84:85]
	ds_read_b128 v[198:201], v0
	ds_read_b128 v[202:205], v0 offset:1024
	ds_read_b128 v[206:209], v0 offset:2048
	ds_read_b128 v[210:213], v0 offset:3072
	global_load_lds_dwordx4 v[150:151], off
	v_lshl_add_u64 v[150:151], v[214:215], 0, s[84:85]
	s_mov_b32 m0, s5
	s_nop 0
	global_load_lds_dwordx4 v[150:151], off
	s_barrier
	s_waitcnt lgkmcnt(0)
	s_waitcnt lgkmcnt(0)
	v_mfma_f32_16x16x32_bf16 v[118:121], v[198:201], v[164:167], v[118:121]
	v_mfma_f32_16x16x32_bf16 v[114:117], v[206:209], v[164:167], v[114:117]
	v_mfma_f32_16x16x32_bf16 v[102:105], v[198:201], v[172:175], v[102:105]
	v_mfma_f32_16x16x32_bf16 v[98:101], v[206:209], v[172:175], v[98:101]
	v_mfma_f32_16x16x32_bf16 v[86:89], v[198:201], v[182:185], v[86:89]
	v_mfma_f32_16x16x32_bf16 v[82:85], v[206:209], v[182:185], v[82:85]
	v_mfma_f32_16x16x32_bf16 v[70:73], v[198:201], v[190:193], v[70:73]
	v_mfma_f32_16x16x32_bf16 v[66:69], v[206:209], v[190:193], v[66:69]
	v_mfma_f32_16x16x32_bf16 v[118:121], v[202:205], v[168:171], v[118:121]
	v_mfma_f32_16x16x32_bf16 v[114:117], v[210:213], v[168:171], v[114:117]
	v_mfma_f32_16x16x32_bf16 v[102:105], v[202:205], v[176:179], v[102:105]
	v_mfma_f32_16x16x32_bf16 v[98:101], v[210:213], v[176:179], v[98:101]
	v_mfma_f32_16x16x32_bf16 v[86:89], v[202:205], v[186:189], v[86:89]
	v_mfma_f32_16x16x32_bf16 v[82:85], v[210:213], v[186:189], v[82:85]
	v_mfma_f32_16x16x32_bf16 v[70:73], v[202:205], v[194:197], v[70:73]
	v_mfma_f32_16x16x32_bf16 v[66:69], v[210:213], v[194:197], v[66:69]
	s_mov_b32 m0, s60
	v_lshl_add_u64 v[150:151], v[216:217], 0, s[84:85]
	s_barrier
	ds_read_b128 v[164:167], v153 offset:49152
	ds_read_b128 v[168:171], v153 offset:50176
	ds_read_b128 v[172:175], v153 offset:51200
	ds_read_b128 v[176:179], v153 offset:52224
	ds_read_b128 v[182:185], v153 offset:53248
	ds_read_b128 v[186:189], v153 offset:54272
	ds_read_b128 v[190:193], v153 offset:55296
	ds_read_b128 v[194:197], v153 offset:56320
	global_load_lds_dwordx4 v[150:151], off
	v_lshl_add_u64 v[150:151], v[222:223], 0, s[84:85]
	s_mov_b32 m0, s92
	s_nop 0
	global_load_lds_dwordx4 v[150:151], off
	s_barrier
	s_waitcnt lgkmcnt(0)
	s_waitcnt lgkmcnt(0)
	v_mfma_f32_16x16x32_bf16 v[62:65], v[130:133], v[164:167], v[62:65]
	v_mfma_f32_16x16x32_bf16 v[58:61], v[156:159], v[164:167], v[58:61]
	v_mfma_f32_16x16x32_bf16 v[46:49], v[130:133], v[172:175], v[46:49]
	v_mfma_f32_16x16x32_bf16 v[42:45], v[156:159], v[172:175], v[42:45]
	v_mfma_f32_16x16x32_bf16 v[30:33], v[130:133], v[182:185], v[30:33]
	v_mfma_f32_16x16x32_bf16 v[26:29], v[156:159], v[182:185], v[26:29]
	v_mfma_f32_16x16x32_bf16 v[14:17], v[130:133], v[190:193], v[14:17]
	v_mfma_f32_16x16x32_bf16 v[10:13], v[156:159], v[190:193], v[10:13]
	v_mfma_f32_16x16x32_bf16 v[62:65], v[146:149], v[168:171], v[62:65]
	v_mfma_f32_16x16x32_bf16 v[58:61], v[160:163], v[168:171], v[58:61]
	v_mfma_f32_16x16x32_bf16 v[46:49], v[146:149], v[176:179], v[46:49]
	v_mfma_f32_16x16x32_bf16 v[42:45], v[160:163], v[176:179], v[42:45]
	v_mfma_f32_16x16x32_bf16 v[30:33], v[146:149], v[186:189], v[30:33]
	v_mfma_f32_16x16x32_bf16 v[26:29], v[160:163], v[186:189], v[26:29]
	v_mfma_f32_16x16x32_bf16 v[14:17], v[146:149], v[194:197], v[14:17]
	v_mfma_f32_16x16x32_bf16 v[10:13], v[160:163], v[194:197], v[10:13]
	s_barrier
	s_add_u32 s28, s28, 0x40080
	s_addc_u32 s29, s29, 0
	s_mov_b32 m0, s93
	v_lshl_add_u64 v[130:131], s[28:29], 0, v[138:139]
	global_load_lds_dwordx4 v[130:131], off
	v_lshl_add_u64 v[130:131], s[28:29], 0, v[134:135]
	s_mov_b32 m0, s3
	s_nop 0
	global_load_lds_dwordx4 v[130:131], off
	s_waitcnt vmcnt(6)
	s_barrier
	v_mfma_f32_16x16x32_bf16 v[54:57], v[198:201], v[164:167], v[54:57]
	v_mfma_f32_16x16x32_bf16 v[50:53], v[206:209], v[164:167], v[50:53]
	v_mfma_f32_16x16x32_bf16 v[38:41], v[198:201], v[172:175], v[38:41]
	v_mfma_f32_16x16x32_bf16 v[34:37], v[206:209], v[172:175], v[34:37]
	v_mfma_f32_16x16x32_bf16 v[22:25], v[198:201], v[182:185], v[22:25]
	v_mfma_f32_16x16x32_bf16 v[18:21], v[206:209], v[182:185], v[18:21]
	v_mfma_f32_16x16x32_bf16 v[6:9], v[198:201], v[190:193], v[6:9]
	v_mfma_f32_16x16x32_bf16 v[2:5], v[206:209], v[190:193], v[2:5]
	v_mfma_f32_16x16x32_bf16 v[54:57], v[202:205], v[168:171], v[54:57]
	v_mfma_f32_16x16x32_bf16 v[50:53], v[210:213], v[168:171], v[50:53]
	v_mfma_f32_16x16x32_bf16 v[38:41], v[202:205], v[176:179], v[38:41]
	v_mfma_f32_16x16x32_bf16 v[34:37], v[210:213], v[176:179], v[34:37]
	v_mfma_f32_16x16x32_bf16 v[22:25], v[202:205], v[186:189], v[22:25]
	v_mfma_f32_16x16x32_bf16 v[18:21], v[210:213], v[186:189], v[18:21]
	v_mfma_f32_16x16x32_bf16 v[6:9], v[202:205], v[194:197], v[6:9]
	v_mfma_f32_16x16x32_bf16 v[2:5], v[210:213], v[194:197], v[2:5]
	s_add_i32 vcc_lo, vcc_lo, 2
	s_add_u32 s26, s26, 0x100
	s_addc_u32 s27, s27, 0
	s_add_u32 s90, s90, 0x100
	s_addc_u32 s94, s94, 0
	s_cmp_gt_u32 vcc_lo, 13
	s_barrier
	s_cbranch_scc0 .LBB0_1359
	v_lshl_add_u32 v159, s24, 8, v152
	v_lshl_add_u32 v156, s22, 8, v155
	v_mul_lo_u32 v157, v159, s71
	v_add_u32_e32 v0, v157, v156
	v_lshl_add_u64 v[130:131], v[0:1], 1, s[6:7]
	global_load_dwordx4 v[130:133], v[130:131], off
	v_mul_lo_u32 v158, v159, s61
	v_mov_b32_e32 v210, v0
	v_add_u32_e32 v211, v0, v158
	v_mov_b32_e32 v213, 0
	v_add_u32_e32 v212, 0x80, v210
	v_lshl_add_u64 v[168:169], v[212:213], 1, s[6:7]
	global_load_dwordx4 v[168:171], v[168:169], off
	v_add_u32_e32 v212, 0x80, v211
	v_lshl_add_u64 v[172:173], v[212:213], 1, s[10:11]
	global_load_dwordx4 v[172:175], v[172:173], off
	v_add_u32_e32 v212, 0x16c00, v210
	v_lshl_add_u64 v[176:177], v[212:213], 1, s[6:7]
	global_load_dwordx4 v[176:179], v[176:177], off
	v_add_u32_e32 v212, 0x4000, v211
	v_lshl_add_u64 v[182:183], v[212:213], 1, s[10:11]
	global_load_dwordx4 v[182:185], v[182:183], off
	v_add_u32_e32 v212, 0x16c80, v210
	v_lshl_add_u64 v[186:187], v[212:213], 1, s[6:7]
	global_load_dwordx4 v[186:189], v[186:187], off
	v_add_u32_e32 v212, 0x4080, v211
	v_lshl_add_u64 v[190:191], v[212:213], 1, s[10:11]
	global_load_dwordx4 v[190:193], v[190:191], off
	v_add_u32_e32 v212, 0x2d800, v210
	v_lshl_add_u64 v[194:195], v[212:213], 1, s[6:7]
	global_load_dwordx4 v[194:197], v[194:195], off
	v_add_u32_e32 v212, 0x8000, v211
	v_lshl_add_u64 v[198:199], v[212:213], 1, s[10:11]
	global_load_dwordx4 v[198:201], v[198:199], off
	v_add_u32_e32 v212, 0x2d880, v210
	v_lshl_add_u64 v[202:203], v[212:213], 1, s[6:7]
	global_load_dwordx4 v[202:205], v[202:203], off
	v_add_u32_e32 v212, 0x8080, v211
	v_lshl_add_u64 v[206:207], v[212:213], 1, s[10:11]
	global_load_dwordx4 v[206:209], v[206:207], off
	v_add_u32_e32 v0, v0, v158
	v_lshl_add_u64 v[146:147], v[0:1], 1, s[10:11]
	s_mov_b32 s22, s14
	s_mov_b32 s24, s16
	s_mov_b64 s[28:29], s[20:21]
	s_waitcnt vmcnt(10)
	v_lshlrev_b32_e32 v148, 16, v130
	v_and_b32_e32 v149, 0xffff0000, v130
	v_lshlrev_b32_e32 v151, 16, v131
	v_and_b32_e32 v163, 0xffff0000, v131
	v_lshlrev_b32_e32 v150, 16, v132
	v_and_b32_e32 v161, 0xffff0000, v132
	v_lshlrev_b32_e32 v164, 16, v133
	v_and_b32_e32 v165, 0xffff0000, v133
	global_load_dwordx4 v[130:133], v[146:147], off
	v_mul_f32_e32 v0, 0xbfb8aa3b, v148
	v_exp_f32_e32 v160, v0
	v_mul_f32_e32 v0, 0xbfb8aa3b, v150
	v_exp_f32_e32 v150, v0
	v_mul_f32_e32 v0, 0xbfb8aa3b, v149
	v_exp_f32_e32 v162, v0
	v_mul_f32_e32 v0, 0xbfb8aa3b, v161
	v_exp_f32_e32 v148, v0
	v_mul_f32_e32 v0, 0xbfb8aa3b, v151
	v_exp_f32_e32 v161, v0
	v_mul_f32_e32 v0, 0xbfb8aa3b, v164
	v_exp_f32_e32 v151, v0
	v_mul_f32_e32 v0, 0xbfb8aa3b, v163
	v_exp_f32_e32 v163, v0
	v_mul_f32_e32 v0, 0xbfb8aa3b, v165
	v_pk_add_f32 v[160:161], v[160:161], 1.0 op_sel_hi:[1,0]
	v_exp_f32_e32 v149, v0
	v_pk_add_f32 v[162:163], v[162:163], 1.0 op_sel_hi:[1,0]
	v_rcp_f32_e32 v161, v161
	s_nop 0
	s_waitcnt vmcnt(0)
	v_lshlrev_b32_e32 v165, 16, v131
	v_rcp_f32_e32 v160, v160
	s_nop 0
	v_mov_b32_e32 v166, v126
	v_mov_b32_e32 v167, v128
	v_lshlrev_b32_e32 v164, 16, v130
	v_pk_fma_f32 v[160:161], v[166:167], v[160:161], v[164:165]
	v_rcp_f32_e32 v163, v163
	s_nop 0
	v_and_b32_e32 v131, 0xffff0000, v131
	v_and_b32_e32 v130, 0xffff0000, v130
	v_rcp_f32_e32 v162, v162
	s_nop 0
	v_mov_b32_e32 v128, v127
	v_pk_fma_f32 v[126:127], v[128:129], v[162:163], v[130:131]
	v_cvt_pk_bf16_f32 v0, v160, v161
	v_cvt_pk_bf16_f32 v126, v126, v127
	v_and_b32_e32 v127, 0xffff0000, v126
	v_lshlrev_b32_e32 v126, 16, v126
	v_lshlrev_b32_e32 v131, 16, v133
	v_lshlrev_b32_e32 v130, 16, v132
	v_and_b32_e32 v129, 0xffff0000, v133
	v_and_b32_e32 v128, 0xffff0000, v132
	v_pk_add_f32 v[132:133], v[150:151], 1.0 op_sel_hi:[1,0]
	v_or_b32_sdwa v127, v127, v0 dst_sel:DWORD dst_unused:UNUSED_PAD src0_sel:DWORD src1_sel:WORD_1
	v_or_b32_sdwa v126, v126, v0 dst_sel:DWORD dst_unused:UNUSED_PAD src0_sel:DWORD src1_sel:WORD_0
	s_nop 0
	v_rcp_f32_e32 v133, v133
	s_nop 0
	s_nop 0
	v_rcp_f32_e32 v132, v132
	s_nop 0
	v_mov_b32_e32 v150, v122
	v_mov_b32_e32 v151, v124
	v_pk_fma_f32 v[130:131], v[150:151], v[132:133], v[130:131]
	v_pk_add_f32 v[132:133], v[148:149], 1.0 op_sel_hi:[1,0]
	s_nop 0
	s_nop 0
	v_rcp_f32_e32 v133, v133
	s_nop 0
	s_nop 0
	v_rcp_f32_e32 v132, v132
	s_nop 0
	v_mov_b32_e32 v124, v123
	v_pk_fma_f32 v[122:123], v[124:125], v[132:133], v[128:129]
	v_cvt_pk_bf16_f32 v0, v130, v131
	v_cvt_pk_bf16_f32 v122, v122, v123
	v_and_b32_e32 v123, 0xffff0000, v122
	v_lshlrev_b32_e32 v122, 16, v122
	v_or_b32_sdwa v129, v123, v0 dst_sel:DWORD dst_unused:UNUSED_PAD src0_sel:DWORD src1_sel:WORD_1
	v_or_b32_sdwa v128, v122, v0 dst_sel:DWORD dst_unused:UNUSED_PAD src0_sel:DWORD src1_sel:WORD_0
	global_store_dwordx4 v[146:147], v[126:129], off
	s_nop 1
	v_add_u32_e32 v126, 0x80, v156
	v_add_u32_e32 v0, v157, v126
	v_add_u32_e32 v0, v0, v158
	s_waitcnt vmcnt(11)
	v_lshlrev_b32_e32 v127, 16, v168
	v_and_b32_e32 v133, 0xffff0000, v168
	v_lshlrev_b32_e32 v147, 16, v169
	v_and_b32_e32 v149, 0xffff0000, v169
	v_lshl_add_u64 v[122:123], v[0:1], 1, s[10:11]
	v_lshlrev_b32_e32 v146, 16, v170
	v_mul_f32_e32 v0, 0xbfb8aa3b, v127
	v_exp_f32_e32 v132, v0
	v_mul_f32_e32 v0, 0xbfb8aa3b, v146
	v_and_b32_e32 v124, 0xffff0000, v170
	v_exp_f32_e32 v146, v0
	v_mul_f32_e32 v0, 0xbfb8aa3b, v133
	v_exp_f32_e32 v148, v0
	v_mul_f32_e32 v0, 0xbfb8aa3b, v124
	v_exp_f32_e32 v124, v0
	v_mul_f32_e32 v0, 0xbfb8aa3b, v147
	v_exp_f32_e32 v133, v0
	v_lshlrev_b32_e32 v150, 16, v171
	v_mul_f32_e32 v0, 0xbfb8aa3b, v150
	v_and_b32_e32 v125, 0xffff0000, v171
	v_exp_f32_e32 v147, v0
	v_mul_f32_e32 v0, 0xbfb8aa3b, v149
	v_exp_f32_e32 v149, v0
	v_mul_f32_e32 v0, 0xbfb8aa3b, v125
	v_pk_add_f32 v[132:133], v[132:133], 1.0 op_sel_hi:[1,0]
	v_exp_f32_e32 v125, v0
	v_pk_add_f32 v[148:149], v[148:149], 1.0 op_sel_hi:[1,0]
	v_pk_add_f32 v[124:125], v[124:125], 1.0 op_sel_hi:[1,0]
	v_rcp_f32_e32 v133, v133
	s_nop 0
	s_waitcnt vmcnt(10)
	v_lshlrev_b32_e32 v151, 16, v173
	v_rcp_f32_e32 v132, v132
	s_nop 0
	v_mov_b32_e32 v160, v118
	v_mov_b32_e32 v161, v120
	v_lshlrev_b32_e32 v150, 16, v172
	v_pk_fma_f32 v[132:133], v[160:161], v[132:133], v[150:151]
	v_rcp_f32_e32 v149, v149
	s_nop 0
	v_and_b32_e32 v129, 0xffff0000, v173
	v_and_b32_e32 v128, 0xffff0000, v172
	v_rcp_f32_e32 v148, v148
	s_nop 0
	v_mov_b32_e32 v120, v119
	v_pk_fma_f32 v[118:119], v[120:121], v[148:149], v[128:129]
	v_cvt_pk_bf16_f32 v0, v132, v133
	v_cvt_pk_bf16_f32 v118, v118, v119
	v_and_b32_e32 v119, 0xffff0000, v118
	v_lshlrev_b32_e32 v118, 16, v118
	v_lshlrev_b32_e32 v121, 16, v175
	v_lshlrev_b32_e32 v120, 16, v174
	v_and_b32_e32 v129, 0xffff0000, v175
	v_and_b32_e32 v128, 0xffff0000, v174
	v_pk_add_f32 v[130:131], v[146:147], 1.0 op_sel_hi:[1,0]
	v_or_b32_sdwa v119, v119, v0 dst_sel:DWORD dst_unused:UNUSED_PAD src0_sel:DWORD src1_sel:WORD_1
	v_or_b32_sdwa v118, v118, v0 dst_sel:DWORD dst_unused:UNUSED_PAD src0_sel:DWORD src1_sel:WORD_0
	s_nop 0
	v_rcp_f32_e32 v131, v131
	s_nop 0
	s_nop 0
	v_rcp_f32_e32 v130, v130
	s_nop 0
	v_mov_b32_e32 v132, v114
	v_mov_b32_e32 v133, v116
	v_pk_fma_f32 v[120:121], v[132:133], v[130:131], v[120:121]
	v_rcp_f32_e32 v125, v125
	s_nop 0
	s_nop 0
	v_rcp_f32_e32 v124, v124
	s_nop 0
	v_mov_b32_e32 v116, v115
	v_pk_fma_f32 v[114:115], v[116:117], v[124:125], v[128:129]
	v_cvt_pk_bf16_f32 v0, v120, v121
	v_cvt_pk_bf16_f32 v114, v114, v115
	v_and_b32_e32 v115, 0xffff0000, v114
	v_lshlrev_b32_e32 v114, 16, v114
	v_add_u32_e32 v127, 0x16c00, v157
	v_or_b32_sdwa v121, v115, v0 dst_sel:DWORD dst_unused:UNUSED_PAD src0_sel:DWORD src1_sel:WORD_1
	v_or_b32_sdwa v120, v114, v0 dst_sel:DWORD dst_unused:UNUSED_PAD src0_sel:DWORD src1_sel:WORD_0
	v_add_u32_e32 v0, v127, v156
	v_add_u32_e32 v212, 0x44400, v210
	v_lshl_add_u64 v[168:169], v[212:213], 1, s[6:7]
	global_load_dwordx4 v[168:171], v[168:169], off
	v_add_u32_e32 v212, 0xc000, v211
	v_lshl_add_u64 v[172:173], v[212:213], 1, s[10:11]
	global_load_dwordx4 v[172:175], v[172:173], off
	global_store_dwordx4 v[122:123], v[118:121], off
	s_nop 1
	v_or_b32_e32 v118, 16, v159
	v_mul_lo_u32 v146, v118, s61
	v_add_u32_e32 v0, v0, v146
	s_waitcnt vmcnt(12)
	v_lshlrev_b32_e32 v122, 16, v176
	v_and_b32_e32 v123, 0xffff0000, v176
	v_lshlrev_b32_e32 v125, 16, v177
	v_and_b32_e32 v129, 0xffff0000, v177
	v_lshl_add_u64 v[114:115], v[0:1], 1, s[10:11]
	v_lshlrev_b32_e32 v124, 16, v178
	v_mul_f32_e32 v0, 0xbfb8aa3b, v122
	v_exp_f32_e32 v122, v0
	v_mul_f32_e32 v0, 0xbfb8aa3b, v124
	v_and_b32_e32 v116, 0xffff0000, v178
	v_exp_f32_e32 v124, v0
	v_mul_f32_e32 v0, 0xbfb8aa3b, v123
	v_exp_f32_e32 v128, v0
	v_mul_f32_e32 v0, 0xbfb8aa3b, v116
	v_exp_f32_e32 v116, v0
	v_mul_f32_e32 v0, 0xbfb8aa3b, v125
	v_exp_f32_e32 v123, v0
	v_lshlrev_b32_e32 v130, 16, v179
	v_mul_f32_e32 v0, 0xbfb8aa3b, v130
	v_and_b32_e32 v117, 0xffff0000, v179
	v_exp_f32_e32 v125, v0
	v_mul_f32_e32 v0, 0xbfb8aa3b, v129
	v_exp_f32_e32 v129, v0
	v_mul_f32_e32 v0, 0xbfb8aa3b, v117
	v_pk_add_f32 v[122:123], v[122:123], 1.0 op_sel_hi:[1,0]
	v_exp_f32_e32 v117, v0
	v_pk_add_f32 v[128:129], v[128:129], 1.0 op_sel_hi:[1,0]
	v_pk_add_f32 v[116:117], v[116:117], 1.0 op_sel_hi:[1,0]
	v_rcp_f32_e32 v123, v123
	s_nop 0
	s_waitcnt vmcnt(11)
	v_lshlrev_b32_e32 v131, 16, v183
	v_rcp_f32_e32 v122, v122
	s_nop 0
	v_mov_b32_e32 v132, v110
	v_mov_b32_e32 v133, v112
	v_lshlrev_b32_e32 v130, 16, v182
	v_pk_fma_f32 v[122:123], v[132:133], v[122:123], v[130:131]
	v_rcp_f32_e32 v129, v129
	s_nop 0
	v_and_b32_e32 v119, 0xffff0000, v183
	v_and_b32_e32 v118, 0xffff0000, v182
	v_rcp_f32_e32 v128, v128
	s_nop 0
	v_mov_b32_e32 v112, v111
	v_pk_fma_f32 v[110:111], v[112:113], v[128:129], v[118:119]
	v_cvt_pk_bf16_f32 v0, v122, v123
	v_cvt_pk_bf16_f32 v110, v110, v111
	v_and_b32_e32 v111, 0xffff0000, v110
	v_lshlrev_b32_e32 v110, 16, v110
	v_lshlrev_b32_e32 v113, 16, v185
	v_lshlrev_b32_e32 v112, 16, v184
	v_and_b32_e32 v119, 0xffff0000, v185
	v_and_b32_e32 v118, 0xffff0000, v184
	v_pk_add_f32 v[120:121], v[124:125], 1.0 op_sel_hi:[1,0]
	v_or_b32_sdwa v111, v111, v0 dst_sel:DWORD dst_unused:UNUSED_PAD src0_sel:DWORD src1_sel:WORD_1
	v_or_b32_sdwa v110, v110, v0 dst_sel:DWORD dst_unused:UNUSED_PAD src0_sel:DWORD src1_sel:WORD_0
	s_nop 0
	v_rcp_f32_e32 v121, v121
	s_nop 0
	s_nop 0
	v_rcp_f32_e32 v120, v120
	s_nop 0
	v_mov_b32_e32 v122, v106
	v_mov_b32_e32 v123, v108
	v_pk_fma_f32 v[112:113], v[122:123], v[120:121], v[112:113]
	v_rcp_f32_e32 v117, v117
	s_nop 0
	s_nop 0
	v_rcp_f32_e32 v116, v116
	s_nop 0
	v_mov_b32_e32 v108, v107
	v_pk_fma_f32 v[106:107], v[108:109], v[116:117], v[118:119]
	v_cvt_pk_bf16_f32 v0, v112, v113
	v_cvt_pk_bf16_f32 v106, v106, v107
	v_and_b32_e32 v107, 0xffff0000, v106
	v_lshlrev_b32_e32 v106, 16, v106
	v_or_b32_sdwa v113, v107, v0 dst_sel:DWORD dst_unused:UNUSED_PAD src0_sel:DWORD src1_sel:WORD_1
	v_or_b32_sdwa v112, v106, v0 dst_sel:DWORD dst_unused:UNUSED_PAD src0_sel:DWORD src1_sel:WORD_0
	v_add_u32_e32 v0, v127, v126
	v_add_u32_e32 v212, 0x44480, v210
	v_lshl_add_u64 v[176:177], v[212:213], 1, s[6:7]
	global_load_dwordx4 v[176:179], v[176:177], off
	v_add_u32_e32 v212, 0xc080, v211
	v_lshl_add_u64 v[182:183], v[212:213], 1, s[10:11]
	global_load_dwordx4 v[182:185], v[182:183], off
	global_store_dwordx4 v[114:115], v[110:113], off
	v_add_u32_e32 v0, v0, v146
	s_waitcnt vmcnt(13)
	v_lshlrev_b32_e32 v114, 16, v186
	v_and_b32_e32 v115, 0xffff0000, v186
	v_lshlrev_b32_e32 v117, 16, v187
	v_and_b32_e32 v119, 0xffff0000, v187
	v_lshl_add_u64 v[106:107], v[0:1], 1, s[10:11]
	v_lshlrev_b32_e32 v116, 16, v188
	v_mul_f32_e32 v0, 0xbfb8aa3b, v114
	v_exp_f32_e32 v114, v0
	v_mul_f32_e32 v0, 0xbfb8aa3b, v116
	v_and_b32_e32 v108, 0xffff0000, v188
	v_exp_f32_e32 v116, v0
	v_mul_f32_e32 v0, 0xbfb8aa3b, v115
	v_exp_f32_e32 v118, v0
	v_mul_f32_e32 v0, 0xbfb8aa3b, v108
	v_exp_f32_e32 v108, v0
	v_mul_f32_e32 v0, 0xbfb8aa3b, v117
	v_exp_f32_e32 v115, v0
	v_lshlrev_b32_e32 v120, 16, v189
	v_mul_f32_e32 v0, 0xbfb8aa3b, v120
	v_and_b32_e32 v109, 0xffff0000, v189
	v_exp_f32_e32 v117, v0
	v_mul_f32_e32 v0, 0xbfb8aa3b, v119
	v_exp_f32_e32 v119, v0
	v_mul_f32_e32 v0, 0xbfb8aa3b, v109
	v_pk_add_f32 v[114:115], v[114:115], 1.0 op_sel_hi:[1,0]
	v_exp_f32_e32 v109, v0
	v_pk_add_f32 v[118:119], v[118:119], 1.0 op_sel_hi:[1,0]
	v_pk_add_f32 v[108:109], v[108:109], 1.0 op_sel_hi:[1,0]
	v_rcp_f32_e32 v115, v115
	s_nop 0
	s_waitcnt vmcnt(12)
	v_lshlrev_b32_e32 v121, 16, v191
	v_rcp_f32_e32 v114, v114
	s_nop 0
	v_mov_b32_e32 v122, v102
	v_mov_b32_e32 v123, v104
	v_lshlrev_b32_e32 v120, 16, v190
	v_pk_fma_f32 v[114:115], v[122:123], v[114:115], v[120:121]
	v_rcp_f32_e32 v119, v119
	s_nop 0
	v_and_b32_e32 v111, 0xffff0000, v191
	v_and_b32_e32 v110, 0xffff0000, v190
	v_rcp_f32_e32 v118, v118
	s_nop 0
	v_mov_b32_e32 v104, v103
	v_pk_fma_f32 v[102:103], v[104:105], v[118:119], v[110:111]
	v_cvt_pk_bf16_f32 v0, v114, v115
	v_cvt_pk_bf16_f32 v102, v102, v103
	v_and_b32_e32 v103, 0xffff0000, v102
	v_lshlrev_b32_e32 v102, 16, v102
	v_lshlrev_b32_e32 v105, 16, v193
	v_lshlrev_b32_e32 v104, 16, v192
	v_and_b32_e32 v111, 0xffff0000, v193
	v_and_b32_e32 v110, 0xffff0000, v192
	v_pk_add_f32 v[112:113], v[116:117], 1.0 op_sel_hi:[1,0]
	v_or_b32_sdwa v103, v103, v0 dst_sel:DWORD dst_unused:UNUSED_PAD src0_sel:DWORD src1_sel:WORD_1
	v_or_b32_sdwa v102, v102, v0 dst_sel:DWORD dst_unused:UNUSED_PAD src0_sel:DWORD src1_sel:WORD_0
	s_nop 0
	v_rcp_f32_e32 v113, v113
	s_nop 0
	s_nop 0
	v_rcp_f32_e32 v112, v112
	s_nop 0
	v_mov_b32_e32 v114, v98
	v_mov_b32_e32 v115, v100
	v_pk_fma_f32 v[104:105], v[114:115], v[112:113], v[104:105]
	v_add_u32_e32 v116, 0x2d800, v157
	v_rcp_f32_e32 v109, v109
	s_nop 0
	s_nop 0
	v_rcp_f32_e32 v108, v108
	s_nop 0
	v_mov_b32_e32 v100, v99
	v_pk_fma_f32 v[98:99], v[100:101], v[108:109], v[110:111]
	v_cvt_pk_bf16_f32 v0, v104, v105
	v_cvt_pk_bf16_f32 v98, v98, v99
	v_and_b32_e32 v99, 0xffff0000, v98
	v_lshlrev_b32_e32 v98, 16, v98
	v_or_b32_sdwa v105, v99, v0 dst_sel:DWORD dst_unused:UNUSED_PAD src0_sel:DWORD src1_sel:WORD_1
	v_or_b32_sdwa v104, v98, v0 dst_sel:DWORD dst_unused:UNUSED_PAD src0_sel:DWORD src1_sel:WORD_0
	v_add_u32_e32 v0, v116, v156
	v_add_u32_e32 v212, 0xb6000, v210
	v_lshl_add_u64 v[186:187], v[212:213], 1, s[6:7]
	global_load_dwordx4 v[186:189], v[186:187], off
	v_add_u32_e32 v212, 0x20000, v211
	v_lshl_add_u64 v[190:191], v[212:213], 1, s[10:11]
	global_load_dwordx4 v[190:193], v[190:191], off
	global_store_dwordx4 v[106:107], v[102:105], off
	s_nop 1
	v_or_b32_e32 v102, 32, v159
	v_mul_lo_u32 v117, v102, s61
	v_add_u32_e32 v0, v0, v117
	s_waitcnt vmcnt(14)
	v_lshlrev_b32_e32 v106, 16, v194
	v_and_b32_e32 v107, 0xffff0000, v194
	v_lshlrev_b32_e32 v109, 16, v195
	v_and_b32_e32 v111, 0xffff0000, v195
	v_lshl_add_u64 v[98:99], v[0:1], 1, s[10:11]
	v_lshlrev_b32_e32 v108, 16, v196
	v_mul_f32_e32 v0, 0xbfb8aa3b, v106
	v_exp_f32_e32 v106, v0
	v_mul_f32_e32 v0, 0xbfb8aa3b, v108
	v_and_b32_e32 v100, 0xffff0000, v196
	v_exp_f32_e32 v108, v0
	v_mul_f32_e32 v0, 0xbfb8aa3b, v107
	v_exp_f32_e32 v110, v0
	v_mul_f32_e32 v0, 0xbfb8aa3b, v100
	v_exp_f32_e32 v100, v0
	v_mul_f32_e32 v0, 0xbfb8aa3b, v109
	v_exp_f32_e32 v107, v0
	v_lshlrev_b32_e32 v112, 16, v197
	v_mul_f32_e32 v0, 0xbfb8aa3b, v112
	v_and_b32_e32 v101, 0xffff0000, v197
	v_exp_f32_e32 v109, v0
	v_mul_f32_e32 v0, 0xbfb8aa3b, v111
	v_exp_f32_e32 v111, v0
	v_mul_f32_e32 v0, 0xbfb8aa3b, v101
	v_pk_add_f32 v[106:107], v[106:107], 1.0 op_sel_hi:[1,0]
	v_exp_f32_e32 v101, v0
	v_pk_add_f32 v[110:111], v[110:111], 1.0 op_sel_hi:[1,0]
	v_pk_add_f32 v[100:101], v[100:101], 1.0 op_sel_hi:[1,0]
	v_rcp_f32_e32 v107, v107
	s_nop 0
	s_waitcnt vmcnt(13)
	v_lshlrev_b32_e32 v113, 16, v199
	v_rcp_f32_e32 v106, v106
	s_nop 0
	v_mov_b32_e32 v114, v94
	v_mov_b32_e32 v115, v96
	v_lshlrev_b32_e32 v112, 16, v198
	v_pk_fma_f32 v[106:107], v[114:115], v[106:107], v[112:113]
	v_rcp_f32_e32 v111, v111
	s_nop 0
	v_and_b32_e32 v103, 0xffff0000, v199
	v_and_b32_e32 v102, 0xffff0000, v198
	v_rcp_f32_e32 v110, v110
	s_nop 0
	v_mov_b32_e32 v96, v95
	v_pk_fma_f32 v[94:95], v[96:97], v[110:111], v[102:103]
	v_cvt_pk_bf16_f32 v0, v106, v107
	v_cvt_pk_bf16_f32 v94, v94, v95
	v_and_b32_e32 v95, 0xffff0000, v94
	v_lshlrev_b32_e32 v94, 16, v94
	v_lshlrev_b32_e32 v97, 16, v201
	v_lshlrev_b32_e32 v96, 16, v200
	v_and_b32_e32 v103, 0xffff0000, v201
	v_and_b32_e32 v102, 0xffff0000, v200
	v_pk_add_f32 v[104:105], v[108:109], 1.0 op_sel_hi:[1,0]
	v_or_b32_sdwa v95, v95, v0 dst_sel:DWORD dst_unused:UNUSED_PAD src0_sel:DWORD src1_sel:WORD_1
	v_or_b32_sdwa v94, v94, v0 dst_sel:DWORD dst_unused:UNUSED_PAD src0_sel:DWORD src1_sel:WORD_0
	s_nop 0
	v_rcp_f32_e32 v105, v105
	s_nop 0
	s_nop 0
	v_rcp_f32_e32 v104, v104
	s_nop 0
	v_mov_b32_e32 v106, v90
	v_mov_b32_e32 v107, v92
	v_pk_fma_f32 v[96:97], v[106:107], v[104:105], v[96:97]
	v_rcp_f32_e32 v101, v101
	s_nop 0
	s_nop 0
	v_rcp_f32_e32 v100, v100
	s_nop 0
	v_mov_b32_e32 v92, v91
	v_pk_fma_f32 v[90:91], v[92:93], v[100:101], v[102:103]
	v_cvt_pk_bf16_f32 v0, v96, v97
	v_cvt_pk_bf16_f32 v90, v90, v91
	v_and_b32_e32 v91, 0xffff0000, v90
	v_lshlrev_b32_e32 v90, 16, v90
	v_or_b32_sdwa v97, v91, v0 dst_sel:DWORD dst_unused:UNUSED_PAD src0_sel:DWORD src1_sel:WORD_1
	v_or_b32_sdwa v96, v90, v0 dst_sel:DWORD dst_unused:UNUSED_PAD src0_sel:DWORD src1_sel:WORD_0
	v_add_u32_e32 v0, v116, v126
	v_add_u32_e32 v212, 0xb6080, v210
	v_lshl_add_u64 v[194:195], v[212:213], 1, s[6:7]
	global_load_dwordx4 v[194:197], v[194:195], off
	v_add_u32_e32 v212, 0x20080, v211
	v_lshl_add_u64 v[198:199], v[212:213], 1, s[10:11]
	global_load_dwordx4 v[198:201], v[198:199], off
	global_store_dwordx4 v[98:99], v[94:97], off
	v_add_u32_e32 v0, v0, v117
	s_waitcnt vmcnt(15)
	v_lshlrev_b32_e32 v98, 16, v202
	v_and_b32_e32 v99, 0xffff0000, v202
	v_lshlrev_b32_e32 v101, 16, v203
	v_and_b32_e32 v103, 0xffff0000, v203
	v_lshl_add_u64 v[90:91], v[0:1], 1, s[10:11]
	v_lshlrev_b32_e32 v100, 16, v204
	v_mul_f32_e32 v0, 0xbfb8aa3b, v98
	v_exp_f32_e32 v98, v0
	v_mul_f32_e32 v0, 0xbfb8aa3b, v100
	v_and_b32_e32 v92, 0xffff0000, v204
	v_exp_f32_e32 v100, v0
	v_mul_f32_e32 v0, 0xbfb8aa3b, v99
	v_exp_f32_e32 v102, v0
	v_mul_f32_e32 v0, 0xbfb8aa3b, v92
	v_exp_f32_e32 v92, v0
	v_mul_f32_e32 v0, 0xbfb8aa3b, v101
	v_exp_f32_e32 v99, v0
	v_lshlrev_b32_e32 v104, 16, v205
	v_mul_f32_e32 v0, 0xbfb8aa3b, v104
	v_and_b32_e32 v93, 0xffff0000, v205
	v_exp_f32_e32 v101, v0
	v_mul_f32_e32 v0, 0xbfb8aa3b, v103
	v_exp_f32_e32 v103, v0
	v_mul_f32_e32 v0, 0xbfb8aa3b, v93
	v_pk_add_f32 v[98:99], v[98:99], 1.0 op_sel_hi:[1,0]
	v_exp_f32_e32 v93, v0
	v_pk_add_f32 v[102:103], v[102:103], 1.0 op_sel_hi:[1,0]
	v_pk_add_f32 v[92:93], v[92:93], 1.0 op_sel_hi:[1,0]
	v_rcp_f32_e32 v99, v99
	s_nop 0
	s_waitcnt vmcnt(14)
	v_lshlrev_b32_e32 v105, 16, v207
	v_rcp_f32_e32 v98, v98
	s_nop 0
	v_mov_b32_e32 v106, v86
	v_mov_b32_e32 v107, v88
	v_lshlrev_b32_e32 v104, 16, v206
	v_pk_fma_f32 v[98:99], v[106:107], v[98:99], v[104:105]
	v_rcp_f32_e32 v103, v103
	s_nop 0
	v_and_b32_e32 v95, 0xffff0000, v207
	v_and_b32_e32 v94, 0xffff0000, v206
	v_rcp_f32_e32 v102, v102
	s_nop 0
	v_mov_b32_e32 v88, v87
	v_pk_fma_f32 v[86:87], v[88:89], v[102:103], v[94:95]
	v_cvt_pk_bf16_f32 v0, v98, v99
	v_cvt_pk_bf16_f32 v86, v86, v87
	v_and_b32_e32 v87, 0xffff0000, v86
	v_lshlrev_b32_e32 v86, 16, v86
	v_lshlrev_b32_e32 v89, 16, v209
	v_lshlrev_b32_e32 v88, 16, v208
	v_and_b32_e32 v95, 0xffff0000, v209
	v_and_b32_e32 v94, 0xffff0000, v208
	v_pk_add_f32 v[96:97], v[100:101], 1.0 op_sel_hi:[1,0]
	v_or_b32_sdwa v87, v87, v0 dst_sel:DWORD dst_unused:UNUSED_PAD src0_sel:DWORD src1_sel:WORD_1
	v_or_b32_sdwa v86, v86, v0 dst_sel:DWORD dst_unused:UNUSED_PAD src0_sel:DWORD src1_sel:WORD_0
	s_nop 0
	v_rcp_f32_e32 v97, v97
	s_nop 0
	s_nop 0
	v_rcp_f32_e32 v96, v96
	s_nop 0
	v_mov_b32_e32 v98, v82
	v_mov_b32_e32 v99, v84
	v_pk_fma_f32 v[88:89], v[98:99], v[96:97], v[88:89]
	v_add_u32_e32 v100, 0x44400, v157
	v_rcp_f32_e32 v93, v93
	s_nop 0
	s_nop 0
	v_rcp_f32_e32 v92, v92
	s_nop 0
	v_mov_b32_e32 v84, v83
	v_pk_fma_f32 v[82:83], v[84:85], v[92:93], v[94:95]
	v_cvt_pk_bf16_f32 v0, v88, v89
	v_cvt_pk_bf16_f32 v82, v82, v83
	v_and_b32_e32 v83, 0xffff0000, v82
	v_lshlrev_b32_e32 v82, 16, v82
	v_or_b32_sdwa v89, v83, v0 dst_sel:DWORD dst_unused:UNUSED_PAD src0_sel:DWORD src1_sel:WORD_1
	v_or_b32_sdwa v88, v82, v0 dst_sel:DWORD dst_unused:UNUSED_PAD src0_sel:DWORD src1_sel:WORD_0
	v_add_u32_e32 v0, v100, v156
	v_add_u32_e32 v212, 0xccc00, v210
	v_lshl_add_u64 v[202:203], v[212:213], 1, s[6:7]
	global_load_dwordx4 v[202:205], v[202:203], off
	v_add_u32_e32 v212, 0x24000, v211
	v_lshl_add_u64 v[206:207], v[212:213], 1, s[10:11]
	global_load_dwordx4 v[206:209], v[206:207], off
	global_store_dwordx4 v[90:91], v[86:89], off
	s_nop 1
	v_or_b32_e32 v86, 48, v159
	v_mul_lo_u32 v101, v86, s61
	v_add_u32_e32 v0, v0, v101
	s_waitcnt vmcnt(14)
	v_lshlrev_b32_e32 v90, 16, v168
	v_and_b32_e32 v91, 0xffff0000, v168
	v_lshlrev_b32_e32 v93, 16, v169
	v_and_b32_e32 v95, 0xffff0000, v169
	v_lshl_add_u64 v[82:83], v[0:1], 1, s[10:11]
	v_lshlrev_b32_e32 v92, 16, v170
	v_mul_f32_e32 v0, 0xbfb8aa3b, v90
	v_exp_f32_e32 v90, v0
	v_mul_f32_e32 v0, 0xbfb8aa3b, v92
	v_and_b32_e32 v84, 0xffff0000, v170
	v_exp_f32_e32 v92, v0
	v_mul_f32_e32 v0, 0xbfb8aa3b, v91
	v_exp_f32_e32 v94, v0
	v_mul_f32_e32 v0, 0xbfb8aa3b, v84
	v_exp_f32_e32 v84, v0
	v_mul_f32_e32 v0, 0xbfb8aa3b, v93
	v_exp_f32_e32 v91, v0
	v_lshlrev_b32_e32 v96, 16, v171
	v_mul_f32_e32 v0, 0xbfb8aa3b, v96
	v_and_b32_e32 v85, 0xffff0000, v171
	v_exp_f32_e32 v93, v0
	v_mul_f32_e32 v0, 0xbfb8aa3b, v95
	v_exp_f32_e32 v95, v0
	v_mul_f32_e32 v0, 0xbfb8aa3b, v85
	v_pk_add_f32 v[90:91], v[90:91], 1.0 op_sel_hi:[1,0]
	v_exp_f32_e32 v85, v0
	v_pk_add_f32 v[94:95], v[94:95], 1.0 op_sel_hi:[1,0]
	v_pk_add_f32 v[84:85], v[84:85], 1.0 op_sel_hi:[1,0]
	v_rcp_f32_e32 v91, v91
	s_nop 0
	s_waitcnt vmcnt(13)
	v_lshlrev_b32_e32 v97, 16, v173
	v_rcp_f32_e32 v90, v90
	s_nop 0
	v_mov_b32_e32 v98, v78
	v_mov_b32_e32 v99, v80
	v_lshlrev_b32_e32 v96, 16, v172
	v_pk_fma_f32 v[90:91], v[98:99], v[90:91], v[96:97]
	v_rcp_f32_e32 v95, v95
	s_nop 0
	v_and_b32_e32 v87, 0xffff0000, v173
	v_and_b32_e32 v86, 0xffff0000, v172
	v_rcp_f32_e32 v94, v94
	s_nop 0
	v_mov_b32_e32 v80, v79
	v_pk_fma_f32 v[78:79], v[80:81], v[94:95], v[86:87]
	v_cvt_pk_bf16_f32 v0, v90, v91
	v_cvt_pk_bf16_f32 v78, v78, v79
	v_and_b32_e32 v79, 0xffff0000, v78
	v_lshlrev_b32_e32 v78, 16, v78
	v_lshlrev_b32_e32 v81, 16, v175
	v_lshlrev_b32_e32 v80, 16, v174
	v_and_b32_e32 v87, 0xffff0000, v175
	v_and_b32_e32 v86, 0xffff0000, v174
	v_pk_add_f32 v[88:89], v[92:93], 1.0 op_sel_hi:[1,0]
	v_or_b32_sdwa v79, v79, v0 dst_sel:DWORD dst_unused:UNUSED_PAD src0_sel:DWORD src1_sel:WORD_1
	v_or_b32_sdwa v78, v78, v0 dst_sel:DWORD dst_unused:UNUSED_PAD src0_sel:DWORD src1_sel:WORD_0
	s_nop 0
	v_rcp_f32_e32 v89, v89
	s_nop 0
	s_nop 0
	v_rcp_f32_e32 v88, v88
	s_nop 0
	v_mov_b32_e32 v90, v74
	v_mov_b32_e32 v91, v76
	v_pk_fma_f32 v[80:81], v[90:91], v[88:89], v[80:81]
	v_rcp_f32_e32 v85, v85
	s_nop 0
	s_nop 0
	v_rcp_f32_e32 v84, v84
	s_nop 0
	v_mov_b32_e32 v76, v75
	v_pk_fma_f32 v[74:75], v[76:77], v[84:85], v[86:87]
	v_cvt_pk_bf16_f32 v0, v80, v81
	v_cvt_pk_bf16_f32 v74, v74, v75
	v_and_b32_e32 v75, 0xffff0000, v74
	v_lshlrev_b32_e32 v74, 16, v74
	v_or_b32_sdwa v81, v75, v0 dst_sel:DWORD dst_unused:UNUSED_PAD src0_sel:DWORD src1_sel:WORD_1
	v_or_b32_sdwa v80, v74, v0 dst_sel:DWORD dst_unused:UNUSED_PAD src0_sel:DWORD src1_sel:WORD_0
	v_add_u32_e32 v0, v100, v126
	v_add_u32_e32 v212, 0xccc80, v210
	v_lshl_add_u64 v[168:169], v[212:213], 1, s[6:7]
	global_load_dwordx4 v[168:171], v[168:169], off
	v_add_u32_e32 v212, 0x24080, v211
	v_lshl_add_u64 v[172:173], v[212:213], 1, s[10:11]
	global_load_dwordx4 v[172:175], v[172:173], off
	global_store_dwordx4 v[82:83], v[78:81], off
	v_add_u32_e32 v0, v0, v101
	s_waitcnt vmcnt(14)
	v_lshlrev_b32_e32 v82, 16, v176
	v_and_b32_e32 v83, 0xffff0000, v176
	v_lshlrev_b32_e32 v85, 16, v177
	v_and_b32_e32 v87, 0xffff0000, v177
	v_lshl_add_u64 v[74:75], v[0:1], 1, s[10:11]
	v_lshlrev_b32_e32 v84, 16, v178
	v_mul_f32_e32 v0, 0xbfb8aa3b, v82
	v_exp_f32_e32 v82, v0
	v_mul_f32_e32 v0, 0xbfb8aa3b, v84
	v_and_b32_e32 v76, 0xffff0000, v178
	v_exp_f32_e32 v84, v0
	v_mul_f32_e32 v0, 0xbfb8aa3b, v83
	v_exp_f32_e32 v86, v0
	v_mul_f32_e32 v0, 0xbfb8aa3b, v76
	v_exp_f32_e32 v76, v0
	v_mul_f32_e32 v0, 0xbfb8aa3b, v85
	v_exp_f32_e32 v83, v0
	v_lshlrev_b32_e32 v88, 16, v179
	v_mul_f32_e32 v0, 0xbfb8aa3b, v88
	v_and_b32_e32 v77, 0xffff0000, v179
	v_exp_f32_e32 v85, v0
	v_mul_f32_e32 v0, 0xbfb8aa3b, v87
	v_exp_f32_e32 v87, v0
	v_mul_f32_e32 v0, 0xbfb8aa3b, v77
	v_pk_add_f32 v[82:83], v[82:83], 1.0 op_sel_hi:[1,0]
	v_exp_f32_e32 v77, v0
	v_pk_add_f32 v[86:87], v[86:87], 1.0 op_sel_hi:[1,0]
	v_pk_add_f32 v[76:77], v[76:77], 1.0 op_sel_hi:[1,0]
	v_rcp_f32_e32 v83, v83
	s_nop 0
	s_waitcnt vmcnt(13)
	v_lshlrev_b32_e32 v89, 16, v183
	v_rcp_f32_e32 v82, v82
	s_nop 0
	v_mov_b32_e32 v90, v70
	v_mov_b32_e32 v91, v72
	v_lshlrev_b32_e32 v88, 16, v182
	v_pk_fma_f32 v[82:83], v[90:91], v[82:83], v[88:89]
	v_rcp_f32_e32 v87, v87
	s_nop 0
	v_and_b32_e32 v79, 0xffff0000, v183
	v_and_b32_e32 v78, 0xffff0000, v182
	v_rcp_f32_e32 v86, v86
	s_nop 0
	v_mov_b32_e32 v72, v71
	v_pk_fma_f32 v[70:71], v[72:73], v[86:87], v[78:79]
	v_cvt_pk_bf16_f32 v0, v82, v83
	v_cvt_pk_bf16_f32 v70, v70, v71
	v_and_b32_e32 v71, 0xffff0000, v70
	v_lshlrev_b32_e32 v70, 16, v70
	v_lshlrev_b32_e32 v73, 16, v185
	v_lshlrev_b32_e32 v72, 16, v184
	v_and_b32_e32 v79, 0xffff0000, v185
	v_and_b32_e32 v78, 0xffff0000, v184
	v_pk_add_f32 v[80:81], v[84:85], 1.0 op_sel_hi:[1,0]
	v_or_b32_sdwa v71, v71, v0 dst_sel:DWORD dst_unused:UNUSED_PAD src0_sel:DWORD src1_sel:WORD_1
	v_or_b32_sdwa v70, v70, v0 dst_sel:DWORD dst_unused:UNUSED_PAD src0_sel:DWORD src1_sel:WORD_0
	s_nop 0
	v_rcp_f32_e32 v81, v81
	s_nop 0
	s_nop 0
	v_rcp_f32_e32 v80, v80
	s_nop 0
	v_mov_b32_e32 v82, v66
	v_mov_b32_e32 v83, v68
	v_pk_fma_f32 v[72:73], v[82:83], v[80:81], v[72:73]
	v_add_u32_e32 v84, 0xb6000, v157
	v_rcp_f32_e32 v77, v77
	s_nop 0
	v_add_u32_e32 v85, 0xfff6a000, v158
	v_rcp_f32_e32 v76, v76
	s_nop 0
	v_mov_b32_e32 v68, v67
	v_pk_fma_f32 v[66:67], v[68:69], v[76:77], v[78:79]
	v_cvt_pk_bf16_f32 v0, v72, v73
	v_cvt_pk_bf16_f32 v66, v66, v67
	v_and_b32_e32 v67, 0xffff0000, v66
	v_lshlrev_b32_e32 v66, 16, v66
	v_or_b32_sdwa v73, v67, v0 dst_sel:DWORD dst_unused:UNUSED_PAD src0_sel:DWORD src1_sel:WORD_1
	v_or_b32_sdwa v72, v66, v0 dst_sel:DWORD dst_unused:UNUSED_PAD src0_sel:DWORD src1_sel:WORD_0
	v_add_u32_e32 v0, v84, v156
	v_add_u32_e32 v212, 0xe3800, v210
	v_lshl_add_u64 v[176:177], v[212:213], 1, s[6:7]
	global_load_dwordx4 v[176:179], v[176:177], off
	v_add_u32_e32 v212, 0x28000, v211
	v_lshl_add_u64 v[182:183], v[212:213], 1, s[10:11]
	global_load_dwordx4 v[182:185], v[182:183], off
	global_store_dwordx4 v[74:75], v[70:73], off
	v_add_u32_e32 v0, v0, v85
	s_waitcnt vmcnt(14)
	v_lshlrev_b32_e32 v74, 16, v186
	v_and_b32_e32 v75, 0xffff0000, v186
	v_lshlrev_b32_e32 v77, 16, v187
	v_and_b32_e32 v79, 0xffff0000, v187
	v_lshl_add_u64 v[66:67], v[0:1], 1, s[10:11]
	v_lshlrev_b32_e32 v76, 16, v188
	v_mul_f32_e32 v0, 0xbfb8aa3b, v74
	v_exp_f32_e32 v74, v0
	v_mul_f32_e32 v0, 0xbfb8aa3b, v76
	v_and_b32_e32 v68, 0xffff0000, v188
	v_exp_f32_e32 v76, v0
	v_mul_f32_e32 v0, 0xbfb8aa3b, v75
	v_exp_f32_e32 v78, v0
	v_mul_f32_e32 v0, 0xbfb8aa3b, v68
	v_exp_f32_e32 v68, v0
	v_mul_f32_e32 v0, 0xbfb8aa3b, v77
	v_exp_f32_e32 v75, v0
	v_lshlrev_b32_e32 v80, 16, v189
	v_mul_f32_e32 v0, 0xbfb8aa3b, v80
	v_and_b32_e32 v69, 0xffff0000, v189
	v_exp_f32_e32 v77, v0
	v_mul_f32_e32 v0, 0xbfb8aa3b, v79
	v_exp_f32_e32 v79, v0
	v_mul_f32_e32 v0, 0xbfb8aa3b, v69
	v_pk_add_f32 v[74:75], v[74:75], 1.0 op_sel_hi:[1,0]
	v_exp_f32_e32 v69, v0
	v_pk_add_f32 v[78:79], v[78:79], 1.0 op_sel_hi:[1,0]
	v_pk_add_f32 v[68:69], v[68:69], 1.0 op_sel_hi:[1,0]
	v_rcp_f32_e32 v75, v75
	s_nop 0
	s_waitcnt vmcnt(13)
	v_lshlrev_b32_e32 v81, 16, v191
	v_rcp_f32_e32 v74, v74
	s_nop 0
	v_mov_b32_e32 v82, v62
	v_mov_b32_e32 v83, v64
	v_lshlrev_b32_e32 v80, 16, v190
	v_pk_fma_f32 v[74:75], v[82:83], v[74:75], v[80:81]
	v_rcp_f32_e32 v79, v79
	s_nop 0
	v_and_b32_e32 v71, 0xffff0000, v191
	v_and_b32_e32 v70, 0xffff0000, v190
	v_rcp_f32_e32 v78, v78
	s_nop 0
	v_mov_b32_e32 v64, v63
	v_pk_fma_f32 v[62:63], v[64:65], v[78:79], v[70:71]
	v_cvt_pk_bf16_f32 v0, v74, v75
	v_cvt_pk_bf16_f32 v62, v62, v63
	v_and_b32_e32 v63, 0xffff0000, v62
	v_lshlrev_b32_e32 v62, 16, v62
	v_lshlrev_b32_e32 v65, 16, v193
	v_lshlrev_b32_e32 v64, 16, v192
	v_and_b32_e32 v71, 0xffff0000, v193
	v_and_b32_e32 v70, 0xffff0000, v192
	v_pk_add_f32 v[72:73], v[76:77], 1.0 op_sel_hi:[1,0]
	v_or_b32_sdwa v63, v63, v0 dst_sel:DWORD dst_unused:UNUSED_PAD src0_sel:DWORD src1_sel:WORD_1
	v_or_b32_sdwa v62, v62, v0 dst_sel:DWORD dst_unused:UNUSED_PAD src0_sel:DWORD src1_sel:WORD_0
	s_nop 0
	v_rcp_f32_e32 v73, v73
	s_nop 0
	s_nop 0
	v_rcp_f32_e32 v72, v72
	s_nop 0
	v_mov_b32_e32 v74, v58
	v_mov_b32_e32 v75, v60
	v_pk_fma_f32 v[64:65], v[74:75], v[72:73], v[64:65]
	v_rcp_f32_e32 v69, v69
	s_nop 0
	s_nop 0
	v_rcp_f32_e32 v68, v68
	s_nop 0
	v_mov_b32_e32 v60, v59
	v_pk_fma_f32 v[58:59], v[60:61], v[68:69], v[70:71]
	v_cvt_pk_bf16_f32 v0, v64, v65
	v_cvt_pk_bf16_f32 v58, v58, v59
	v_and_b32_e32 v59, 0xffff0000, v58
	v_lshlrev_b32_e32 v58, 16, v58
	v_or_b32_sdwa v65, v59, v0 dst_sel:DWORD dst_unused:UNUSED_PAD src0_sel:DWORD src1_sel:WORD_1
	v_or_b32_sdwa v64, v58, v0 dst_sel:DWORD dst_unused:UNUSED_PAD src0_sel:DWORD src1_sel:WORD_0
	v_add_u32_e32 v0, v84, v126
	v_add_u32_e32 v212, 0xe3880, v210
	v_lshl_add_u64 v[186:187], v[212:213], 1, s[6:7]
	global_load_dwordx4 v[186:189], v[186:187], off
	v_add_u32_e32 v212, 0x28080, v211
	v_lshl_add_u64 v[190:191], v[212:213], 1, s[10:11]
	global_load_dwordx4 v[190:193], v[190:191], off
	global_store_dwordx4 v[66:67], v[62:65], off
	v_add_u32_e32 v0, v0, v85
	s_waitcnt vmcnt(14)
	v_lshlrev_b32_e32 v66, 16, v194
	v_and_b32_e32 v67, 0xffff0000, v194
	v_lshlrev_b32_e32 v69, 16, v195
	v_and_b32_e32 v71, 0xffff0000, v195
	v_lshl_add_u64 v[58:59], v[0:1], 1, s[10:11]
	v_lshlrev_b32_e32 v68, 16, v196
	v_mul_f32_e32 v0, 0xbfb8aa3b, v66
	v_exp_f32_e32 v66, v0
	v_mul_f32_e32 v0, 0xbfb8aa3b, v68
	v_and_b32_e32 v60, 0xffff0000, v196
	v_exp_f32_e32 v68, v0
	v_mul_f32_e32 v0, 0xbfb8aa3b, v67
	v_exp_f32_e32 v70, v0
	v_mul_f32_e32 v0, 0xbfb8aa3b, v60
	v_exp_f32_e32 v60, v0
	v_mul_f32_e32 v0, 0xbfb8aa3b, v69
	v_exp_f32_e32 v67, v0
	v_lshlrev_b32_e32 v72, 16, v197
	v_mul_f32_e32 v0, 0xbfb8aa3b, v72
	v_and_b32_e32 v61, 0xffff0000, v197
	v_exp_f32_e32 v69, v0
	v_mul_f32_e32 v0, 0xbfb8aa3b, v71
	v_exp_f32_e32 v71, v0
	v_mul_f32_e32 v0, 0xbfb8aa3b, v61
	v_pk_add_f32 v[66:67], v[66:67], 1.0 op_sel_hi:[1,0]
	v_exp_f32_e32 v61, v0
	v_pk_add_f32 v[70:71], v[70:71], 1.0 op_sel_hi:[1,0]
	v_pk_add_f32 v[60:61], v[60:61], 1.0 op_sel_hi:[1,0]
	v_rcp_f32_e32 v67, v67
	s_nop 0
	s_waitcnt vmcnt(13)
	v_lshlrev_b32_e32 v73, 16, v199
	v_rcp_f32_e32 v66, v66
	s_nop 0
	v_mov_b32_e32 v74, v54
	v_mov_b32_e32 v75, v56
	v_lshlrev_b32_e32 v72, 16, v198
	v_pk_fma_f32 v[66:67], v[74:75], v[66:67], v[72:73]
	v_rcp_f32_e32 v71, v71
	s_nop 0
	v_and_b32_e32 v63, 0xffff0000, v199
	v_and_b32_e32 v62, 0xffff0000, v198
	v_rcp_f32_e32 v70, v70
	s_nop 0
	v_mov_b32_e32 v56, v55
	v_pk_fma_f32 v[54:55], v[56:57], v[70:71], v[62:63]
	v_cvt_pk_bf16_f32 v0, v66, v67
	v_cvt_pk_bf16_f32 v54, v54, v55
	v_and_b32_e32 v55, 0xffff0000, v54
	v_lshlrev_b32_e32 v54, 16, v54
	v_lshlrev_b32_e32 v57, 16, v201
	v_lshlrev_b32_e32 v56, 16, v200
	v_and_b32_e32 v63, 0xffff0000, v201
	v_and_b32_e32 v62, 0xffff0000, v200
	v_pk_add_f32 v[64:65], v[68:69], 1.0 op_sel_hi:[1,0]
	v_or_b32_sdwa v55, v55, v0 dst_sel:DWORD dst_unused:UNUSED_PAD src0_sel:DWORD src1_sel:WORD_1
	v_or_b32_sdwa v54, v54, v0 dst_sel:DWORD dst_unused:UNUSED_PAD src0_sel:DWORD src1_sel:WORD_0
	s_nop 0
	v_rcp_f32_e32 v65, v65
	s_nop 0
	s_nop 0
	v_rcp_f32_e32 v64, v64
	s_nop 0
	v_mov_b32_e32 v66, v50
	v_mov_b32_e32 v67, v52
	v_pk_fma_f32 v[56:57], v[66:67], v[64:65], v[56:57]
	v_add_u32_e32 v68, 0xccc00, v157
	v_rcp_f32_e32 v61, v61
	s_nop 0
	v_add_u32_e32 v69, 0xfff57400, v158
	v_rcp_f32_e32 v60, v60
	s_nop 0
	v_mov_b32_e32 v52, v51
	v_pk_fma_f32 v[50:51], v[52:53], v[60:61], v[62:63]
	v_cvt_pk_bf16_f32 v0, v56, v57
	v_cvt_pk_bf16_f32 v50, v50, v51
	v_and_b32_e32 v51, 0xffff0000, v50
	v_lshlrev_b32_e32 v50, 16, v50
	v_or_b32_sdwa v57, v51, v0 dst_sel:DWORD dst_unused:UNUSED_PAD src0_sel:DWORD src1_sel:WORD_1
	v_or_b32_sdwa v56, v50, v0 dst_sel:DWORD dst_unused:UNUSED_PAD src0_sel:DWORD src1_sel:WORD_0
	v_add_u32_e32 v0, v68, v156
	v_add_u32_e32 v212, 0xfa400, v210
	v_lshl_add_u64 v[194:195], v[212:213], 1, s[6:7]
	global_load_dwordx4 v[194:197], v[194:195], off
	v_add_u32_e32 v212, 0x2c000, v211
	v_lshl_add_u64 v[198:199], v[212:213], 1, s[10:11]
	global_load_dwordx4 v[198:201], v[198:199], off
	global_store_dwordx4 v[58:59], v[54:57], off
	v_add_u32_e32 v0, v0, v69
	s_waitcnt vmcnt(14)
	v_lshlrev_b32_e32 v58, 16, v202
	v_and_b32_e32 v59, 0xffff0000, v202
	v_lshlrev_b32_e32 v61, 16, v203
	v_and_b32_e32 v63, 0xffff0000, v203
	v_lshl_add_u64 v[50:51], v[0:1], 1, s[10:11]
	v_lshlrev_b32_e32 v60, 16, v204
	v_mul_f32_e32 v0, 0xbfb8aa3b, v58
	v_exp_f32_e32 v58, v0
	v_mul_f32_e32 v0, 0xbfb8aa3b, v60
	v_and_b32_e32 v52, 0xffff0000, v204
	v_exp_f32_e32 v60, v0
	v_mul_f32_e32 v0, 0xbfb8aa3b, v59
	v_exp_f32_e32 v62, v0
	v_mul_f32_e32 v0, 0xbfb8aa3b, v52
	v_exp_f32_e32 v52, v0
	v_mul_f32_e32 v0, 0xbfb8aa3b, v61
	v_exp_f32_e32 v59, v0
	v_lshlrev_b32_e32 v64, 16, v205
	v_mul_f32_e32 v0, 0xbfb8aa3b, v64
	v_and_b32_e32 v53, 0xffff0000, v205
	v_exp_f32_e32 v61, v0
	v_mul_f32_e32 v0, 0xbfb8aa3b, v63
	v_exp_f32_e32 v63, v0
	v_mul_f32_e32 v0, 0xbfb8aa3b, v53
	v_pk_add_f32 v[58:59], v[58:59], 1.0 op_sel_hi:[1,0]
	v_exp_f32_e32 v53, v0
	v_pk_add_f32 v[62:63], v[62:63], 1.0 op_sel_hi:[1,0]
	v_pk_add_f32 v[52:53], v[52:53], 1.0 op_sel_hi:[1,0]
	v_rcp_f32_e32 v59, v59
	s_nop 0
	s_waitcnt vmcnt(13)
	v_lshlrev_b32_e32 v65, 16, v207
	v_rcp_f32_e32 v58, v58
	s_nop 0
	v_mov_b32_e32 v66, v46
	v_mov_b32_e32 v67, v48
	v_lshlrev_b32_e32 v64, 16, v206
	v_pk_fma_f32 v[58:59], v[66:67], v[58:59], v[64:65]
	v_rcp_f32_e32 v63, v63
	s_nop 0
	v_and_b32_e32 v55, 0xffff0000, v207
	v_and_b32_e32 v54, 0xffff0000, v206
	v_rcp_f32_e32 v62, v62
	s_nop 0
	v_mov_b32_e32 v48, v47
	v_pk_fma_f32 v[46:47], v[48:49], v[62:63], v[54:55]
	v_cvt_pk_bf16_f32 v0, v58, v59
	v_cvt_pk_bf16_f32 v46, v46, v47
	v_and_b32_e32 v47, 0xffff0000, v46
	v_lshlrev_b32_e32 v46, 16, v46
	v_lshlrev_b32_e32 v49, 16, v209
	v_lshlrev_b32_e32 v48, 16, v208
	v_and_b32_e32 v55, 0xffff0000, v209
	v_and_b32_e32 v54, 0xffff0000, v208
	v_pk_add_f32 v[56:57], v[60:61], 1.0 op_sel_hi:[1,0]
	v_or_b32_sdwa v47, v47, v0 dst_sel:DWORD dst_unused:UNUSED_PAD src0_sel:DWORD src1_sel:WORD_1
	v_or_b32_sdwa v46, v46, v0 dst_sel:DWORD dst_unused:UNUSED_PAD src0_sel:DWORD src1_sel:WORD_0
	s_nop 0
	v_rcp_f32_e32 v57, v57
	s_nop 0
	s_nop 0
	v_rcp_f32_e32 v56, v56
	s_nop 0
	v_mov_b32_e32 v58, v42
	v_mov_b32_e32 v59, v44
	v_pk_fma_f32 v[48:49], v[58:59], v[56:57], v[48:49]
	v_rcp_f32_e32 v53, v53
	s_nop 0
	s_nop 0
	v_rcp_f32_e32 v52, v52
	s_nop 0
	v_mov_b32_e32 v44, v43
	v_pk_fma_f32 v[42:43], v[44:45], v[52:53], v[54:55]
	v_cvt_pk_bf16_f32 v0, v48, v49
	v_cvt_pk_bf16_f32 v42, v42, v43
	v_and_b32_e32 v43, 0xffff0000, v42
	v_lshlrev_b32_e32 v42, 16, v42
	v_or_b32_sdwa v49, v43, v0 dst_sel:DWORD dst_unused:UNUSED_PAD src0_sel:DWORD src1_sel:WORD_1
	v_or_b32_sdwa v48, v42, v0 dst_sel:DWORD dst_unused:UNUSED_PAD src0_sel:DWORD src1_sel:WORD_0
	v_add_u32_e32 v0, v68, v126
	v_add_u32_e32 v212, 0xfa480, v210
	v_lshl_add_u64 v[202:203], v[212:213], 1, s[6:7]
	global_load_dwordx4 v[202:205], v[202:203], off
	v_add_u32_e32 v212, 0x2c080, v211
	v_lshl_add_u64 v[206:207], v[212:213], 1, s[10:11]
	global_load_dwordx4 v[206:209], v[206:207], off
	global_store_dwordx4 v[50:51], v[46:49], off
	v_add_u32_e32 v0, v0, v69
	s_waitcnt vmcnt(14)
	v_lshlrev_b32_e32 v50, 16, v168
	v_and_b32_e32 v51, 0xffff0000, v168
	v_lshlrev_b32_e32 v53, 16, v169
	v_and_b32_e32 v55, 0xffff0000, v169
	v_lshl_add_u64 v[42:43], v[0:1], 1, s[10:11]
	v_lshlrev_b32_e32 v52, 16, v170
	v_mul_f32_e32 v0, 0xbfb8aa3b, v50
	v_exp_f32_e32 v50, v0
	v_mul_f32_e32 v0, 0xbfb8aa3b, v52
	v_and_b32_e32 v44, 0xffff0000, v170
	v_exp_f32_e32 v52, v0
	v_mul_f32_e32 v0, 0xbfb8aa3b, v51
	v_exp_f32_e32 v54, v0
	v_mul_f32_e32 v0, 0xbfb8aa3b, v44
	v_exp_f32_e32 v44, v0
	v_mul_f32_e32 v0, 0xbfb8aa3b, v53
	v_exp_f32_e32 v51, v0
	v_lshlrev_b32_e32 v56, 16, v171
	v_mul_f32_e32 v0, 0xbfb8aa3b, v56
	v_and_b32_e32 v45, 0xffff0000, v171
	v_exp_f32_e32 v53, v0
	v_mul_f32_e32 v0, 0xbfb8aa3b, v55
	v_exp_f32_e32 v55, v0
	v_mul_f32_e32 v0, 0xbfb8aa3b, v45
	v_pk_add_f32 v[50:51], v[50:51], 1.0 op_sel_hi:[1,0]
	v_exp_f32_e32 v45, v0
	v_pk_add_f32 v[54:55], v[54:55], 1.0 op_sel_hi:[1,0]
	v_pk_add_f32 v[44:45], v[44:45], 1.0 op_sel_hi:[1,0]
	v_rcp_f32_e32 v51, v51
	s_nop 0
	s_waitcnt vmcnt(13)
	v_lshlrev_b32_e32 v57, 16, v173
	v_rcp_f32_e32 v50, v50
	s_nop 0
	v_mov_b32_e32 v58, v38
	v_mov_b32_e32 v59, v40
	v_lshlrev_b32_e32 v56, 16, v172
	v_pk_fma_f32 v[50:51], v[58:59], v[50:51], v[56:57]
	v_rcp_f32_e32 v55, v55
	s_nop 0
	v_and_b32_e32 v47, 0xffff0000, v173
	v_and_b32_e32 v46, 0xffff0000, v172
	v_rcp_f32_e32 v54, v54
	s_nop 0
	v_mov_b32_e32 v40, v39
	v_pk_fma_f32 v[38:39], v[40:41], v[54:55], v[46:47]
	v_cvt_pk_bf16_f32 v0, v50, v51
	v_cvt_pk_bf16_f32 v38, v38, v39
	v_and_b32_e32 v39, 0xffff0000, v38
	v_lshlrev_b32_e32 v38, 16, v38
	v_lshlrev_b32_e32 v41, 16, v175
	v_lshlrev_b32_e32 v40, 16, v174
	v_and_b32_e32 v47, 0xffff0000, v175
	v_and_b32_e32 v46, 0xffff0000, v174
	v_pk_add_f32 v[48:49], v[52:53], 1.0 op_sel_hi:[1,0]
	v_or_b32_sdwa v39, v39, v0 dst_sel:DWORD dst_unused:UNUSED_PAD src0_sel:DWORD src1_sel:WORD_1
	v_or_b32_sdwa v38, v38, v0 dst_sel:DWORD dst_unused:UNUSED_PAD src0_sel:DWORD src1_sel:WORD_0
	s_nop 0
	v_rcp_f32_e32 v49, v49
	s_nop 0
	s_nop 0
	v_rcp_f32_e32 v48, v48
	s_nop 0
	v_mov_b32_e32 v50, v34
	v_mov_b32_e32 v51, v36
	v_pk_fma_f32 v[40:41], v[50:51], v[48:49], v[40:41]
	v_add_u32_e32 v52, 0xe3800, v157
	v_rcp_f32_e32 v45, v45
	s_nop 0
	v_add_u32_e32 v53, 0xfff44800, v158
	v_rcp_f32_e32 v44, v44
	s_nop 0
	v_mov_b32_e32 v36, v35
	v_pk_fma_f32 v[34:35], v[36:37], v[44:45], v[46:47]
	v_cvt_pk_bf16_f32 v0, v40, v41
	v_cvt_pk_bf16_f32 v34, v34, v35
	v_and_b32_e32 v35, 0xffff0000, v34
	v_lshlrev_b32_e32 v34, 16, v34
	v_or_b32_sdwa v41, v35, v0 dst_sel:DWORD dst_unused:UNUSED_PAD src0_sel:DWORD src1_sel:WORD_1
	v_or_b32_sdwa v40, v34, v0 dst_sel:DWORD dst_unused:UNUSED_PAD src0_sel:DWORD src1_sel:WORD_0
	v_add_u32_e32 v0, v52, v156
	global_store_dwordx4 v[42:43], v[38:41], off
	v_add_u32_e32 v0, v0, v53
	s_waitcnt vmcnt(12)
	v_lshlrev_b32_e32 v42, 16, v176
	v_and_b32_e32 v43, 0xffff0000, v176
	v_lshlrev_b32_e32 v45, 16, v177
	v_and_b32_e32 v47, 0xffff0000, v177
	v_lshl_add_u64 v[34:35], v[0:1], 1, s[10:11]
	v_lshlrev_b32_e32 v44, 16, v178
	v_mul_f32_e32 v0, 0xbfb8aa3b, v42
	v_exp_f32_e32 v42, v0
	v_mul_f32_e32 v0, 0xbfb8aa3b, v44
	v_and_b32_e32 v36, 0xffff0000, v178
	v_exp_f32_e32 v44, v0
	v_mul_f32_e32 v0, 0xbfb8aa3b, v43
	v_exp_f32_e32 v46, v0
	v_mul_f32_e32 v0, 0xbfb8aa3b, v36
	v_exp_f32_e32 v36, v0
	v_mul_f32_e32 v0, 0xbfb8aa3b, v45
	v_exp_f32_e32 v43, v0
	v_lshlrev_b32_e32 v48, 16, v179
	v_mul_f32_e32 v0, 0xbfb8aa3b, v48
	v_and_b32_e32 v37, 0xffff0000, v179
	v_exp_f32_e32 v45, v0
	v_mul_f32_e32 v0, 0xbfb8aa3b, v47
	v_exp_f32_e32 v47, v0
	v_mul_f32_e32 v0, 0xbfb8aa3b, v37
	v_pk_add_f32 v[42:43], v[42:43], 1.0 op_sel_hi:[1,0]
	v_exp_f32_e32 v37, v0
	v_pk_add_f32 v[46:47], v[46:47], 1.0 op_sel_hi:[1,0]
	v_pk_add_f32 v[36:37], v[36:37], 1.0 op_sel_hi:[1,0]
	v_rcp_f32_e32 v43, v43
	s_nop 0
	s_waitcnt vmcnt(11)
	v_lshlrev_b32_e32 v49, 16, v183
	v_rcp_f32_e32 v42, v42
	s_nop 0
	v_mov_b32_e32 v50, v30
	v_mov_b32_e32 v51, v32
	v_lshlrev_b32_e32 v48, 16, v182
	v_pk_fma_f32 v[42:43], v[50:51], v[42:43], v[48:49]
	v_rcp_f32_e32 v47, v47
	s_nop 0
	v_and_b32_e32 v39, 0xffff0000, v183
	v_and_b32_e32 v38, 0xffff0000, v182
	v_rcp_f32_e32 v46, v46
	s_nop 0
	v_mov_b32_e32 v32, v31
	v_pk_fma_f32 v[30:31], v[32:33], v[46:47], v[38:39]
	v_cvt_pk_bf16_f32 v0, v42, v43
	v_cvt_pk_bf16_f32 v30, v30, v31
	v_and_b32_e32 v31, 0xffff0000, v30
	v_lshlrev_b32_e32 v30, 16, v30
	v_lshlrev_b32_e32 v33, 16, v185
	v_lshlrev_b32_e32 v32, 16, v184
	v_and_b32_e32 v39, 0xffff0000, v185
	v_and_b32_e32 v38, 0xffff0000, v184
	v_pk_add_f32 v[40:41], v[44:45], 1.0 op_sel_hi:[1,0]
	v_or_b32_sdwa v31, v31, v0 dst_sel:DWORD dst_unused:UNUSED_PAD src0_sel:DWORD src1_sel:WORD_1
	v_or_b32_sdwa v30, v30, v0 dst_sel:DWORD dst_unused:UNUSED_PAD src0_sel:DWORD src1_sel:WORD_0
	s_nop 0
	v_rcp_f32_e32 v41, v41
	s_nop 0
	s_nop 0
	v_rcp_f32_e32 v40, v40
	s_nop 0
	v_mov_b32_e32 v42, v26
	v_mov_b32_e32 v43, v28
	v_pk_fma_f32 v[32:33], v[42:43], v[40:41], v[32:33]
	v_rcp_f32_e32 v37, v37
	s_nop 0
	s_nop 0
	v_rcp_f32_e32 v36, v36
	s_nop 0
	v_mov_b32_e32 v28, v27
	v_pk_fma_f32 v[26:27], v[28:29], v[36:37], v[38:39]
	v_cvt_pk_bf16_f32 v0, v32, v33
	v_cvt_pk_bf16_f32 v26, v26, v27
	v_and_b32_e32 v27, 0xffff0000, v26
	v_lshlrev_b32_e32 v26, 16, v26
	v_or_b32_sdwa v33, v27, v0 dst_sel:DWORD dst_unused:UNUSED_PAD src0_sel:DWORD src1_sel:WORD_1
	v_or_b32_sdwa v32, v26, v0 dst_sel:DWORD dst_unused:UNUSED_PAD src0_sel:DWORD src1_sel:WORD_0
	v_add_u32_e32 v0, v52, v126
	global_store_dwordx4 v[34:35], v[30:33], off
	v_add_u32_e32 v0, v0, v53
	s_waitcnt vmcnt(10)
	v_lshlrev_b32_e32 v34, 16, v186
	v_and_b32_e32 v35, 0xffff0000, v186
	v_lshlrev_b32_e32 v37, 16, v187
	v_and_b32_e32 v39, 0xffff0000, v187
	v_lshl_add_u64 v[26:27], v[0:1], 1, s[10:11]
	v_lshlrev_b32_e32 v36, 16, v188
	v_mul_f32_e32 v0, 0xbfb8aa3b, v34
	v_exp_f32_e32 v34, v0
	v_mul_f32_e32 v0, 0xbfb8aa3b, v36
	v_and_b32_e32 v28, 0xffff0000, v188
	v_exp_f32_e32 v36, v0
	v_mul_f32_e32 v0, 0xbfb8aa3b, v35
	v_exp_f32_e32 v38, v0
	v_mul_f32_e32 v0, 0xbfb8aa3b, v28
	v_exp_f32_e32 v28, v0
	v_mul_f32_e32 v0, 0xbfb8aa3b, v37
	v_exp_f32_e32 v35, v0
	v_lshlrev_b32_e32 v40, 16, v189
	v_mul_f32_e32 v0, 0xbfb8aa3b, v40
	v_and_b32_e32 v29, 0xffff0000, v189
	v_exp_f32_e32 v37, v0
	v_mul_f32_e32 v0, 0xbfb8aa3b, v39
	v_exp_f32_e32 v39, v0
	v_mul_f32_e32 v0, 0xbfb8aa3b, v29
	v_pk_add_f32 v[34:35], v[34:35], 1.0 op_sel_hi:[1,0]
	v_exp_f32_e32 v29, v0
	v_pk_add_f32 v[38:39], v[38:39], 1.0 op_sel_hi:[1,0]
	v_pk_add_f32 v[28:29], v[28:29], 1.0 op_sel_hi:[1,0]
	v_rcp_f32_e32 v35, v35
	s_nop 0
	s_waitcnt vmcnt(9)
	v_lshlrev_b32_e32 v41, 16, v191
	v_rcp_f32_e32 v34, v34
	s_nop 0
	v_mov_b32_e32 v42, v22
	v_mov_b32_e32 v43, v24
	v_lshlrev_b32_e32 v40, 16, v190
	v_pk_fma_f32 v[34:35], v[42:43], v[34:35], v[40:41]
	v_rcp_f32_e32 v39, v39
	s_nop 0
	v_and_b32_e32 v31, 0xffff0000, v191
	v_and_b32_e32 v30, 0xffff0000, v190
	v_rcp_f32_e32 v38, v38
	s_nop 0
	v_mov_b32_e32 v24, v23
	v_pk_fma_f32 v[22:23], v[24:25], v[38:39], v[30:31]
	v_cvt_pk_bf16_f32 v0, v34, v35
	v_cvt_pk_bf16_f32 v22, v22, v23
	v_and_b32_e32 v23, 0xffff0000, v22
	v_lshlrev_b32_e32 v22, 16, v22
	v_lshlrev_b32_e32 v25, 16, v193
	v_lshlrev_b32_e32 v24, 16, v192
	v_and_b32_e32 v31, 0xffff0000, v193
	v_and_b32_e32 v30, 0xffff0000, v192
	v_pk_add_f32 v[32:33], v[36:37], 1.0 op_sel_hi:[1,0]
	v_or_b32_sdwa v23, v23, v0 dst_sel:DWORD dst_unused:UNUSED_PAD src0_sel:DWORD src1_sel:WORD_1
	v_or_b32_sdwa v22, v22, v0 dst_sel:DWORD dst_unused:UNUSED_PAD src0_sel:DWORD src1_sel:WORD_0
	s_nop 0
	v_rcp_f32_e32 v33, v33
	s_nop 0
	s_nop 0
	v_rcp_f32_e32 v32, v32
	s_nop 0
	v_mov_b32_e32 v34, v18
	v_mov_b32_e32 v35, v20
	v_pk_fma_f32 v[24:25], v[34:35], v[32:33], v[24:25]
	v_add_u32_e32 v36, 0xfa400, v157
	v_rcp_f32_e32 v29, v29
	s_nop 0
	v_add_u32_e32 v37, 0xfff31c00, v158
	v_rcp_f32_e32 v28, v28
	s_nop 0
	v_mov_b32_e32 v20, v19
	v_pk_fma_f32 v[18:19], v[20:21], v[28:29], v[30:31]
	v_cvt_pk_bf16_f32 v0, v24, v25
	v_cvt_pk_bf16_f32 v18, v18, v19
	v_and_b32_e32 v19, 0xffff0000, v18
	v_lshlrev_b32_e32 v18, 16, v18
	v_or_b32_sdwa v25, v19, v0 dst_sel:DWORD dst_unused:UNUSED_PAD src0_sel:DWORD src1_sel:WORD_1
	v_or_b32_sdwa v24, v18, v0 dst_sel:DWORD dst_unused:UNUSED_PAD src0_sel:DWORD src1_sel:WORD_0
	v_add_u32_e32 v0, v36, v156
	global_store_dwordx4 v[26:27], v[22:25], off
	v_add_u32_e32 v0, v0, v37
	s_waitcnt vmcnt(8)
	v_lshlrev_b32_e32 v26, 16, v194
	v_and_b32_e32 v27, 0xffff0000, v194
	v_lshlrev_b32_e32 v29, 16, v195
	v_and_b32_e32 v31, 0xffff0000, v195
	v_lshl_add_u64 v[18:19], v[0:1], 1, s[10:11]
	v_lshlrev_b32_e32 v28, 16, v196
	v_mul_f32_e32 v0, 0xbfb8aa3b, v26
	v_exp_f32_e32 v26, v0
	v_mul_f32_e32 v0, 0xbfb8aa3b, v28
	v_and_b32_e32 v20, 0xffff0000, v196
	v_exp_f32_e32 v28, v0
	v_mul_f32_e32 v0, 0xbfb8aa3b, v27
	v_exp_f32_e32 v30, v0
	v_mul_f32_e32 v0, 0xbfb8aa3b, v20
	v_exp_f32_e32 v20, v0
	v_mul_f32_e32 v0, 0xbfb8aa3b, v29
	v_exp_f32_e32 v27, v0
	v_lshlrev_b32_e32 v32, 16, v197
	v_mul_f32_e32 v0, 0xbfb8aa3b, v32
	v_and_b32_e32 v21, 0xffff0000, v197
	v_exp_f32_e32 v29, v0
	v_mul_f32_e32 v0, 0xbfb8aa3b, v31
	v_exp_f32_e32 v31, v0
	v_mul_f32_e32 v0, 0xbfb8aa3b, v21
	v_pk_add_f32 v[26:27], v[26:27], 1.0 op_sel_hi:[1,0]
	v_exp_f32_e32 v21, v0
	v_pk_add_f32 v[30:31], v[30:31], 1.0 op_sel_hi:[1,0]
	v_pk_add_f32 v[20:21], v[20:21], 1.0 op_sel_hi:[1,0]
	v_rcp_f32_e32 v27, v27
	s_nop 0
	s_waitcnt vmcnt(7)
	v_lshlrev_b32_e32 v33, 16, v199
	v_rcp_f32_e32 v26, v26
	s_nop 0
	v_mov_b32_e32 v34, v14
	v_mov_b32_e32 v35, v16
	v_lshlrev_b32_e32 v32, 16, v198
	v_pk_fma_f32 v[26:27], v[34:35], v[26:27], v[32:33]
	v_rcp_f32_e32 v31, v31
	s_nop 0
	v_and_b32_e32 v23, 0xffff0000, v199
	v_and_b32_e32 v22, 0xffff0000, v198
	v_rcp_f32_e32 v30, v30
	s_nop 0
	v_mov_b32_e32 v16, v15
	v_pk_fma_f32 v[14:15], v[16:17], v[30:31], v[22:23]
	v_cvt_pk_bf16_f32 v0, v26, v27
	v_cvt_pk_bf16_f32 v14, v14, v15
	v_and_b32_e32 v15, 0xffff0000, v14
	v_lshlrev_b32_e32 v14, 16, v14
	v_lshlrev_b32_e32 v17, 16, v201
	v_lshlrev_b32_e32 v16, 16, v200
	v_and_b32_e32 v23, 0xffff0000, v201
	v_and_b32_e32 v22, 0xffff0000, v200
	v_pk_add_f32 v[24:25], v[28:29], 1.0 op_sel_hi:[1,0]
	v_or_b32_sdwa v15, v15, v0 dst_sel:DWORD dst_unused:UNUSED_PAD src0_sel:DWORD src1_sel:WORD_1
	v_or_b32_sdwa v14, v14, v0 dst_sel:DWORD dst_unused:UNUSED_PAD src0_sel:DWORD src1_sel:WORD_0
	s_nop 0
	v_rcp_f32_e32 v25, v25
	s_nop 0
	s_nop 0
	v_rcp_f32_e32 v24, v24
	s_nop 0
	v_mov_b32_e32 v26, v10
	v_mov_b32_e32 v27, v12
	v_pk_fma_f32 v[16:17], v[26:27], v[24:25], v[16:17]
	v_rcp_f32_e32 v21, v21
	s_nop 0
	s_nop 0
	v_rcp_f32_e32 v20, v20
	s_nop 0
	v_mov_b32_e32 v12, v11
	v_pk_fma_f32 v[10:11], v[12:13], v[20:21], v[22:23]
	v_cvt_pk_bf16_f32 v0, v16, v17
	v_cvt_pk_bf16_f32 v10, v10, v11
	v_and_b32_e32 v11, 0xffff0000, v10
	v_lshlrev_b32_e32 v10, 16, v10
	v_or_b32_sdwa v17, v11, v0 dst_sel:DWORD dst_unused:UNUSED_PAD src0_sel:DWORD src1_sel:WORD_1
	v_or_b32_sdwa v16, v10, v0 dst_sel:DWORD dst_unused:UNUSED_PAD src0_sel:DWORD src1_sel:WORD_0
	v_add_u32_e32 v0, v36, v126
	global_store_dwordx4 v[18:19], v[14:17], off
	v_add_u32_e32 v0, v0, v37
	s_waitcnt vmcnt(6)
	v_lshlrev_b32_e32 v18, 16, v202
	v_and_b32_e32 v19, 0xffff0000, v202
	v_lshlrev_b32_e32 v21, 16, v203
	v_and_b32_e32 v23, 0xffff0000, v203
	v_lshl_add_u64 v[10:11], v[0:1], 1, s[10:11]
	v_lshlrev_b32_e32 v20, 16, v204
	v_mul_f32_e32 v0, 0xbfb8aa3b, v18
	v_exp_f32_e32 v18, v0
	v_mul_f32_e32 v0, 0xbfb8aa3b, v20
	v_and_b32_e32 v12, 0xffff0000, v204
	v_exp_f32_e32 v20, v0
	v_mul_f32_e32 v0, 0xbfb8aa3b, v19
	v_exp_f32_e32 v22, v0
	v_mul_f32_e32 v0, 0xbfb8aa3b, v12
	v_exp_f32_e32 v12, v0
	v_mul_f32_e32 v0, 0xbfb8aa3b, v21
	v_exp_f32_e32 v19, v0
	v_lshlrev_b32_e32 v24, 16, v205
	v_mul_f32_e32 v0, 0xbfb8aa3b, v24
	v_and_b32_e32 v13, 0xffff0000, v205
	v_exp_f32_e32 v21, v0
	v_mul_f32_e32 v0, 0xbfb8aa3b, v23
	v_exp_f32_e32 v23, v0
	v_mul_f32_e32 v0, 0xbfb8aa3b, v13
	v_pk_add_f32 v[18:19], v[18:19], 1.0 op_sel_hi:[1,0]
	v_exp_f32_e32 v13, v0
	v_pk_add_f32 v[22:23], v[22:23], 1.0 op_sel_hi:[1,0]
	v_pk_add_f32 v[12:13], v[12:13], 1.0 op_sel_hi:[1,0]
	v_rcp_f32_e32 v19, v19
	s_nop 0
	s_waitcnt vmcnt(5)
	v_lshlrev_b32_e32 v25, 16, v207
	v_rcp_f32_e32 v18, v18
	s_nop 0
	v_mov_b32_e32 v26, v6
	v_mov_b32_e32 v27, v8
	v_lshlrev_b32_e32 v24, 16, v206
	v_pk_fma_f32 v[18:19], v[26:27], v[18:19], v[24:25]
	v_rcp_f32_e32 v23, v23
	s_nop 0
	v_and_b32_e32 v15, 0xffff0000, v207
	v_and_b32_e32 v14, 0xffff0000, v206
	v_rcp_f32_e32 v22, v22
	s_nop 0
	v_mov_b32_e32 v8, v7
	v_pk_fma_f32 v[6:7], v[8:9], v[22:23], v[14:15]
	v_cvt_pk_bf16_f32 v0, v18, v19
	v_cvt_pk_bf16_f32 v6, v6, v7
	v_and_b32_e32 v7, 0xffff0000, v6
	v_lshlrev_b32_e32 v6, 16, v6
	v_lshlrev_b32_e32 v9, 16, v209
	v_lshlrev_b32_e32 v8, 16, v208
	v_and_b32_e32 v15, 0xffff0000, v209
	v_and_b32_e32 v14, 0xffff0000, v208
	v_pk_add_f32 v[16:17], v[20:21], 1.0 op_sel_hi:[1,0]
	v_or_b32_sdwa v7, v7, v0 dst_sel:DWORD dst_unused:UNUSED_PAD src0_sel:DWORD src1_sel:WORD_1
	v_or_b32_sdwa v6, v6, v0 dst_sel:DWORD dst_unused:UNUSED_PAD src0_sel:DWORD src1_sel:WORD_0
	s_nop 0
	v_rcp_f32_e32 v17, v17
	s_nop 0
	s_nop 0
	v_rcp_f32_e32 v16, v16
	s_nop 0
	v_mov_b32_e32 v18, v2
	v_mov_b32_e32 v19, v4
	v_pk_fma_f32 v[8:9], v[18:19], v[16:17], v[8:9]
	v_rcp_f32_e32 v13, v13
	s_nop 0
	s_mov_b64 s[26:27], s[18:19]
	v_rcp_f32_e32 v12, v12
	s_nop 0
	v_mov_b32_e32 v4, v3
	v_pk_fma_f32 v[2:3], v[4:5], v[12:13], v[14:15]
	v_cvt_pk_bf16_f32 v0, v8, v9
	v_cvt_pk_bf16_f32 v2, v2, v3
	v_and_b32_e32 v3, 0xffff0000, v2
	v_lshlrev_b32_e32 v2, 16, v2
	v_or_b32_sdwa v9, v3, v0 dst_sel:DWORD dst_unused:UNUSED_PAD src0_sel:DWORD src1_sel:WORD_1
	v_or_b32_sdwa v8, v2, v0 dst_sel:DWORD dst_unused:UNUSED_PAD src0_sel:DWORD src1_sel:WORD_0
	s_and_b64 vcc, exec, s[12:13]
	global_store_dwordx4 v[10:11], v[6:9], off
	s_cbranch_vccz .LBB0_1356
	s_waitcnt vmcnt(0)
	v_readlane_b32 s76, v255, 8
	s_mov_b32 s92, 0x3b2aaaab
	s_cmp_gt_u32 s36, 3
	v_readlane_b32 s77, v255, 9
	s_mul_i32 s60, s33, 0x1800
	s_mul_hi_i32 s62, s64, 0x300
	s_mul_i32 s75, s33, 0x16c00
	s_mov_b32 s93, 0x3c800000
	s_cbranch_scc1 .LBB0_1363
	s_barrier

.LBB0_1372:
	v_add_u32_e32 v0, 0x10000, v154
	ds_read_b128 v[130:133], v0
	ds_read_b128 v[146:149], v0 offset:1024
	ds_read_b128 v[156:159], v0 offset:2048
	ds_read_b128 v[160:163], v0 offset:3072
	s_add_u32 s28, s26, 0xfffc0080
	s_addc_u32 s29, s27, -1
	s_cmp_eq_u32 s97, 12
	s_cselect_b32 s31, s2, s29
	s_cselect_b32 s30, s17, s28
	s_cselect_b32 s29, s15, s94
	s_cselect_b32 s28, s89, s90
	v_lshl_add_u64 v[150:151], s[26:27], 0, v[142:143]
	s_add_i32 m0, s38, 0xc000
	ds_read_b128 v[164:167], v153
	ds_read_b128 v[168:171], v153 offset:1024
	ds_read_b128 v[172:175], v153 offset:2048
	ds_read_b128 v[176:179], v153 offset:3072
	ds_read_b128 v[182:185], v153 offset:4096
	ds_read_b128 v[186:189], v153 offset:5120
	ds_read_b128 v[190:193], v153 offset:6144
	ds_read_b128 v[194:197], v153 offset:7168
	global_load_lds_dwordx4 v[150:151], off
	v_lshl_add_u64 v[150:151], s[26:27], 0, v[144:145]
	s_add_i32 m0, s38, 0xe000
	s_nop 0
	global_load_lds_dwordx4 v[150:151], off
	s_waitcnt lgkmcnt(8)
	s_barrier
	s_waitcnt lgkmcnt(0)
	s_waitcnt lgkmcnt(0)
	v_mfma_f32_16x16x32_bf16 v[126:129], v[130:133], v[164:167], v[126:129]
	v_mfma_f32_16x16x32_bf16 v[122:125], v[156:159], v[164:167], v[122:125]
	v_mfma_f32_16x16x32_bf16 v[110:113], v[130:133], v[172:175], v[110:113]
	v_mfma_f32_16x16x32_bf16 v[106:109], v[156:159], v[172:175], v[106:109]
	v_mfma_f32_16x16x32_bf16 v[94:97], v[130:133], v[182:185], v[94:97]
	v_mfma_f32_16x16x32_bf16 v[90:93], v[156:159], v[182:185], v[90:93]
	v_mfma_f32_16x16x32_bf16 v[78:81], v[130:133], v[190:193], v[78:81]
	v_mfma_f32_16x16x32_bf16 v[74:77], v[156:159], v[190:193], v[74:77]
	v_mfma_f32_16x16x32_bf16 v[126:129], v[146:149], v[168:171], v[126:129]
	v_mfma_f32_16x16x32_bf16 v[122:125], v[160:163], v[168:171], v[122:125]
	v_mfma_f32_16x16x32_bf16 v[110:113], v[146:149], v[176:179], v[110:113]
	v_mfma_f32_16x16x32_bf16 v[106:109], v[160:163], v[176:179], v[106:109]
	v_mfma_f32_16x16x32_bf16 v[94:97], v[146:149], v[186:189], v[94:97]
	v_mfma_f32_16x16x32_bf16 v[90:93], v[160:163], v[186:189], v[90:93]
	v_mfma_f32_16x16x32_bf16 v[78:81], v[146:149], v[194:197], v[78:81]
	v_mfma_f32_16x16x32_bf16 v[74:77], v[160:163], v[194:197], v[74:77]
	s_barrier
	s_mov_b32 m0, s23
	v_add_u32_e32 v0, 0x14000, v154
	v_lshl_add_u64 v[150:151], s[28:29], 0, v[138:139]
	ds_read_b128 v[198:201], v0
	ds_read_b128 v[202:205], v0 offset:1024
	ds_read_b128 v[206:209], v0 offset:2048
	ds_read_b128 v[210:213], v0 offset:3072
	global_load_lds_dwordx4 v[150:151], off
	v_lshl_add_u64 v[214:215], s[28:29], 0, v[134:135]
	s_mov_b32 m0, s25
	s_nop 0
	global_load_lds_dwordx4 v[214:215], off
	s_barrier
	s_waitcnt lgkmcnt(0)
	s_waitcnt lgkmcnt(0)
	v_mfma_f32_16x16x32_bf16 v[118:121], v[198:201], v[164:167], v[118:121]
	v_mfma_f32_16x16x32_bf16 v[114:117], v[206:209], v[164:167], v[114:117]
	v_mfma_f32_16x16x32_bf16 v[102:105], v[198:201], v[172:175], v[102:105]
	v_mfma_f32_16x16x32_bf16 v[98:101], v[206:209], v[172:175], v[98:101]
	v_mfma_f32_16x16x32_bf16 v[86:89], v[198:201], v[182:185], v[86:89]
	v_mfma_f32_16x16x32_bf16 v[82:85], v[206:209], v[182:185], v[82:85]
	v_mfma_f32_16x16x32_bf16 v[70:73], v[198:201], v[190:193], v[70:73]
	v_mfma_f32_16x16x32_bf16 v[66:69], v[206:209], v[190:193], v[66:69]
	v_mfma_f32_16x16x32_bf16 v[118:121], v[202:205], v[168:171], v[118:121]
	v_mfma_f32_16x16x32_bf16 v[114:117], v[210:213], v[168:171], v[114:117]
	v_mfma_f32_16x16x32_bf16 v[102:105], v[202:205], v[176:179], v[102:105]
	v_mfma_f32_16x16x32_bf16 v[98:101], v[210:213], v[176:179], v[98:101]
	v_mfma_f32_16x16x32_bf16 v[86:89], v[202:205], v[186:189], v[86:89]
	v_mfma_f32_16x16x32_bf16 v[82:85], v[210:213], v[186:189], v[82:85]
	v_mfma_f32_16x16x32_bf16 v[70:73], v[202:205], v[194:197], v[70:73]
	v_mfma_f32_16x16x32_bf16 v[66:69], v[210:213], v[194:197], v[66:69]
	s_mov_b32 m0, s38
	v_lshl_add_u64 v[216:217], s[30:31], 0, v[140:141]
	s_barrier
	ds_read_b128 v[164:167], v153 offset:16384
	ds_read_b128 v[168:171], v153 offset:17408
	ds_read_b128 v[172:175], v153 offset:18432
	ds_read_b128 v[176:179], v153 offset:19456
	ds_read_b128 v[182:185], v153 offset:20480
	ds_read_b128 v[186:189], v153 offset:21504
	ds_read_b128 v[190:193], v153 offset:22528
	ds_read_b128 v[194:197], v153 offset:23552
	global_load_lds_dwordx4 v[216:217], off
	v_lshl_add_u64 v[222:223], s[30:31], 0, v[136:137]
	s_mov_b32 m0, s39
	s_nop 0
	global_load_lds_dwordx4 v[222:223], off
	s_barrier
	s_waitcnt lgkmcnt(0)
	s_waitcnt lgkmcnt(0)
	v_mfma_f32_16x16x32_bf16 v[62:65], v[130:133], v[164:167], v[62:65]
	v_mfma_f32_16x16x32_bf16 v[58:61], v[156:159], v[164:167], v[58:61]
	v_mfma_f32_16x16x32_bf16 v[46:49], v[130:133], v[172:175], v[46:49]
	v_mfma_f32_16x16x32_bf16 v[42:45], v[156:159], v[172:175], v[42:45]
	v_mfma_f32_16x16x32_bf16 v[30:33], v[130:133], v[182:185], v[30:33]
	v_mfma_f32_16x16x32_bf16 v[26:29], v[156:159], v[182:185], v[26:29]
	v_mfma_f32_16x16x32_bf16 v[14:17], v[130:133], v[190:193], v[14:17]
	v_mfma_f32_16x16x32_bf16 v[10:13], v[156:159], v[190:193], v[10:13]
	v_mfma_f32_16x16x32_bf16 v[62:65], v[146:149], v[168:171], v[62:65]
	v_mfma_f32_16x16x32_bf16 v[58:61], v[160:163], v[168:171], v[58:61]
	v_mfma_f32_16x16x32_bf16 v[46:49], v[146:149], v[176:179], v[46:49]
	v_mfma_f32_16x16x32_bf16 v[42:45], v[160:163], v[176:179], v[42:45]
	v_mfma_f32_16x16x32_bf16 v[30:33], v[146:149], v[186:189], v[30:33]
	v_mfma_f32_16x16x32_bf16 v[26:29], v[160:163], v[186:189], v[26:29]
	v_mfma_f32_16x16x32_bf16 v[14:17], v[146:149], v[194:197], v[14:17]
	v_mfma_f32_16x16x32_bf16 v[10:13], v[160:163], v[194:197], v[10:13]
	s_barrier
	s_add_u32 s76, s28, 0x40000
	s_addc_u32 s77, s29, 0
	s_mov_b32 m0, s68
	v_lshl_add_u64 v[130:131], s[76:77], 0, v[138:139]
	global_load_lds_dwordx4 v[130:131], off
	v_lshl_add_u64 v[130:131], s[76:77], 0, v[134:135]
	s_mov_b32 m0, s69
	s_nop 0
	global_load_lds_dwordx4 v[130:131], off
	s_waitcnt vmcnt(6)
	s_barrier
	v_mfma_f32_16x16x32_bf16 v[54:57], v[198:201], v[164:167], v[54:57]
	v_mfma_f32_16x16x32_bf16 v[50:53], v[206:209], v[164:167], v[50:53]
	v_mfma_f32_16x16x32_bf16 v[38:41], v[198:201], v[172:175], v[38:41]
	v_mfma_f32_16x16x32_bf16 v[34:37], v[206:209], v[172:175], v[34:37]
	v_mfma_f32_16x16x32_bf16 v[22:25], v[198:201], v[182:185], v[22:25]
	v_mfma_f32_16x16x32_bf16 v[18:21], v[206:209], v[182:185], v[18:21]
	v_mfma_f32_16x16x32_bf16 v[6:9], v[198:201], v[190:193], v[6:9]
	v_mfma_f32_16x16x32_bf16 v[2:5], v[206:209], v[190:193], v[2:5]
	v_mfma_f32_16x16x32_bf16 v[54:57], v[202:205], v[168:171], v[54:57]
	v_mfma_f32_16x16x32_bf16 v[50:53], v[210:213], v[168:171], v[50:53]
	v_mfma_f32_16x16x32_bf16 v[38:41], v[202:205], v[176:179], v[38:41]
	v_mfma_f32_16x16x32_bf16 v[34:37], v[210:213], v[176:179], v[34:37]
	v_mfma_f32_16x16x32_bf16 v[22:25], v[202:205], v[186:189], v[22:25]
	v_mfma_f32_16x16x32_bf16 v[18:21], v[210:213], v[186:189], v[18:21]
	v_mfma_f32_16x16x32_bf16 v[6:9], v[202:205], v[194:197], v[6:9]
	v_mfma_f32_16x16x32_bf16 v[2:5], v[210:213], v[194:197], v[2:5]
	v_add_u32_e32 v0, 0x18000, v154
	s_barrier
	ds_read_b128 v[130:133], v0
	ds_read_b128 v[146:149], v0 offset:1024
	ds_read_b128 v[156:159], v0 offset:2048
	ds_read_b128 v[160:163], v0 offset:3072
	s_add_u32 s30, s30, 0x40000
	s_addc_u32 s31, s31, 0
	s_mov_b32 m0, s82
	v_lshl_add_u64 v[198:199], s[30:31], 0, v[140:141]
	ds_read_b128 v[164:167], v153 offset:32768
	ds_read_b128 v[168:171], v153 offset:33792
	ds_read_b128 v[172:175], v153 offset:34816
	ds_read_b128 v[176:179], v153 offset:35840
	ds_read_b128 v[182:185], v153 offset:36864
	ds_read_b128 v[186:189], v153 offset:37888
	ds_read_b128 v[190:193], v153 offset:38912
	ds_read_b128 v[194:197], v153 offset:39936
	global_load_lds_dwordx4 v[198:199], off
	v_lshl_add_u64 v[198:199], s[30:31], 0, v[136:137]
	s_mov_b32 m0, s96
	s_nop 0
	global_load_lds_dwordx4 v[198:199], off
	s_waitcnt lgkmcnt(8)
	s_barrier
	s_waitcnt lgkmcnt(0)
	s_waitcnt lgkmcnt(0)
	v_mfma_f32_16x16x32_bf16 v[126:129], v[130:133], v[164:167], v[126:129]
	v_mfma_f32_16x16x32_bf16 v[122:125], v[156:159], v[164:167], v[122:125]
	v_mfma_f32_16x16x32_bf16 v[110:113], v[130:133], v[172:175], v[110:113]
	v_mfma_f32_16x16x32_bf16 v[106:109], v[156:159], v[172:175], v[106:109]
	v_mfma_f32_16x16x32_bf16 v[94:97], v[130:133], v[182:185], v[94:97]
	v_mfma_f32_16x16x32_bf16 v[90:93], v[156:159], v[182:185], v[90:93]
	v_mfma_f32_16x16x32_bf16 v[78:81], v[130:133], v[190:193], v[78:81]
	v_mfma_f32_16x16x32_bf16 v[74:77], v[156:159], v[190:193], v[74:77]
	v_mfma_f32_16x16x32_bf16 v[126:129], v[146:149], v[168:171], v[126:129]
	v_mfma_f32_16x16x32_bf16 v[122:125], v[160:163], v[168:171], v[122:125]
	v_mfma_f32_16x16x32_bf16 v[110:113], v[146:149], v[176:179], v[110:113]
	v_mfma_f32_16x16x32_bf16 v[106:109], v[160:163], v[176:179], v[106:109]
	v_mfma_f32_16x16x32_bf16 v[94:97], v[146:149], v[186:189], v[94:97]
	v_mfma_f32_16x16x32_bf16 v[90:93], v[160:163], v[186:189], v[90:93]
	v_mfma_f32_16x16x32_bf16 v[78:81], v[146:149], v[194:197], v[78:81]
	v_mfma_f32_16x16x32_bf16 v[74:77], v[160:163], v[194:197], v[74:77]
	s_barrier
	s_mov_b32 m0, s4
	v_add_u32_e32 v0, 0x1c000, v154
	v_lshl_add_u64 v[150:151], v[150:151], 0, s[84:85]
	ds_read_b128 v[198:201], v0
	ds_read_b128 v[202:205], v0 offset:1024
	ds_read_b128 v[206:209], v0 offset:2048
	ds_read_b128 v[210:213], v0 offset:3072
	global_load_lds_dwordx4 v[150:151], off
	v_lshl_add_u64 v[150:151], v[214:215], 0, s[84:85]
	s_mov_b32 m0, s5
	s_nop 0
	global_load_lds_dwordx4 v[150:151], off
	s_barrier
	s_waitcnt lgkmcnt(0)
	s_waitcnt lgkmcnt(0)
	v_mfma_f32_16x16x32_bf16 v[118:121], v[198:201], v[164:167], v[118:121]
	v_mfma_f32_16x16x32_bf16 v[114:117], v[206:209], v[164:167], v[114:117]
	v_mfma_f32_16x16x32_bf16 v[102:105], v[198:201], v[172:175], v[102:105]
	v_mfma_f32_16x16x32_bf16 v[98:101], v[206:209], v[172:175], v[98:101]
	v_mfma_f32_16x16x32_bf16 v[86:89], v[198:201], v[182:185], v[86:89]
	v_mfma_f32_16x16x32_bf16 v[82:85], v[206:209], v[182:185], v[82:85]
	v_mfma_f32_16x16x32_bf16 v[70:73], v[198:201], v[190:193], v[70:73]
	v_mfma_f32_16x16x32_bf16 v[66:69], v[206:209], v[190:193], v[66:69]
	v_mfma_f32_16x16x32_bf16 v[118:121], v[202:205], v[168:171], v[118:121]
	v_mfma_f32_16x16x32_bf16 v[114:117], v[210:213], v[168:171], v[114:117]
	v_mfma_f32_16x16x32_bf16 v[102:105], v[202:205], v[176:179], v[102:105]
	v_mfma_f32_16x16x32_bf16 v[98:101], v[210:213], v[176:179], v[98:101]
	v_mfma_f32_16x16x32_bf16 v[86:89], v[202:205], v[186:189], v[86:89]
	v_mfma_f32_16x16x32_bf16 v[82:85], v[210:213], v[186:189], v[82:85]
	v_mfma_f32_16x16x32_bf16 v[70:73], v[202:205], v[194:197], v[70:73]
	v_mfma_f32_16x16x32_bf16 v[66:69], v[210:213], v[194:197], v[66:69]
	s_mov_b32 m0, s60
	v_lshl_add_u64 v[150:151], v[216:217], 0, s[84:85]
	s_barrier
	ds_read_b128 v[164:167], v153 offset:49152
	ds_read_b128 v[168:171], v153 offset:50176
	ds_read_b128 v[172:175], v153 offset:51200
	ds_read_b128 v[176:179], v153 offset:52224
	ds_read_b128 v[182:185], v153 offset:53248
	ds_read_b128 v[186:189], v153 offset:54272
	ds_read_b128 v[190:193], v153 offset:55296
	ds_read_b128 v[194:197], v153 offset:56320
	global_load_lds_dwordx4 v[150:151], off
	v_lshl_add_u64 v[150:151], v[222:223], 0, s[84:85]
	s_mov_b32 m0, s92
	s_nop 0
	global_load_lds_dwordx4 v[150:151], off
	s_barrier
	s_waitcnt lgkmcnt(0)
	s_waitcnt lgkmcnt(0)
	v_mfma_f32_16x16x32_bf16 v[62:65], v[130:133], v[164:167], v[62:65]
	v_mfma_f32_16x16x32_bf16 v[58:61], v[156:159], v[164:167], v[58:61]
	v_mfma_f32_16x16x32_bf16 v[46:49], v[130:133], v[172:175], v[46:49]
	v_mfma_f32_16x16x32_bf16 v[42:45], v[156:159], v[172:175], v[42:45]
	v_mfma_f32_16x16x32_bf16 v[30:33], v[130:133], v[182:185], v[30:33]
	v_mfma_f32_16x16x32_bf16 v[26:29], v[156:159], v[182:185], v[26:29]
	v_mfma_f32_16x16x32_bf16 v[14:17], v[130:133], v[190:193], v[14:17]
	v_mfma_f32_16x16x32_bf16 v[10:13], v[156:159], v[190:193], v[10:13]
	v_mfma_f32_16x16x32_bf16 v[62:65], v[146:149], v[168:171], v[62:65]
	v_mfma_f32_16x16x32_bf16 v[58:61], v[160:163], v[168:171], v[58:61]
	v_mfma_f32_16x16x32_bf16 v[46:49], v[146:149], v[176:179], v[46:49]
	v_mfma_f32_16x16x32_bf16 v[42:45], v[160:163], v[176:179], v[42:45]
	v_mfma_f32_16x16x32_bf16 v[30:33], v[146:149], v[186:189], v[30:33]
	v_mfma_f32_16x16x32_bf16 v[26:29], v[160:163], v[186:189], v[26:29]
	v_mfma_f32_16x16x32_bf16 v[14:17], v[146:149], v[194:197], v[14:17]
	v_mfma_f32_16x16x32_bf16 v[10:13], v[160:163], v[194:197], v[10:13]
	s_barrier
	s_add_u32 s28, s28, 0x40080
	s_addc_u32 s29, s29, 0
	s_mov_b32 m0, s93
	v_lshl_add_u64 v[130:131], s[28:29], 0, v[138:139]
	global_load_lds_dwordx4 v[130:131], off
	v_lshl_add_u64 v[130:131], s[28:29], 0, v[134:135]
	s_mov_b32 m0, s3
	s_nop 0
	global_load_lds_dwordx4 v[130:131], off
	s_waitcnt vmcnt(6)
	s_barrier
	v_mfma_f32_16x16x32_bf16 v[54:57], v[198:201], v[164:167], v[54:57]
	v_mfma_f32_16x16x32_bf16 v[50:53], v[206:209], v[164:167], v[50:53]
	v_mfma_f32_16x16x32_bf16 v[38:41], v[198:201], v[172:175], v[38:41]
	v_mfma_f32_16x16x32_bf16 v[34:37], v[206:209], v[172:175], v[34:37]
	v_mfma_f32_16x16x32_bf16 v[22:25], v[198:201], v[182:185], v[22:25]
	v_mfma_f32_16x16x32_bf16 v[18:21], v[206:209], v[182:185], v[18:21]
	v_mfma_f32_16x16x32_bf16 v[6:9], v[198:201], v[190:193], v[6:9]
	v_mfma_f32_16x16x32_bf16 v[2:5], v[206:209], v[190:193], v[2:5]
	v_mfma_f32_16x16x32_bf16 v[54:57], v[202:205], v[168:171], v[54:57]
	v_mfma_f32_16x16x32_bf16 v[50:53], v[210:213], v[168:171], v[50:53]
	v_mfma_f32_16x16x32_bf16 v[38:41], v[202:205], v[176:179], v[38:41]
	v_mfma_f32_16x16x32_bf16 v[34:37], v[210:213], v[176:179], v[34:37]
	v_mfma_f32_16x16x32_bf16 v[22:25], v[202:205], v[186:189], v[22:25]
	v_mfma_f32_16x16x32_bf16 v[18:21], v[210:213], v[186:189], v[18:21]
	v_mfma_f32_16x16x32_bf16 v[6:9], v[202:205], v[194:197], v[6:9]
	v_mfma_f32_16x16x32_bf16 v[2:5], v[210:213], v[194:197], v[2:5]
	s_add_i32 s97, s97, 2
	s_add_u32 s26, s26, 0x100
	s_addc_u32 s27, s27, 0
	s_add_u32 s90, s90, 0x100
	s_addc_u32 s94, s94, 0
	s_cmp_gt_u32 s97, 13
	s_barrier
	s_cbranch_scc0 .LBB0_1372
	v_lshl_add_u32 v159, s24, 8, v152
	v_lshl_add_u32 v156, s22, 8, v155
	v_mul_lo_u32 v157, v159, s71
	v_add_u32_e32 v0, v157, v156
	v_lshl_add_u64 v[130:131], v[0:1], 1, s[6:7]
	global_load_dwordx4 v[130:133], v[130:131], off
	v_mul_lo_u32 v158, v159, s61
	v_mov_b32_e32 v210, v0
	v_add_u32_e32 v211, v0, v158
	v_mov_b32_e32 v213, 0
	v_add_u32_e32 v212, 0x80, v210
	v_lshl_add_u64 v[168:169], v[212:213], 1, s[6:7]
	global_load_dwordx4 v[168:171], v[168:169], off
	v_add_u32_e32 v212, 0x80, v211
	v_lshl_add_u64 v[172:173], v[212:213], 1, s[10:11]
	global_load_dwordx4 v[172:175], v[172:173], off
	v_add_u32_e32 v212, 0x16c00, v210
	v_lshl_add_u64 v[176:177], v[212:213], 1, s[6:7]
	global_load_dwordx4 v[176:179], v[176:177], off
	v_add_u32_e32 v212, 0x4000, v211
	v_lshl_add_u64 v[182:183], v[212:213], 1, s[10:11]
	global_load_dwordx4 v[182:185], v[182:183], off
	v_add_u32_e32 v212, 0x16c80, v210
	v_lshl_add_u64 v[186:187], v[212:213], 1, s[6:7]
	global_load_dwordx4 v[186:189], v[186:187], off
	v_add_u32_e32 v212, 0x4080, v211
	v_lshl_add_u64 v[190:191], v[212:213], 1, s[10:11]
	global_load_dwordx4 v[190:193], v[190:191], off
	v_add_u32_e32 v212, 0x2d800, v210
	v_lshl_add_u64 v[194:195], v[212:213], 1, s[6:7]
	global_load_dwordx4 v[194:197], v[194:195], off
	v_add_u32_e32 v212, 0x8000, v211
	v_lshl_add_u64 v[198:199], v[212:213], 1, s[10:11]
	global_load_dwordx4 v[198:201], v[198:199], off
	v_add_u32_e32 v212, 0x2d880, v210
	v_lshl_add_u64 v[202:203], v[212:213], 1, s[6:7]
	global_load_dwordx4 v[202:205], v[202:203], off
	v_add_u32_e32 v212, 0x8080, v211
	v_lshl_add_u64 v[206:207], v[212:213], 1, s[10:11]
	global_load_dwordx4 v[206:209], v[206:207], off
	v_add_u32_e32 v0, v0, v158
	v_lshl_add_u64 v[146:147], v[0:1], 1, s[10:11]
	s_mov_b32 s22, s14
	s_mov_b32 s24, s16
	s_mov_b64 s[28:29], s[20:21]
	s_waitcnt vmcnt(10)
	v_lshlrev_b32_e32 v148, 16, v130
	v_and_b32_e32 v149, 0xffff0000, v130
	v_lshlrev_b32_e32 v151, 16, v131
	v_and_b32_e32 v163, 0xffff0000, v131
	v_lshlrev_b32_e32 v150, 16, v132
	v_and_b32_e32 v161, 0xffff0000, v132
	v_lshlrev_b32_e32 v164, 16, v133
	v_and_b32_e32 v165, 0xffff0000, v133
	global_load_dwordx4 v[130:133], v[146:147], off
	v_mul_f32_e32 v0, 0xbfb8aa3b, v148
	v_exp_f32_e32 v160, v0
	v_mul_f32_e32 v0, 0xbfb8aa3b, v150
	v_exp_f32_e32 v150, v0
	v_mul_f32_e32 v0, 0xbfb8aa3b, v149
	v_exp_f32_e32 v162, v0
	v_mul_f32_e32 v0, 0xbfb8aa3b, v161
	v_exp_f32_e32 v148, v0
	v_mul_f32_e32 v0, 0xbfb8aa3b, v151
	v_exp_f32_e32 v161, v0
	v_mul_f32_e32 v0, 0xbfb8aa3b, v164
	v_exp_f32_e32 v151, v0
	v_mul_f32_e32 v0, 0xbfb8aa3b, v163
	v_exp_f32_e32 v163, v0
	v_mul_f32_e32 v0, 0xbfb8aa3b, v165
	v_pk_add_f32 v[160:161], v[160:161], 1.0 op_sel_hi:[1,0]
	v_exp_f32_e32 v149, v0
	v_pk_add_f32 v[162:163], v[162:163], 1.0 op_sel_hi:[1,0]
	v_rcp_f32_e32 v161, v161
	s_nop 0
	s_waitcnt vmcnt(0)
	v_lshlrev_b32_e32 v165, 16, v131
	v_rcp_f32_e32 v160, v160
	s_nop 0
	v_mov_b32_e32 v166, v126
	v_mov_b32_e32 v167, v128
	v_lshlrev_b32_e32 v164, 16, v130
	v_pk_fma_f32 v[160:161], v[166:167], v[160:161], v[164:165]
	v_rcp_f32_e32 v163, v163
	s_nop 0
	v_and_b32_e32 v131, 0xffff0000, v131
	v_and_b32_e32 v130, 0xffff0000, v130
	v_rcp_f32_e32 v162, v162
	s_nop 0
	v_mov_b32_e32 v128, v127
	v_pk_fma_f32 v[126:127], v[128:129], v[162:163], v[130:131]
	v_cvt_pk_bf16_f32 v0, v160, v161
	v_cvt_pk_bf16_f32 v126, v126, v127
	v_and_b32_e32 v127, 0xffff0000, v126
	v_lshlrev_b32_e32 v126, 16, v126
	v_lshlrev_b32_e32 v131, 16, v133
	v_lshlrev_b32_e32 v130, 16, v132
	v_and_b32_e32 v129, 0xffff0000, v133
	v_and_b32_e32 v128, 0xffff0000, v132
	v_pk_add_f32 v[132:133], v[150:151], 1.0 op_sel_hi:[1,0]
	v_or_b32_sdwa v127, v127, v0 dst_sel:DWORD dst_unused:UNUSED_PAD src0_sel:DWORD src1_sel:WORD_1
	v_or_b32_sdwa v126, v126, v0 dst_sel:DWORD dst_unused:UNUSED_PAD src0_sel:DWORD src1_sel:WORD_0
	s_nop 0
	v_rcp_f32_e32 v133, v133
	s_nop 0
	s_nop 0
	v_rcp_f32_e32 v132, v132
	s_nop 0
	v_mov_b32_e32 v150, v122
	v_mov_b32_e32 v151, v124
	v_pk_fma_f32 v[130:131], v[150:151], v[132:133], v[130:131]
	v_pk_add_f32 v[132:133], v[148:149], 1.0 op_sel_hi:[1,0]
	s_nop 0
	s_nop 0
	v_rcp_f32_e32 v133, v133
	s_nop 0
	s_nop 0
	v_rcp_f32_e32 v132, v132
	s_nop 0
	v_mov_b32_e32 v124, v123
	v_pk_fma_f32 v[122:123], v[124:125], v[132:133], v[128:129]
	v_cvt_pk_bf16_f32 v0, v130, v131
	v_cvt_pk_bf16_f32 v122, v122, v123
	v_and_b32_e32 v123, 0xffff0000, v122
	v_lshlrev_b32_e32 v122, 16, v122
	v_or_b32_sdwa v129, v123, v0 dst_sel:DWORD dst_unused:UNUSED_PAD src0_sel:DWORD src1_sel:WORD_1
	v_or_b32_sdwa v128, v122, v0 dst_sel:DWORD dst_unused:UNUSED_PAD src0_sel:DWORD src1_sel:WORD_0
	global_store_dwordx4 v[146:147], v[126:129], off
	s_nop 1
	v_add_u32_e32 v126, 0x80, v156
	v_add_u32_e32 v0, v157, v126
	v_add_u32_e32 v0, v0, v158
	s_waitcnt vmcnt(11)
	v_lshlrev_b32_e32 v127, 16, v168
	v_and_b32_e32 v133, 0xffff0000, v168
	v_lshlrev_b32_e32 v147, 16, v169
	v_and_b32_e32 v149, 0xffff0000, v169
	v_lshl_add_u64 v[122:123], v[0:1], 1, s[10:11]
	v_lshlrev_b32_e32 v146, 16, v170
	v_mul_f32_e32 v0, 0xbfb8aa3b, v127
	v_exp_f32_e32 v132, v0
	v_mul_f32_e32 v0, 0xbfb8aa3b, v146
	v_and_b32_e32 v124, 0xffff0000, v170
	v_exp_f32_e32 v146, v0
	v_mul_f32_e32 v0, 0xbfb8aa3b, v133
	v_exp_f32_e32 v148, v0
	v_mul_f32_e32 v0, 0xbfb8aa3b, v124
	v_exp_f32_e32 v124, v0
	v_mul_f32_e32 v0, 0xbfb8aa3b, v147
	v_exp_f32_e32 v133, v0
	v_lshlrev_b32_e32 v150, 16, v171
	v_mul_f32_e32 v0, 0xbfb8aa3b, v150
	v_and_b32_e32 v125, 0xffff0000, v171
	v_exp_f32_e32 v147, v0
	v_mul_f32_e32 v0, 0xbfb8aa3b, v149
	v_exp_f32_e32 v149, v0
	v_mul_f32_e32 v0, 0xbfb8aa3b, v125
	v_pk_add_f32 v[132:133], v[132:133], 1.0 op_sel_hi:[1,0]
	v_exp_f32_e32 v125, v0
	v_pk_add_f32 v[148:149], v[148:149], 1.0 op_sel_hi:[1,0]
	v_pk_add_f32 v[124:125], v[124:125], 1.0 op_sel_hi:[1,0]
	v_rcp_f32_e32 v133, v133
	s_nop 0
	s_waitcnt vmcnt(10)
	v_lshlrev_b32_e32 v151, 16, v173
	v_rcp_f32_e32 v132, v132
	s_nop 0
	v_mov_b32_e32 v160, v118
	v_mov_b32_e32 v161, v120
	v_lshlrev_b32_e32 v150, 16, v172
	v_pk_fma_f32 v[132:133], v[160:161], v[132:133], v[150:151]
	v_rcp_f32_e32 v149, v149
	s_nop 0
	v_and_b32_e32 v129, 0xffff0000, v173
	v_and_b32_e32 v128, 0xffff0000, v172
	v_rcp_f32_e32 v148, v148
	s_nop 0
	v_mov_b32_e32 v120, v119
	v_pk_fma_f32 v[118:119], v[120:121], v[148:149], v[128:129]
	v_cvt_pk_bf16_f32 v0, v132, v133
	v_cvt_pk_bf16_f32 v118, v118, v119
	v_and_b32_e32 v119, 0xffff0000, v118
	v_lshlrev_b32_e32 v118, 16, v118
	v_lshlrev_b32_e32 v121, 16, v175
	v_lshlrev_b32_e32 v120, 16, v174
	v_and_b32_e32 v129, 0xffff0000, v175
	v_and_b32_e32 v128, 0xffff0000, v174
	v_pk_add_f32 v[130:131], v[146:147], 1.0 op_sel_hi:[1,0]
	v_or_b32_sdwa v119, v119, v0 dst_sel:DWORD dst_unused:UNUSED_PAD src0_sel:DWORD src1_sel:WORD_1
	v_or_b32_sdwa v118, v118, v0 dst_sel:DWORD dst_unused:UNUSED_PAD src0_sel:DWORD src1_sel:WORD_0
	s_nop 0
	v_rcp_f32_e32 v131, v131
	s_nop 0
	s_nop 0
	v_rcp_f32_e32 v130, v130
	s_nop 0
	v_mov_b32_e32 v132, v114
	v_mov_b32_e32 v133, v116
	v_pk_fma_f32 v[120:121], v[132:133], v[130:131], v[120:121]
	v_rcp_f32_e32 v125, v125
	s_nop 0
	s_nop 0
	v_rcp_f32_e32 v124, v124
	s_nop 0
	v_mov_b32_e32 v116, v115
	v_pk_fma_f32 v[114:115], v[116:117], v[124:125], v[128:129]
	v_cvt_pk_bf16_f32 v0, v120, v121
	v_cvt_pk_bf16_f32 v114, v114, v115
	v_and_b32_e32 v115, 0xffff0000, v114
	v_lshlrev_b32_e32 v114, 16, v114
	v_add_u32_e32 v127, 0x16c00, v157
	v_or_b32_sdwa v121, v115, v0 dst_sel:DWORD dst_unused:UNUSED_PAD src0_sel:DWORD src1_sel:WORD_1
	v_or_b32_sdwa v120, v114, v0 dst_sel:DWORD dst_unused:UNUSED_PAD src0_sel:DWORD src1_sel:WORD_0
	v_add_u32_e32 v0, v127, v156
	v_add_u32_e32 v212, 0x44400, v210
	v_lshl_add_u64 v[168:169], v[212:213], 1, s[6:7]
	global_load_dwordx4 v[168:171], v[168:169], off
	v_add_u32_e32 v212, 0xc000, v211
	v_lshl_add_u64 v[172:173], v[212:213], 1, s[10:11]
	global_load_dwordx4 v[172:175], v[172:173], off
	global_store_dwordx4 v[122:123], v[118:121], off
	s_nop 1
	v_or_b32_e32 v118, 16, v159
	v_mul_lo_u32 v146, v118, s61
	v_add_u32_e32 v0, v0, v146
	s_waitcnt vmcnt(12)
	v_lshlrev_b32_e32 v122, 16, v176
	v_and_b32_e32 v123, 0xffff0000, v176
	v_lshlrev_b32_e32 v125, 16, v177
	v_and_b32_e32 v129, 0xffff0000, v177
	v_lshl_add_u64 v[114:115], v[0:1], 1, s[10:11]
	v_lshlrev_b32_e32 v124, 16, v178
	v_mul_f32_e32 v0, 0xbfb8aa3b, v122
	v_exp_f32_e32 v122, v0
	v_mul_f32_e32 v0, 0xbfb8aa3b, v124
	v_and_b32_e32 v116, 0xffff0000, v178
	v_exp_f32_e32 v124, v0
	v_mul_f32_e32 v0, 0xbfb8aa3b, v123
	v_exp_f32_e32 v128, v0
	v_mul_f32_e32 v0, 0xbfb8aa3b, v116
	v_exp_f32_e32 v116, v0
	v_mul_f32_e32 v0, 0xbfb8aa3b, v125
	v_exp_f32_e32 v123, v0
	v_lshlrev_b32_e32 v130, 16, v179
	v_mul_f32_e32 v0, 0xbfb8aa3b, v130
	v_and_b32_e32 v117, 0xffff0000, v179
	v_exp_f32_e32 v125, v0
	v_mul_f32_e32 v0, 0xbfb8aa3b, v129
	v_exp_f32_e32 v129, v0
	v_mul_f32_e32 v0, 0xbfb8aa3b, v117
	v_pk_add_f32 v[122:123], v[122:123], 1.0 op_sel_hi:[1,0]
	v_exp_f32_e32 v117, v0
	v_pk_add_f32 v[128:129], v[128:129], 1.0 op_sel_hi:[1,0]
	v_pk_add_f32 v[116:117], v[116:117], 1.0 op_sel_hi:[1,0]
	v_rcp_f32_e32 v123, v123
	s_nop 0
	s_waitcnt vmcnt(11)
	v_lshlrev_b32_e32 v131, 16, v183
	v_rcp_f32_e32 v122, v122
	s_nop 0
	v_mov_b32_e32 v132, v110
	v_mov_b32_e32 v133, v112
	v_lshlrev_b32_e32 v130, 16, v182
	v_pk_fma_f32 v[122:123], v[132:133], v[122:123], v[130:131]
	v_rcp_f32_e32 v129, v129
	s_nop 0
	v_and_b32_e32 v119, 0xffff0000, v183
	v_and_b32_e32 v118, 0xffff0000, v182
	v_rcp_f32_e32 v128, v128
	s_nop 0
	v_mov_b32_e32 v112, v111
	v_pk_fma_f32 v[110:111], v[112:113], v[128:129], v[118:119]
	v_cvt_pk_bf16_f32 v0, v122, v123
	v_cvt_pk_bf16_f32 v110, v110, v111
	v_and_b32_e32 v111, 0xffff0000, v110
	v_lshlrev_b32_e32 v110, 16, v110
	v_lshlrev_b32_e32 v113, 16, v185
	v_lshlrev_b32_e32 v112, 16, v184
	v_and_b32_e32 v119, 0xffff0000, v185
	v_and_b32_e32 v118, 0xffff0000, v184
	v_pk_add_f32 v[120:121], v[124:125], 1.0 op_sel_hi:[1,0]
	v_or_b32_sdwa v111, v111, v0 dst_sel:DWORD dst_unused:UNUSED_PAD src0_sel:DWORD src1_sel:WORD_1
	v_or_b32_sdwa v110, v110, v0 dst_sel:DWORD dst_unused:UNUSED_PAD src0_sel:DWORD src1_sel:WORD_0
	s_nop 0
	v_rcp_f32_e32 v121, v121
	s_nop 0
	s_nop 0
	v_rcp_f32_e32 v120, v120
	s_nop 0
	v_mov_b32_e32 v122, v106
	v_mov_b32_e32 v123, v108
	v_pk_fma_f32 v[112:113], v[122:123], v[120:121], v[112:113]
	v_rcp_f32_e32 v117, v117
	s_nop 0
	s_nop 0
	v_rcp_f32_e32 v116, v116
	s_nop 0
	v_mov_b32_e32 v108, v107
	v_pk_fma_f32 v[106:107], v[108:109], v[116:117], v[118:119]
	v_cvt_pk_bf16_f32 v0, v112, v113
	v_cvt_pk_bf16_f32 v106, v106, v107
	v_and_b32_e32 v107, 0xffff0000, v106
	v_lshlrev_b32_e32 v106, 16, v106
	v_or_b32_sdwa v113, v107, v0 dst_sel:DWORD dst_unused:UNUSED_PAD src0_sel:DWORD src1_sel:WORD_1
	v_or_b32_sdwa v112, v106, v0 dst_sel:DWORD dst_unused:UNUSED_PAD src0_sel:DWORD src1_sel:WORD_0
	v_add_u32_e32 v0, v127, v126
	v_add_u32_e32 v212, 0x44480, v210
	v_lshl_add_u64 v[176:177], v[212:213], 1, s[6:7]
	global_load_dwordx4 v[176:179], v[176:177], off
	v_add_u32_e32 v212, 0xc080, v211
	v_lshl_add_u64 v[182:183], v[212:213], 1, s[10:11]
	global_load_dwordx4 v[182:185], v[182:183], off
	global_store_dwordx4 v[114:115], v[110:113], off
	v_add_u32_e32 v0, v0, v146
	s_waitcnt vmcnt(13)
	v_lshlrev_b32_e32 v114, 16, v186
	v_and_b32_e32 v115, 0xffff0000, v186
	v_lshlrev_b32_e32 v117, 16, v187
	v_and_b32_e32 v119, 0xffff0000, v187
	v_lshl_add_u64 v[106:107], v[0:1], 1, s[10:11]
	v_lshlrev_b32_e32 v116, 16, v188
	v_mul_f32_e32 v0, 0xbfb8aa3b, v114
	v_exp_f32_e32 v114, v0
	v_mul_f32_e32 v0, 0xbfb8aa3b, v116
	v_and_b32_e32 v108, 0xffff0000, v188
	v_exp_f32_e32 v116, v0
	v_mul_f32_e32 v0, 0xbfb8aa3b, v115
	v_exp_f32_e32 v118, v0
	v_mul_f32_e32 v0, 0xbfb8aa3b, v108
	v_exp_f32_e32 v108, v0
	v_mul_f32_e32 v0, 0xbfb8aa3b, v117
	v_exp_f32_e32 v115, v0
	v_lshlrev_b32_e32 v120, 16, v189
	v_mul_f32_e32 v0, 0xbfb8aa3b, v120
	v_and_b32_e32 v109, 0xffff0000, v189
	v_exp_f32_e32 v117, v0
	v_mul_f32_e32 v0, 0xbfb8aa3b, v119
	v_exp_f32_e32 v119, v0
	v_mul_f32_e32 v0, 0xbfb8aa3b, v109
	v_pk_add_f32 v[114:115], v[114:115], 1.0 op_sel_hi:[1,0]
	v_exp_f32_e32 v109, v0
	v_pk_add_f32 v[118:119], v[118:119], 1.0 op_sel_hi:[1,0]
	v_pk_add_f32 v[108:109], v[108:109], 1.0 op_sel_hi:[1,0]
	v_rcp_f32_e32 v115, v115
	s_nop 0
	s_waitcnt vmcnt(12)
	v_lshlrev_b32_e32 v121, 16, v191
	v_rcp_f32_e32 v114, v114
	s_nop 0
	v_mov_b32_e32 v122, v102
	v_mov_b32_e32 v123, v104
	v_lshlrev_b32_e32 v120, 16, v190
	v_pk_fma_f32 v[114:115], v[122:123], v[114:115], v[120:121]
	v_rcp_f32_e32 v119, v119
	s_nop 0
	v_and_b32_e32 v111, 0xffff0000, v191
	v_and_b32_e32 v110, 0xffff0000, v190
	v_rcp_f32_e32 v118, v118
	s_nop 0
	v_mov_b32_e32 v104, v103
	v_pk_fma_f32 v[102:103], v[104:105], v[118:119], v[110:111]
	v_cvt_pk_bf16_f32 v0, v114, v115
	v_cvt_pk_bf16_f32 v102, v102, v103
	v_and_b32_e32 v103, 0xffff0000, v102
	v_lshlrev_b32_e32 v102, 16, v102
	v_lshlrev_b32_e32 v105, 16, v193
	v_lshlrev_b32_e32 v104, 16, v192
	v_and_b32_e32 v111, 0xffff0000, v193
	v_and_b32_e32 v110, 0xffff0000, v192
	v_pk_add_f32 v[112:113], v[116:117], 1.0 op_sel_hi:[1,0]
	v_or_b32_sdwa v103, v103, v0 dst_sel:DWORD dst_unused:UNUSED_PAD src0_sel:DWORD src1_sel:WORD_1
	v_or_b32_sdwa v102, v102, v0 dst_sel:DWORD dst_unused:UNUSED_PAD src0_sel:DWORD src1_sel:WORD_0
	s_nop 0
	v_rcp_f32_e32 v113, v113
	s_nop 0
	s_nop 0
	v_rcp_f32_e32 v112, v112
	s_nop 0
	v_mov_b32_e32 v114, v98
	v_mov_b32_e32 v115, v100
	v_pk_fma_f32 v[104:105], v[114:115], v[112:113], v[104:105]
	v_add_u32_e32 v116, 0x2d800, v157
	v_rcp_f32_e32 v109, v109
	s_nop 0
	s_nop 0
	v_rcp_f32_e32 v108, v108
	s_nop 0
	v_mov_b32_e32 v100, v99
	v_pk_fma_f32 v[98:99], v[100:101], v[108:109], v[110:111]
	v_cvt_pk_bf16_f32 v0, v104, v105
	v_cvt_pk_bf16_f32 v98, v98, v99
	v_and_b32_e32 v99, 0xffff0000, v98
	v_lshlrev_b32_e32 v98, 16, v98
	v_or_b32_sdwa v105, v99, v0 dst_sel:DWORD dst_unused:UNUSED_PAD src0_sel:DWORD src1_sel:WORD_1
	v_or_b32_sdwa v104, v98, v0 dst_sel:DWORD dst_unused:UNUSED_PAD src0_sel:DWORD src1_sel:WORD_0
	v_add_u32_e32 v0, v116, v156
	v_add_u32_e32 v212, 0xb6000, v210
	v_lshl_add_u64 v[186:187], v[212:213], 1, s[6:7]
	global_load_dwordx4 v[186:189], v[186:187], off
	v_add_u32_e32 v212, 0x20000, v211
	v_lshl_add_u64 v[190:191], v[212:213], 1, s[10:11]
	global_load_dwordx4 v[190:193], v[190:191], off
	global_store_dwordx4 v[106:107], v[102:105], off
	s_nop 1
	v_or_b32_e32 v102, 32, v159
	v_mul_lo_u32 v117, v102, s61
	v_add_u32_e32 v0, v0, v117
	s_waitcnt vmcnt(14)
	v_lshlrev_b32_e32 v106, 16, v194
	v_and_b32_e32 v107, 0xffff0000, v194
	v_lshlrev_b32_e32 v109, 16, v195
	v_and_b32_e32 v111, 0xffff0000, v195
	v_lshl_add_u64 v[98:99], v[0:1], 1, s[10:11]
	v_lshlrev_b32_e32 v108, 16, v196
	v_mul_f32_e32 v0, 0xbfb8aa3b, v106
	v_exp_f32_e32 v106, v0
	v_mul_f32_e32 v0, 0xbfb8aa3b, v108
	v_and_b32_e32 v100, 0xffff0000, v196
	v_exp_f32_e32 v108, v0
	v_mul_f32_e32 v0, 0xbfb8aa3b, v107
	v_exp_f32_e32 v110, v0
	v_mul_f32_e32 v0, 0xbfb8aa3b, v100
	v_exp_f32_e32 v100, v0
	v_mul_f32_e32 v0, 0xbfb8aa3b, v109
	v_exp_f32_e32 v107, v0
	v_lshlrev_b32_e32 v112, 16, v197
	v_mul_f32_e32 v0, 0xbfb8aa3b, v112
	v_and_b32_e32 v101, 0xffff0000, v197
	v_exp_f32_e32 v109, v0
	v_mul_f32_e32 v0, 0xbfb8aa3b, v111
	v_exp_f32_e32 v111, v0
	v_mul_f32_e32 v0, 0xbfb8aa3b, v101
	v_pk_add_f32 v[106:107], v[106:107], 1.0 op_sel_hi:[1,0]
	v_exp_f32_e32 v101, v0
	v_pk_add_f32 v[110:111], v[110:111], 1.0 op_sel_hi:[1,0]
	v_pk_add_f32 v[100:101], v[100:101], 1.0 op_sel_hi:[1,0]
	v_rcp_f32_e32 v107, v107
	s_nop 0
	s_waitcnt vmcnt(13)
	v_lshlrev_b32_e32 v113, 16, v199
	v_rcp_f32_e32 v106, v106
	s_nop 0
	v_mov_b32_e32 v114, v94
	v_mov_b32_e32 v115, v96
	v_lshlrev_b32_e32 v112, 16, v198
	v_pk_fma_f32 v[106:107], v[114:115], v[106:107], v[112:113]
	v_rcp_f32_e32 v111, v111
	s_nop 0
	v_and_b32_e32 v103, 0xffff0000, v199
	v_and_b32_e32 v102, 0xffff0000, v198
	v_rcp_f32_e32 v110, v110
	s_nop 0
	v_mov_b32_e32 v96, v95
	v_pk_fma_f32 v[94:95], v[96:97], v[110:111], v[102:103]
	v_cvt_pk_bf16_f32 v0, v106, v107
	v_cvt_pk_bf16_f32 v94, v94, v95
	v_and_b32_e32 v95, 0xffff0000, v94
	v_lshlrev_b32_e32 v94, 16, v94
	v_lshlrev_b32_e32 v97, 16, v201
	v_lshlrev_b32_e32 v96, 16, v200
	v_and_b32_e32 v103, 0xffff0000, v201
	v_and_b32_e32 v102, 0xffff0000, v200
	v_pk_add_f32 v[104:105], v[108:109], 1.0 op_sel_hi:[1,0]
	v_or_b32_sdwa v95, v95, v0 dst_sel:DWORD dst_unused:UNUSED_PAD src0_sel:DWORD src1_sel:WORD_1
	v_or_b32_sdwa v94, v94, v0 dst_sel:DWORD dst_unused:UNUSED_PAD src0_sel:DWORD src1_sel:WORD_0
	s_nop 0
	v_rcp_f32_e32 v105, v105
	s_nop 0
	s_nop 0
	v_rcp_f32_e32 v104, v104
	s_nop 0
	v_mov_b32_e32 v106, v90
	v_mov_b32_e32 v107, v92
	v_pk_fma_f32 v[96:97], v[106:107], v[104:105], v[96:97]
	v_rcp_f32_e32 v101, v101
	s_nop 0
	s_nop 0
	v_rcp_f32_e32 v100, v100
	s_nop 0
	v_mov_b32_e32 v92, v91
	v_pk_fma_f32 v[90:91], v[92:93], v[100:101], v[102:103]
	v_cvt_pk_bf16_f32 v0, v96, v97
	v_cvt_pk_bf16_f32 v90, v90, v91
	v_and_b32_e32 v91, 0xffff0000, v90
	v_lshlrev_b32_e32 v90, 16, v90
	v_or_b32_sdwa v97, v91, v0 dst_sel:DWORD dst_unused:UNUSED_PAD src0_sel:DWORD src1_sel:WORD_1
	v_or_b32_sdwa v96, v90, v0 dst_sel:DWORD dst_unused:UNUSED_PAD src0_sel:DWORD src1_sel:WORD_0
	v_add_u32_e32 v0, v116, v126
	v_add_u32_e32 v212, 0xb6080, v210
	v_lshl_add_u64 v[194:195], v[212:213], 1, s[6:7]
	global_load_dwordx4 v[194:197], v[194:195], off
	v_add_u32_e32 v212, 0x20080, v211
	v_lshl_add_u64 v[198:199], v[212:213], 1, s[10:11]
	global_load_dwordx4 v[198:201], v[198:199], off
	global_store_dwordx4 v[98:99], v[94:97], off
	v_add_u32_e32 v0, v0, v117
	s_waitcnt vmcnt(15)
	v_lshlrev_b32_e32 v98, 16, v202
	v_and_b32_e32 v99, 0xffff0000, v202
	v_lshlrev_b32_e32 v101, 16, v203
	v_and_b32_e32 v103, 0xffff0000, v203
	v_lshl_add_u64 v[90:91], v[0:1], 1, s[10:11]
	v_lshlrev_b32_e32 v100, 16, v204
	v_mul_f32_e32 v0, 0xbfb8aa3b, v98
	v_exp_f32_e32 v98, v0
	v_mul_f32_e32 v0, 0xbfb8aa3b, v100
	v_and_b32_e32 v92, 0xffff0000, v204
	v_exp_f32_e32 v100, v0
	v_mul_f32_e32 v0, 0xbfb8aa3b, v99
	v_exp_f32_e32 v102, v0
	v_mul_f32_e32 v0, 0xbfb8aa3b, v92
	v_exp_f32_e32 v92, v0
	v_mul_f32_e32 v0, 0xbfb8aa3b, v101
	v_exp_f32_e32 v99, v0
	v_lshlrev_b32_e32 v104, 16, v205
	v_mul_f32_e32 v0, 0xbfb8aa3b, v104
	v_and_b32_e32 v93, 0xffff0000, v205
	v_exp_f32_e32 v101, v0
	v_mul_f32_e32 v0, 0xbfb8aa3b, v103
	v_exp_f32_e32 v103, v0
	v_mul_f32_e32 v0, 0xbfb8aa3b, v93
	v_pk_add_f32 v[98:99], v[98:99], 1.0 op_sel_hi:[1,0]
	v_exp_f32_e32 v93, v0
	v_pk_add_f32 v[102:103], v[102:103], 1.0 op_sel_hi:[1,0]
	v_pk_add_f32 v[92:93], v[92:93], 1.0 op_sel_hi:[1,0]
	v_rcp_f32_e32 v99, v99
	s_nop 0
	s_waitcnt vmcnt(14)
	v_lshlrev_b32_e32 v105, 16, v207
	v_rcp_f32_e32 v98, v98
	s_nop 0
	v_mov_b32_e32 v106, v86
	v_mov_b32_e32 v107, v88
	v_lshlrev_b32_e32 v104, 16, v206
	v_pk_fma_f32 v[98:99], v[106:107], v[98:99], v[104:105]
	v_rcp_f32_e32 v103, v103
	s_nop 0
	v_and_b32_e32 v95, 0xffff0000, v207
	v_and_b32_e32 v94, 0xffff0000, v206
	v_rcp_f32_e32 v102, v102
	s_nop 0
	v_mov_b32_e32 v88, v87
	v_pk_fma_f32 v[86:87], v[88:89], v[102:103], v[94:95]
	v_cvt_pk_bf16_f32 v0, v98, v99
	v_cvt_pk_bf16_f32 v86, v86, v87
	v_and_b32_e32 v87, 0xffff0000, v86
	v_lshlrev_b32_e32 v86, 16, v86
	v_lshlrev_b32_e32 v89, 16, v209
	v_lshlrev_b32_e32 v88, 16, v208
	v_and_b32_e32 v95, 0xffff0000, v209
	v_and_b32_e32 v94, 0xffff0000, v208
	v_pk_add_f32 v[96:97], v[100:101], 1.0 op_sel_hi:[1,0]
	v_or_b32_sdwa v87, v87, v0 dst_sel:DWORD dst_unused:UNUSED_PAD src0_sel:DWORD src1_sel:WORD_1
	v_or_b32_sdwa v86, v86, v0 dst_sel:DWORD dst_unused:UNUSED_PAD src0_sel:DWORD src1_sel:WORD_0
	s_nop 0
	v_rcp_f32_e32 v97, v97
	s_nop 0
	s_nop 0
	v_rcp_f32_e32 v96, v96
	s_nop 0
	v_mov_b32_e32 v98, v82
	v_mov_b32_e32 v99, v84
	v_pk_fma_f32 v[88:89], v[98:99], v[96:97], v[88:89]
	v_add_u32_e32 v100, 0x44400, v157
	v_rcp_f32_e32 v93, v93
	s_nop 0
	s_nop 0
	v_rcp_f32_e32 v92, v92
	s_nop 0
	v_mov_b32_e32 v84, v83
	v_pk_fma_f32 v[82:83], v[84:85], v[92:93], v[94:95]
	v_cvt_pk_bf16_f32 v0, v88, v89
	v_cvt_pk_bf16_f32 v82, v82, v83
	v_and_b32_e32 v83, 0xffff0000, v82
	v_lshlrev_b32_e32 v82, 16, v82
	v_or_b32_sdwa v89, v83, v0 dst_sel:DWORD dst_unused:UNUSED_PAD src0_sel:DWORD src1_sel:WORD_1
	v_or_b32_sdwa v88, v82, v0 dst_sel:DWORD dst_unused:UNUSED_PAD src0_sel:DWORD src1_sel:WORD_0
	v_add_u32_e32 v0, v100, v156
	v_add_u32_e32 v212, 0xccc00, v210
	v_lshl_add_u64 v[202:203], v[212:213], 1, s[6:7]
	global_load_dwordx4 v[202:205], v[202:203], off
	v_add_u32_e32 v212, 0x24000, v211
	v_lshl_add_u64 v[206:207], v[212:213], 1, s[10:11]
	global_load_dwordx4 v[206:209], v[206:207], off
	global_store_dwordx4 v[90:91], v[86:89], off
	s_nop 1
	v_or_b32_e32 v86, 48, v159
	v_mul_lo_u32 v101, v86, s61
	v_add_u32_e32 v0, v0, v101
	s_waitcnt vmcnt(14)
	v_lshlrev_b32_e32 v90, 16, v168
	v_and_b32_e32 v91, 0xffff0000, v168
	v_lshlrev_b32_e32 v93, 16, v169
	v_and_b32_e32 v95, 0xffff0000, v169
	v_lshl_add_u64 v[82:83], v[0:1], 1, s[10:11]
	v_lshlrev_b32_e32 v92, 16, v170
	v_mul_f32_e32 v0, 0xbfb8aa3b, v90
	v_exp_f32_e32 v90, v0
	v_mul_f32_e32 v0, 0xbfb8aa3b, v92
	v_and_b32_e32 v84, 0xffff0000, v170
	v_exp_f32_e32 v92, v0
	v_mul_f32_e32 v0, 0xbfb8aa3b, v91
	v_exp_f32_e32 v94, v0
	v_mul_f32_e32 v0, 0xbfb8aa3b, v84
	v_exp_f32_e32 v84, v0
	v_mul_f32_e32 v0, 0xbfb8aa3b, v93
	v_exp_f32_e32 v91, v0
	v_lshlrev_b32_e32 v96, 16, v171
	v_mul_f32_e32 v0, 0xbfb8aa3b, v96
	v_and_b32_e32 v85, 0xffff0000, v171
	v_exp_f32_e32 v93, v0
	v_mul_f32_e32 v0, 0xbfb8aa3b, v95
	v_exp_f32_e32 v95, v0
	v_mul_f32_e32 v0, 0xbfb8aa3b, v85
	v_pk_add_f32 v[90:91], v[90:91], 1.0 op_sel_hi:[1,0]
	v_exp_f32_e32 v85, v0
	v_pk_add_f32 v[94:95], v[94:95], 1.0 op_sel_hi:[1,0]
	v_pk_add_f32 v[84:85], v[84:85], 1.0 op_sel_hi:[1,0]
	v_rcp_f32_e32 v91, v91
	s_nop 0
	s_waitcnt vmcnt(13)
	v_lshlrev_b32_e32 v97, 16, v173
	v_rcp_f32_e32 v90, v90
	s_nop 0
	v_mov_b32_e32 v98, v78
	v_mov_b32_e32 v99, v80
	v_lshlrev_b32_e32 v96, 16, v172
	v_pk_fma_f32 v[90:91], v[98:99], v[90:91], v[96:97]
	v_rcp_f32_e32 v95, v95
	s_nop 0
	v_and_b32_e32 v87, 0xffff0000, v173
	v_and_b32_e32 v86, 0xffff0000, v172
	v_rcp_f32_e32 v94, v94
	s_nop 0
	v_mov_b32_e32 v80, v79
	v_pk_fma_f32 v[78:79], v[80:81], v[94:95], v[86:87]
	v_cvt_pk_bf16_f32 v0, v90, v91
	v_cvt_pk_bf16_f32 v78, v78, v79
	v_and_b32_e32 v79, 0xffff0000, v78
	v_lshlrev_b32_e32 v78, 16, v78
	v_lshlrev_b32_e32 v81, 16, v175
	v_lshlrev_b32_e32 v80, 16, v174
	v_and_b32_e32 v87, 0xffff0000, v175
	v_and_b32_e32 v86, 0xffff0000, v174
	v_pk_add_f32 v[88:89], v[92:93], 1.0 op_sel_hi:[1,0]
	v_or_b32_sdwa v79, v79, v0 dst_sel:DWORD dst_unused:UNUSED_PAD src0_sel:DWORD src1_sel:WORD_1
	v_or_b32_sdwa v78, v78, v0 dst_sel:DWORD dst_unused:UNUSED_PAD src0_sel:DWORD src1_sel:WORD_0
	s_nop 0
	v_rcp_f32_e32 v89, v89
	s_nop 0
	s_nop 0
	v_rcp_f32_e32 v88, v88
	s_nop 0
	v_mov_b32_e32 v90, v74
	v_mov_b32_e32 v91, v76
	v_pk_fma_f32 v[80:81], v[90:91], v[88:89], v[80:81]
	v_rcp_f32_e32 v85, v85
	s_nop 0
	s_nop 0
	v_rcp_f32_e32 v84, v84
	s_nop 0
	v_mov_b32_e32 v76, v75
	v_pk_fma_f32 v[74:75], v[76:77], v[84:85], v[86:87]
	v_cvt_pk_bf16_f32 v0, v80, v81
	v_cvt_pk_bf16_f32 v74, v74, v75
	v_and_b32_e32 v75, 0xffff0000, v74
	v_lshlrev_b32_e32 v74, 16, v74
	v_or_b32_sdwa v81, v75, v0 dst_sel:DWORD dst_unused:UNUSED_PAD src0_sel:DWORD src1_sel:WORD_1
	v_or_b32_sdwa v80, v74, v0 dst_sel:DWORD dst_unused:UNUSED_PAD src0_sel:DWORD src1_sel:WORD_0
	v_add_u32_e32 v0, v100, v126
	v_add_u32_e32 v212, 0xccc80, v210
	v_lshl_add_u64 v[168:169], v[212:213], 1, s[6:7]
	global_load_dwordx4 v[168:171], v[168:169], off
	v_add_u32_e32 v212, 0x24080, v211
	v_lshl_add_u64 v[172:173], v[212:213], 1, s[10:11]
	global_load_dwordx4 v[172:175], v[172:173], off
	global_store_dwordx4 v[82:83], v[78:81], off
	v_add_u32_e32 v0, v0, v101
	s_waitcnt vmcnt(14)
	v_lshlrev_b32_e32 v82, 16, v176
	v_and_b32_e32 v83, 0xffff0000, v176
	v_lshlrev_b32_e32 v85, 16, v177
	v_and_b32_e32 v87, 0xffff0000, v177
	v_lshl_add_u64 v[74:75], v[0:1], 1, s[10:11]
	v_lshlrev_b32_e32 v84, 16, v178
	v_mul_f32_e32 v0, 0xbfb8aa3b, v82
	v_exp_f32_e32 v82, v0
	v_mul_f32_e32 v0, 0xbfb8aa3b, v84
	v_and_b32_e32 v76, 0xffff0000, v178
	v_exp_f32_e32 v84, v0
	v_mul_f32_e32 v0, 0xbfb8aa3b, v83
	v_exp_f32_e32 v86, v0
	v_mul_f32_e32 v0, 0xbfb8aa3b, v76
	v_exp_f32_e32 v76, v0
	v_mul_f32_e32 v0, 0xbfb8aa3b, v85
	v_exp_f32_e32 v83, v0
	v_lshlrev_b32_e32 v88, 16, v179
	v_mul_f32_e32 v0, 0xbfb8aa3b, v88
	v_and_b32_e32 v77, 0xffff0000, v179
	v_exp_f32_e32 v85, v0
	v_mul_f32_e32 v0, 0xbfb8aa3b, v87
	v_exp_f32_e32 v87, v0
	v_mul_f32_e32 v0, 0xbfb8aa3b, v77
	v_pk_add_f32 v[82:83], v[82:83], 1.0 op_sel_hi:[1,0]
	v_exp_f32_e32 v77, v0
	v_pk_add_f32 v[86:87], v[86:87], 1.0 op_sel_hi:[1,0]
	v_pk_add_f32 v[76:77], v[76:77], 1.0 op_sel_hi:[1,0]
	v_rcp_f32_e32 v83, v83
	s_nop 0
	s_waitcnt vmcnt(13)
	v_lshlrev_b32_e32 v89, 16, v183
	v_rcp_f32_e32 v82, v82
	s_nop 0
	v_mov_b32_e32 v90, v70
	v_mov_b32_e32 v91, v72
	v_lshlrev_b32_e32 v88, 16, v182
	v_pk_fma_f32 v[82:83], v[90:91], v[82:83], v[88:89]
	v_rcp_f32_e32 v87, v87
	s_nop 0
	v_and_b32_e32 v79, 0xffff0000, v183
	v_and_b32_e32 v78, 0xffff0000, v182
	v_rcp_f32_e32 v86, v86
	s_nop 0
	v_mov_b32_e32 v72, v71
	v_pk_fma_f32 v[70:71], v[72:73], v[86:87], v[78:79]
	v_cvt_pk_bf16_f32 v0, v82, v83
	v_cvt_pk_bf16_f32 v70, v70, v71
	v_and_b32_e32 v71, 0xffff0000, v70
	v_lshlrev_b32_e32 v70, 16, v70
	v_lshlrev_b32_e32 v73, 16, v185
	v_lshlrev_b32_e32 v72, 16, v184
	v_and_b32_e32 v79, 0xffff0000, v185
	v_and_b32_e32 v78, 0xffff0000, v184
	v_pk_add_f32 v[80:81], v[84:85], 1.0 op_sel_hi:[1,0]
	v_or_b32_sdwa v71, v71, v0 dst_sel:DWORD dst_unused:UNUSED_PAD src0_sel:DWORD src1_sel:WORD_1
	v_or_b32_sdwa v70, v70, v0 dst_sel:DWORD dst_unused:UNUSED_PAD src0_sel:DWORD src1_sel:WORD_0
	s_nop 0
	v_rcp_f32_e32 v81, v81
	s_nop 0
	s_nop 0
	v_rcp_f32_e32 v80, v80
	s_nop 0
	v_mov_b32_e32 v82, v66
	v_mov_b32_e32 v83, v68
	v_pk_fma_f32 v[72:73], v[82:83], v[80:81], v[72:73]
	v_add_u32_e32 v84, 0xb6000, v157
	v_rcp_f32_e32 v77, v77
	s_nop 0
	v_add_u32_e32 v85, 0xfff6a000, v158
	v_rcp_f32_e32 v76, v76
	s_nop 0
	v_mov_b32_e32 v68, v67
	v_pk_fma_f32 v[66:67], v[68:69], v[76:77], v[78:79]
	v_cvt_pk_bf16_f32 v0, v72, v73
	v_cvt_pk_bf16_f32 v66, v66, v67
	v_and_b32_e32 v67, 0xffff0000, v66
	v_lshlrev_b32_e32 v66, 16, v66
	v_or_b32_sdwa v73, v67, v0 dst_sel:DWORD dst_unused:UNUSED_PAD src0_sel:DWORD src1_sel:WORD_1
	v_or_b32_sdwa v72, v66, v0 dst_sel:DWORD dst_unused:UNUSED_PAD src0_sel:DWORD src1_sel:WORD_0
	v_add_u32_e32 v0, v84, v156
	v_add_u32_e32 v212, 0xe3800, v210
	v_lshl_add_u64 v[176:177], v[212:213], 1, s[6:7]
	global_load_dwordx4 v[176:179], v[176:177], off
	v_add_u32_e32 v212, 0x28000, v211
	v_lshl_add_u64 v[182:183], v[212:213], 1, s[10:11]
	global_load_dwordx4 v[182:185], v[182:183], off
	global_store_dwordx4 v[74:75], v[70:73], off
	v_add_u32_e32 v0, v0, v85
	s_waitcnt vmcnt(14)
	v_lshlrev_b32_e32 v74, 16, v186
	v_and_b32_e32 v75, 0xffff0000, v186
	v_lshlrev_b32_e32 v77, 16, v187
	v_and_b32_e32 v79, 0xffff0000, v187
	v_lshl_add_u64 v[66:67], v[0:1], 1, s[10:11]
	v_lshlrev_b32_e32 v76, 16, v188
	v_mul_f32_e32 v0, 0xbfb8aa3b, v74
	v_exp_f32_e32 v74, v0
	v_mul_f32_e32 v0, 0xbfb8aa3b, v76
	v_and_b32_e32 v68, 0xffff0000, v188
	v_exp_f32_e32 v76, v0
	v_mul_f32_e32 v0, 0xbfb8aa3b, v75
	v_exp_f32_e32 v78, v0
	v_mul_f32_e32 v0, 0xbfb8aa3b, v68
	v_exp_f32_e32 v68, v0
	v_mul_f32_e32 v0, 0xbfb8aa3b, v77
	v_exp_f32_e32 v75, v0
	v_lshlrev_b32_e32 v80, 16, v189
	v_mul_f32_e32 v0, 0xbfb8aa3b, v80
	v_and_b32_e32 v69, 0xffff0000, v189
	v_exp_f32_e32 v77, v0
	v_mul_f32_e32 v0, 0xbfb8aa3b, v79
	v_exp_f32_e32 v79, v0
	v_mul_f32_e32 v0, 0xbfb8aa3b, v69
	v_pk_add_f32 v[74:75], v[74:75], 1.0 op_sel_hi:[1,0]
	v_exp_f32_e32 v69, v0
	v_pk_add_f32 v[78:79], v[78:79], 1.0 op_sel_hi:[1,0]
	v_pk_add_f32 v[68:69], v[68:69], 1.0 op_sel_hi:[1,0]
	v_rcp_f32_e32 v75, v75
	s_nop 0
	s_waitcnt vmcnt(13)
	v_lshlrev_b32_e32 v81, 16, v191
	v_rcp_f32_e32 v74, v74
	s_nop 0
	v_mov_b32_e32 v82, v62
	v_mov_b32_e32 v83, v64
	v_lshlrev_b32_e32 v80, 16, v190
	v_pk_fma_f32 v[74:75], v[82:83], v[74:75], v[80:81]
	v_rcp_f32_e32 v79, v79
	s_nop 0
	v_and_b32_e32 v71, 0xffff0000, v191
	v_and_b32_e32 v70, 0xffff0000, v190
	v_rcp_f32_e32 v78, v78
	s_nop 0
	v_mov_b32_e32 v64, v63
	v_pk_fma_f32 v[62:63], v[64:65], v[78:79], v[70:71]
	v_cvt_pk_bf16_f32 v0, v74, v75
	v_cvt_pk_bf16_f32 v62, v62, v63
	v_and_b32_e32 v63, 0xffff0000, v62
	v_lshlrev_b32_e32 v62, 16, v62
	v_lshlrev_b32_e32 v65, 16, v193
	v_lshlrev_b32_e32 v64, 16, v192
	v_and_b32_e32 v71, 0xffff0000, v193
	v_and_b32_e32 v70, 0xffff0000, v192
	v_pk_add_f32 v[72:73], v[76:77], 1.0 op_sel_hi:[1,0]
	v_or_b32_sdwa v63, v63, v0 dst_sel:DWORD dst_unused:UNUSED_PAD src0_sel:DWORD src1_sel:WORD_1
	v_or_b32_sdwa v62, v62, v0 dst_sel:DWORD dst_unused:UNUSED_PAD src0_sel:DWORD src1_sel:WORD_0
	s_nop 0
	v_rcp_f32_e32 v73, v73
	s_nop 0
	s_nop 0
	v_rcp_f32_e32 v72, v72
	s_nop 0
	v_mov_b32_e32 v74, v58
	v_mov_b32_e32 v75, v60
	v_pk_fma_f32 v[64:65], v[74:75], v[72:73], v[64:65]
	v_rcp_f32_e32 v69, v69
	s_nop 0
	s_nop 0
	v_rcp_f32_e32 v68, v68
	s_nop 0
	v_mov_b32_e32 v60, v59
	v_pk_fma_f32 v[58:59], v[60:61], v[68:69], v[70:71]
	v_cvt_pk_bf16_f32 v0, v64, v65
	v_cvt_pk_bf16_f32 v58, v58, v59
	v_and_b32_e32 v59, 0xffff0000, v58
	v_lshlrev_b32_e32 v58, 16, v58
	v_or_b32_sdwa v65, v59, v0 dst_sel:DWORD dst_unused:UNUSED_PAD src0_sel:DWORD src1_sel:WORD_1
	v_or_b32_sdwa v64, v58, v0 dst_sel:DWORD dst_unused:UNUSED_PAD src0_sel:DWORD src1_sel:WORD_0
	v_add_u32_e32 v0, v84, v126
	v_add_u32_e32 v212, 0xe3880, v210
	v_lshl_add_u64 v[186:187], v[212:213], 1, s[6:7]
	global_load_dwordx4 v[186:189], v[186:187], off
	v_add_u32_e32 v212, 0x28080, v211
	v_lshl_add_u64 v[190:191], v[212:213], 1, s[10:11]
	global_load_dwordx4 v[190:193], v[190:191], off
	global_store_dwordx4 v[66:67], v[62:65], off
	v_add_u32_e32 v0, v0, v85
	s_waitcnt vmcnt(14)
	v_lshlrev_b32_e32 v66, 16, v194
	v_and_b32_e32 v67, 0xffff0000, v194
	v_lshlrev_b32_e32 v69, 16, v195
	v_and_b32_e32 v71, 0xffff0000, v195
	v_lshl_add_u64 v[58:59], v[0:1], 1, s[10:11]
	v_lshlrev_b32_e32 v68, 16, v196
	v_mul_f32_e32 v0, 0xbfb8aa3b, v66
	v_exp_f32_e32 v66, v0
	v_mul_f32_e32 v0, 0xbfb8aa3b, v68
	v_and_b32_e32 v60, 0xffff0000, v196
	v_exp_f32_e32 v68, v0
	v_mul_f32_e32 v0, 0xbfb8aa3b, v67
	v_exp_f32_e32 v70, v0
	v_mul_f32_e32 v0, 0xbfb8aa3b, v60
	v_exp_f32_e32 v60, v0
	v_mul_f32_e32 v0, 0xbfb8aa3b, v69
	v_exp_f32_e32 v67, v0
	v_lshlrev_b32_e32 v72, 16, v197
	v_mul_f32_e32 v0, 0xbfb8aa3b, v72
	v_and_b32_e32 v61, 0xffff0000, v197
	v_exp_f32_e32 v69, v0
	v_mul_f32_e32 v0, 0xbfb8aa3b, v71
	v_exp_f32_e32 v71, v0
	v_mul_f32_e32 v0, 0xbfb8aa3b, v61
	v_pk_add_f32 v[66:67], v[66:67], 1.0 op_sel_hi:[1,0]
	v_exp_f32_e32 v61, v0
	v_pk_add_f32 v[70:71], v[70:71], 1.0 op_sel_hi:[1,0]
	v_pk_add_f32 v[60:61], v[60:61], 1.0 op_sel_hi:[1,0]
	v_rcp_f32_e32 v67, v67
	s_nop 0
	s_waitcnt vmcnt(13)
	v_lshlrev_b32_e32 v73, 16, v199
	v_rcp_f32_e32 v66, v66
	s_nop 0
	v_mov_b32_e32 v74, v54
	v_mov_b32_e32 v75, v56
	v_lshlrev_b32_e32 v72, 16, v198
	v_pk_fma_f32 v[66:67], v[74:75], v[66:67], v[72:73]
	v_rcp_f32_e32 v71, v71
	s_nop 0
	v_and_b32_e32 v63, 0xffff0000, v199
	v_and_b32_e32 v62, 0xffff0000, v198
	v_rcp_f32_e32 v70, v70
	s_nop 0
	v_mov_b32_e32 v56, v55
	v_pk_fma_f32 v[54:55], v[56:57], v[70:71], v[62:63]
	v_cvt_pk_bf16_f32 v0, v66, v67
	v_cvt_pk_bf16_f32 v54, v54, v55
	v_and_b32_e32 v55, 0xffff0000, v54
	v_lshlrev_b32_e32 v54, 16, v54
	v_lshlrev_b32_e32 v57, 16, v201
	v_lshlrev_b32_e32 v56, 16, v200
	v_and_b32_e32 v63, 0xffff0000, v201
	v_and_b32_e32 v62, 0xffff0000, v200
	v_pk_add_f32 v[64:65], v[68:69], 1.0 op_sel_hi:[1,0]
	v_or_b32_sdwa v55, v55, v0 dst_sel:DWORD dst_unused:UNUSED_PAD src0_sel:DWORD src1_sel:WORD_1
	v_or_b32_sdwa v54, v54, v0 dst_sel:DWORD dst_unused:UNUSED_PAD src0_sel:DWORD src1_sel:WORD_0
	s_nop 0
	v_rcp_f32_e32 v65, v65
	s_nop 0
	s_nop 0
	v_rcp_f32_e32 v64, v64
	s_nop 0
	v_mov_b32_e32 v66, v50
	v_mov_b32_e32 v67, v52
	v_pk_fma_f32 v[56:57], v[66:67], v[64:65], v[56:57]
	v_add_u32_e32 v68, 0xccc00, v157
	v_rcp_f32_e32 v61, v61
	s_nop 0
	v_add_u32_e32 v69, 0xfff57400, v158
	v_rcp_f32_e32 v60, v60
	s_nop 0
	v_mov_b32_e32 v52, v51
	v_pk_fma_f32 v[50:51], v[52:53], v[60:61], v[62:63]
	v_cvt_pk_bf16_f32 v0, v56, v57
	v_cvt_pk_bf16_f32 v50, v50, v51
	v_and_b32_e32 v51, 0xffff0000, v50
	v_lshlrev_b32_e32 v50, 16, v50
	v_or_b32_sdwa v57, v51, v0 dst_sel:DWORD dst_unused:UNUSED_PAD src0_sel:DWORD src1_sel:WORD_1
	v_or_b32_sdwa v56, v50, v0 dst_sel:DWORD dst_unused:UNUSED_PAD src0_sel:DWORD src1_sel:WORD_0
	v_add_u32_e32 v0, v68, v156
	v_add_u32_e32 v212, 0xfa400, v210
	v_lshl_add_u64 v[194:195], v[212:213], 1, s[6:7]
	global_load_dwordx4 v[194:197], v[194:195], off
	v_add_u32_e32 v212, 0x2c000, v211
	v_lshl_add_u64 v[198:199], v[212:213], 1, s[10:11]
	global_load_dwordx4 v[198:201], v[198:199], off
	global_store_dwordx4 v[58:59], v[54:57], off
	v_add_u32_e32 v0, v0, v69
	s_waitcnt vmcnt(14)
	v_lshlrev_b32_e32 v58, 16, v202
	v_and_b32_e32 v59, 0xffff0000, v202
	v_lshlrev_b32_e32 v61, 16, v203
	v_and_b32_e32 v63, 0xffff0000, v203
	v_lshl_add_u64 v[50:51], v[0:1], 1, s[10:11]
	v_lshlrev_b32_e32 v60, 16, v204
	v_mul_f32_e32 v0, 0xbfb8aa3b, v58
	v_exp_f32_e32 v58, v0
	v_mul_f32_e32 v0, 0xbfb8aa3b, v60
	v_and_b32_e32 v52, 0xffff0000, v204
	v_exp_f32_e32 v60, v0
	v_mul_f32_e32 v0, 0xbfb8aa3b, v59
	v_exp_f32_e32 v62, v0
	v_mul_f32_e32 v0, 0xbfb8aa3b, v52
	v_exp_f32_e32 v52, v0
	v_mul_f32_e32 v0, 0xbfb8aa3b, v61
	v_exp_f32_e32 v59, v0
	v_lshlrev_b32_e32 v64, 16, v205
	v_mul_f32_e32 v0, 0xbfb8aa3b, v64
	v_and_b32_e32 v53, 0xffff0000, v205
	v_exp_f32_e32 v61, v0
	v_mul_f32_e32 v0, 0xbfb8aa3b, v63
	v_exp_f32_e32 v63, v0
	v_mul_f32_e32 v0, 0xbfb8aa3b, v53
	v_pk_add_f32 v[58:59], v[58:59], 1.0 op_sel_hi:[1,0]
	v_exp_f32_e32 v53, v0
	v_pk_add_f32 v[62:63], v[62:63], 1.0 op_sel_hi:[1,0]
	v_pk_add_f32 v[52:53], v[52:53], 1.0 op_sel_hi:[1,0]
	v_rcp_f32_e32 v59, v59
	s_nop 0
	s_waitcnt vmcnt(13)
	v_lshlrev_b32_e32 v65, 16, v207
	v_rcp_f32_e32 v58, v58
	s_nop 0
	v_mov_b32_e32 v66, v46
	v_mov_b32_e32 v67, v48
	v_lshlrev_b32_e32 v64, 16, v206
	v_pk_fma_f32 v[58:59], v[66:67], v[58:59], v[64:65]
	v_rcp_f32_e32 v63, v63
	s_nop 0
	v_and_b32_e32 v55, 0xffff0000, v207
	v_and_b32_e32 v54, 0xffff0000, v206
	v_rcp_f32_e32 v62, v62
	s_nop 0
	v_mov_b32_e32 v48, v47
	v_pk_fma_f32 v[46:47], v[48:49], v[62:63], v[54:55]
	v_cvt_pk_bf16_f32 v0, v58, v59
	v_cvt_pk_bf16_f32 v46, v46, v47
	v_and_b32_e32 v47, 0xffff0000, v46
	v_lshlrev_b32_e32 v46, 16, v46
	v_lshlrev_b32_e32 v49, 16, v209
	v_lshlrev_b32_e32 v48, 16, v208
	v_and_b32_e32 v55, 0xffff0000, v209
	v_and_b32_e32 v54, 0xffff0000, v208
	v_pk_add_f32 v[56:57], v[60:61], 1.0 op_sel_hi:[1,0]
	v_or_b32_sdwa v47, v47, v0 dst_sel:DWORD dst_unused:UNUSED_PAD src0_sel:DWORD src1_sel:WORD_1
	v_or_b32_sdwa v46, v46, v0 dst_sel:DWORD dst_unused:UNUSED_PAD src0_sel:DWORD src1_sel:WORD_0
	s_nop 0
	v_rcp_f32_e32 v57, v57
	s_nop 0
	s_nop 0
	v_rcp_f32_e32 v56, v56
	s_nop 0
	v_mov_b32_e32 v58, v42
	v_mov_b32_e32 v59, v44
	v_pk_fma_f32 v[48:49], v[58:59], v[56:57], v[48:49]
	v_rcp_f32_e32 v53, v53
	s_nop 0
	s_nop 0
	v_rcp_f32_e32 v52, v52
	s_nop 0
	v_mov_b32_e32 v44, v43
	v_pk_fma_f32 v[42:43], v[44:45], v[52:53], v[54:55]
	v_cvt_pk_bf16_f32 v0, v48, v49
	v_cvt_pk_bf16_f32 v42, v42, v43
	v_and_b32_e32 v43, 0xffff0000, v42
	v_lshlrev_b32_e32 v42, 16, v42
	v_or_b32_sdwa v49, v43, v0 dst_sel:DWORD dst_unused:UNUSED_PAD src0_sel:DWORD src1_sel:WORD_1
	v_or_b32_sdwa v48, v42, v0 dst_sel:DWORD dst_unused:UNUSED_PAD src0_sel:DWORD src1_sel:WORD_0
	v_add_u32_e32 v0, v68, v126
	v_add_u32_e32 v212, 0xfa480, v210
	v_lshl_add_u64 v[202:203], v[212:213], 1, s[6:7]
	global_load_dwordx4 v[202:205], v[202:203], off
	v_add_u32_e32 v212, 0x2c080, v211
	v_lshl_add_u64 v[206:207], v[212:213], 1, s[10:11]
	global_load_dwordx4 v[206:209], v[206:207], off
	global_store_dwordx4 v[50:51], v[46:49], off
	v_add_u32_e32 v0, v0, v69
	s_waitcnt vmcnt(14)
	v_lshlrev_b32_e32 v50, 16, v168
	v_and_b32_e32 v51, 0xffff0000, v168
	v_lshlrev_b32_e32 v53, 16, v169
	v_and_b32_e32 v55, 0xffff0000, v169
	v_lshl_add_u64 v[42:43], v[0:1], 1, s[10:11]
	v_lshlrev_b32_e32 v52, 16, v170
	v_mul_f32_e32 v0, 0xbfb8aa3b, v50
	v_exp_f32_e32 v50, v0
	v_mul_f32_e32 v0, 0xbfb8aa3b, v52
	v_and_b32_e32 v44, 0xffff0000, v170
	v_exp_f32_e32 v52, v0
	v_mul_f32_e32 v0, 0xbfb8aa3b, v51
	v_exp_f32_e32 v54, v0
	v_mul_f32_e32 v0, 0xbfb8aa3b, v44
	v_exp_f32_e32 v44, v0
	v_mul_f32_e32 v0, 0xbfb8aa3b, v53
	v_exp_f32_e32 v51, v0
	v_lshlrev_b32_e32 v56, 16, v171
	v_mul_f32_e32 v0, 0xbfb8aa3b, v56
	v_and_b32_e32 v45, 0xffff0000, v171
	v_exp_f32_e32 v53, v0
	v_mul_f32_e32 v0, 0xbfb8aa3b, v55
	v_exp_f32_e32 v55, v0
	v_mul_f32_e32 v0, 0xbfb8aa3b, v45
	v_pk_add_f32 v[50:51], v[50:51], 1.0 op_sel_hi:[1,0]
	v_exp_f32_e32 v45, v0
	v_pk_add_f32 v[54:55], v[54:55], 1.0 op_sel_hi:[1,0]
	v_pk_add_f32 v[44:45], v[44:45], 1.0 op_sel_hi:[1,0]
	v_rcp_f32_e32 v51, v51
	s_nop 0
	s_waitcnt vmcnt(13)
	v_lshlrev_b32_e32 v57, 16, v173
	v_rcp_f32_e32 v50, v50
	s_nop 0
	v_mov_b32_e32 v58, v38
	v_mov_b32_e32 v59, v40
	v_lshlrev_b32_e32 v56, 16, v172
	v_pk_fma_f32 v[50:51], v[58:59], v[50:51], v[56:57]
	v_rcp_f32_e32 v55, v55
	s_nop 0
	v_and_b32_e32 v47, 0xffff0000, v173
	v_and_b32_e32 v46, 0xffff0000, v172
	v_rcp_f32_e32 v54, v54
	s_nop 0
	v_mov_b32_e32 v40, v39
	v_pk_fma_f32 v[38:39], v[40:41], v[54:55], v[46:47]
	v_cvt_pk_bf16_f32 v0, v50, v51
	v_cvt_pk_bf16_f32 v38, v38, v39
	v_and_b32_e32 v39, 0xffff0000, v38
	v_lshlrev_b32_e32 v38, 16, v38
	v_lshlrev_b32_e32 v41, 16, v175
	v_lshlrev_b32_e32 v40, 16, v174
	v_and_b32_e32 v47, 0xffff0000, v175
	v_and_b32_e32 v46, 0xffff0000, v174
	v_pk_add_f32 v[48:49], v[52:53], 1.0 op_sel_hi:[1,0]
	v_or_b32_sdwa v39, v39, v0 dst_sel:DWORD dst_unused:UNUSED_PAD src0_sel:DWORD src1_sel:WORD_1
	v_or_b32_sdwa v38, v38, v0 dst_sel:DWORD dst_unused:UNUSED_PAD src0_sel:DWORD src1_sel:WORD_0
	s_nop 0
	v_rcp_f32_e32 v49, v49
	s_nop 0
	s_nop 0
	v_rcp_f32_e32 v48, v48
	s_nop 0
	v_mov_b32_e32 v50, v34
	v_mov_b32_e32 v51, v36
	v_pk_fma_f32 v[40:41], v[50:51], v[48:49], v[40:41]
	v_add_u32_e32 v52, 0xe3800, v157
	v_rcp_f32_e32 v45, v45
	s_nop 0
	v_add_u32_e32 v53, 0xfff44800, v158
	v_rcp_f32_e32 v44, v44
	s_nop 0
	v_mov_b32_e32 v36, v35
	v_pk_fma_f32 v[34:35], v[36:37], v[44:45], v[46:47]
	v_cvt_pk_bf16_f32 v0, v40, v41
	v_cvt_pk_bf16_f32 v34, v34, v35
	v_and_b32_e32 v35, 0xffff0000, v34
	v_lshlrev_b32_e32 v34, 16, v34
	v_or_b32_sdwa v41, v35, v0 dst_sel:DWORD dst_unused:UNUSED_PAD src0_sel:DWORD src1_sel:WORD_1
	v_or_b32_sdwa v40, v34, v0 dst_sel:DWORD dst_unused:UNUSED_PAD src0_sel:DWORD src1_sel:WORD_0
	v_add_u32_e32 v0, v52, v156
	global_store_dwordx4 v[42:43], v[38:41], off
	v_add_u32_e32 v0, v0, v53
	s_waitcnt vmcnt(12)
	v_lshlrev_b32_e32 v42, 16, v176
	v_and_b32_e32 v43, 0xffff0000, v176
	v_lshlrev_b32_e32 v45, 16, v177
	v_and_b32_e32 v47, 0xffff0000, v177
	v_lshl_add_u64 v[34:35], v[0:1], 1, s[10:11]
	v_lshlrev_b32_e32 v44, 16, v178
	v_mul_f32_e32 v0, 0xbfb8aa3b, v42
	v_exp_f32_e32 v42, v0
	v_mul_f32_e32 v0, 0xbfb8aa3b, v44
	v_and_b32_e32 v36, 0xffff0000, v178
	v_exp_f32_e32 v44, v0
	v_mul_f32_e32 v0, 0xbfb8aa3b, v43
	v_exp_f32_e32 v46, v0
	v_mul_f32_e32 v0, 0xbfb8aa3b, v36
	v_exp_f32_e32 v36, v0
	v_mul_f32_e32 v0, 0xbfb8aa3b, v45
	v_exp_f32_e32 v43, v0
	v_lshlrev_b32_e32 v48, 16, v179
	v_mul_f32_e32 v0, 0xbfb8aa3b, v48
	v_and_b32_e32 v37, 0xffff0000, v179
	v_exp_f32_e32 v45, v0
	v_mul_f32_e32 v0, 0xbfb8aa3b, v47
	v_exp_f32_e32 v47, v0
	v_mul_f32_e32 v0, 0xbfb8aa3b, v37
	v_pk_add_f32 v[42:43], v[42:43], 1.0 op_sel_hi:[1,0]
	v_exp_f32_e32 v37, v0
	v_pk_add_f32 v[46:47], v[46:47], 1.0 op_sel_hi:[1,0]
	v_pk_add_f32 v[36:37], v[36:37], 1.0 op_sel_hi:[1,0]
	v_rcp_f32_e32 v43, v43
	s_nop 0
	s_waitcnt vmcnt(11)
	v_lshlrev_b32_e32 v49, 16, v183
	v_rcp_f32_e32 v42, v42
	s_nop 0
	v_mov_b32_e32 v50, v30
	v_mov_b32_e32 v51, v32
	v_lshlrev_b32_e32 v48, 16, v182
	v_pk_fma_f32 v[42:43], v[50:51], v[42:43], v[48:49]
	v_rcp_f32_e32 v47, v47
	s_nop 0
	v_and_b32_e32 v39, 0xffff0000, v183
	v_and_b32_e32 v38, 0xffff0000, v182
	v_rcp_f32_e32 v46, v46
	s_nop 0
	v_mov_b32_e32 v32, v31
	v_pk_fma_f32 v[30:31], v[32:33], v[46:47], v[38:39]
	v_cvt_pk_bf16_f32 v0, v42, v43
	v_cvt_pk_bf16_f32 v30, v30, v31
	v_and_b32_e32 v31, 0xffff0000, v30
	v_lshlrev_b32_e32 v30, 16, v30
	v_lshlrev_b32_e32 v33, 16, v185
	v_lshlrev_b32_e32 v32, 16, v184
	v_and_b32_e32 v39, 0xffff0000, v185
	v_and_b32_e32 v38, 0xffff0000, v184
	v_pk_add_f32 v[40:41], v[44:45], 1.0 op_sel_hi:[1,0]
	v_or_b32_sdwa v31, v31, v0 dst_sel:DWORD dst_unused:UNUSED_PAD src0_sel:DWORD src1_sel:WORD_1
	v_or_b32_sdwa v30, v30, v0 dst_sel:DWORD dst_unused:UNUSED_PAD src0_sel:DWORD src1_sel:WORD_0
	s_nop 0
	v_rcp_f32_e32 v41, v41
	s_nop 0
	s_nop 0
	v_rcp_f32_e32 v40, v40
	s_nop 0
	v_mov_b32_e32 v42, v26
	v_mov_b32_e32 v43, v28
	v_pk_fma_f32 v[32:33], v[42:43], v[40:41], v[32:33]
	v_rcp_f32_e32 v37, v37
	s_nop 0
	s_nop 0
	v_rcp_f32_e32 v36, v36
	s_nop 0
	v_mov_b32_e32 v28, v27
	v_pk_fma_f32 v[26:27], v[28:29], v[36:37], v[38:39]
	v_cvt_pk_bf16_f32 v0, v32, v33
	v_cvt_pk_bf16_f32 v26, v26, v27
	v_and_b32_e32 v27, 0xffff0000, v26
	v_lshlrev_b32_e32 v26, 16, v26
	v_or_b32_sdwa v33, v27, v0 dst_sel:DWORD dst_unused:UNUSED_PAD src0_sel:DWORD src1_sel:WORD_1
	v_or_b32_sdwa v32, v26, v0 dst_sel:DWORD dst_unused:UNUSED_PAD src0_sel:DWORD src1_sel:WORD_0
	v_add_u32_e32 v0, v52, v126
	global_store_dwordx4 v[34:35], v[30:33], off
	v_add_u32_e32 v0, v0, v53
	s_waitcnt vmcnt(10)
	v_lshlrev_b32_e32 v34, 16, v186
	v_and_b32_e32 v35, 0xffff0000, v186
	v_lshlrev_b32_e32 v37, 16, v187
	v_and_b32_e32 v39, 0xffff0000, v187
	v_lshl_add_u64 v[26:27], v[0:1], 1, s[10:11]
	v_lshlrev_b32_e32 v36, 16, v188
	v_mul_f32_e32 v0, 0xbfb8aa3b, v34
	v_exp_f32_e32 v34, v0
	v_mul_f32_e32 v0, 0xbfb8aa3b, v36
	v_and_b32_e32 v28, 0xffff0000, v188
	v_exp_f32_e32 v36, v0
	v_mul_f32_e32 v0, 0xbfb8aa3b, v35
	v_exp_f32_e32 v38, v0
	v_mul_f32_e32 v0, 0xbfb8aa3b, v28
	v_exp_f32_e32 v28, v0
	v_mul_f32_e32 v0, 0xbfb8aa3b, v37
	v_exp_f32_e32 v35, v0
	v_lshlrev_b32_e32 v40, 16, v189
	v_mul_f32_e32 v0, 0xbfb8aa3b, v40
	v_and_b32_e32 v29, 0xffff0000, v189
	v_exp_f32_e32 v37, v0
	v_mul_f32_e32 v0, 0xbfb8aa3b, v39
	v_exp_f32_e32 v39, v0
	v_mul_f32_e32 v0, 0xbfb8aa3b, v29
	v_pk_add_f32 v[34:35], v[34:35], 1.0 op_sel_hi:[1,0]
	v_exp_f32_e32 v29, v0
	v_pk_add_f32 v[38:39], v[38:39], 1.0 op_sel_hi:[1,0]
	v_pk_add_f32 v[28:29], v[28:29], 1.0 op_sel_hi:[1,0]
	v_rcp_f32_e32 v35, v35
	s_nop 0
	s_waitcnt vmcnt(9)
	v_lshlrev_b32_e32 v41, 16, v191
	v_rcp_f32_e32 v34, v34
	s_nop 0
	v_mov_b32_e32 v42, v22
	v_mov_b32_e32 v43, v24
	v_lshlrev_b32_e32 v40, 16, v190
	v_pk_fma_f32 v[34:35], v[42:43], v[34:35], v[40:41]
	v_rcp_f32_e32 v39, v39
	s_nop 0
	v_and_b32_e32 v31, 0xffff0000, v191
	v_and_b32_e32 v30, 0xffff0000, v190
	v_rcp_f32_e32 v38, v38
	s_nop 0
	v_mov_b32_e32 v24, v23
	v_pk_fma_f32 v[22:23], v[24:25], v[38:39], v[30:31]
	v_cvt_pk_bf16_f32 v0, v34, v35
	v_cvt_pk_bf16_f32 v22, v22, v23
	v_and_b32_e32 v23, 0xffff0000, v22
	v_lshlrev_b32_e32 v22, 16, v22
	v_lshlrev_b32_e32 v25, 16, v193
	v_lshlrev_b32_e32 v24, 16, v192
	v_and_b32_e32 v31, 0xffff0000, v193
	v_and_b32_e32 v30, 0xffff0000, v192
	v_pk_add_f32 v[32:33], v[36:37], 1.0 op_sel_hi:[1,0]
	v_or_b32_sdwa v23, v23, v0 dst_sel:DWORD dst_unused:UNUSED_PAD src0_sel:DWORD src1_sel:WORD_1
	v_or_b32_sdwa v22, v22, v0 dst_sel:DWORD dst_unused:UNUSED_PAD src0_sel:DWORD src1_sel:WORD_0
	s_nop 0
	v_rcp_f32_e32 v33, v33
	s_nop 0
	s_nop 0
	v_rcp_f32_e32 v32, v32
	s_nop 0
	v_mov_b32_e32 v34, v18
	v_mov_b32_e32 v35, v20
	v_pk_fma_f32 v[24:25], v[34:35], v[32:33], v[24:25]
	v_add_u32_e32 v36, 0xfa400, v157
	v_rcp_f32_e32 v29, v29
	s_nop 0
	v_add_u32_e32 v37, 0xfff31c00, v158
	v_rcp_f32_e32 v28, v28
	s_nop 0
	v_mov_b32_e32 v20, v19
	v_pk_fma_f32 v[18:19], v[20:21], v[28:29], v[30:31]
	v_cvt_pk_bf16_f32 v0, v24, v25
	v_cvt_pk_bf16_f32 v18, v18, v19
	v_and_b32_e32 v19, 0xffff0000, v18
	v_lshlrev_b32_e32 v18, 16, v18
	v_or_b32_sdwa v25, v19, v0 dst_sel:DWORD dst_unused:UNUSED_PAD src0_sel:DWORD src1_sel:WORD_1
	v_or_b32_sdwa v24, v18, v0 dst_sel:DWORD dst_unused:UNUSED_PAD src0_sel:DWORD src1_sel:WORD_0
	v_add_u32_e32 v0, v36, v156
	global_store_dwordx4 v[26:27], v[22:25], off
	v_add_u32_e32 v0, v0, v37
	s_waitcnt vmcnt(8)
	v_lshlrev_b32_e32 v26, 16, v194
	v_and_b32_e32 v27, 0xffff0000, v194
	v_lshlrev_b32_e32 v29, 16, v195
	v_and_b32_e32 v31, 0xffff0000, v195
	v_lshl_add_u64 v[18:19], v[0:1], 1, s[10:11]
	v_lshlrev_b32_e32 v28, 16, v196
	v_mul_f32_e32 v0, 0xbfb8aa3b, v26
	v_exp_f32_e32 v26, v0
	v_mul_f32_e32 v0, 0xbfb8aa3b, v28
	v_and_b32_e32 v20, 0xffff0000, v196
	v_exp_f32_e32 v28, v0
	v_mul_f32_e32 v0, 0xbfb8aa3b, v27
	v_exp_f32_e32 v30, v0
	v_mul_f32_e32 v0, 0xbfb8aa3b, v20
	v_exp_f32_e32 v20, v0
	v_mul_f32_e32 v0, 0xbfb8aa3b, v29
	v_exp_f32_e32 v27, v0
	v_lshlrev_b32_e32 v32, 16, v197
	v_mul_f32_e32 v0, 0xbfb8aa3b, v32
	v_and_b32_e32 v21, 0xffff0000, v197
	v_exp_f32_e32 v29, v0
	v_mul_f32_e32 v0, 0xbfb8aa3b, v31
	v_exp_f32_e32 v31, v0
	v_mul_f32_e32 v0, 0xbfb8aa3b, v21
	v_pk_add_f32 v[26:27], v[26:27], 1.0 op_sel_hi:[1,0]
	v_exp_f32_e32 v21, v0
	v_pk_add_f32 v[30:31], v[30:31], 1.0 op_sel_hi:[1,0]
	v_pk_add_f32 v[20:21], v[20:21], 1.0 op_sel_hi:[1,0]
	v_rcp_f32_e32 v27, v27
	s_nop 0
	s_waitcnt vmcnt(7)
	v_lshlrev_b32_e32 v33, 16, v199
	v_rcp_f32_e32 v26, v26
	s_nop 0
	v_mov_b32_e32 v34, v14
	v_mov_b32_e32 v35, v16
	v_lshlrev_b32_e32 v32, 16, v198
	v_pk_fma_f32 v[26:27], v[34:35], v[26:27], v[32:33]
	v_rcp_f32_e32 v31, v31
	s_nop 0
	v_and_b32_e32 v23, 0xffff0000, v199
	v_and_b32_e32 v22, 0xffff0000, v198
	v_rcp_f32_e32 v30, v30
	s_nop 0
	v_mov_b32_e32 v16, v15
	v_pk_fma_f32 v[14:15], v[16:17], v[30:31], v[22:23]
	v_cvt_pk_bf16_f32 v0, v26, v27
	v_cvt_pk_bf16_f32 v14, v14, v15
	v_and_b32_e32 v15, 0xffff0000, v14
	v_lshlrev_b32_e32 v14, 16, v14
	v_lshlrev_b32_e32 v17, 16, v201
	v_lshlrev_b32_e32 v16, 16, v200
	v_and_b32_e32 v23, 0xffff0000, v201
	v_and_b32_e32 v22, 0xffff0000, v200
	v_pk_add_f32 v[24:25], v[28:29], 1.0 op_sel_hi:[1,0]
	v_or_b32_sdwa v15, v15, v0 dst_sel:DWORD dst_unused:UNUSED_PAD src0_sel:DWORD src1_sel:WORD_1
	v_or_b32_sdwa v14, v14, v0 dst_sel:DWORD dst_unused:UNUSED_PAD src0_sel:DWORD src1_sel:WORD_0
	s_nop 0
	v_rcp_f32_e32 v25, v25
	s_nop 0
	s_nop 0
	v_rcp_f32_e32 v24, v24
	s_nop 0
	v_mov_b32_e32 v26, v10
	v_mov_b32_e32 v27, v12
	v_pk_fma_f32 v[16:17], v[26:27], v[24:25], v[16:17]
	v_rcp_f32_e32 v21, v21
	s_nop 0
	s_nop 0
	v_rcp_f32_e32 v20, v20
	s_nop 0
	v_mov_b32_e32 v12, v11
	v_pk_fma_f32 v[10:11], v[12:13], v[20:21], v[22:23]
	v_cvt_pk_bf16_f32 v0, v16, v17
	v_cvt_pk_bf16_f32 v10, v10, v11
	v_and_b32_e32 v11, 0xffff0000, v10
	v_lshlrev_b32_e32 v10, 16, v10
	v_or_b32_sdwa v17, v11, v0 dst_sel:DWORD dst_unused:UNUSED_PAD src0_sel:DWORD src1_sel:WORD_1
	v_or_b32_sdwa v16, v10, v0 dst_sel:DWORD dst_unused:UNUSED_PAD src0_sel:DWORD src1_sel:WORD_0
	v_add_u32_e32 v0, v36, v126
	global_store_dwordx4 v[18:19], v[14:17], off
	v_add_u32_e32 v0, v0, v37
	s_waitcnt vmcnt(6)
	v_lshlrev_b32_e32 v18, 16, v202
	v_and_b32_e32 v19, 0xffff0000, v202
	v_lshlrev_b32_e32 v21, 16, v203
	v_and_b32_e32 v23, 0xffff0000, v203
	v_lshl_add_u64 v[10:11], v[0:1], 1, s[10:11]
	v_lshlrev_b32_e32 v20, 16, v204
	v_mul_f32_e32 v0, 0xbfb8aa3b, v18
	v_exp_f32_e32 v18, v0
	v_mul_f32_e32 v0, 0xbfb8aa3b, v20
	v_and_b32_e32 v12, 0xffff0000, v204
	v_exp_f32_e32 v20, v0
	v_mul_f32_e32 v0, 0xbfb8aa3b, v19
	v_exp_f32_e32 v22, v0
	v_mul_f32_e32 v0, 0xbfb8aa3b, v12
	v_exp_f32_e32 v12, v0
	v_mul_f32_e32 v0, 0xbfb8aa3b, v21
	v_exp_f32_e32 v19, v0
	v_lshlrev_b32_e32 v24, 16, v205
	v_mul_f32_e32 v0, 0xbfb8aa3b, v24
	v_and_b32_e32 v13, 0xffff0000, v205
	v_exp_f32_e32 v21, v0
	v_mul_f32_e32 v0, 0xbfb8aa3b, v23
	v_exp_f32_e32 v23, v0
	v_mul_f32_e32 v0, 0xbfb8aa3b, v13
	v_pk_add_f32 v[18:19], v[18:19], 1.0 op_sel_hi:[1,0]
	v_exp_f32_e32 v13, v0
	v_pk_add_f32 v[22:23], v[22:23], 1.0 op_sel_hi:[1,0]
	v_pk_add_f32 v[12:13], v[12:13], 1.0 op_sel_hi:[1,0]
	v_rcp_f32_e32 v19, v19
	s_nop 0
	s_waitcnt vmcnt(5)
	v_lshlrev_b32_e32 v25, 16, v207
	v_rcp_f32_e32 v18, v18
	s_nop 0
	v_mov_b32_e32 v26, v6
	v_mov_b32_e32 v27, v8
	v_lshlrev_b32_e32 v24, 16, v206
	v_pk_fma_f32 v[18:19], v[26:27], v[18:19], v[24:25]
	v_rcp_f32_e32 v23, v23
	s_nop 0
	v_and_b32_e32 v15, 0xffff0000, v207
	v_and_b32_e32 v14, 0xffff0000, v206
	v_rcp_f32_e32 v22, v22
	s_nop 0
	v_mov_b32_e32 v8, v7
	v_pk_fma_f32 v[6:7], v[8:9], v[22:23], v[14:15]
	v_cvt_pk_bf16_f32 v0, v18, v19
	v_cvt_pk_bf16_f32 v6, v6, v7
	v_and_b32_e32 v7, 0xffff0000, v6
	v_lshlrev_b32_e32 v6, 16, v6
	v_lshlrev_b32_e32 v9, 16, v209
	v_lshlrev_b32_e32 v8, 16, v208
	v_and_b32_e32 v15, 0xffff0000, v209
	v_and_b32_e32 v14, 0xffff0000, v208
	v_pk_add_f32 v[16:17], v[20:21], 1.0 op_sel_hi:[1,0]
	v_or_b32_sdwa v7, v7, v0 dst_sel:DWORD dst_unused:UNUSED_PAD src0_sel:DWORD src1_sel:WORD_1
	v_or_b32_sdwa v6, v6, v0 dst_sel:DWORD dst_unused:UNUSED_PAD src0_sel:DWORD src1_sel:WORD_0
	s_nop 0
	v_rcp_f32_e32 v17, v17
	s_nop 0
	s_nop 0
	v_rcp_f32_e32 v16, v16
	s_nop 0
	v_mov_b32_e32 v18, v2
	v_mov_b32_e32 v19, v4
	v_pk_fma_f32 v[8:9], v[18:19], v[16:17], v[8:9]
	v_rcp_f32_e32 v13, v13
	s_nop 0
	s_mov_b64 s[26:27], s[18:19]
	v_rcp_f32_e32 v12, v12
	s_nop 0
	v_mov_b32_e32 v4, v3
	v_pk_fma_f32 v[2:3], v[4:5], v[12:13], v[14:15]
	v_cvt_pk_bf16_f32 v0, v8, v9
	v_cvt_pk_bf16_f32 v2, v2, v3
	v_and_b32_e32 v3, 0xffff0000, v2
	v_lshlrev_b32_e32 v2, 16, v2
	v_or_b32_sdwa v9, v3, v0 dst_sel:DWORD dst_unused:UNUSED_PAD src0_sel:DWORD src1_sel:WORD_1
	v_or_b32_sdwa v8, v2, v0 dst_sel:DWORD dst_unused:UNUSED_PAD src0_sel:DWORD src1_sel:WORD_0
	s_and_b64 vcc, exec, s[12:13]
	global_store_dwordx4 v[10:11], v[6:9], off
	s_cbranch_vccz .LBB0_1369
	s_waitcnt vmcnt(0)
	v_readlane_b32 s76, v255, 8
	s_mov_b32 s92, 0x3b2aaaab
	s_cmp_gt_u32 s35, 3
	v_readlane_b32 s77, v255, 9
	s_mul_i32 s60, s33, 0x1800
	s_mul_hi_i32 s62, s64, 0x300
	s_mul_i32 s75, s33, 0x16c00
	s_mov_b32 s93, 0x3c800000
	s_cbranch_scc1 .LBB0_1376
	s_barrier

.LBB0_1428:
	v_add_u32_e32 v0, 0x10000, v139
	ds_read_b128 v[142:145], v0
	ds_read_b128 v[146:149], v0 offset:1024
	ds_read_b128 v[150:153], v0 offset:2048
	ds_read_b128 v[154:157], v0 offset:3072
	s_add_u32 s28, s26, 0xfffc0080
	s_addc_u32 s29, s27, -1
	s_cmp_eq_u32 vcc_lo, 12
	s_cselect_b32 s31, s15, s29
	s_cselect_b32 s30, s89, s28
	s_cselect_b32 s29, s13, s97
	s_cselect_b32 s28, s90, s94
	v_lshl_add_u64 v[178:179], s[26:27], 0, v[134:135]
	s_add_i32 m0, s35, 0xc000
	ds_read_b128 v[158:161], v138
	ds_read_b128 v[162:165], v138 offset:1024
	ds_read_b128 v[166:169], v138 offset:2048
	ds_read_b128 v[170:173], v138 offset:3072
	ds_read_b128 v[174:177], v138 offset:4096
	ds_read_b128 v[182:185], v138 offset:5120
	ds_read_b128 v[186:189], v138 offset:6144
	ds_read_b128 v[190:193], v138 offset:7168
	global_load_lds_dwordx4 v[178:179], off
	v_lshl_add_u64 v[178:179], s[26:27], 0, v[136:137]
	s_add_i32 m0, s35, 0xe000
	s_nop 0
	global_load_lds_dwordx4 v[178:179], off
	s_waitcnt lgkmcnt(8)
	s_barrier
	s_waitcnt lgkmcnt(0)
	s_waitcnt lgkmcnt(0)
	v_mfma_f32_16x16x32_bf16 v[126:129], v[142:145], v[158:161], v[126:129]
	v_mfma_f32_16x16x32_bf16 v[122:125], v[150:153], v[158:161], v[122:125]
	v_mfma_f32_16x16x32_bf16 v[110:113], v[142:145], v[166:169], v[110:113]
	v_mfma_f32_16x16x32_bf16 v[106:109], v[150:153], v[166:169], v[106:109]
	v_mfma_f32_16x16x32_bf16 v[94:97], v[142:145], v[174:177], v[94:97]
	v_mfma_f32_16x16x32_bf16 v[90:93], v[150:153], v[174:177], v[90:93]
	v_mfma_f32_16x16x32_bf16 v[78:81], v[142:145], v[186:189], v[78:81]
	v_mfma_f32_16x16x32_bf16 v[74:77], v[150:153], v[186:189], v[74:77]
	v_mfma_f32_16x16x32_bf16 v[126:129], v[146:149], v[162:165], v[126:129]
	v_mfma_f32_16x16x32_bf16 v[122:125], v[154:157], v[162:165], v[122:125]
	v_mfma_f32_16x16x32_bf16 v[110:113], v[146:149], v[170:173], v[110:113]
	v_mfma_f32_16x16x32_bf16 v[106:109], v[154:157], v[170:173], v[106:109]
	v_mfma_f32_16x16x32_bf16 v[94:97], v[146:149], v[182:185], v[94:97]
	v_mfma_f32_16x16x32_bf16 v[90:93], v[154:157], v[182:185], v[90:93]
	v_mfma_f32_16x16x32_bf16 v[78:81], v[146:149], v[190:193], v[78:81]
	v_mfma_f32_16x16x32_bf16 v[74:77], v[154:157], v[190:193], v[74:77]
	s_barrier
	s_mov_b32 m0, s23
	v_add_u32_e32 v0, 0x14000, v139
	v_lshl_add_u64 v[178:179], s[28:29], 0, v[132:133]
	ds_read_b128 v[194:197], v0
	ds_read_b128 v[198:201], v0 offset:1024
	ds_read_b128 v[202:205], v0 offset:2048
	ds_read_b128 v[206:209], v0 offset:3072
	global_load_lds_dwordx4 v[178:179], off
	v_lshl_add_u64 v[210:211], s[28:29], 0, v[130:131]
	s_mov_b32 m0, s25
	s_nop 0
	global_load_lds_dwordx4 v[210:211], off
	s_barrier
	s_waitcnt lgkmcnt(0)
	s_waitcnt lgkmcnt(0)
	v_mfma_f32_16x16x32_bf16 v[118:121], v[194:197], v[158:161], v[118:121]
	v_mfma_f32_16x16x32_bf16 v[114:117], v[202:205], v[158:161], v[114:117]
	v_mfma_f32_16x16x32_bf16 v[102:105], v[194:197], v[166:169], v[102:105]
	v_mfma_f32_16x16x32_bf16 v[98:101], v[202:205], v[166:169], v[98:101]
	v_mfma_f32_16x16x32_bf16 v[86:89], v[194:197], v[174:177], v[86:89]
	v_mfma_f32_16x16x32_bf16 v[82:85], v[202:205], v[174:177], v[82:85]
	v_mfma_f32_16x16x32_bf16 v[70:73], v[194:197], v[186:189], v[70:73]
	v_mfma_f32_16x16x32_bf16 v[66:69], v[202:205], v[186:189], v[66:69]
	v_mfma_f32_16x16x32_bf16 v[118:121], v[198:201], v[162:165], v[118:121]
	v_mfma_f32_16x16x32_bf16 v[114:117], v[206:209], v[162:165], v[114:117]
	v_mfma_f32_16x16x32_bf16 v[102:105], v[198:201], v[170:173], v[102:105]
	v_mfma_f32_16x16x32_bf16 v[98:101], v[206:209], v[170:173], v[98:101]
	v_mfma_f32_16x16x32_bf16 v[86:89], v[198:201], v[182:185], v[86:89]
	v_mfma_f32_16x16x32_bf16 v[82:85], v[206:209], v[182:185], v[82:85]
	v_mfma_f32_16x16x32_bf16 v[70:73], v[198:201], v[190:193], v[70:73]
	v_mfma_f32_16x16x32_bf16 v[66:69], v[206:209], v[190:193], v[66:69]
	s_mov_b32 m0, s35
	v_lshl_add_u64 v[212:213], s[30:31], 0, v[132:133]
	s_barrier
	ds_read_b128 v[158:161], v138 offset:16384
	ds_read_b128 v[162:165], v138 offset:17408
	ds_read_b128 v[166:169], v138 offset:18432
	ds_read_b128 v[170:173], v138 offset:19456
	ds_read_b128 v[174:177], v138 offset:20480
	ds_read_b128 v[182:185], v138 offset:21504
	ds_read_b128 v[186:189], v138 offset:22528
	ds_read_b128 v[190:193], v138 offset:23552
	global_load_lds_dwordx4 v[212:213], off
	v_lshl_add_u64 v[214:215], s[30:31], 0, v[130:131]
	s_mov_b32 m0, s36
	s_nop 0
	global_load_lds_dwordx4 v[214:215], off
	s_barrier
	s_waitcnt lgkmcnt(0)
	s_waitcnt lgkmcnt(0)
	v_mfma_f32_16x16x32_bf16 v[62:65], v[142:145], v[158:161], v[62:65]
	v_mfma_f32_16x16x32_bf16 v[58:61], v[150:153], v[158:161], v[58:61]
	v_mfma_f32_16x16x32_bf16 v[46:49], v[142:145], v[166:169], v[46:49]
	v_mfma_f32_16x16x32_bf16 v[42:45], v[150:153], v[166:169], v[42:45]
	v_mfma_f32_16x16x32_bf16 v[30:33], v[142:145], v[174:177], v[30:33]
	v_mfma_f32_16x16x32_bf16 v[26:29], v[150:153], v[174:177], v[26:29]
	v_mfma_f32_16x16x32_bf16 v[14:17], v[142:145], v[186:189], v[14:17]
	v_mfma_f32_16x16x32_bf16 v[10:13], v[150:153], v[186:189], v[10:13]
	v_mfma_f32_16x16x32_bf16 v[62:65], v[146:149], v[162:165], v[62:65]
	v_mfma_f32_16x16x32_bf16 v[58:61], v[154:157], v[162:165], v[58:61]
	v_mfma_f32_16x16x32_bf16 v[46:49], v[146:149], v[170:173], v[46:49]
	v_mfma_f32_16x16x32_bf16 v[42:45], v[154:157], v[170:173], v[42:45]
	v_mfma_f32_16x16x32_bf16 v[30:33], v[146:149], v[182:185], v[30:33]
	v_mfma_f32_16x16x32_bf16 v[26:29], v[154:157], v[182:185], v[26:29]
	v_mfma_f32_16x16x32_bf16 v[14:17], v[146:149], v[190:193], v[14:17]
	v_mfma_f32_16x16x32_bf16 v[10:13], v[154:157], v[190:193], v[10:13]
	s_barrier
	s_add_u32 s76, s28, 0x40000
	s_addc_u32 s77, s29, 0
	s_mov_b32 m0, s37
	v_lshl_add_u64 v[142:143], s[76:77], 0, v[132:133]
	global_load_lds_dwordx4 v[142:143], off
	v_lshl_add_u64 v[142:143], s[76:77], 0, v[130:131]
	s_mov_b32 m0, s38
	s_nop 0
	global_load_lds_dwordx4 v[142:143], off
	s_waitcnt vmcnt(6)
	s_barrier
	v_mfma_f32_16x16x32_bf16 v[54:57], v[194:197], v[158:161], v[54:57]
	v_mfma_f32_16x16x32_bf16 v[50:53], v[202:205], v[158:161], v[50:53]
	v_mfma_f32_16x16x32_bf16 v[38:41], v[194:197], v[166:169], v[38:41]
	v_mfma_f32_16x16x32_bf16 v[34:37], v[202:205], v[166:169], v[34:37]
	v_mfma_f32_16x16x32_bf16 v[22:25], v[194:197], v[174:177], v[22:25]
	v_mfma_f32_16x16x32_bf16 v[18:21], v[202:205], v[174:177], v[18:21]
	v_mfma_f32_16x16x32_bf16 v[6:9], v[194:197], v[186:189], v[6:9]
	v_mfma_f32_16x16x32_bf16 v[2:5], v[202:205], v[186:189], v[2:5]
	v_mfma_f32_16x16x32_bf16 v[54:57], v[198:201], v[162:165], v[54:57]
	v_mfma_f32_16x16x32_bf16 v[50:53], v[206:209], v[162:165], v[50:53]
	v_mfma_f32_16x16x32_bf16 v[38:41], v[198:201], v[170:173], v[38:41]
	v_mfma_f32_16x16x32_bf16 v[34:37], v[206:209], v[170:173], v[34:37]
	v_mfma_f32_16x16x32_bf16 v[22:25], v[198:201], v[182:185], v[22:25]
	v_mfma_f32_16x16x32_bf16 v[18:21], v[206:209], v[182:185], v[18:21]
	v_mfma_f32_16x16x32_bf16 v[6:9], v[198:201], v[190:193], v[6:9]
	v_mfma_f32_16x16x32_bf16 v[2:5], v[206:209], v[190:193], v[2:5]
	v_add_u32_e32 v0, 0x18000, v139
	s_barrier
	ds_read_b128 v[142:145], v0
	ds_read_b128 v[146:149], v0 offset:1024
	ds_read_b128 v[150:153], v0 offset:2048
	ds_read_b128 v[154:157], v0 offset:3072
	s_add_u32 s30, s30, 0x40000
	s_addc_u32 s31, s31, 0
	s_mov_b32 m0, s39
	v_lshl_add_u64 v[194:195], s[30:31], 0, v[132:133]
	ds_read_b128 v[158:161], v138 offset:32768
	ds_read_b128 v[162:165], v138 offset:33792
	ds_read_b128 v[166:169], v138 offset:34816
	ds_read_b128 v[170:173], v138 offset:35840
	ds_read_b128 v[174:177], v138 offset:36864
	ds_read_b128 v[182:185], v138 offset:37888
	ds_read_b128 v[186:189], v138 offset:38912
	ds_read_b128 v[190:193], v138 offset:39936
	global_load_lds_dwordx4 v[194:195], off
	v_lshl_add_u64 v[194:195], s[30:31], 0, v[130:131]
	s_mov_b32 m0, s60
	s_nop 0
	global_load_lds_dwordx4 v[194:195], off
	s_waitcnt lgkmcnt(8)
	s_barrier
	s_waitcnt lgkmcnt(0)
	s_waitcnt lgkmcnt(0)
	v_mfma_f32_16x16x32_bf16 v[126:129], v[142:145], v[158:161], v[126:129]
	v_mfma_f32_16x16x32_bf16 v[122:125], v[150:153], v[158:161], v[122:125]
	v_mfma_f32_16x16x32_bf16 v[110:113], v[142:145], v[166:169], v[110:113]
	v_mfma_f32_16x16x32_bf16 v[106:109], v[150:153], v[166:169], v[106:109]
	v_mfma_f32_16x16x32_bf16 v[94:97], v[142:145], v[174:177], v[94:97]
	v_mfma_f32_16x16x32_bf16 v[90:93], v[150:153], v[174:177], v[90:93]
	v_mfma_f32_16x16x32_bf16 v[78:81], v[142:145], v[186:189], v[78:81]
	v_mfma_f32_16x16x32_bf16 v[74:77], v[150:153], v[186:189], v[74:77]
	v_mfma_f32_16x16x32_bf16 v[126:129], v[146:149], v[162:165], v[126:129]
	v_mfma_f32_16x16x32_bf16 v[122:125], v[154:157], v[162:165], v[122:125]
	v_mfma_f32_16x16x32_bf16 v[110:113], v[146:149], v[170:173], v[110:113]
	v_mfma_f32_16x16x32_bf16 v[106:109], v[154:157], v[170:173], v[106:109]
	v_mfma_f32_16x16x32_bf16 v[94:97], v[146:149], v[182:185], v[94:97]
	v_mfma_f32_16x16x32_bf16 v[90:93], v[154:157], v[182:185], v[90:93]
	v_mfma_f32_16x16x32_bf16 v[78:81], v[146:149], v[190:193], v[78:81]
	v_mfma_f32_16x16x32_bf16 v[74:77], v[154:157], v[190:193], v[74:77]
	s_barrier
	s_mov_b32 m0, s68
	v_add_u32_e32 v0, 0x1c000, v139
	v_lshl_add_u64 v[178:179], v[178:179], 0, s[84:85]
	ds_read_b128 v[194:197], v0
	ds_read_b128 v[198:201], v0 offset:1024
	ds_read_b128 v[202:205], v0 offset:2048
	ds_read_b128 v[206:209], v0 offset:3072
	global_load_lds_dwordx4 v[178:179], off
	v_lshl_add_u64 v[178:179], v[210:211], 0, s[84:85]
	s_mov_b32 m0, s69
	s_nop 0
	global_load_lds_dwordx4 v[178:179], off
	s_barrier
	s_waitcnt lgkmcnt(0)
	s_waitcnt lgkmcnt(0)
	v_mfma_f32_16x16x32_bf16 v[118:121], v[194:197], v[158:161], v[118:121]
	v_mfma_f32_16x16x32_bf16 v[114:117], v[202:205], v[158:161], v[114:117]
	v_mfma_f32_16x16x32_bf16 v[102:105], v[194:197], v[166:169], v[102:105]
	v_mfma_f32_16x16x32_bf16 v[98:101], v[202:205], v[166:169], v[98:101]
	v_mfma_f32_16x16x32_bf16 v[86:89], v[194:197], v[174:177], v[86:89]
	v_mfma_f32_16x16x32_bf16 v[82:85], v[202:205], v[174:177], v[82:85]
	v_mfma_f32_16x16x32_bf16 v[70:73], v[194:197], v[186:189], v[70:73]
	v_mfma_f32_16x16x32_bf16 v[66:69], v[202:205], v[186:189], v[66:69]
	v_mfma_f32_16x16x32_bf16 v[118:121], v[198:201], v[162:165], v[118:121]
	v_mfma_f32_16x16x32_bf16 v[114:117], v[206:209], v[162:165], v[114:117]
	v_mfma_f32_16x16x32_bf16 v[102:105], v[198:201], v[170:173], v[102:105]
	v_mfma_f32_16x16x32_bf16 v[98:101], v[206:209], v[170:173], v[98:101]
	v_mfma_f32_16x16x32_bf16 v[86:89], v[198:201], v[182:185], v[86:89]
	v_mfma_f32_16x16x32_bf16 v[82:85], v[206:209], v[182:185], v[82:85]
	v_mfma_f32_16x16x32_bf16 v[70:73], v[198:201], v[190:193], v[70:73]
	v_mfma_f32_16x16x32_bf16 v[66:69], v[206:209], v[190:193], v[66:69]
	s_mov_b32 m0, s75
	v_lshl_add_u64 v[178:179], v[212:213], 0, s[84:85]
	s_barrier
	ds_read_b128 v[158:161], v138 offset:49152
	ds_read_b128 v[162:165], v138 offset:50176
	ds_read_b128 v[166:169], v138 offset:51200
	ds_read_b128 v[170:173], v138 offset:52224
	ds_read_b128 v[174:177], v138 offset:53248
	ds_read_b128 v[182:185], v138 offset:54272
	ds_read_b128 v[186:189], v138 offset:55296
	ds_read_b128 v[190:193], v138 offset:56320
	global_load_lds_dwordx4 v[178:179], off
	v_lshl_add_u64 v[178:179], v[214:215], 0, s[84:85]
	s_mov_b32 m0, s82
	s_nop 0
	global_load_lds_dwordx4 v[178:179], off
	s_barrier
	s_waitcnt lgkmcnt(0)
	s_waitcnt lgkmcnt(0)
	v_mfma_f32_16x16x32_bf16 v[62:65], v[142:145], v[158:161], v[62:65]
	v_mfma_f32_16x16x32_bf16 v[58:61], v[150:153], v[158:161], v[58:61]
	v_mfma_f32_16x16x32_bf16 v[46:49], v[142:145], v[166:169], v[46:49]
	v_mfma_f32_16x16x32_bf16 v[42:45], v[150:153], v[166:169], v[42:45]
	v_mfma_f32_16x16x32_bf16 v[30:33], v[142:145], v[174:177], v[30:33]
	v_mfma_f32_16x16x32_bf16 v[26:29], v[150:153], v[174:177], v[26:29]
	v_mfma_f32_16x16x32_bf16 v[14:17], v[142:145], v[186:189], v[14:17]
	v_mfma_f32_16x16x32_bf16 v[10:13], v[150:153], v[186:189], v[10:13]
	v_mfma_f32_16x16x32_bf16 v[62:65], v[146:149], v[162:165], v[62:65]
	v_mfma_f32_16x16x32_bf16 v[58:61], v[154:157], v[162:165], v[58:61]
	v_mfma_f32_16x16x32_bf16 v[46:49], v[146:149], v[170:173], v[46:49]
	v_mfma_f32_16x16x32_bf16 v[42:45], v[154:157], v[170:173], v[42:45]
	v_mfma_f32_16x16x32_bf16 v[30:33], v[146:149], v[182:185], v[30:33]
	v_mfma_f32_16x16x32_bf16 v[26:29], v[154:157], v[182:185], v[26:29]
	v_mfma_f32_16x16x32_bf16 v[14:17], v[146:149], v[190:193], v[14:17]
	v_mfma_f32_16x16x32_bf16 v[10:13], v[154:157], v[190:193], v[10:13]
	s_barrier
	s_add_u32 s28, s28, 0x40080
	s_addc_u32 s29, s29, 0
	s_mov_b32 m0, s92
	v_lshl_add_u64 v[142:143], s[28:29], 0, v[132:133]
	global_load_lds_dwordx4 v[142:143], off
	v_lshl_add_u64 v[142:143], s[28:29], 0, v[130:131]
	s_mov_b32 m0, s93
	s_nop 0
	global_load_lds_dwordx4 v[142:143], off
	s_waitcnt vmcnt(6)
	s_barrier
	v_mfma_f32_16x16x32_bf16 v[54:57], v[194:197], v[158:161], v[54:57]
	v_mfma_f32_16x16x32_bf16 v[50:53], v[202:205], v[158:161], v[50:53]
	v_mfma_f32_16x16x32_bf16 v[38:41], v[194:197], v[166:169], v[38:41]
	v_mfma_f32_16x16x32_bf16 v[34:37], v[202:205], v[166:169], v[34:37]
	v_mfma_f32_16x16x32_bf16 v[22:25], v[194:197], v[174:177], v[22:25]
	v_mfma_f32_16x16x32_bf16 v[18:21], v[202:205], v[174:177], v[18:21]
	v_mfma_f32_16x16x32_bf16 v[6:9], v[194:197], v[186:189], v[6:9]
	v_mfma_f32_16x16x32_bf16 v[2:5], v[202:205], v[186:189], v[2:5]
	v_mfma_f32_16x16x32_bf16 v[54:57], v[198:201], v[162:165], v[54:57]
	v_mfma_f32_16x16x32_bf16 v[50:53], v[206:209], v[162:165], v[50:53]
	v_mfma_f32_16x16x32_bf16 v[38:41], v[198:201], v[170:173], v[38:41]
	v_mfma_f32_16x16x32_bf16 v[34:37], v[206:209], v[170:173], v[34:37]
	v_mfma_f32_16x16x32_bf16 v[22:25], v[198:201], v[182:185], v[22:25]
	v_mfma_f32_16x16x32_bf16 v[18:21], v[206:209], v[182:185], v[18:21]
	v_mfma_f32_16x16x32_bf16 v[6:9], v[198:201], v[190:193], v[6:9]
	v_mfma_f32_16x16x32_bf16 v[2:5], v[206:209], v[190:193], v[2:5]
	s_add_i32 vcc_lo, vcc_lo, 2
	s_add_u32 s26, s26, 0x100
	s_addc_u32 s27, s27, 0
	s_add_u32 s94, s94, 0x100
	s_addc_u32 s97, s97, 0
	s_cmp_gt_u32 vcc_lo, 13
	s_barrier
	s_cbranch_scc0 .LBB0_1428
	s_lshl_b32 s13, s22, 8
	s_lshl_b32 s15, s24, 18
	s_add_i32 s15, s15, s13
	v_add_u32_e32 v0, s15, v140
	v_mov_b32_e32 v148, v0
	v_mov_b32_e32 v207, 0
	v_mov_b32_e32 v206, v148
	v_lshlrev_b64 v[150:151], 2, v[206:207]
	v_lshl_add_u64 v[150:151], s[8:9], 0, v[150:151]
	global_load_dwordx4 v[150:153], v[150:151], off
	v_add_u32_e32 v206, 0x10, v148
	v_lshlrev_b64 v[154:155], 2, v[206:207]
	v_lshl_add_u64 v[154:155], s[8:9], 0, v[154:155]
	global_load_dwordx4 v[154:157], v[154:155], off
	v_add_u32_e32 v206, 0x80, v148
	v_lshlrev_b64 v[158:159], 2, v[206:207]
	v_lshl_add_u64 v[158:159], s[8:9], 0, v[158:159]
	global_load_dwordx4 v[158:161], v[158:159], off
	v_add_u32_e32 v206, 0x90, v148
	v_lshlrev_b64 v[162:163], 2, v[206:207]
	v_lshl_add_u64 v[162:163], s[8:9], 0, v[162:163]
	global_load_dwordx4 v[162:165], v[162:163], off
	v_add_u32_e32 v206, 0x4000, v148
	v_lshlrev_b64 v[166:167], 2, v[206:207]
	v_lshl_add_u64 v[166:167], s[8:9], 0, v[166:167]
	global_load_dwordx4 v[166:169], v[166:167], off
	v_add_u32_e32 v206, 0x4010, v148
	v_lshlrev_b64 v[170:171], 2, v[206:207]
	v_lshl_add_u64 v[170:171], s[8:9], 0, v[170:171]
	global_load_dwordx4 v[170:173], v[170:171], off
	v_add_u32_e32 v206, 0x4080, v148
	v_lshlrev_b64 v[174:175], 2, v[206:207]
	v_lshl_add_u64 v[174:175], s[8:9], 0, v[174:175]
	global_load_dwordx4 v[174:177], v[174:175], off
	v_add_u32_e32 v206, 0x4090, v148
	v_lshlrev_b64 v[182:183], 2, v[206:207]
	v_lshl_add_u64 v[182:183], s[8:9], 0, v[182:183]
	global_load_dwordx4 v[182:185], v[182:183], off
	v_add_u32_e32 v206, 0x8000, v148
	v_lshlrev_b64 v[186:187], 2, v[206:207]
	v_lshl_add_u64 v[186:187], s[8:9], 0, v[186:187]
	global_load_dwordx4 v[186:189], v[186:187], off
	v_add_u32_e32 v206, 0x8010, v148
	v_lshlrev_b64 v[190:191], 2, v[206:207]
	v_lshl_add_u64 v[190:191], s[8:9], 0, v[190:191]
	global_load_dwordx4 v[190:193], v[190:191], off
	v_add_u32_e32 v206, 0x8080, v148
	v_lshlrev_b64 v[194:195], 2, v[206:207]
	v_lshl_add_u64 v[194:195], s[8:9], 0, v[194:195]
	global_load_dwordx4 v[194:197], v[194:195], off
	v_add_u32_e32 v206, 0x8090, v148
	v_lshlrev_b64 v[198:199], 2, v[206:207]
	v_lshl_add_u64 v[198:199], s[8:9], 0, v[198:199]
	global_load_dwordx4 v[198:201], v[198:199], off
	v_add_u32_e32 v206, 0xc000, v148
	v_lshlrev_b64 v[202:203], 2, v[206:207]
	v_lshl_add_u64 v[202:203], s[8:9], 0, v[202:203]
	global_load_dwordx4 v[202:205], v[202:203], off
	v_lshlrev_b64 v[146:147], 2, v[0:1]
	s_and_b64 vcc, exec, s[16:17]
	s_mov_b32 s22, s12
	s_mov_b32 s24, s14
	s_mov_b64 s[28:29], s[20:21]
	s_mov_b64 s[26:27], s[18:19]
	s_waitcnt vmcnt(12)
	v_pk_add_f32 v[128:129], v[128:129], v[152:153]
	v_pk_add_f32 v[126:127], v[126:127], v[150:151]
	v_lshl_add_u64 v[142:143], s[10:11], 0, v[146:147]
	v_add_u32_e32 v206, 0xc010, v148
	v_lshlrev_b64 v[150:151], 2, v[206:207]
	v_lshl_add_u64 v[150:151], s[8:9], 0, v[150:151]
	global_load_dwordx4 v[150:153], v[150:151], off
	global_store_dwordx4 v[142:143], v[126:129], off
	s_nop 1
	v_add_u32_e32 v126, 16, v0
	v_mov_b32_e32 v127, v1
	v_lshlrev_b64 v[142:143], 2, v[126:127]
	s_waitcnt vmcnt(13)
	v_pk_add_f32 v[124:125], v[124:125], v[156:157]
	v_pk_add_f32 v[122:123], v[122:123], v[154:155]
	v_lshl_add_u64 v[126:127], s[10:11], 0, v[142:143]
	v_add_u32_e32 v206, 0xc080, v148
	v_lshlrev_b64 v[154:155], 2, v[206:207]
	v_lshl_add_u64 v[154:155], s[8:9], 0, v[154:155]
	global_load_dwordx4 v[154:157], v[154:155], off
	global_store_dwordx4 v[126:127], v[122:125], off
	s_nop 1
	v_add_u32_e32 v122, 0x80, v0
	v_mov_b32_e32 v123, v1
	v_lshlrev_b64 v[126:127], 2, v[122:123]
	s_waitcnt vmcnt(14)
	v_pk_add_f32 v[120:121], v[120:121], v[160:161]
	v_pk_add_f32 v[118:119], v[118:119], v[158:159]
	v_lshl_add_u64 v[122:123], s[10:11], 0, v[126:127]
	v_add_u32_e32 v206, 0xc090, v148
	v_lshlrev_b64 v[158:159], 2, v[206:207]
	v_lshl_add_u64 v[158:159], s[8:9], 0, v[158:159]
	global_load_dwordx4 v[158:161], v[158:159], off
	global_store_dwordx4 v[122:123], v[118:121], off
	s_nop 1
	v_add_u32_e32 v118, 0x90, v0
	v_mov_b32_e32 v119, v1
	v_lshlrev_b64 v[122:123], 2, v[118:119]
	s_waitcnt vmcnt(15)
	v_pk_add_f32 v[116:117], v[116:117], v[164:165]
	v_pk_add_f32 v[114:115], v[114:115], v[162:163]
	v_lshl_add_u64 v[118:119], s[10:11], 0, v[122:123]
	v_add_u32_e32 v206, 0x20000, v148
	v_lshlrev_b64 v[162:163], 2, v[206:207]
	v_lshl_add_u64 v[162:163], s[8:9], 0, v[162:163]
	global_load_dwordx4 v[162:165], v[162:163], off
	global_store_dwordx4 v[118:119], v[114:117], off
	s_nop 1
	v_add_u32_e32 v114, 0x4000, v0
	v_mov_b32_e32 v115, v1
	v_lshlrev_b64 v[118:119], 2, v[114:115]
	s_waitcnt vmcnt(16)
	v_pk_add_f32 v[112:113], v[112:113], v[168:169]
	v_pk_add_f32 v[110:111], v[110:111], v[166:167]
	v_lshl_add_u64 v[114:115], s[10:11], 0, v[118:119]
	v_add_u32_e32 v206, 0x20010, v148
	v_lshlrev_b64 v[166:167], 2, v[206:207]
	v_lshl_add_u64 v[166:167], s[8:9], 0, v[166:167]
	global_load_dwordx4 v[166:169], v[166:167], off
	global_store_dwordx4 v[114:115], v[110:113], off
	s_nop 1
	v_add_u32_e32 v110, 0x4010, v0
	v_mov_b32_e32 v111, v1
	v_lshlrev_b64 v[114:115], 2, v[110:111]
	s_waitcnt vmcnt(17)
	v_pk_add_f32 v[108:109], v[108:109], v[172:173]
	v_pk_add_f32 v[106:107], v[106:107], v[170:171]
	v_lshl_add_u64 v[110:111], s[10:11], 0, v[114:115]
	v_add_u32_e32 v206, 0x20080, v148
	v_lshlrev_b64 v[170:171], 2, v[206:207]
	v_lshl_add_u64 v[170:171], s[8:9], 0, v[170:171]
	global_load_dwordx4 v[170:173], v[170:171], off
	global_store_dwordx4 v[110:111], v[106:109], off
	s_nop 1
	v_add_u32_e32 v106, 0x4080, v0
	v_mov_b32_e32 v107, v1
	v_lshlrev_b64 v[110:111], 2, v[106:107]
	s_waitcnt vmcnt(18)
	v_pk_add_f32 v[104:105], v[104:105], v[176:177]
	v_pk_add_f32 v[102:103], v[102:103], v[174:175]
	v_lshl_add_u64 v[106:107], s[10:11], 0, v[110:111]
	v_add_u32_e32 v206, 0x20090, v148
	v_lshlrev_b64 v[174:175], 2, v[206:207]
	v_lshl_add_u64 v[174:175], s[8:9], 0, v[174:175]
	global_load_dwordx4 v[174:177], v[174:175], off
	global_store_dwordx4 v[106:107], v[102:105], off
	s_nop 1
	v_add_u32_e32 v102, 0x4090, v0
	v_mov_b32_e32 v103, v1
	v_lshlrev_b64 v[106:107], 2, v[102:103]
	s_waitcnt vmcnt(19)
	v_pk_add_f32 v[100:101], v[100:101], v[184:185]
	v_pk_add_f32 v[98:99], v[98:99], v[182:183]
	v_lshl_add_u64 v[102:103], s[10:11], 0, v[106:107]
	v_add_u32_e32 v206, 0x24000, v148
	v_lshlrev_b64 v[182:183], 2, v[206:207]
	v_lshl_add_u64 v[182:183], s[8:9], 0, v[182:183]
	global_load_dwordx4 v[182:185], v[182:183], off
	global_store_dwordx4 v[102:103], v[98:101], off
	s_nop 1
	v_add_u32_e32 v98, 0x8000, v0
	v_mov_b32_e32 v99, v1
	v_lshlrev_b64 v[102:103], 2, v[98:99]
	s_waitcnt vmcnt(20)
	v_pk_add_f32 v[96:97], v[96:97], v[188:189]
	v_pk_add_f32 v[94:95], v[94:95], v[186:187]
	v_lshl_add_u64 v[98:99], s[10:11], 0, v[102:103]
	v_add_u32_e32 v206, 0x24010, v148
	v_lshlrev_b64 v[186:187], 2, v[206:207]
	v_lshl_add_u64 v[186:187], s[8:9], 0, v[186:187]
	global_load_dwordx4 v[186:189], v[186:187], off
	global_store_dwordx4 v[98:99], v[94:97], off
	s_nop 1
	v_add_u32_e32 v94, 0x8010, v0
	v_mov_b32_e32 v95, v1
	v_lshlrev_b64 v[98:99], 2, v[94:95]
	s_waitcnt vmcnt(21)
	v_pk_add_f32 v[92:93], v[92:93], v[192:193]
	v_pk_add_f32 v[90:91], v[90:91], v[190:191]
	v_lshl_add_u64 v[94:95], s[10:11], 0, v[98:99]
	v_add_u32_e32 v206, 0x24080, v148
	v_lshlrev_b64 v[190:191], 2, v[206:207]
	v_lshl_add_u64 v[190:191], s[8:9], 0, v[190:191]
	global_load_dwordx4 v[190:193], v[190:191], off
	global_store_dwordx4 v[94:95], v[90:93], off
	s_nop 1
	v_add_u32_e32 v90, 0x8080, v0
	v_mov_b32_e32 v91, v1
	v_lshlrev_b64 v[94:95], 2, v[90:91]
	s_waitcnt vmcnt(22)
	v_pk_add_f32 v[88:89], v[88:89], v[196:197]
	v_pk_add_f32 v[86:87], v[86:87], v[194:195]
	v_lshl_add_u64 v[90:91], s[10:11], 0, v[94:95]
	v_add_u32_e32 v206, 0x24090, v148
	v_lshlrev_b64 v[194:195], 2, v[206:207]
	v_lshl_add_u64 v[194:195], s[8:9], 0, v[194:195]
	global_load_dwordx4 v[194:197], v[194:195], off
	global_store_dwordx4 v[90:91], v[86:89], off
	s_nop 1
	v_add_u32_e32 v86, 0x8090, v0
	v_mov_b32_e32 v87, v1
	v_lshlrev_b64 v[90:91], 2, v[86:87]
	s_waitcnt vmcnt(23)
	v_pk_add_f32 v[84:85], v[84:85], v[200:201]
	v_pk_add_f32 v[82:83], v[82:83], v[198:199]
	v_lshl_add_u64 v[86:87], s[10:11], 0, v[90:91]
	v_add_u32_e32 v206, 0x28000, v148
	v_lshlrev_b64 v[198:199], 2, v[206:207]
	v_lshl_add_u64 v[198:199], s[8:9], 0, v[198:199]
	global_load_dwordx4 v[198:201], v[198:199], off
	global_store_dwordx4 v[86:87], v[82:85], off
	s_nop 1
	v_add_u32_e32 v82, 0xc000, v0
	v_mov_b32_e32 v83, v1
	v_lshlrev_b64 v[86:87], 2, v[82:83]
	s_waitcnt vmcnt(24)
	v_pk_add_f32 v[80:81], v[80:81], v[204:205]
	v_pk_add_f32 v[78:79], v[78:79], v[202:203]
	v_lshl_add_u64 v[82:83], s[10:11], 0, v[86:87]
	v_add_u32_e32 v206, 0x28010, v148
	v_lshlrev_b64 v[202:203], 2, v[206:207]
	v_lshl_add_u64 v[202:203], s[8:9], 0, v[202:203]
	global_load_dwordx4 v[202:205], v[202:203], off
	global_store_dwordx4 v[82:83], v[78:81], off
	s_nop 1
	v_add_u32_e32 v78, 0xc010, v0
	v_mov_b32_e32 v79, v1
	v_lshlrev_b64 v[82:83], 2, v[78:79]
	s_waitcnt vmcnt(25)
	v_pk_add_f32 v[76:77], v[76:77], v[152:153]
	v_pk_add_f32 v[74:75], v[74:75], v[150:151]
	v_lshl_add_u64 v[78:79], s[10:11], 0, v[82:83]
	v_add_u32_e32 v206, 0x28080, v148
	v_lshlrev_b64 v[150:151], 2, v[206:207]
	v_lshl_add_u64 v[150:151], s[8:9], 0, v[150:151]
	global_load_dwordx4 v[150:153], v[150:151], off
	global_store_dwordx4 v[78:79], v[74:77], off
	s_nop 1
	v_add_u32_e32 v74, 0xc080, v0
	v_mov_b32_e32 v75, v1
	v_lshlrev_b64 v[78:79], 2, v[74:75]
	s_waitcnt vmcnt(25)
	v_pk_add_f32 v[72:73], v[72:73], v[156:157]
	v_pk_add_f32 v[70:71], v[70:71], v[154:155]
	v_lshl_add_u64 v[74:75], s[10:11], 0, v[78:79]
	v_add_u32_e32 v206, 0x28090, v148
	v_lshlrev_b64 v[154:155], 2, v[206:207]
	v_lshl_add_u64 v[154:155], s[8:9], 0, v[154:155]
	global_load_dwordx4 v[154:157], v[154:155], off
	global_store_dwordx4 v[74:75], v[70:73], off
	s_nop 1
	v_add_u32_e32 v70, 0xc090, v0
	v_mov_b32_e32 v71, v1
	v_lshlrev_b64 v[74:75], 2, v[70:71]
	s_waitcnt vmcnt(25)
	v_pk_add_f32 v[68:69], v[68:69], v[160:161]
	v_pk_add_f32 v[66:67], v[66:67], v[158:159]
	v_lshl_add_u64 v[70:71], s[10:11], 0, v[74:75]
	v_add_u32_e32 v206, 0x2c000, v148
	v_lshlrev_b64 v[158:159], 2, v[206:207]
	v_lshl_add_u64 v[158:159], s[8:9], 0, v[158:159]
	global_load_dwordx4 v[158:161], v[158:159], off
	global_store_dwordx4 v[70:71], v[66:69], off
	s_nop 1
	v_add_u32_e32 v66, 0x20000, v0
	v_mov_b32_e32 v67, v1
	v_lshlrev_b64 v[70:71], 2, v[66:67]
	s_waitcnt vmcnt(25)
	v_pk_add_f32 v[64:65], v[64:65], v[164:165]
	v_pk_add_f32 v[62:63], v[62:63], v[162:163]
	v_lshl_add_u64 v[66:67], s[10:11], 0, v[70:71]
	v_add_u32_e32 v206, 0x2c010, v148
	v_lshlrev_b64 v[162:163], 2, v[206:207]
	v_lshl_add_u64 v[162:163], s[8:9], 0, v[162:163]
	global_load_dwordx4 v[162:165], v[162:163], off
	global_store_dwordx4 v[66:67], v[62:65], off
	s_nop 1
	v_add_u32_e32 v62, 0x20010, v0
	v_mov_b32_e32 v63, v1
	v_lshlrev_b64 v[66:67], 2, v[62:63]
	s_waitcnt vmcnt(25)
	v_pk_add_f32 v[60:61], v[60:61], v[168:169]
	v_pk_add_f32 v[58:59], v[58:59], v[166:167]
	v_lshl_add_u64 v[62:63], s[10:11], 0, v[66:67]
	v_add_u32_e32 v206, 0x2c080, v148
	v_lshlrev_b64 v[166:167], 2, v[206:207]
	v_lshl_add_u64 v[166:167], s[8:9], 0, v[166:167]
	global_load_dwordx4 v[166:169], v[166:167], off
	global_store_dwordx4 v[62:63], v[58:61], off
	s_nop 1
	v_add_u32_e32 v58, 0x20080, v0
	v_mov_b32_e32 v59, v1
	v_lshlrev_b64 v[62:63], 2, v[58:59]
	s_waitcnt vmcnt(25)
	v_pk_add_f32 v[56:57], v[56:57], v[172:173]
	v_pk_add_f32 v[54:55], v[54:55], v[170:171]
	v_lshl_add_u64 v[58:59], s[10:11], 0, v[62:63]
	v_add_u32_e32 v206, 0x2c090, v148
	v_lshlrev_b64 v[170:171], 2, v[206:207]
	v_lshl_add_u64 v[170:171], s[8:9], 0, v[170:171]
	global_load_dwordx4 v[170:173], v[170:171], off
	global_store_dwordx4 v[58:59], v[54:57], off
	s_nop 1
	v_add_u32_e32 v54, 0x20090, v0
	v_mov_b32_e32 v55, v1
	v_lshlrev_b64 v[58:59], 2, v[54:55]
	s_waitcnt vmcnt(25)
	v_pk_add_f32 v[52:53], v[52:53], v[176:177]
	v_pk_add_f32 v[50:51], v[50:51], v[174:175]
	v_lshl_add_u64 v[54:55], s[10:11], 0, v[58:59]
	global_store_dwordx4 v[54:55], v[50:53], off
	s_nop 1
	v_add_u32_e32 v50, 0x24000, v0
	v_mov_b32_e32 v51, v1
	v_lshlrev_b64 v[54:55], 2, v[50:51]
	s_waitcnt vmcnt(24)
	v_pk_add_f32 v[48:49], v[48:49], v[184:185]
	v_pk_add_f32 v[46:47], v[46:47], v[182:183]
	v_lshl_add_u64 v[50:51], s[10:11], 0, v[54:55]
	global_store_dwordx4 v[50:51], v[46:49], off
	s_nop 1
	v_add_u32_e32 v46, 0x24010, v0
	v_mov_b32_e32 v47, v1
	v_lshlrev_b64 v[50:51], 2, v[46:47]
	s_waitcnt vmcnt(23)
	v_pk_add_f32 v[44:45], v[44:45], v[188:189]
	v_pk_add_f32 v[42:43], v[42:43], v[186:187]
	v_lshl_add_u64 v[46:47], s[10:11], 0, v[50:51]
	global_store_dwordx4 v[46:47], v[42:45], off
	s_nop 1
	v_add_u32_e32 v42, 0x24080, v0
	v_mov_b32_e32 v43, v1
	v_lshlrev_b64 v[46:47], 2, v[42:43]
	s_waitcnt vmcnt(22)
	v_pk_add_f32 v[40:41], v[40:41], v[192:193]
	v_pk_add_f32 v[38:39], v[38:39], v[190:191]
	v_lshl_add_u64 v[42:43], s[10:11], 0, v[46:47]
	global_store_dwordx4 v[42:43], v[38:41], off
	s_nop 1
	v_add_u32_e32 v38, 0x24090, v0
	v_mov_b32_e32 v39, v1
	v_lshlrev_b64 v[42:43], 2, v[38:39]
	s_waitcnt vmcnt(21)
	v_pk_add_f32 v[36:37], v[36:37], v[196:197]
	v_pk_add_f32 v[34:35], v[34:35], v[194:195]
	v_lshl_add_u64 v[38:39], s[10:11], 0, v[42:43]
	global_store_dwordx4 v[38:39], v[34:37], off
	s_nop 1
	v_add_u32_e32 v34, 0x28000, v0
	v_mov_b32_e32 v35, v1
	v_lshlrev_b64 v[38:39], 2, v[34:35]
	s_waitcnt vmcnt(20)
	v_pk_add_f32 v[32:33], v[32:33], v[200:201]
	v_pk_add_f32 v[30:31], v[30:31], v[198:199]
	v_lshl_add_u64 v[34:35], s[10:11], 0, v[38:39]
	global_store_dwordx4 v[34:35], v[30:33], off
	s_nop 1
	v_add_u32_e32 v30, 0x28010, v0
	v_mov_b32_e32 v31, v1
	v_lshlrev_b64 v[34:35], 2, v[30:31]
	s_waitcnt vmcnt(19)
	v_pk_add_f32 v[28:29], v[28:29], v[204:205]
	v_pk_add_f32 v[26:27], v[26:27], v[202:203]
	v_lshl_add_u64 v[30:31], s[10:11], 0, v[34:35]
	global_store_dwordx4 v[30:31], v[26:29], off
	s_nop 1
	v_add_u32_e32 v26, 0x28080, v0
	v_mov_b32_e32 v27, v1
	v_lshlrev_b64 v[30:31], 2, v[26:27]
	s_waitcnt vmcnt(18)
	v_pk_add_f32 v[24:25], v[24:25], v[152:153]
	v_pk_add_f32 v[22:23], v[22:23], v[150:151]
	v_lshl_add_u64 v[26:27], s[10:11], 0, v[30:31]
	global_store_dwordx4 v[26:27], v[22:25], off
	s_nop 1
	v_add_u32_e32 v22, 0x28090, v0
	v_mov_b32_e32 v23, v1
	v_lshlrev_b64 v[26:27], 2, v[22:23]
	s_waitcnt vmcnt(17)
	v_pk_add_f32 v[20:21], v[20:21], v[156:157]
	v_pk_add_f32 v[18:19], v[18:19], v[154:155]
	v_lshl_add_u64 v[22:23], s[10:11], 0, v[26:27]
	global_store_dwordx4 v[22:23], v[18:21], off
	s_nop 1
	v_add_u32_e32 v18, 0x2c000, v0
	v_mov_b32_e32 v19, v1
	v_lshlrev_b64 v[22:23], 2, v[18:19]
	s_waitcnt vmcnt(16)
	v_pk_add_f32 v[16:17], v[16:17], v[160:161]
	v_pk_add_f32 v[14:15], v[14:15], v[158:159]
	v_lshl_add_u64 v[18:19], s[10:11], 0, v[22:23]
	global_store_dwordx4 v[18:19], v[14:17], off
	s_nop 1
	v_add_u32_e32 v14, 0x2c010, v0
	v_mov_b32_e32 v15, v1
	v_lshlrev_b64 v[18:19], 2, v[14:15]
	s_waitcnt vmcnt(15)
	v_pk_add_f32 v[12:13], v[12:13], v[164:165]
	v_pk_add_f32 v[10:11], v[10:11], v[162:163]
	v_lshl_add_u64 v[14:15], s[10:11], 0, v[18:19]
	global_store_dwordx4 v[14:15], v[10:13], off
	s_nop 1
	v_add_u32_e32 v10, 0x2c080, v0
	v_mov_b32_e32 v11, v1
	v_lshlrev_b64 v[14:15], 2, v[10:11]
	v_add_u32_e32 v0, 0x2c090, v0
	s_waitcnt vmcnt(14)
	v_pk_add_f32 v[8:9], v[8:9], v[168:169]
	v_pk_add_f32 v[6:7], v[6:7], v[166:167]
	v_lshl_add_u64 v[10:11], s[10:11], 0, v[14:15]
	global_store_dwordx4 v[10:11], v[6:9], off
	v_lshlrev_b64 v[10:11], 2, v[0:1]
	s_nop 0
	s_waitcnt vmcnt(13)
	v_pk_add_f32 v[4:5], v[4:5], v[172:173]
	v_pk_add_f32 v[2:3], v[2:3], v[170:171]
	v_lshl_add_u64 v[6:7], s[10:11], 0, v[10:11]
	global_store_dwordx4 v[6:7], v[2:5], off
	s_cbranch_vccz .LBB0_1425
	s_waitcnt vmcnt(0)
	v_readlane_b32 s76, v255, 8
	s_mov_b32 s92, 0x3b2aaaab
	s_cmp_gt_u32 s4, 3
	v_readlane_b32 s77, v255, 9
	s_mul_i32 s60, s33, 0x1800
	s_mul_hi_i32 s62, s64, 0x300
	s_mul_i32 s75, s33, 0x16c00
	s_mov_b32 s93, 0x3c800000
	s_cbranch_scc1 .LBB0_1432
	s_barrier

.LBB0_1441:
	v_add_u32_e32 v0, 0x10000, v139
	ds_read_b128 v[142:145], v0
	ds_read_b128 v[146:149], v0 offset:1024
	ds_read_b128 v[150:153], v0 offset:2048
	ds_read_b128 v[154:157], v0 offset:3072
	s_add_u32 s26, s24, 0xfffc0080
	s_addc_u32 s27, s25, -1
	s_cmp_eq_u32 s97, 12
	s_cselect_b32 s29, s13, s27
	s_cselect_b32 s28, s89, s26
	s_cselect_b32 s27, s11, s96
	s_cselect_b32 s26, s90, s94
	v_lshl_add_u64 v[178:179], s[24:25], 0, v[134:135]
	s_add_i32 m0, s34, 0xc000
	ds_read_b128 v[158:161], v138
	ds_read_b128 v[162:165], v138 offset:1024
	ds_read_b128 v[166:169], v138 offset:2048
	ds_read_b128 v[170:173], v138 offset:3072
	ds_read_b128 v[174:177], v138 offset:4096
	ds_read_b128 v[182:185], v138 offset:5120
	ds_read_b128 v[186:189], v138 offset:6144
	ds_read_b128 v[190:193], v138 offset:7168
	global_load_lds_dwordx4 v[178:179], off
	v_lshl_add_u64 v[178:179], s[24:25], 0, v[136:137]
	s_add_i32 m0, s34, 0xe000
	s_nop 0
	global_load_lds_dwordx4 v[178:179], off
	s_waitcnt lgkmcnt(8)
	s_barrier
	s_waitcnt lgkmcnt(0)
	s_waitcnt lgkmcnt(0)
	v_mfma_f32_16x16x32_bf16 v[126:129], v[142:145], v[158:161], v[126:129]
	v_mfma_f32_16x16x32_bf16 v[122:125], v[150:153], v[158:161], v[122:125]
	v_mfma_f32_16x16x32_bf16 v[110:113], v[142:145], v[166:169], v[110:113]
	v_mfma_f32_16x16x32_bf16 v[106:109], v[150:153], v[166:169], v[106:109]
	v_mfma_f32_16x16x32_bf16 v[94:97], v[142:145], v[174:177], v[94:97]
	v_mfma_f32_16x16x32_bf16 v[90:93], v[150:153], v[174:177], v[90:93]
	v_mfma_f32_16x16x32_bf16 v[78:81], v[142:145], v[186:189], v[78:81]
	v_mfma_f32_16x16x32_bf16 v[74:77], v[150:153], v[186:189], v[74:77]
	v_mfma_f32_16x16x32_bf16 v[126:129], v[146:149], v[162:165], v[126:129]
	v_mfma_f32_16x16x32_bf16 v[122:125], v[154:157], v[162:165], v[122:125]
	v_mfma_f32_16x16x32_bf16 v[110:113], v[146:149], v[170:173], v[110:113]
	v_mfma_f32_16x16x32_bf16 v[106:109], v[154:157], v[170:173], v[106:109]
	v_mfma_f32_16x16x32_bf16 v[94:97], v[146:149], v[182:185], v[94:97]
	v_mfma_f32_16x16x32_bf16 v[90:93], v[154:157], v[182:185], v[90:93]
	v_mfma_f32_16x16x32_bf16 v[78:81], v[146:149], v[190:193], v[78:81]
	v_mfma_f32_16x16x32_bf16 v[74:77], v[154:157], v[190:193], v[74:77]
	s_barrier
	s_mov_b32 m0, s21
	v_add_u32_e32 v0, 0x14000, v139
	v_lshl_add_u64 v[178:179], s[26:27], 0, v[132:133]
	ds_read_b128 v[194:197], v0
	ds_read_b128 v[198:201], v0 offset:1024
	ds_read_b128 v[202:205], v0 offset:2048
	ds_read_b128 v[206:209], v0 offset:3072
	global_load_lds_dwordx4 v[178:179], off
	v_lshl_add_u64 v[210:211], s[26:27], 0, v[130:131]
	s_mov_b32 m0, s23
	s_nop 0
	global_load_lds_dwordx4 v[210:211], off
	s_barrier
	s_waitcnt lgkmcnt(0)
	s_waitcnt lgkmcnt(0)
	v_mfma_f32_16x16x32_bf16 v[118:121], v[194:197], v[158:161], v[118:121]
	v_mfma_f32_16x16x32_bf16 v[114:117], v[202:205], v[158:161], v[114:117]
	v_mfma_f32_16x16x32_bf16 v[102:105], v[194:197], v[166:169], v[102:105]
	v_mfma_f32_16x16x32_bf16 v[98:101], v[202:205], v[166:169], v[98:101]
	v_mfma_f32_16x16x32_bf16 v[86:89], v[194:197], v[174:177], v[86:89]
	v_mfma_f32_16x16x32_bf16 v[82:85], v[202:205], v[174:177], v[82:85]
	v_mfma_f32_16x16x32_bf16 v[70:73], v[194:197], v[186:189], v[70:73]
	v_mfma_f32_16x16x32_bf16 v[66:69], v[202:205], v[186:189], v[66:69]
	v_mfma_f32_16x16x32_bf16 v[118:121], v[198:201], v[162:165], v[118:121]
	v_mfma_f32_16x16x32_bf16 v[114:117], v[206:209], v[162:165], v[114:117]
	v_mfma_f32_16x16x32_bf16 v[102:105], v[198:201], v[170:173], v[102:105]
	v_mfma_f32_16x16x32_bf16 v[98:101], v[206:209], v[170:173], v[98:101]
	v_mfma_f32_16x16x32_bf16 v[86:89], v[198:201], v[182:185], v[86:89]
	v_mfma_f32_16x16x32_bf16 v[82:85], v[206:209], v[182:185], v[82:85]
	v_mfma_f32_16x16x32_bf16 v[70:73], v[198:201], v[190:193], v[70:73]
	v_mfma_f32_16x16x32_bf16 v[66:69], v[206:209], v[190:193], v[66:69]
	s_mov_b32 m0, s34
	v_lshl_add_u64 v[212:213], s[28:29], 0, v[132:133]
	s_barrier
	ds_read_b128 v[158:161], v138 offset:16384
	ds_read_b128 v[162:165], v138 offset:17408
	ds_read_b128 v[166:169], v138 offset:18432
	ds_read_b128 v[170:173], v138 offset:19456
	ds_read_b128 v[174:177], v138 offset:20480
	ds_read_b128 v[182:185], v138 offset:21504
	ds_read_b128 v[186:189], v138 offset:22528
	ds_read_b128 v[190:193], v138 offset:23552
	global_load_lds_dwordx4 v[212:213], off
	v_lshl_add_u64 v[214:215], s[28:29], 0, v[130:131]
	s_mov_b32 m0, s35
	s_nop 0
	global_load_lds_dwordx4 v[214:215], off
	s_barrier
	s_waitcnt lgkmcnt(0)
	s_waitcnt lgkmcnt(0)
	v_mfma_f32_16x16x32_bf16 v[62:65], v[142:145], v[158:161], v[62:65]
	v_mfma_f32_16x16x32_bf16 v[58:61], v[150:153], v[158:161], v[58:61]
	v_mfma_f32_16x16x32_bf16 v[46:49], v[142:145], v[166:169], v[46:49]
	v_mfma_f32_16x16x32_bf16 v[42:45], v[150:153], v[166:169], v[42:45]
	v_mfma_f32_16x16x32_bf16 v[30:33], v[142:145], v[174:177], v[30:33]
	v_mfma_f32_16x16x32_bf16 v[26:29], v[150:153], v[174:177], v[26:29]
	v_mfma_f32_16x16x32_bf16 v[14:17], v[142:145], v[186:189], v[14:17]
	v_mfma_f32_16x16x32_bf16 v[10:13], v[150:153], v[186:189], v[10:13]
	v_mfma_f32_16x16x32_bf16 v[62:65], v[146:149], v[162:165], v[62:65]
	v_mfma_f32_16x16x32_bf16 v[58:61], v[154:157], v[162:165], v[58:61]
	v_mfma_f32_16x16x32_bf16 v[46:49], v[146:149], v[170:173], v[46:49]
	v_mfma_f32_16x16x32_bf16 v[42:45], v[154:157], v[170:173], v[42:45]
	v_mfma_f32_16x16x32_bf16 v[30:33], v[146:149], v[182:185], v[30:33]
	v_mfma_f32_16x16x32_bf16 v[26:29], v[154:157], v[182:185], v[26:29]
	v_mfma_f32_16x16x32_bf16 v[14:17], v[146:149], v[190:193], v[14:17]
	v_mfma_f32_16x16x32_bf16 v[10:13], v[154:157], v[190:193], v[10:13]
	s_barrier
	s_add_u32 s76, s26, 0x40000
	s_addc_u32 s77, s27, 0
	s_mov_b32 m0, s36
	v_lshl_add_u64 v[142:143], s[76:77], 0, v[132:133]
	global_load_lds_dwordx4 v[142:143], off
	v_lshl_add_u64 v[142:143], s[76:77], 0, v[130:131]
	s_mov_b32 m0, s37
	s_nop 0
	global_load_lds_dwordx4 v[142:143], off
	s_waitcnt vmcnt(6)
	s_barrier
	v_mfma_f32_16x16x32_bf16 v[54:57], v[194:197], v[158:161], v[54:57]
	v_mfma_f32_16x16x32_bf16 v[50:53], v[202:205], v[158:161], v[50:53]
	v_mfma_f32_16x16x32_bf16 v[38:41], v[194:197], v[166:169], v[38:41]
	v_mfma_f32_16x16x32_bf16 v[34:37], v[202:205], v[166:169], v[34:37]
	v_mfma_f32_16x16x32_bf16 v[22:25], v[194:197], v[174:177], v[22:25]
	v_mfma_f32_16x16x32_bf16 v[18:21], v[202:205], v[174:177], v[18:21]
	v_mfma_f32_16x16x32_bf16 v[6:9], v[194:197], v[186:189], v[6:9]
	v_mfma_f32_16x16x32_bf16 v[2:5], v[202:205], v[186:189], v[2:5]
	v_mfma_f32_16x16x32_bf16 v[54:57], v[198:201], v[162:165], v[54:57]
	v_mfma_f32_16x16x32_bf16 v[50:53], v[206:209], v[162:165], v[50:53]
	v_mfma_f32_16x16x32_bf16 v[38:41], v[198:201], v[170:173], v[38:41]
	v_mfma_f32_16x16x32_bf16 v[34:37], v[206:209], v[170:173], v[34:37]
	v_mfma_f32_16x16x32_bf16 v[22:25], v[198:201], v[182:185], v[22:25]
	v_mfma_f32_16x16x32_bf16 v[18:21], v[206:209], v[182:185], v[18:21]
	v_mfma_f32_16x16x32_bf16 v[6:9], v[198:201], v[190:193], v[6:9]
	v_mfma_f32_16x16x32_bf16 v[2:5], v[206:209], v[190:193], v[2:5]
	v_add_u32_e32 v0, 0x18000, v139
	s_barrier
	ds_read_b128 v[142:145], v0
	ds_read_b128 v[146:149], v0 offset:1024
	ds_read_b128 v[150:153], v0 offset:2048
	ds_read_b128 v[154:157], v0 offset:3072
	s_add_u32 s28, s28, 0x40000
	s_addc_u32 s29, s29, 0
	s_mov_b32 m0, s38
	v_lshl_add_u64 v[194:195], s[28:29], 0, v[132:133]
	ds_read_b128 v[158:161], v138 offset:32768
	ds_read_b128 v[162:165], v138 offset:33792
	ds_read_b128 v[166:169], v138 offset:34816
	ds_read_b128 v[170:173], v138 offset:35840
	ds_read_b128 v[174:177], v138 offset:36864
	ds_read_b128 v[182:185], v138 offset:37888
	ds_read_b128 v[186:189], v138 offset:38912
	ds_read_b128 v[190:193], v138 offset:39936
	global_load_lds_dwordx4 v[194:195], off
	v_lshl_add_u64 v[194:195], s[28:29], 0, v[130:131]
	s_mov_b32 m0, s39
	s_nop 0
	global_load_lds_dwordx4 v[194:195], off
	s_waitcnt lgkmcnt(8)
	s_barrier
	s_waitcnt lgkmcnt(0)
	s_waitcnt lgkmcnt(0)
	v_mfma_f32_16x16x32_bf16 v[126:129], v[142:145], v[158:161], v[126:129]
	v_mfma_f32_16x16x32_bf16 v[122:125], v[150:153], v[158:161], v[122:125]
	v_mfma_f32_16x16x32_bf16 v[110:113], v[142:145], v[166:169], v[110:113]
	v_mfma_f32_16x16x32_bf16 v[106:109], v[150:153], v[166:169], v[106:109]
	v_mfma_f32_16x16x32_bf16 v[94:97], v[142:145], v[174:177], v[94:97]
	v_mfma_f32_16x16x32_bf16 v[90:93], v[150:153], v[174:177], v[90:93]
	v_mfma_f32_16x16x32_bf16 v[78:81], v[142:145], v[186:189], v[78:81]
	v_mfma_f32_16x16x32_bf16 v[74:77], v[150:153], v[186:189], v[74:77]
	v_mfma_f32_16x16x32_bf16 v[126:129], v[146:149], v[162:165], v[126:129]
	v_mfma_f32_16x16x32_bf16 v[122:125], v[154:157], v[162:165], v[122:125]
	v_mfma_f32_16x16x32_bf16 v[110:113], v[146:149], v[170:173], v[110:113]
	v_mfma_f32_16x16x32_bf16 v[106:109], v[154:157], v[170:173], v[106:109]
	v_mfma_f32_16x16x32_bf16 v[94:97], v[146:149], v[182:185], v[94:97]
	v_mfma_f32_16x16x32_bf16 v[90:93], v[154:157], v[182:185], v[90:93]
	v_mfma_f32_16x16x32_bf16 v[78:81], v[146:149], v[190:193], v[78:81]
	v_mfma_f32_16x16x32_bf16 v[74:77], v[154:157], v[190:193], v[74:77]
	s_barrier
	s_mov_b32 m0, s60
	v_add_u32_e32 v0, 0x1c000, v139
	v_lshl_add_u64 v[178:179], v[178:179], 0, s[84:85]
	ds_read_b128 v[194:197], v0
	ds_read_b128 v[198:201], v0 offset:1024
	ds_read_b128 v[202:205], v0 offset:2048
	ds_read_b128 v[206:209], v0 offset:3072
	global_load_lds_dwordx4 v[178:179], off
	v_lshl_add_u64 v[178:179], v[210:211], 0, s[84:85]
	s_mov_b32 m0, s68
	s_nop 0
	global_load_lds_dwordx4 v[178:179], off
	s_barrier
	s_waitcnt lgkmcnt(0)
	s_waitcnt lgkmcnt(0)
	v_mfma_f32_16x16x32_bf16 v[118:121], v[194:197], v[158:161], v[118:121]
	v_mfma_f32_16x16x32_bf16 v[114:117], v[202:205], v[158:161], v[114:117]
	v_mfma_f32_16x16x32_bf16 v[102:105], v[194:197], v[166:169], v[102:105]
	v_mfma_f32_16x16x32_bf16 v[98:101], v[202:205], v[166:169], v[98:101]
	v_mfma_f32_16x16x32_bf16 v[86:89], v[194:197], v[174:177], v[86:89]
	v_mfma_f32_16x16x32_bf16 v[82:85], v[202:205], v[174:177], v[82:85]
	v_mfma_f32_16x16x32_bf16 v[70:73], v[194:197], v[186:189], v[70:73]
	v_mfma_f32_16x16x32_bf16 v[66:69], v[202:205], v[186:189], v[66:69]
	v_mfma_f32_16x16x32_bf16 v[118:121], v[198:201], v[162:165], v[118:121]
	v_mfma_f32_16x16x32_bf16 v[114:117], v[206:209], v[162:165], v[114:117]
	v_mfma_f32_16x16x32_bf16 v[102:105], v[198:201], v[170:173], v[102:105]
	v_mfma_f32_16x16x32_bf16 v[98:101], v[206:209], v[170:173], v[98:101]
	v_mfma_f32_16x16x32_bf16 v[86:89], v[198:201], v[182:185], v[86:89]
	v_mfma_f32_16x16x32_bf16 v[82:85], v[206:209], v[182:185], v[82:85]
	v_mfma_f32_16x16x32_bf16 v[70:73], v[198:201], v[190:193], v[70:73]
	v_mfma_f32_16x16x32_bf16 v[66:69], v[206:209], v[190:193], v[66:69]
	s_mov_b32 m0, s69
	v_lshl_add_u64 v[178:179], v[212:213], 0, s[84:85]
	s_barrier
	ds_read_b128 v[158:161], v138 offset:49152
	ds_read_b128 v[162:165], v138 offset:50176
	ds_read_b128 v[166:169], v138 offset:51200
	ds_read_b128 v[170:173], v138 offset:52224
	ds_read_b128 v[174:177], v138 offset:53248
	ds_read_b128 v[182:185], v138 offset:54272
	ds_read_b128 v[186:189], v138 offset:55296
	ds_read_b128 v[190:193], v138 offset:56320
	global_load_lds_dwordx4 v[178:179], off
	v_lshl_add_u64 v[178:179], v[214:215], 0, s[84:85]
	s_mov_b32 m0, s75
	s_nop 0
	global_load_lds_dwordx4 v[178:179], off
	s_barrier
	s_waitcnt lgkmcnt(0)
	s_waitcnt lgkmcnt(0)
	v_mfma_f32_16x16x32_bf16 v[62:65], v[142:145], v[158:161], v[62:65]
	v_mfma_f32_16x16x32_bf16 v[58:61], v[150:153], v[158:161], v[58:61]
	v_mfma_f32_16x16x32_bf16 v[46:49], v[142:145], v[166:169], v[46:49]
	v_mfma_f32_16x16x32_bf16 v[42:45], v[150:153], v[166:169], v[42:45]
	v_mfma_f32_16x16x32_bf16 v[30:33], v[142:145], v[174:177], v[30:33]
	v_mfma_f32_16x16x32_bf16 v[26:29], v[150:153], v[174:177], v[26:29]
	v_mfma_f32_16x16x32_bf16 v[14:17], v[142:145], v[186:189], v[14:17]
	v_mfma_f32_16x16x32_bf16 v[10:13], v[150:153], v[186:189], v[10:13]
	v_mfma_f32_16x16x32_bf16 v[62:65], v[146:149], v[162:165], v[62:65]
	v_mfma_f32_16x16x32_bf16 v[58:61], v[154:157], v[162:165], v[58:61]
	v_mfma_f32_16x16x32_bf16 v[46:49], v[146:149], v[170:173], v[46:49]
	v_mfma_f32_16x16x32_bf16 v[42:45], v[154:157], v[170:173], v[42:45]
	v_mfma_f32_16x16x32_bf16 v[30:33], v[146:149], v[182:185], v[30:33]
	v_mfma_f32_16x16x32_bf16 v[26:29], v[154:157], v[182:185], v[26:29]
	v_mfma_f32_16x16x32_bf16 v[14:17], v[146:149], v[190:193], v[14:17]
	v_mfma_f32_16x16x32_bf16 v[10:13], v[154:157], v[190:193], v[10:13]
	s_barrier
	s_add_u32 s26, s26, 0x40080
	s_addc_u32 s27, s27, 0
	s_mov_b32 m0, s82
	v_lshl_add_u64 v[142:143], s[26:27], 0, v[132:133]
	global_load_lds_dwordx4 v[142:143], off
	v_lshl_add_u64 v[142:143], s[26:27], 0, v[130:131]
	s_mov_b32 m0, s92
	s_nop 0
	global_load_lds_dwordx4 v[142:143], off
	s_waitcnt vmcnt(6)
	s_barrier
	v_mfma_f32_16x16x32_bf16 v[54:57], v[194:197], v[158:161], v[54:57]
	v_mfma_f32_16x16x32_bf16 v[50:53], v[202:205], v[158:161], v[50:53]
	v_mfma_f32_16x16x32_bf16 v[38:41], v[194:197], v[166:169], v[38:41]
	v_mfma_f32_16x16x32_bf16 v[34:37], v[202:205], v[166:169], v[34:37]
	v_mfma_f32_16x16x32_bf16 v[22:25], v[194:197], v[174:177], v[22:25]
	v_mfma_f32_16x16x32_bf16 v[18:21], v[202:205], v[174:177], v[18:21]
	v_mfma_f32_16x16x32_bf16 v[6:9], v[194:197], v[186:189], v[6:9]
	v_mfma_f32_16x16x32_bf16 v[2:5], v[202:205], v[186:189], v[2:5]
	v_mfma_f32_16x16x32_bf16 v[54:57], v[198:201], v[162:165], v[54:57]
	v_mfma_f32_16x16x32_bf16 v[50:53], v[206:209], v[162:165], v[50:53]
	v_mfma_f32_16x16x32_bf16 v[38:41], v[198:201], v[170:173], v[38:41]
	v_mfma_f32_16x16x32_bf16 v[34:37], v[206:209], v[170:173], v[34:37]
	v_mfma_f32_16x16x32_bf16 v[22:25], v[198:201], v[182:185], v[22:25]
	v_mfma_f32_16x16x32_bf16 v[18:21], v[206:209], v[182:185], v[18:21]
	v_mfma_f32_16x16x32_bf16 v[6:9], v[198:201], v[190:193], v[6:9]
	v_mfma_f32_16x16x32_bf16 v[2:5], v[206:209], v[190:193], v[2:5]
	s_add_i32 s97, s97, 2
	s_add_u32 s24, s24, 0x100
	s_addc_u32 s25, s25, 0
	s_add_u32 s94, s94, 0x100
	s_addc_u32 s96, s96, 0
	s_cmp_gt_u32 s97, 13
	s_barrier
	s_cbranch_scc0 .LBB0_1441
	s_lshl_b32 s11, s20, 8
	s_lshl_b32 s13, s22, 18
	s_add_i32 s13, s13, s11
	v_add_u32_e32 v0, s13, v140
	v_mov_b32_e32 v148, v0
	v_mov_b32_e32 v207, 0
	v_mov_b32_e32 v206, v148
	v_lshlrev_b64 v[150:151], 2, v[206:207]
	v_lshl_add_u64 v[150:151], s[6:7], 0, v[150:151]
	global_load_dwordx4 v[150:153], v[150:151], off
	v_add_u32_e32 v206, 0x10, v148
	v_lshlrev_b64 v[154:155], 2, v[206:207]
	v_lshl_add_u64 v[154:155], s[6:7], 0, v[154:155]
	global_load_dwordx4 v[154:157], v[154:155], off
	v_add_u32_e32 v206, 0x80, v148
	v_lshlrev_b64 v[158:159], 2, v[206:207]
	v_lshl_add_u64 v[158:159], s[6:7], 0, v[158:159]
	global_load_dwordx4 v[158:161], v[158:159], off
	v_add_u32_e32 v206, 0x90, v148
	v_lshlrev_b64 v[162:163], 2, v[206:207]
	v_lshl_add_u64 v[162:163], s[6:7], 0, v[162:163]
	global_load_dwordx4 v[162:165], v[162:163], off
	v_add_u32_e32 v206, 0x4000, v148
	v_lshlrev_b64 v[166:167], 2, v[206:207]
	v_lshl_add_u64 v[166:167], s[6:7], 0, v[166:167]
	global_load_dwordx4 v[166:169], v[166:167], off
	v_add_u32_e32 v206, 0x4010, v148
	v_lshlrev_b64 v[170:171], 2, v[206:207]
	v_lshl_add_u64 v[170:171], s[6:7], 0, v[170:171]
	global_load_dwordx4 v[170:173], v[170:171], off
	v_add_u32_e32 v206, 0x4080, v148
	v_lshlrev_b64 v[174:175], 2, v[206:207]
	v_lshl_add_u64 v[174:175], s[6:7], 0, v[174:175]
	global_load_dwordx4 v[174:177], v[174:175], off
	v_add_u32_e32 v206, 0x4090, v148
	v_lshlrev_b64 v[182:183], 2, v[206:207]
	v_lshl_add_u64 v[182:183], s[6:7], 0, v[182:183]
	global_load_dwordx4 v[182:185], v[182:183], off
	v_add_u32_e32 v206, 0x8000, v148
	v_lshlrev_b64 v[186:187], 2, v[206:207]
	v_lshl_add_u64 v[186:187], s[6:7], 0, v[186:187]
	global_load_dwordx4 v[186:189], v[186:187], off
	v_add_u32_e32 v206, 0x8010, v148
	v_lshlrev_b64 v[190:191], 2, v[206:207]
	v_lshl_add_u64 v[190:191], s[6:7], 0, v[190:191]
	global_load_dwordx4 v[190:193], v[190:191], off
	v_add_u32_e32 v206, 0x8080, v148
	v_lshlrev_b64 v[194:195], 2, v[206:207]
	v_lshl_add_u64 v[194:195], s[6:7], 0, v[194:195]
	global_load_dwordx4 v[194:197], v[194:195], off
	v_add_u32_e32 v206, 0x8090, v148
	v_lshlrev_b64 v[198:199], 2, v[206:207]
	v_lshl_add_u64 v[198:199], s[6:7], 0, v[198:199]
	global_load_dwordx4 v[198:201], v[198:199], off
	v_add_u32_e32 v206, 0xc000, v148
	v_lshlrev_b64 v[202:203], 2, v[206:207]
	v_lshl_add_u64 v[202:203], s[6:7], 0, v[202:203]
	global_load_dwordx4 v[202:205], v[202:203], off
	v_lshlrev_b64 v[146:147], 2, v[0:1]
	s_and_b64 vcc, exec, s[14:15]
	s_mov_b32 s20, s10
	s_mov_b32 s22, s12
	s_mov_b64 s[26:27], s[18:19]
	s_mov_b64 s[24:25], s[16:17]
	s_waitcnt vmcnt(12)
	v_pk_add_f32 v[128:129], v[128:129], v[152:153]
	v_pk_add_f32 v[126:127], v[126:127], v[150:151]
	v_lshl_add_u64 v[142:143], s[8:9], 0, v[146:147]
	v_add_u32_e32 v206, 0xc010, v148
	v_lshlrev_b64 v[150:151], 2, v[206:207]
	v_lshl_add_u64 v[150:151], s[6:7], 0, v[150:151]
	global_load_dwordx4 v[150:153], v[150:151], off
	global_store_dwordx4 v[142:143], v[126:129], off
	s_nop 1
	v_add_u32_e32 v126, 16, v0
	v_mov_b32_e32 v127, v1
	v_lshlrev_b64 v[142:143], 2, v[126:127]
	s_waitcnt vmcnt(13)
	v_pk_add_f32 v[124:125], v[124:125], v[156:157]
	v_pk_add_f32 v[122:123], v[122:123], v[154:155]
	v_lshl_add_u64 v[126:127], s[8:9], 0, v[142:143]
	v_add_u32_e32 v206, 0xc080, v148
	v_lshlrev_b64 v[154:155], 2, v[206:207]
	v_lshl_add_u64 v[154:155], s[6:7], 0, v[154:155]
	global_load_dwordx4 v[154:157], v[154:155], off
	global_store_dwordx4 v[126:127], v[122:125], off
	s_nop 1
	v_add_u32_e32 v122, 0x80, v0
	v_mov_b32_e32 v123, v1
	v_lshlrev_b64 v[126:127], 2, v[122:123]
	s_waitcnt vmcnt(14)
	v_pk_add_f32 v[120:121], v[120:121], v[160:161]
	v_pk_add_f32 v[118:119], v[118:119], v[158:159]
	v_lshl_add_u64 v[122:123], s[8:9], 0, v[126:127]
	v_add_u32_e32 v206, 0xc090, v148
	v_lshlrev_b64 v[158:159], 2, v[206:207]
	v_lshl_add_u64 v[158:159], s[6:7], 0, v[158:159]
	global_load_dwordx4 v[158:161], v[158:159], off
	global_store_dwordx4 v[122:123], v[118:121], off
	s_nop 1
	v_add_u32_e32 v118, 0x90, v0
	v_mov_b32_e32 v119, v1
	v_lshlrev_b64 v[122:123], 2, v[118:119]
	s_waitcnt vmcnt(15)
	v_pk_add_f32 v[116:117], v[116:117], v[164:165]
	v_pk_add_f32 v[114:115], v[114:115], v[162:163]
	v_lshl_add_u64 v[118:119], s[8:9], 0, v[122:123]
	v_add_u32_e32 v206, 0x20000, v148
	v_lshlrev_b64 v[162:163], 2, v[206:207]
	v_lshl_add_u64 v[162:163], s[6:7], 0, v[162:163]
	global_load_dwordx4 v[162:165], v[162:163], off
	global_store_dwordx4 v[118:119], v[114:117], off
	s_nop 1
	v_add_u32_e32 v114, 0x4000, v0
	v_mov_b32_e32 v115, v1
	v_lshlrev_b64 v[118:119], 2, v[114:115]
	s_waitcnt vmcnt(16)
	v_pk_add_f32 v[112:113], v[112:113], v[168:169]
	v_pk_add_f32 v[110:111], v[110:111], v[166:167]
	v_lshl_add_u64 v[114:115], s[8:9], 0, v[118:119]
	v_add_u32_e32 v206, 0x20010, v148
	v_lshlrev_b64 v[166:167], 2, v[206:207]
	v_lshl_add_u64 v[166:167], s[6:7], 0, v[166:167]
	global_load_dwordx4 v[166:169], v[166:167], off
	global_store_dwordx4 v[114:115], v[110:113], off
	s_nop 1
	v_add_u32_e32 v110, 0x4010, v0
	v_mov_b32_e32 v111, v1
	v_lshlrev_b64 v[114:115], 2, v[110:111]
	s_waitcnt vmcnt(17)
	v_pk_add_f32 v[108:109], v[108:109], v[172:173]
	v_pk_add_f32 v[106:107], v[106:107], v[170:171]
	v_lshl_add_u64 v[110:111], s[8:9], 0, v[114:115]
	v_add_u32_e32 v206, 0x20080, v148
	v_lshlrev_b64 v[170:171], 2, v[206:207]
	v_lshl_add_u64 v[170:171], s[6:7], 0, v[170:171]
	global_load_dwordx4 v[170:173], v[170:171], off
	global_store_dwordx4 v[110:111], v[106:109], off
	s_nop 1
	v_add_u32_e32 v106, 0x4080, v0
	v_mov_b32_e32 v107, v1
	v_lshlrev_b64 v[110:111], 2, v[106:107]
	s_waitcnt vmcnt(18)
	v_pk_add_f32 v[104:105], v[104:105], v[176:177]
	v_pk_add_f32 v[102:103], v[102:103], v[174:175]
	v_lshl_add_u64 v[106:107], s[8:9], 0, v[110:111]
	v_add_u32_e32 v206, 0x20090, v148
	v_lshlrev_b64 v[174:175], 2, v[206:207]
	v_lshl_add_u64 v[174:175], s[6:7], 0, v[174:175]
	global_load_dwordx4 v[174:177], v[174:175], off
	global_store_dwordx4 v[106:107], v[102:105], off
	s_nop 1
	v_add_u32_e32 v102, 0x4090, v0
	v_mov_b32_e32 v103, v1
	v_lshlrev_b64 v[106:107], 2, v[102:103]
	s_waitcnt vmcnt(19)
	v_pk_add_f32 v[100:101], v[100:101], v[184:185]
	v_pk_add_f32 v[98:99], v[98:99], v[182:183]
	v_lshl_add_u64 v[102:103], s[8:9], 0, v[106:107]
	v_add_u32_e32 v206, 0x24000, v148
	v_lshlrev_b64 v[182:183], 2, v[206:207]
	v_lshl_add_u64 v[182:183], s[6:7], 0, v[182:183]
	global_load_dwordx4 v[182:185], v[182:183], off
	global_store_dwordx4 v[102:103], v[98:101], off
	s_nop 1
	v_add_u32_e32 v98, 0x8000, v0
	v_mov_b32_e32 v99, v1
	v_lshlrev_b64 v[102:103], 2, v[98:99]
	s_waitcnt vmcnt(20)
	v_pk_add_f32 v[96:97], v[96:97], v[188:189]
	v_pk_add_f32 v[94:95], v[94:95], v[186:187]
	v_lshl_add_u64 v[98:99], s[8:9], 0, v[102:103]
	v_add_u32_e32 v206, 0x24010, v148
	v_lshlrev_b64 v[186:187], 2, v[206:207]
	v_lshl_add_u64 v[186:187], s[6:7], 0, v[186:187]
	global_load_dwordx4 v[186:189], v[186:187], off
	global_store_dwordx4 v[98:99], v[94:97], off
	s_nop 1
	v_add_u32_e32 v94, 0x8010, v0
	v_mov_b32_e32 v95, v1
	v_lshlrev_b64 v[98:99], 2, v[94:95]
	s_waitcnt vmcnt(21)
	v_pk_add_f32 v[92:93], v[92:93], v[192:193]
	v_pk_add_f32 v[90:91], v[90:91], v[190:191]
	v_lshl_add_u64 v[94:95], s[8:9], 0, v[98:99]
	v_add_u32_e32 v206, 0x24080, v148
	v_lshlrev_b64 v[190:191], 2, v[206:207]
	v_lshl_add_u64 v[190:191], s[6:7], 0, v[190:191]
	global_load_dwordx4 v[190:193], v[190:191], off
	global_store_dwordx4 v[94:95], v[90:93], off
	s_nop 1
	v_add_u32_e32 v90, 0x8080, v0
	v_mov_b32_e32 v91, v1
	v_lshlrev_b64 v[94:95], 2, v[90:91]
	s_waitcnt vmcnt(22)
	v_pk_add_f32 v[88:89], v[88:89], v[196:197]
	v_pk_add_f32 v[86:87], v[86:87], v[194:195]
	v_lshl_add_u64 v[90:91], s[8:9], 0, v[94:95]
	v_add_u32_e32 v206, 0x24090, v148
	v_lshlrev_b64 v[194:195], 2, v[206:207]
	v_lshl_add_u64 v[194:195], s[6:7], 0, v[194:195]
	global_load_dwordx4 v[194:197], v[194:195], off
	global_store_dwordx4 v[90:91], v[86:89], off
	s_nop 1
	v_add_u32_e32 v86, 0x8090, v0
	v_mov_b32_e32 v87, v1
	v_lshlrev_b64 v[90:91], 2, v[86:87]
	s_waitcnt vmcnt(23)
	v_pk_add_f32 v[84:85], v[84:85], v[200:201]
	v_pk_add_f32 v[82:83], v[82:83], v[198:199]
	v_lshl_add_u64 v[86:87], s[8:9], 0, v[90:91]
	v_add_u32_e32 v206, 0x28000, v148
	v_lshlrev_b64 v[198:199], 2, v[206:207]
	v_lshl_add_u64 v[198:199], s[6:7], 0, v[198:199]
	global_load_dwordx4 v[198:201], v[198:199], off
	global_store_dwordx4 v[86:87], v[82:85], off
	s_nop 1
	v_add_u32_e32 v82, 0xc000, v0
	v_mov_b32_e32 v83, v1
	v_lshlrev_b64 v[86:87], 2, v[82:83]
	s_waitcnt vmcnt(24)
	v_pk_add_f32 v[80:81], v[80:81], v[204:205]
	v_pk_add_f32 v[78:79], v[78:79], v[202:203]
	v_lshl_add_u64 v[82:83], s[8:9], 0, v[86:87]
	v_add_u32_e32 v206, 0x28010, v148
	v_lshlrev_b64 v[202:203], 2, v[206:207]
	v_lshl_add_u64 v[202:203], s[6:7], 0, v[202:203]
	global_load_dwordx4 v[202:205], v[202:203], off
	global_store_dwordx4 v[82:83], v[78:81], off
	s_nop 1
	v_add_u32_e32 v78, 0xc010, v0
	v_mov_b32_e32 v79, v1
	v_lshlrev_b64 v[82:83], 2, v[78:79]
	s_waitcnt vmcnt(25)
	v_pk_add_f32 v[76:77], v[76:77], v[152:153]
	v_pk_add_f32 v[74:75], v[74:75], v[150:151]
	v_lshl_add_u64 v[78:79], s[8:9], 0, v[82:83]
	v_add_u32_e32 v206, 0x28080, v148
	v_lshlrev_b64 v[150:151], 2, v[206:207]
	v_lshl_add_u64 v[150:151], s[6:7], 0, v[150:151]
	global_load_dwordx4 v[150:153], v[150:151], off
	global_store_dwordx4 v[78:79], v[74:77], off
	s_nop 1
	v_add_u32_e32 v74, 0xc080, v0
	v_mov_b32_e32 v75, v1
	v_lshlrev_b64 v[78:79], 2, v[74:75]
	s_waitcnt vmcnt(25)
	v_pk_add_f32 v[72:73], v[72:73], v[156:157]
	v_pk_add_f32 v[70:71], v[70:71], v[154:155]
	v_lshl_add_u64 v[74:75], s[8:9], 0, v[78:79]
	v_add_u32_e32 v206, 0x28090, v148
	v_lshlrev_b64 v[154:155], 2, v[206:207]
	v_lshl_add_u64 v[154:155], s[6:7], 0, v[154:155]
	global_load_dwordx4 v[154:157], v[154:155], off
	global_store_dwordx4 v[74:75], v[70:73], off
	s_nop 1
	v_add_u32_e32 v70, 0xc090, v0
	v_mov_b32_e32 v71, v1
	v_lshlrev_b64 v[74:75], 2, v[70:71]
	s_waitcnt vmcnt(25)
	v_pk_add_f32 v[68:69], v[68:69], v[160:161]
	v_pk_add_f32 v[66:67], v[66:67], v[158:159]
	v_lshl_add_u64 v[70:71], s[8:9], 0, v[74:75]
	v_add_u32_e32 v206, 0x2c000, v148
	v_lshlrev_b64 v[158:159], 2, v[206:207]
	v_lshl_add_u64 v[158:159], s[6:7], 0, v[158:159]
	global_load_dwordx4 v[158:161], v[158:159], off
	global_store_dwordx4 v[70:71], v[66:69], off
	s_nop 1
	v_add_u32_e32 v66, 0x20000, v0
	v_mov_b32_e32 v67, v1
	v_lshlrev_b64 v[70:71], 2, v[66:67]
	s_waitcnt vmcnt(25)
	v_pk_add_f32 v[64:65], v[64:65], v[164:165]
	v_pk_add_f32 v[62:63], v[62:63], v[162:163]
	v_lshl_add_u64 v[66:67], s[8:9], 0, v[70:71]
	v_add_u32_e32 v206, 0x2c010, v148
	v_lshlrev_b64 v[162:163], 2, v[206:207]
	v_lshl_add_u64 v[162:163], s[6:7], 0, v[162:163]
	global_load_dwordx4 v[162:165], v[162:163], off
	global_store_dwordx4 v[66:67], v[62:65], off
	s_nop 1
	v_add_u32_e32 v62, 0x20010, v0
	v_mov_b32_e32 v63, v1
	v_lshlrev_b64 v[66:67], 2, v[62:63]
	s_waitcnt vmcnt(25)
	v_pk_add_f32 v[60:61], v[60:61], v[168:169]
	v_pk_add_f32 v[58:59], v[58:59], v[166:167]
	v_lshl_add_u64 v[62:63], s[8:9], 0, v[66:67]
	v_add_u32_e32 v206, 0x2c080, v148
	v_lshlrev_b64 v[166:167], 2, v[206:207]
	v_lshl_add_u64 v[166:167], s[6:7], 0, v[166:167]
	global_load_dwordx4 v[166:169], v[166:167], off
	global_store_dwordx4 v[62:63], v[58:61], off
	s_nop 1
	v_add_u32_e32 v58, 0x20080, v0
	v_mov_b32_e32 v59, v1
	v_lshlrev_b64 v[62:63], 2, v[58:59]
	s_waitcnt vmcnt(25)
	v_pk_add_f32 v[56:57], v[56:57], v[172:173]
	v_pk_add_f32 v[54:55], v[54:55], v[170:171]
	v_lshl_add_u64 v[58:59], s[8:9], 0, v[62:63]
	v_add_u32_e32 v206, 0x2c090, v148
	v_lshlrev_b64 v[170:171], 2, v[206:207]
	v_lshl_add_u64 v[170:171], s[6:7], 0, v[170:171]
	global_load_dwordx4 v[170:173], v[170:171], off
	global_store_dwordx4 v[58:59], v[54:57], off
	s_nop 1
	v_add_u32_e32 v54, 0x20090, v0
	v_mov_b32_e32 v55, v1
	v_lshlrev_b64 v[58:59], 2, v[54:55]
	s_waitcnt vmcnt(25)
	v_pk_add_f32 v[52:53], v[52:53], v[176:177]
	v_pk_add_f32 v[50:51], v[50:51], v[174:175]
	v_lshl_add_u64 v[54:55], s[8:9], 0, v[58:59]
	global_store_dwordx4 v[54:55], v[50:53], off
	s_nop 1
	v_add_u32_e32 v50, 0x24000, v0
	v_mov_b32_e32 v51, v1
	v_lshlrev_b64 v[54:55], 2, v[50:51]
	s_waitcnt vmcnt(24)
	v_pk_add_f32 v[48:49], v[48:49], v[184:185]
	v_pk_add_f32 v[46:47], v[46:47], v[182:183]
	v_lshl_add_u64 v[50:51], s[8:9], 0, v[54:55]
	global_store_dwordx4 v[50:51], v[46:49], off
	s_nop 1
	v_add_u32_e32 v46, 0x24010, v0
	v_mov_b32_e32 v47, v1
	v_lshlrev_b64 v[50:51], 2, v[46:47]
	s_waitcnt vmcnt(23)
	v_pk_add_f32 v[44:45], v[44:45], v[188:189]
	v_pk_add_f32 v[42:43], v[42:43], v[186:187]
	v_lshl_add_u64 v[46:47], s[8:9], 0, v[50:51]
	global_store_dwordx4 v[46:47], v[42:45], off
	s_nop 1
	v_add_u32_e32 v42, 0x24080, v0
	v_mov_b32_e32 v43, v1
	v_lshlrev_b64 v[46:47], 2, v[42:43]
	s_waitcnt vmcnt(22)
	v_pk_add_f32 v[40:41], v[40:41], v[192:193]
	v_pk_add_f32 v[38:39], v[38:39], v[190:191]
	v_lshl_add_u64 v[42:43], s[8:9], 0, v[46:47]
	global_store_dwordx4 v[42:43], v[38:41], off
	s_nop 1
	v_add_u32_e32 v38, 0x24090, v0
	v_mov_b32_e32 v39, v1
	v_lshlrev_b64 v[42:43], 2, v[38:39]
	s_waitcnt vmcnt(21)
	v_pk_add_f32 v[36:37], v[36:37], v[196:197]
	v_pk_add_f32 v[34:35], v[34:35], v[194:195]
	v_lshl_add_u64 v[38:39], s[8:9], 0, v[42:43]
	global_store_dwordx4 v[38:39], v[34:37], off
	s_nop 1
	v_add_u32_e32 v34, 0x28000, v0
	v_mov_b32_e32 v35, v1
	v_lshlrev_b64 v[38:39], 2, v[34:35]
	s_waitcnt vmcnt(20)
	v_pk_add_f32 v[32:33], v[32:33], v[200:201]
	v_pk_add_f32 v[30:31], v[30:31], v[198:199]
	v_lshl_add_u64 v[34:35], s[8:9], 0, v[38:39]
	global_store_dwordx4 v[34:35], v[30:33], off
	s_nop 1
	v_add_u32_e32 v30, 0x28010, v0
	v_mov_b32_e32 v31, v1
	v_lshlrev_b64 v[34:35], 2, v[30:31]
	s_waitcnt vmcnt(19)
	v_pk_add_f32 v[28:29], v[28:29], v[204:205]
	v_pk_add_f32 v[26:27], v[26:27], v[202:203]
	v_lshl_add_u64 v[30:31], s[8:9], 0, v[34:35]
	global_store_dwordx4 v[30:31], v[26:29], off
	s_nop 1
	v_add_u32_e32 v26, 0x28080, v0
	v_mov_b32_e32 v27, v1
	v_lshlrev_b64 v[30:31], 2, v[26:27]
	s_waitcnt vmcnt(18)
	v_pk_add_f32 v[24:25], v[24:25], v[152:153]
	v_pk_add_f32 v[22:23], v[22:23], v[150:151]
	v_lshl_add_u64 v[26:27], s[8:9], 0, v[30:31]
	global_store_dwordx4 v[26:27], v[22:25], off
	s_nop 1
	v_add_u32_e32 v22, 0x28090, v0
	v_mov_b32_e32 v23, v1
	v_lshlrev_b64 v[26:27], 2, v[22:23]
	s_waitcnt vmcnt(17)
	v_pk_add_f32 v[20:21], v[20:21], v[156:157]
	v_pk_add_f32 v[18:19], v[18:19], v[154:155]
	v_lshl_add_u64 v[22:23], s[8:9], 0, v[26:27]
	global_store_dwordx4 v[22:23], v[18:21], off
	s_nop 1
	v_add_u32_e32 v18, 0x2c000, v0
	v_mov_b32_e32 v19, v1
	v_lshlrev_b64 v[22:23], 2, v[18:19]
	s_waitcnt vmcnt(16)
	v_pk_add_f32 v[16:17], v[16:17], v[160:161]
	v_pk_add_f32 v[14:15], v[14:15], v[158:159]
	v_lshl_add_u64 v[18:19], s[8:9], 0, v[22:23]
	global_store_dwordx4 v[18:19], v[14:17], off
	s_nop 1
	v_add_u32_e32 v14, 0x2c010, v0
	v_mov_b32_e32 v15, v1
	v_lshlrev_b64 v[18:19], 2, v[14:15]
	s_waitcnt vmcnt(15)
	v_pk_add_f32 v[12:13], v[12:13], v[164:165]
	v_pk_add_f32 v[10:11], v[10:11], v[162:163]
	v_lshl_add_u64 v[14:15], s[8:9], 0, v[18:19]
	global_store_dwordx4 v[14:15], v[10:13], off
	s_nop 1
	v_add_u32_e32 v10, 0x2c080, v0
	v_mov_b32_e32 v11, v1
	v_lshlrev_b64 v[14:15], 2, v[10:11]
	v_add_u32_e32 v0, 0x2c090, v0
	s_waitcnt vmcnt(14)
	v_pk_add_f32 v[8:9], v[8:9], v[168:169]
	v_pk_add_f32 v[6:7], v[6:7], v[166:167]
	v_lshl_add_u64 v[10:11], s[8:9], 0, v[14:15]
	global_store_dwordx4 v[10:11], v[6:9], off
	v_lshlrev_b64 v[10:11], 2, v[0:1]
	s_nop 0
	s_waitcnt vmcnt(13)
	v_pk_add_f32 v[4:5], v[4:5], v[172:173]
	v_pk_add_f32 v[2:3], v[2:3], v[170:171]
	v_lshl_add_u64 v[6:7], s[8:9], 0, v[10:11]
	global_store_dwordx4 v[6:7], v[2:5], off
	s_cbranch_vccz .LBB0_1438
	s_waitcnt vmcnt(0)
	v_readlane_b32 s76, v255, 8
	s_mov_b32 s92, 0x3b2aaaab
	s_cmp_gt_u32 s3, 3
	v_readlane_b32 s77, v255, 9
	s_mul_i32 s60, s33, 0x1800
	s_mul_hi_i32 s62, s64, 0x300
	s_mul_i32 s75, s33, 0x16c00
	s_mov_b32 s93, 0x3c800000
	s_cbranch_scc1 .LBB0_1445
	s_barrier
